# speedup vs baseline: 1.0093x; 1.0016x over previous
; #define STAGE_A(P, hf, kt) do { if constexpr (ABLK) { const bf16* _gp = A + ((long)(brow >> 8) * nt + (kt)) * 16384 + (hf) * 8192; GLDS2(_gp, 4096, offA, P); } \
;     else { const bf16* _gp = A + (long)(brow + (hf) * HALF) * lda + (long)(kt) * BK; GLDS2(_gp, 64 * (long)lda, offA, P); } } while (0)
; #define STAGE_B(P, hf, kt) do { const bf16* _gp = Bt + (long)(bcol + (hf) * 2) * ldb + (long)(kt) * BK; GLDS2(_gp, 128 * (long)ldb, offB, P); } while (0)
; #define LDA(dst, b, h) for (int m = 0; m < 4; ++m) for (int k = 0; k < 2; ++k) \
;     dst[m][k] = *reinterpret_cast<const bf16x8*>((char*)SA(b, h) + lds_byte(wr * 64 + m * 16 + fr, k * 32 + fq * 8))
; #define LDB(dst, b, h) for (int n = 0; n < 2; ++n) for (int k = 0; k < 2; ++k) \
;     dst[n][k] = *reinterpret_cast<const bf16x8*>((char*)SB(b, h) + lds_byte(wc * 32 + n * 16 + fr, k * 32 + fq * 8))
; #define MMA(ai, bj, At, Bt_) do { __builtin_amdgcn_s_setprio(1); \
;     for (int m = 0; m < 4; ++m) for (int n = 0; n < 2; ++n) for (int k = 0; k < 2; ++k) \
;       acc[ai][bj][m][n] = __builtin_amdgcn_mfma_f32_16x16x32_bf16(At[m][k], Bt_[n][k], acc[ai][bj][m][n], 0, 0, 0); \
;     __builtin_amdgcn_s_setprio(0); } while (0)
; #define WAIT_V(n) asm volatile("s_waitcnt vmcnt(" #n ")" ::: "memory")
; #define WAIT_L(n) asm volatile("s_waitcnt lgkmcnt(" #n ")" ::: "memory")
; #define BAR __builtin_amdgcn_s_barrier()
; #define SCHED __builtin_amdgcn_sched_barrier(0)
; template <bool ABLK, class Epi>
; __device__ __forceinline__ void gemm_tile(const bf16* __restrict__ A, int lda, const bf16* __restrict__ Bt, int ldb, int K,
;                                           int brow, int bcol, bf16* shm, const Epi& epi, int wv) {
;     ...
;     LDB(B0, 0, 0); SCHED; LDA(At, 0, 0); STAGE_A(SA(1, 1), 1, t + 1);
;     WAIT_L(8); BAR; MMA(0, 0, At, B0); BAR; SCHED;
;     LDB(B1, 0, 1); STAGE_B(SB(0, 0), 0, t + 2);
;     BAR; MMA(0, 1, At, B1); BAR;
;     LDA(At, 0, 1); STAGE_A(SA(0, 0), 0, t + 2);
;     BAR; MMA(1, 0, At, B0); BAR; SCHED;
;     STAGE_B(SB(0, 1), 1, t + 2);
;     WAIT_V(6); BAR; MMA(1, 1, At, B1); BAR;
.LBB0_86:
	ds_read_b128 v[164:167], v161
	ds_read_b128 v[168:171], v161 offset:1024
	ds_read_b128 v[172:175], v161 offset:2048
	ds_read_b128 v[176:179], v161 offset:3072
	v_add_u32_e32 v162, 0xc000, v147
	v_add_u32_e32 v163, 0xe000, v147
	v_lshl_add_u64 v[198:199], v[130:131], 0, s[26:27]
	s_add_i32 m0, s99, 0xc000
	ds_read_b128 v[180:183], v143
	ds_read_b128 v[184:187], v143 offset:1024
	ds_read_b128 v[188:191], v142
	ds_read_b128 v[194:197], v142 offset:1024
	ds_read_b128 v[208:211], v141
	ds_read_b128 v[212:215], v141 offset:1024
	ds_read_b128 v[216:219], v140
	ds_read_b128 v[220:223], v140 offset:1024
	global_load_lds_dwordx4 v[198:199], off
	s_add_i32 m0, s99, 0xe000
	v_lshl_add_u64 v[198:199], v[130:131], 0, s[28:29]
	global_load_lds_dwordx4 v[198:199], off
	s_waitcnt lgkmcnt(8)
	s_barrier
	s_waitcnt lgkmcnt(0)
	v_mfma_f32_16x16x32_bf16 v[124:127], v[180:183], v[164:167], v[124:127]
	v_mfma_f32_16x16x32_bf16 v[120:123], v[180:183], v[172:175], v[120:123]
	v_mfma_f32_16x16x32_bf16 v[116:119], v[188:191], v[164:167], v[116:119]
	v_mfma_f32_16x16x32_bf16 v[112:115], v[188:191], v[172:175], v[112:115]
	v_mfma_f32_16x16x32_bf16 v[108:111], v[208:211], v[164:167], v[108:111]
	v_mfma_f32_16x16x32_bf16 v[104:107], v[208:211], v[172:175], v[104:107]
	v_mfma_f32_16x16x32_bf16 v[100:103], v[216:219], v[164:167], v[100:103]
	v_mfma_f32_16x16x32_bf16 v[96:99], v[216:219], v[172:175], v[96:99]
	v_mfma_f32_16x16x32_bf16 v[124:127], v[184:187], v[168:171], v[124:127]
	v_mfma_f32_16x16x32_bf16 v[120:123], v[184:187], v[176:179], v[120:123]
	v_mfma_f32_16x16x32_bf16 v[116:119], v[194:197], v[168:171], v[116:119]
	v_mfma_f32_16x16x32_bf16 v[112:115], v[194:197], v[176:179], v[112:115]
	v_mfma_f32_16x16x32_bf16 v[108:111], v[212:215], v[168:171], v[108:111]
	v_mfma_f32_16x16x32_bf16 v[104:107], v[212:215], v[176:179], v[104:107]
	v_mfma_f32_16x16x32_bf16 v[100:103], v[220:223], v[168:171], v[100:103]
	v_mfma_f32_16x16x32_bf16 v[96:99], v[220:223], v[176:179], v[96:99]
	s_barrier
	v_lshl_add_u64 v[198:199], v[132:133], 0, s[30:31]
	s_add_i32 m0, s99, 0x10000
	ds_read_b128 v[224:227], v160
	ds_read_b128 v[228:231], v160 offset:1024
	ds_read_b128 v[232:235], v160 offset:2048
	ds_read_b128 v[236:239], v160 offset:3072
	global_load_lds_dwordx4 v[198:199], off
	s_add_i32 m0, s99, 0x12000
	v_lshl_add_u64 v[198:199], v[132:133], 0, s[34:35]
	global_load_lds_dwordx4 v[198:199], off
	s_barrier
	s_waitcnt lgkmcnt(0)
	v_mfma_f32_16x16x32_bf16 v[92:95], v[180:183], v[224:227], v[92:95]
	v_mfma_f32_16x16x32_bf16 v[88:91], v[180:183], v[232:235], v[88:91]
	v_mfma_f32_16x16x32_bf16 v[84:87], v[188:191], v[224:227], v[84:87]
	v_mfma_f32_16x16x32_bf16 v[80:83], v[188:191], v[232:235], v[80:83]
	v_mfma_f32_16x16x32_bf16 v[76:79], v[208:211], v[224:227], v[76:79]
	v_mfma_f32_16x16x32_bf16 v[72:75], v[208:211], v[232:235], v[72:75]
	v_mfma_f32_16x16x32_bf16 v[68:71], v[216:219], v[224:227], v[68:71]
	v_mfma_f32_16x16x32_bf16 v[64:67], v[216:219], v[232:235], v[64:67]
	v_mfma_f32_16x16x32_bf16 v[92:95], v[184:187], v[228:231], v[92:95]
	v_mfma_f32_16x16x32_bf16 v[88:91], v[184:187], v[236:239], v[88:91]
	v_mfma_f32_16x16x32_bf16 v[84:87], v[194:197], v[228:231], v[84:87]
	v_mfma_f32_16x16x32_bf16 v[80:83], v[194:197], v[236:239], v[80:83]
	v_mfma_f32_16x16x32_bf16 v[76:79], v[212:215], v[228:231], v[76:79]
	v_mfma_f32_16x16x32_bf16 v[72:75], v[212:215], v[236:239], v[72:75]
	v_mfma_f32_16x16x32_bf16 v[68:71], v[220:223], v[228:231], v[68:71]
	v_mfma_f32_16x16x32_bf16 v[64:67], v[220:223], v[236:239], v[64:67]
	v_lshl_add_u64 v[198:199], v[130:131], 0, s[36:37]
	s_add_i32 m0, s99, 0x0
	s_barrier
	ds_read_b128 v[180:183], v143 offset:16384
	ds_read_b128 v[184:187], v143 offset:17408
	ds_read_b128 v[188:191], v142 offset:16384
	ds_read_b128 v[194:197], v142 offset:17408
	ds_read_b128 v[208:211], v141 offset:16384
	ds_read_b128 v[212:215], v141 offset:17408
	ds_read_b128 v[216:219], v140 offset:16384
	ds_read_b128 v[220:223], v140 offset:17408
	global_load_lds_dwordx4 v[198:199], off
	s_add_i32 m0, s99, 0x2000
	v_lshl_add_u64 v[198:199], v[130:131], 0, s[38:39]
	global_load_lds_dwordx4 v[198:199], off
	s_barrier
	s_waitcnt lgkmcnt(0)
	v_mfma_f32_16x16x32_bf16 v[60:63], v[180:183], v[164:167], v[60:63]
	v_mfma_f32_16x16x32_bf16 v[56:59], v[180:183], v[172:175], v[56:59]
	v_mfma_f32_16x16x32_bf16 v[52:55], v[188:191], v[164:167], v[52:55]
	v_mfma_f32_16x16x32_bf16 v[48:51], v[188:191], v[172:175], v[48:51]
	v_mfma_f32_16x16x32_bf16 v[44:47], v[208:211], v[164:167], v[44:47]
	v_mfma_f32_16x16x32_bf16 v[40:43], v[208:211], v[172:175], v[40:43]
	v_mfma_f32_16x16x32_bf16 v[36:39], v[216:219], v[164:167], v[36:39]
	v_mfma_f32_16x16x32_bf16 v[32:35], v[216:219], v[172:175], v[32:35]
	v_mfma_f32_16x16x32_bf16 v[60:63], v[184:187], v[168:171], v[60:63]
	v_mfma_f32_16x16x32_bf16 v[56:59], v[184:187], v[176:179], v[56:59]
	v_mfma_f32_16x16x32_bf16 v[52:55], v[194:197], v[168:171], v[52:55]
	v_mfma_f32_16x16x32_bf16 v[48:51], v[194:197], v[176:179], v[48:51]
	v_mfma_f32_16x16x32_bf16 v[44:47], v[212:215], v[168:171], v[44:47]
	v_mfma_f32_16x16x32_bf16 v[40:43], v[212:215], v[176:179], v[40:43]
	v_mfma_f32_16x16x32_bf16 v[36:39], v[220:223], v[168:171], v[36:39]
	v_mfma_f32_16x16x32_bf16 v[32:35], v[220:223], v[176:179], v[32:35]
	s_barrier
	s_add_i32 m0, s99, 0x14000
	v_lshl_add_u64 v[164:165], v[132:133], 0, s[40:41]
	global_load_lds_dwordx4 v[164:165], off
	s_add_i32 m0, s99, 0x16000
	v_lshl_add_u64 v[164:165], v[132:133], 0, s[42:43]
	global_load_lds_dwordx4 v[164:165], off
	s_waitcnt vmcnt(6)
	s_barrier
; #define STAGE_A(P, hf, kt) do { if constexpr (ABLK) { const bf16* _gp = A + ((long)(brow >> 8) * nt + (kt)) * 16384 + (hf) * 8192; GLDS2(_gp, 4096, offA, P); } \
;     else { const bf16* _gp = A + (long)(brow + (hf) * HALF) * lda + (long)(kt) * BK; GLDS2(_gp, 64 * (long)lda, offA, P); } } while (0)
; #define STAGE_B(P, hf, kt) do { const bf16* _gp = Bt + (long)(bcol + (hf) * 2) * ldb + (long)(kt) * BK; GLDS2(_gp, 128 * (long)ldb, offB, P); } while (0)
; #define LDA(dst, b, h) for (int m = 0; m < 4; ++m) for (int k = 0; k < 2; ++k) \
;     dst[m][k] = *reinterpret_cast<const bf16x8*>((char*)SA(b, h) + lds_byte(wr * 64 + m * 16 + fr, k * 32 + fq * 8))
; #define LDB(dst, b, h) for (int n = 0; n < 2; ++n) for (int k = 0; k < 2; ++k) \
;     dst[n][k] = *reinterpret_cast<const bf16x8*>((char*)SB(b, h) + lds_byte(wc * 32 + n * 16 + fr, k * 32 + fq * 8))
; #define MMA(ai, bj, At, Bt_) do { __builtin_amdgcn_s_setprio(1); \
;     for (int m = 0; m < 4; ++m) for (int n = 0; n < 2; ++n) for (int k = 0; k < 2; ++k) \
;       acc[ai][bj][m][n] = __builtin_amdgcn_mfma_f32_16x16x32_bf16(At[m][k], Bt_[n][k], acc[ai][bj][m][n], 0, 0, 0); \
;     __builtin_amdgcn_s_setprio(0); } while (0)
; #define WAIT_V(n) asm volatile("s_waitcnt vmcnt(" #n ")" ::: "memory")
; #define WAIT_L(n) asm volatile("s_waitcnt lgkmcnt(" #n ")" ::: "memory")
; #define BAR __builtin_amdgcn_s_barrier()
; #define SCHED __builtin_amdgcn_sched_barrier(0)
; template <bool ABLK, class Epi>
; __device__ __forceinline__ void gemm_tile(const bf16* __restrict__ A, int lda, const bf16* __restrict__ Bt, int ldb, int K,
;                                           int brow, int bcol, bf16* shm, const Epi& epi, int wv) {
;     ...
;     WAIT_V(6); BAR; MMA(1, 1, At, B1); BAR;
;     LDB(B0, 1, 0); SCHED; LDA(At, 1, 0); STAGE_A(SA(0, 1), 1, t + 2);
;     WAIT_L(8); BAR; MMA(0, 0, At, B0); BAR; SCHED;
;     LDB(B1, 1, 1); STAGE_B(SB(1, 0), 0, t + 3);
;     BAR; MMA(0, 1, At, B1); BAR;
;     LDA(At, 1, 1); STAGE_A(SA(1, 0), 0, t + 3);
	v_mfma_f32_16x16x32_bf16 v[28:31], v[180:183], v[224:227], v[28:31]
	v_mfma_f32_16x16x32_bf16 v[24:27], v[180:183], v[232:235], v[24:27]
	v_mfma_f32_16x16x32_bf16 v[20:23], v[188:191], v[224:227], v[20:23]
	v_mfma_f32_16x16x32_bf16 v[16:19], v[188:191], v[232:235], v[16:19]
	v_mfma_f32_16x16x32_bf16 v[12:15], v[208:211], v[224:227], v[12:15]
	v_mfma_f32_16x16x32_bf16 v[8:11], v[208:211], v[232:235], v[8:11]
	v_mfma_f32_16x16x32_bf16 v[4:7], v[216:219], v[224:227], v[4:7]
	v_mfma_f32_16x16x32_bf16 v[0:3], v[216:219], v[232:235], v[0:3]
	v_mfma_f32_16x16x32_bf16 v[28:31], v[184:187], v[228:231], v[28:31]
	v_mfma_f32_16x16x32_bf16 v[24:27], v[184:187], v[236:239], v[24:27]
	v_mfma_f32_16x16x32_bf16 v[20:23], v[194:197], v[228:231], v[20:23]
	v_mfma_f32_16x16x32_bf16 v[16:19], v[194:197], v[236:239], v[16:19]
	v_mfma_f32_16x16x32_bf16 v[12:15], v[212:215], v[228:231], v[12:15]
	v_mfma_f32_16x16x32_bf16 v[8:11], v[212:215], v[236:239], v[8:11]
	v_mfma_f32_16x16x32_bf16 v[4:7], v[220:223], v[228:231], v[4:7]
	v_mfma_f32_16x16x32_bf16 v[0:3], v[220:223], v[236:239], v[0:3]
	s_barrier
	ds_read_b128 v[164:167], v149
	ds_read_b128 v[168:171], v149 offset:1024
	ds_read_b128 v[172:175], v149 offset:2048
	ds_read_b128 v[176:179], v149 offset:3072
	v_lshl_add_u64 v[198:199], v[130:131], 0, s[44:45]
	s_add_i32 m0, s99, 0x4000
	ds_read_b128 v[180:183], v143 offset:32768
	ds_read_b128 v[184:187], v143 offset:33792
	ds_read_b128 v[188:191], v142 offset:32768
	ds_read_b128 v[194:197], v142 offset:33792
	ds_read_b128 v[208:211], v141 offset:32768
	ds_read_b128 v[212:215], v141 offset:33792
	ds_read_b128 v[216:219], v140 offset:32768
	ds_read_b128 v[220:223], v140 offset:33792
	global_load_lds_dwordx4 v[198:199], off
	s_add_i32 m0, s99, 0x6000
	v_lshl_add_u64 v[198:199], v[130:131], 0, s[46:47]
	global_load_lds_dwordx4 v[198:199], off
	s_waitcnt lgkmcnt(8)
	s_barrier
	s_waitcnt lgkmcnt(0)
	v_mfma_f32_16x16x32_bf16 v[124:127], v[180:183], v[164:167], v[124:127]
	v_mfma_f32_16x16x32_bf16 v[120:123], v[180:183], v[172:175], v[120:123]
	v_mfma_f32_16x16x32_bf16 v[116:119], v[188:191], v[164:167], v[116:119]
	v_mfma_f32_16x16x32_bf16 v[112:115], v[188:191], v[172:175], v[112:115]
	v_mfma_f32_16x16x32_bf16 v[108:111], v[208:211], v[164:167], v[108:111]
	v_mfma_f32_16x16x32_bf16 v[104:107], v[208:211], v[172:175], v[104:107]
	v_mfma_f32_16x16x32_bf16 v[100:103], v[216:219], v[164:167], v[100:103]
	v_mfma_f32_16x16x32_bf16 v[96:99], v[216:219], v[172:175], v[96:99]
	v_mfma_f32_16x16x32_bf16 v[124:127], v[184:187], v[168:171], v[124:127]
	v_mfma_f32_16x16x32_bf16 v[120:123], v[184:187], v[176:179], v[120:123]
	v_mfma_f32_16x16x32_bf16 v[116:119], v[194:197], v[168:171], v[116:119]
	v_mfma_f32_16x16x32_bf16 v[112:115], v[194:197], v[176:179], v[112:115]
	v_mfma_f32_16x16x32_bf16 v[108:111], v[212:215], v[168:171], v[108:111]
	v_mfma_f32_16x16x32_bf16 v[104:107], v[212:215], v[176:179], v[104:107]
	v_mfma_f32_16x16x32_bf16 v[100:103], v[220:223], v[168:171], v[100:103]
	v_mfma_f32_16x16x32_bf16 v[96:99], v[220:223], v[176:179], v[96:99]
	s_barrier
	v_lshl_add_u64 v[198:199], v[132:133], 0, s[48:49]
	s_add_i32 m0, s99, 0x18000
	ds_read_b128 v[224:227], v146
	ds_read_b128 v[228:231], v146 offset:1024
	ds_read_b128 v[232:235], v146 offset:2048
	ds_read_b128 v[236:239], v146 offset:3072
	global_load_lds_dwordx4 v[198:199], off
	s_add_i32 m0, s99, 0x1a000
	v_lshl_add_u64 v[198:199], v[132:133], 0, s[50:51]
	global_load_lds_dwordx4 v[198:199], off
	s_barrier
	s_waitcnt lgkmcnt(0)
	v_mfma_f32_16x16x32_bf16 v[92:95], v[180:183], v[224:227], v[92:95]
	v_mfma_f32_16x16x32_bf16 v[88:91], v[180:183], v[232:235], v[88:91]
	v_mfma_f32_16x16x32_bf16 v[84:87], v[188:191], v[224:227], v[84:87]
	v_mfma_f32_16x16x32_bf16 v[80:83], v[188:191], v[232:235], v[80:83]
	v_mfma_f32_16x16x32_bf16 v[76:79], v[208:211], v[224:227], v[76:79]
	v_mfma_f32_16x16x32_bf16 v[72:75], v[208:211], v[232:235], v[72:75]
	v_mfma_f32_16x16x32_bf16 v[68:71], v[216:219], v[224:227], v[68:71]
	v_mfma_f32_16x16x32_bf16 v[64:67], v[216:219], v[232:235], v[64:67]
	v_mfma_f32_16x16x32_bf16 v[92:95], v[184:187], v[228:231], v[92:95]
	v_mfma_f32_16x16x32_bf16 v[88:91], v[184:187], v[236:239], v[88:91]
	v_mfma_f32_16x16x32_bf16 v[84:87], v[194:197], v[228:231], v[84:87]
	v_mfma_f32_16x16x32_bf16 v[80:83], v[194:197], v[236:239], v[80:83]
	v_mfma_f32_16x16x32_bf16 v[76:79], v[212:215], v[228:231], v[76:79]
	v_mfma_f32_16x16x32_bf16 v[72:75], v[212:215], v[236:239], v[72:75]
	v_mfma_f32_16x16x32_bf16 v[68:71], v[220:223], v[228:231], v[68:71]
	v_mfma_f32_16x16x32_bf16 v[64:67], v[220:223], v[236:239], v[64:67]
	v_lshl_add_u64 v[198:199], v[130:131], 0, s[50:51]
	s_add_i32 m0, s99, 0x8000
	s_barrier
	ds_read_b128 v[180:183], v143 offset:49152
	ds_read_b128 v[184:187], v143 offset:50176
	ds_read_b128 v[188:191], v142 offset:49152
	ds_read_b128 v[194:197], v142 offset:50176
	ds_read_b128 v[208:211], v141 offset:49152
	ds_read_b128 v[212:215], v141 offset:50176
	ds_read_b128 v[216:219], v140 offset:49152
	ds_read_b128 v[220:223], v140 offset:50176
	global_load_lds_dwordx4 v[198:199], off
	s_add_i32 m0, s99, 0xa000
	s_nop 0
	global_load_lds_dwordx4 v[130:131], off
	s_barrier
; #define STAGE_A(P, hf, kt) do { if constexpr (ABLK) { const bf16* _gp = A + ((long)(brow >> 8) * nt + (kt)) * 16384 + (hf) * 8192; GLDS2(_gp, 4096, offA, P); } \
;     else { const bf16* _gp = A + (long)(brow + (hf) * HALF) * lda + (long)(kt) * BK; GLDS2(_gp, 64 * (long)lda, offA, P); } } while (0)
; #define STAGE_B(P, hf, kt) do { const bf16* _gp = Bt + (long)(bcol + (hf) * 2) * ldb + (long)(kt) * BK; GLDS2(_gp, 128 * (long)ldb, offB, P); } while (0)
; #define LDA(dst, b, h) for (int m = 0; m < 4; ++m) for (int k = 0; k < 2; ++k) \
;     dst[m][k] = *reinterpret_cast<const bf16x8*>((char*)SA(b, h) + lds_byte(wr * 64 + m * 16 + fr, k * 32 + fq * 8))
; #define LDB(dst, b, h) for (int n = 0; n < 2; ++n) for (int k = 0; k < 2; ++k) \
;     dst[n][k] = *reinterpret_cast<const bf16x8*>((char*)SB(b, h) + lds_byte(wc * 32 + n * 16 + fr, k * 32 + fq * 8))
; #define MMA(ai, bj, At, Bt_) do { __builtin_amdgcn_s_setprio(1); \
;     for (int m = 0; m < 4; ++m) for (int n = 0; n < 2; ++n) for (int k = 0; k < 2; ++k) \
;       acc[ai][bj][m][n] = __builtin_amdgcn_mfma_f32_16x16x32_bf16(At[m][k], Bt_[n][k], acc[ai][bj][m][n], 0, 0, 0); \
;     __builtin_amdgcn_s_setprio(0); } while (0)
; #define WAIT_V(n) asm volatile("s_waitcnt vmcnt(" #n ")" ::: "memory")
; #define WAIT_L(n) asm volatile("s_waitcnt lgkmcnt(" #n ")" ::: "memory")
; #define BAR __builtin_amdgcn_s_barrier()
; #define SCHED __builtin_amdgcn_sched_barrier(0)
; template <bool ABLK, class Epi>
; __device__ __forceinline__ void gemm_tile(const bf16* __restrict__ A, int lda, const bf16* __restrict__ Bt, int ldb, int K,
;                                           int brow, int bcol, bf16* shm, const Epi& epi, int wv) {
;     ...
;     BAR; MMA(1, 0, At, B0); BAR; SCHED;
;     STAGE_B(SB(1, 1), 1, t + 3);
;     WAIT_V(6); BAR; MMA(1, 1, At, B1); BAR;
;   }
;   { LDB(B0, 0, 0); LDA(At, 0, 0); STAGE_A(SA(1, 1), 1, nt - 1);
;     BAR; WAIT_L(0); MMA(0, 0, At, B0); BAR;
;     LDB(B1, 0, 1); BAR; WAIT_L(0); MMA(0, 1, At, B1); BAR;
	s_waitcnt lgkmcnt(0)
	v_mfma_f32_16x16x32_bf16 v[60:63], v[180:183], v[164:167], v[60:63]
	v_mfma_f32_16x16x32_bf16 v[56:59], v[180:183], v[172:175], v[56:59]
	v_mfma_f32_16x16x32_bf16 v[52:55], v[188:191], v[164:167], v[52:55]
	v_mfma_f32_16x16x32_bf16 v[48:51], v[188:191], v[172:175], v[48:51]
	v_mfma_f32_16x16x32_bf16 v[44:47], v[208:211], v[164:167], v[44:47]
	v_mfma_f32_16x16x32_bf16 v[40:43], v[208:211], v[172:175], v[40:43]
	v_mfma_f32_16x16x32_bf16 v[36:39], v[216:219], v[164:167], v[36:39]
	v_mfma_f32_16x16x32_bf16 v[32:35], v[216:219], v[172:175], v[32:35]
	v_mfma_f32_16x16x32_bf16 v[60:63], v[184:187], v[168:171], v[60:63]
	v_mfma_f32_16x16x32_bf16 v[56:59], v[184:187], v[176:179], v[56:59]
	v_mfma_f32_16x16x32_bf16 v[52:55], v[194:197], v[168:171], v[52:55]
	v_mfma_f32_16x16x32_bf16 v[48:51], v[194:197], v[176:179], v[48:51]
	v_mfma_f32_16x16x32_bf16 v[44:47], v[212:215], v[168:171], v[44:47]
	v_mfma_f32_16x16x32_bf16 v[40:43], v[212:215], v[176:179], v[40:43]
	v_mfma_f32_16x16x32_bf16 v[36:39], v[220:223], v[168:171], v[36:39]
	v_mfma_f32_16x16x32_bf16 v[32:35], v[220:223], v[176:179], v[32:35]
	s_barrier
	s_add_i32 m0, s99, 0x1c000
	v_lshl_add_u64 v[164:165], v[132:133], 0, s[52:53]
	global_load_lds_dwordx4 v[164:165], off
	s_add_i32 m0, s99, 0x1e000
	s_nop 0
	global_load_lds_dwordx4 v[132:133], off
	s_waitcnt vmcnt(6)
	s_barrier
	v_mfma_f32_16x16x32_bf16 v[28:31], v[180:183], v[224:227], v[28:31]
	v_mfma_f32_16x16x32_bf16 v[24:27], v[180:183], v[232:235], v[24:27]
	v_mfma_f32_16x16x32_bf16 v[20:23], v[188:191], v[224:227], v[20:23]
	v_mfma_f32_16x16x32_bf16 v[16:19], v[188:191], v[232:235], v[16:19]
	v_mfma_f32_16x16x32_bf16 v[12:15], v[208:211], v[224:227], v[12:15]
	v_mfma_f32_16x16x32_bf16 v[8:11], v[208:211], v[232:235], v[8:11]
	v_mfma_f32_16x16x32_bf16 v[4:7], v[216:219], v[224:227], v[4:7]
	v_mfma_f32_16x16x32_bf16 v[0:3], v[216:219], v[232:235], v[0:3]
	v_mfma_f32_16x16x32_bf16 v[28:31], v[184:187], v[228:231], v[28:31]
	v_mfma_f32_16x16x32_bf16 v[24:27], v[184:187], v[236:239], v[24:27]
	v_mfma_f32_16x16x32_bf16 v[20:23], v[194:197], v[228:231], v[20:23]
	v_mfma_f32_16x16x32_bf16 v[16:19], v[194:197], v[236:239], v[16:19]
	v_mfma_f32_16x16x32_bf16 v[12:15], v[212:215], v[228:231], v[12:15]
	v_mfma_f32_16x16x32_bf16 v[8:11], v[212:215], v[236:239], v[8:11]
	v_mfma_f32_16x16x32_bf16 v[4:7], v[220:223], v[228:231], v[4:7]
	v_mfma_f32_16x16x32_bf16 v[0:3], v[220:223], v[236:239], v[0:3]
	s_add_i32 s33, s33, 2
	v_lshl_add_u64 v[130:131], v[130:131], 0, s[54:55]
	s_cmp_lt_u32 s33, 28
	v_lshl_add_u64 v[132:133], v[132:133], 0, s[56:57]
	s_barrier
	s_cbranch_scc1 .LBB0_86
	v_readfirstlane_b32 s2, v162
	v_lshl_add_u64 v[144:145], v[128:129], 0, s[58:59]
	s_mov_b32 m0, s2
	v_readfirstlane_b32 s2, v163
	ds_read_b128 v[130:133], v161
	ds_read_b128 v[150:153], v161 offset:1024
	ds_read_b128 v[154:157], v161 offset:2048
	ds_read_b128 v[164:167], v161 offset:3072
	ds_read_b128 v[168:171], v143
	ds_read_b128 v[172:175], v143 offset:1024
	ds_read_b128 v[176:179], v142
	ds_read_b128 v[180:183], v142 offset:1024
	ds_read_b128 v[184:187], v141
	ds_read_b128 v[188:191], v141 offset:1024
	ds_read_b128 v[194:197], v140
	ds_read_b128 v[208:211], v140 offset:1024
	global_load_lds_dwordx4 v[144:145], off
	v_lshl_add_u64 v[128:129], v[128:129], 0, s[60:61]
	s_mov_b32 m0, s2
	s_nop 0
	global_load_lds_dwordx4 v[128:129], off
	s_barrier
	s_waitcnt lgkmcnt(0)
	s_waitcnt lgkmcnt(0)
	v_mfma_f32_16x16x32_bf16 v[124:127], v[168:171], v[130:133], v[124:127]
	v_mfma_f32_16x16x32_bf16 v[120:123], v[168:171], v[154:157], v[120:123]
	v_mfma_f32_16x16x32_bf16 v[108:111], v[184:187], v[130:133], v[108:111]
	v_mfma_f32_16x16x32_bf16 v[104:107], v[184:187], v[154:157], v[104:107]
	v_mfma_f32_16x16x32_bf16 v[124:127], v[172:175], v[150:153], v[124:127]
	v_mfma_f32_16x16x32_bf16 v[120:123], v[172:175], v[164:167], v[120:123]
	v_mfma_f32_16x16x32_bf16 v[116:119], v[176:179], v[130:133], v[116:119]
	v_mfma_f32_16x16x32_bf16 v[112:115], v[176:179], v[154:157], v[112:115]
	v_mfma_f32_16x16x32_bf16 v[108:111], v[188:191], v[150:153], v[108:111]
	v_mfma_f32_16x16x32_bf16 v[104:107], v[188:191], v[164:167], v[104:107]
	v_mfma_f32_16x16x32_bf16 v[100:103], v[194:197], v[130:133], v[100:103]
	v_mfma_f32_16x16x32_bf16 v[96:99], v[194:197], v[154:157], v[96:99]
	v_mfma_f32_16x16x32_bf16 v[212:215], v[180:183], v[150:153], v[116:119]
	v_mfma_f32_16x16x32_bf16 v[216:219], v[180:183], v[164:167], v[112:115]
	v_mfma_f32_16x16x32_bf16 v[220:223], v[208:211], v[150:153], v[100:103]
	v_mfma_f32_16x16x32_bf16 v[224:227], v[208:211], v[164:167], v[96:99]
	s_barrier
	s_nop 1
	ds_read_b128 v[96:99], v160
	ds_read_b128 v[100:103], v160 offset:1024
	ds_read_b128 v[112:115], v160 offset:2048
	ds_read_b128 v[116:119], v160 offset:3072
	s_barrier
	s_waitcnt lgkmcnt(0)
	s_waitcnt lgkmcnt(0)
	v_mfma_f32_16x16x32_bf16 v[92:95], v[168:171], v[96:99], v[92:95]
	v_mfma_f32_16x16x32_bf16 v[88:91], v[168:171], v[112:115], v[88:91]
	v_mfma_f32_16x16x32_bf16 v[76:79], v[184:187], v[96:99], v[76:79]
	v_mfma_f32_16x16x32_bf16 v[72:75], v[184:187], v[112:115], v[72:75]
	v_mfma_f32_16x16x32_bf16 v[92:95], v[172:175], v[100:103], v[92:95]
	v_mfma_f32_16x16x32_bf16 v[88:91], v[172:175], v[116:119], v[88:91]
	v_mfma_f32_16x16x32_bf16 v[84:87], v[176:179], v[96:99], v[84:87]
	v_mfma_f32_16x16x32_bf16 v[80:83], v[176:179], v[112:115], v[80:83]
	v_mfma_f32_16x16x32_bf16 v[76:79], v[188:191], v[100:103], v[76:79]
	v_mfma_f32_16x16x32_bf16 v[72:75], v[188:191], v[116:119], v[72:75]
	v_mfma_f32_16x16x32_bf16 v[68:71], v[194:197], v[96:99], v[68:71]
	v_mfma_f32_16x16x32_bf16 v[64:67], v[194:197], v[112:115], v[64:67]
	v_mfma_f32_16x16x32_bf16 v[158:161], v[180:183], v[100:103], v[84:87]
	v_mfma_f32_16x16x32_bf16 v[168:171], v[180:183], v[116:119], v[80:83]
	v_mfma_f32_16x16x32_bf16 v[172:175], v[208:211], v[100:103], v[68:71]
	v_mfma_f32_16x16x32_bf16 v[176:179], v[208:211], v[116:119], v[64:67]
	s_barrier
; #define LDA(dst, b, h) for (int m = 0; m < 4; ++m) for (int k = 0; k < 2; ++k) \
;     dst[m][k] = *reinterpret_cast<const bf16x8*>((char*)SA(b, h) + lds_byte(wr * 64 + m * 16 + fr, k * 32 + fq * 8))
; #define LDB(dst, b, h) for (int n = 0; n < 2; ++n) for (int k = 0; k < 2; ++k) \
;     dst[n][k] = *reinterpret_cast<const bf16x8*>((char*)SB(b, h) + lds_byte(wc * 32 + n * 16 + fr, k * 32 + fq * 8))
; #define MMA(ai, bj, At, Bt_) do { __builtin_amdgcn_s_setprio(1); \
;     for (int m = 0; m < 4; ++m) for (int n = 0; n < 2; ++n) for (int k = 0; k < 2; ++k) \
;       acc[ai][bj][m][n] = __builtin_amdgcn_mfma_f32_16x16x32_bf16(At[m][k], Bt_[n][k], acc[ai][bj][m][n], 0, 0, 0); \
;     __builtin_amdgcn_s_setprio(0); } while (0)
; #define WAIT_V(n) asm volatile("s_waitcnt vmcnt(" #n ")" ::: "memory")
; #define WAIT_L(n) asm volatile("s_waitcnt lgkmcnt(" #n ")" ::: "memory")
; #define BAR __builtin_amdgcn_s_barrier()
; template <bool ABLK, class Epi>
; __device__ __forceinline__ void gemm_tile(const bf16* __restrict__ A, int lda, const bf16* __restrict__ Bt, int ldb, int K,
;                                           int brow, int bcol, bf16* shm, const Epi& epi, int wv) {
;     ...
;     LDA(At, 0, 1); WAIT_V(4); BAR; WAIT_L(0); MMA(1, 0, At, B0); MMA(1, 1, At, B1); BAR; }
;   { LDB(B0, 1, 0); LDA(At, 1, 0); WAIT_V(2); BAR; WAIT_L(0); MMA(0, 0, At, B0); BAR;
	s_nop 1
	ds_read_b128 v[64:67], v143 offset:16384
	ds_read_b128 v[68:71], v143 offset:17408
	ds_read_b128 v[80:83], v142 offset:16384
	ds_read_b128 v[84:87], v142 offset:17408
	ds_read_b128 v[180:183], v141 offset:16384
	ds_read_b128 v[184:187], v141 offset:17408
	ds_read_b128 v[188:191], v140 offset:16384
	ds_read_b128 v[194:197], v140 offset:17408
	s_waitcnt vmcnt(4)
	s_barrier
	s_waitcnt lgkmcnt(0)
	s_waitcnt lgkmcnt(0)
	v_mfma_f32_16x16x32_bf16 v[60:63], v[64:67], v[130:133], v[60:63]
	v_mfma_f32_16x16x32_bf16 v[56:59], v[64:67], v[154:157], v[56:59]
	v_mfma_f32_16x16x32_bf16 v[44:47], v[180:183], v[130:133], v[44:47]
	v_mfma_f32_16x16x32_bf16 v[40:43], v[180:183], v[154:157], v[40:43]
	v_mfma_f32_16x16x32_bf16 v[60:63], v[68:71], v[150:153], v[60:63]
	v_mfma_f32_16x16x32_bf16 v[56:59], v[68:71], v[164:167], v[56:59]
	v_mfma_f32_16x16x32_bf16 v[52:55], v[80:83], v[130:133], v[52:55]
	v_mfma_f32_16x16x32_bf16 v[48:51], v[80:83], v[154:157], v[48:51]
	v_mfma_f32_16x16x32_bf16 v[44:47], v[184:187], v[150:153], v[44:47]
	v_mfma_f32_16x16x32_bf16 v[40:43], v[184:187], v[164:167], v[40:43]
	v_mfma_f32_16x16x32_bf16 v[36:39], v[188:191], v[130:133], v[36:39]
	v_mfma_f32_16x16x32_bf16 v[32:35], v[188:191], v[154:157], v[32:35]
	v_mfma_f32_16x16x32_bf16 v[208:211], v[84:87], v[150:153], v[52:55]
	v_mfma_f32_16x16x32_bf16 v[228:231], v[84:87], v[164:167], v[48:51]
	v_mfma_f32_16x16x32_bf16 v[128:131], v[194:197], v[150:153], v[36:39]
	v_mfma_f32_16x16x32_bf16 v[150:153], v[194:197], v[164:167], v[32:35]
	v_mfma_f32_16x16x32_bf16 v[28:31], v[64:67], v[96:99], v[28:31]
	v_mfma_f32_16x16x32_bf16 v[24:27], v[64:67], v[112:115], v[24:27]
	v_mfma_f32_16x16x32_bf16 v[12:15], v[180:183], v[96:99], v[12:15]
	v_mfma_f32_16x16x32_bf16 v[8:11], v[180:183], v[112:115], v[8:11]
	v_mfma_f32_16x16x32_bf16 v[28:31], v[68:71], v[100:103], v[28:31]
	v_mfma_f32_16x16x32_bf16 v[24:27], v[68:71], v[116:119], v[24:27]
	v_mfma_f32_16x16x32_bf16 v[20:23], v[80:83], v[96:99], v[20:23]
	v_mfma_f32_16x16x32_bf16 v[16:19], v[80:83], v[112:115], v[16:19]
	v_mfma_f32_16x16x32_bf16 v[12:15], v[184:187], v[100:103], v[12:15]
	v_mfma_f32_16x16x32_bf16 v[8:11], v[184:187], v[116:119], v[8:11]
	v_mfma_f32_16x16x32_bf16 v[4:7], v[188:191], v[96:99], v[4:7]
	v_mfma_f32_16x16x32_bf16 v[0:3], v[188:191], v[112:115], v[0:3]
	v_mfma_f32_16x16x32_bf16 v[154:157], v[84:87], v[100:103], v[20:23]
	v_mfma_f32_16x16x32_bf16 v[162:165], v[84:87], v[116:119], v[16:19]
	v_mfma_f32_16x16x32_bf16 v[180:183], v[194:197], v[100:103], v[4:7]
	v_mfma_f32_16x16x32_bf16 v[184:187], v[194:197], v[116:119], v[0:3]
	s_barrier
	s_nop 1
	ds_read_b128 v[0:3], v149
	ds_read_b128 v[4:7], v149 offset:1024
	ds_read_b128 v[188:191], v149 offset:2048
	ds_read_b128 v[194:197], v149 offset:3072
	ds_read_b128 v[16:19], v143 offset:32768
	ds_read_b128 v[20:23], v143 offset:33792
	ds_read_b128 v[32:35], v142 offset:32768
	ds_read_b128 v[36:39], v142 offset:33792
	ds_read_b128 v[48:51], v141 offset:32768
	ds_read_b128 v[52:55], v141 offset:33792
	ds_read_b128 v[232:235], v140 offset:32768
	ds_read_b128 v[236:239], v140 offset:33792
	s_waitcnt vmcnt(2)
	s_barrier
	s_waitcnt lgkmcnt(0)
	s_waitcnt lgkmcnt(0)
	v_mfma_f32_16x16x32_bf16 v[64:67], v[16:19], v[0:3], v[124:127]
	v_mfma_f32_16x16x32_bf16 v[112:115], v[20:23], v[4:7], v[64:67]
	v_mfma_f32_16x16x32_bf16 v[64:67], v[16:19], v[188:191], v[120:123]
	v_mfma_f32_16x16x32_bf16 v[116:119], v[20:23], v[194:197], v[64:67]
	v_mfma_f32_16x16x32_bf16 v[64:67], v[32:35], v[0:3], v[212:215]
	v_mfma_f32_16x16x32_bf16 v[96:99], v[36:39], v[4:7], v[64:67]
	v_mfma_f32_16x16x32_bf16 v[64:67], v[32:35], v[188:191], v[216:219]
	v_mfma_f32_16x16x32_bf16 v[100:103], v[36:39], v[194:197], v[64:67]
	v_mfma_f32_16x16x32_bf16 v[64:67], v[48:51], v[0:3], v[108:111]
	v_mfma_f32_16x16x32_bf16 v[80:83], v[52:55], v[4:7], v[64:67]
	v_mfma_f32_16x16x32_bf16 v[64:67], v[48:51], v[188:191], v[104:107]
	v_mfma_f32_16x16x32_bf16 v[84:87], v[52:55], v[194:197], v[64:67]
	v_mfma_f32_16x16x32_bf16 v[64:67], v[232:235], v[0:3], v[220:223]
	v_mfma_f32_16x16x32_bf16 v[68:71], v[232:235], v[188:191], v[224:227]
	v_mfma_f32_16x16x32_bf16 v[64:67], v[236:239], v[4:7], v[64:67]
	v_mfma_f32_16x16x32_bf16 v[68:71], v[236:239], v[194:197], v[68:71]
	s_barrier
; #define LDA(dst, b, h) for (int m = 0; m < 4; ++m) for (int k = 0; k < 2; ++k) \
;     dst[m][k] = *reinterpret_cast<const bf16x8*>((char*)SA(b, h) + lds_byte(wr * 64 + m * 16 + fr, k * 32 + fq * 8))
; #define LDB(dst, b, h) for (int n = 0; n < 2; ++n) for (int k = 0; k < 2; ++k) \
;     dst[n][k] = *reinterpret_cast<const bf16x8*>((char*)SB(b, h) + lds_byte(wc * 32 + n * 16 + fr, k * 32 + fq * 8))
; #define MMA(ai, bj, At, Bt_) do { __builtin_amdgcn_s_setprio(1); \
;     for (int m = 0; m < 4; ++m) for (int n = 0; n < 2; ++n) for (int k = 0; k < 2; ++k) \
;       acc[ai][bj][m][n] = __builtin_amdgcn_mfma_f32_16x16x32_bf16(At[m][k], Bt_[n][k], acc[ai][bj][m][n], 0, 0, 0); \
;     __builtin_amdgcn_s_setprio(0); } while (0)
; #define WAIT_V(n) asm volatile("s_waitcnt vmcnt(" #n ")" ::: "memory")
; #define WAIT_L(n) asm volatile("s_waitcnt lgkmcnt(" #n ")" ::: "memory")
; #define BAR __builtin_amdgcn_s_barrier()
; template <bool ABLK, class Epi>
; __device__ __forceinline__ void gemm_tile(const bf16* __restrict__ A, int lda, const bf16* __restrict__ Bt, int ldb, int K,
;                                           int brow, int bcol, bf16* shm, const Epi& epi, int wv) {
;     ...
;     LDB(B1, 1, 1); WAIT_V(0); BAR; WAIT_L(0); MMA(0, 1, At, B1); BAR;
;     LDA(At, 1, 1); BAR; WAIT_L(0); MMA(1, 0, At, B0); MMA(1, 1, At, B1); BAR; }
;   if (wr == 0) BAR;
	ds_read_b128 v[212:215], v146
	ds_read_b128 v[216:219], v146 offset:1024
	ds_read_b128 v[220:223], v146 offset:2048
	ds_read_b128 v[144:147], v146 offset:3072
	s_waitcnt vmcnt(0)
	s_barrier
	s_waitcnt lgkmcnt(0)
	s_waitcnt lgkmcnt(0)
	v_mfma_f32_16x16x32_bf16 v[92:95], v[16:19], v[212:215], v[92:95]
	v_mfma_f32_16x16x32_bf16 v[16:19], v[16:19], v[220:223], v[88:91]
	v_mfma_f32_16x16x32_bf16 v[124:127], v[20:23], v[144:147], v[16:19]
	v_mfma_f32_16x16x32_bf16 v[16:19], v[32:35], v[212:215], v[158:161]
	v_mfma_f32_16x16x32_bf16 v[104:107], v[36:39], v[216:219], v[16:19]
	v_mfma_f32_16x16x32_bf16 v[16:19], v[32:35], v[220:223], v[168:171]
	v_mfma_f32_16x16x32_bf16 v[108:111], v[36:39], v[144:147], v[16:19]
	v_mfma_f32_16x16x32_bf16 v[16:19], v[48:51], v[212:215], v[76:79]
	v_mfma_f32_16x16x32_bf16 v[88:91], v[52:55], v[216:219], v[16:19]
	v_mfma_f32_16x16x32_bf16 v[16:19], v[48:51], v[220:223], v[72:75]
	v_mfma_f32_16x16x32_bf16 v[120:123], v[20:23], v[216:219], v[92:95]
	v_mfma_f32_16x16x32_bf16 v[92:95], v[52:55], v[144:147], v[16:19]
	v_mfma_f32_16x16x32_bf16 v[16:19], v[232:235], v[212:215], v[172:175]
	v_mfma_f32_16x16x32_bf16 v[72:75], v[236:239], v[216:219], v[16:19]
	v_mfma_f32_16x16x32_bf16 v[16:19], v[232:235], v[220:223], v[176:179]
	v_mfma_f32_16x16x32_bf16 v[76:79], v[236:239], v[144:147], v[16:19]
	s_barrier
	ds_read_b128 v[158:161], v143 offset:49152
	ds_read_b128 v[166:169], v143 offset:50176
	ds_read_b128 v[170:173], v142 offset:49152
	ds_read_b128 v[174:177], v142 offset:50176
	ds_read_b128 v[224:227], v141 offset:49152
	ds_read_b128 v[232:235], v141 offset:50176
	ds_read_b128 v[236:239], v140 offset:49152
	ds_read_b128 v[140:143], v140 offset:50176
	s_barrier
	s_waitcnt lgkmcnt(0)
	s_waitcnt lgkmcnt(0)
	v_mfma_f32_16x16x32_bf16 v[16:19], v[158:161], v[0:3], v[60:63]
	v_mfma_f32_16x16x32_bf16 v[48:51], v[166:169], v[4:7], v[16:19]
	v_mfma_f32_16x16x32_bf16 v[16:19], v[158:161], v[188:191], v[56:59]
	v_mfma_f32_16x16x32_bf16 v[52:55], v[166:169], v[194:197], v[16:19]
	v_mfma_f32_16x16x32_bf16 v[16:19], v[170:173], v[0:3], v[208:211]
	v_mfma_f32_16x16x32_bf16 v[32:35], v[174:177], v[4:7], v[16:19]
	v_mfma_f32_16x16x32_bf16 v[16:19], v[170:173], v[188:191], v[228:231]
	v_mfma_f32_16x16x32_bf16 v[36:39], v[174:177], v[194:197], v[16:19]
	v_mfma_f32_16x16x32_bf16 v[16:19], v[224:227], v[0:3], v[44:47]
	v_mfma_f32_16x16x32_bf16 v[0:3], v[236:239], v[0:3], v[128:131]
	v_mfma_f32_16x16x32_bf16 v[16:19], v[232:235], v[4:7], v[16:19]
	v_mfma_f32_16x16x32_bf16 v[20:23], v[224:227], v[188:191], v[40:43]
	v_mfma_f32_16x16x32_bf16 v[0:3], v[140:143], v[4:7], v[0:3]
	v_mfma_f32_16x16x32_bf16 v[4:7], v[236:239], v[188:191], v[150:153]
	v_mfma_f32_16x16x32_bf16 v[20:23], v[232:235], v[194:197], v[20:23]
	v_mfma_f32_16x16x32_bf16 v[4:7], v[140:143], v[194:197], v[4:7]
	v_mfma_f32_16x16x32_bf16 v[24:27], v[158:161], v[220:223], v[24:27]
	v_mfma_f32_16x16x32_bf16 v[60:63], v[166:169], v[144:147], v[24:27]
	v_mfma_f32_16x16x32_bf16 v[24:27], v[170:173], v[212:215], v[154:157]
	v_mfma_f32_16x16x32_bf16 v[28:31], v[158:161], v[212:215], v[28:31]
	v_mfma_f32_16x16x32_bf16 v[40:43], v[174:177], v[216:219], v[24:27]
	v_mfma_f32_16x16x32_bf16 v[24:27], v[170:173], v[220:223], v[162:165]
	v_mfma_f32_16x16x32_bf16 v[12:15], v[224:227], v[212:215], v[12:15]
	v_mfma_f32_16x16x32_bf16 v[8:11], v[224:227], v[220:223], v[8:11]
	v_mfma_f32_16x16x32_bf16 v[56:59], v[166:169], v[216:219], v[28:31]
	v_mfma_f32_16x16x32_bf16 v[44:47], v[174:177], v[144:147], v[24:27]
	v_mfma_f32_16x16x32_bf16 v[24:27], v[232:235], v[216:219], v[12:15]
	v_mfma_f32_16x16x32_bf16 v[28:31], v[232:235], v[144:147], v[8:11]
	v_mfma_f32_16x16x32_bf16 v[8:11], v[236:239], v[212:215], v[180:183]
	v_mfma_f32_16x16x32_bf16 v[12:15], v[236:239], v[220:223], v[184:187]
	v_mfma_f32_16x16x32_bf16 v[8:11], v[140:143], v[216:219], v[8:11]
	v_mfma_f32_16x16x32_bf16 v[12:15], v[140:143], v[144:147], v[12:15]
	v_cmp_gt_u32_e32 vcc, s81, v135
	s_barrier
	s_and_saveexec_b64 s[66:67], vcc
	s_cbranch_execz .LBB0_82
	s_barrier
	s_branch .LBB0_82

; #define STAGE_A(P, hf, kt) do { if constexpr (ABLK) { const bf16* _gp = A + ((long)(brow >> 8) * nt + (kt)) * 16384 + (hf) * 8192; GLDS2(_gp, 4096, offA, P); } \
;     else { const bf16* _gp = A + (long)(brow + (hf) * HALF) * lda + (long)(kt) * BK; GLDS2(_gp, 64 * (long)lda, offA, P); } } while (0)
; #define STAGE_B(P, hf, kt) do { const bf16* _gp = Bt + (long)(bcol + (hf) * 2) * ldb + (long)(kt) * BK; GLDS2(_gp, 128 * (long)ldb, offB, P); } while (0)
; #define LDA(dst, b, h) for (int m = 0; m < 4; ++m) for (int k = 0; k < 2; ++k) \
;     dst[m][k] = *reinterpret_cast<const bf16x8*>((char*)SA(b, h) + lds_byte(wr * 64 + m * 16 + fr, k * 32 + fq * 8))
; #define LDB(dst, b, h) for (int n = 0; n < 2; ++n) for (int k = 0; k < 2; ++k) \
;     dst[n][k] = *reinterpret_cast<const bf16x8*>((char*)SB(b, h) + lds_byte(wc * 32 + n * 16 + fr, k * 32 + fq * 8))
; #define MMA(ai, bj, At, Bt_) do { __builtin_amdgcn_s_setprio(1); \
;     for (int m = 0; m < 4; ++m) for (int n = 0; n < 2; ++n) for (int k = 0; k < 2; ++k) \
;       acc[ai][bj][m][n] = __builtin_amdgcn_mfma_f32_16x16x32_bf16(At[m][k], Bt_[n][k], acc[ai][bj][m][n], 0, 0, 0); \
;     __builtin_amdgcn_s_setprio(0); } while (0)
; #define WAIT_V(n) asm volatile("s_waitcnt vmcnt(" #n ")" ::: "memory")
; #define WAIT_L(n) asm volatile("s_waitcnt lgkmcnt(" #n ")" ::: "memory")
; #define BAR __builtin_amdgcn_s_barrier()
; #define SCHED __builtin_amdgcn_sched_barrier(0)
; template <bool ABLK, class Epi>
; __device__ __forceinline__ void gemm_tile(const bf16* __restrict__ A, int lda, const bf16* __restrict__ Bt, int ldb, int K,
;                                           int brow, int bcol, bf16* shm, const Epi& epi, int wv) {
;     ...
;     LDB(B0, 0, 0); SCHED; LDA(At, 0, 0); STAGE_A(SA(1, 1), 1, t + 1);
;     WAIT_L(8); BAR; MMA(0, 0, At, B0); BAR; SCHED;
;     LDB(B1, 0, 1); STAGE_B(SB(0, 0), 0, t + 2);
;     BAR; MMA(0, 1, At, B1); BAR;
;     LDA(At, 0, 1); STAGE_A(SA(0, 0), 0, t + 2);
;     BAR; MMA(1, 0, At, B0); BAR; SCHED;
;     STAGE_B(SB(0, 1), 1, t + 2);
;     WAIT_V(6); BAR; MMA(1, 1, At, B1); BAR;
.LBB0_370:
	ds_read_b128 v[166:169], v162
	ds_read_b128 v[170:173], v162 offset:1024
	ds_read_b128 v[174:177], v162 offset:2048
	ds_read_b128 v[178:181], v162 offset:3072
	v_add_u32_e32 v163, 0xc000, v148
	v_lshl_add_u64 v[164:165], v[132:133], 0, s[22:23]
	s_add_i32 m0, s99, 0xc000
	ds_read_b128 v[182:185], v144
	ds_read_b128 v[186:189], v144 offset:1024
	ds_read_b128 v[194:197], v143
	ds_read_b128 v[202:205], v143 offset:1024
	ds_read_b128 v[208:211], v142
	ds_read_b128 v[212:215], v142 offset:1024
	ds_read_b128 v[216:219], v141
	ds_read_b128 v[220:223], v141 offset:1024
	global_load_lds_dwordx4 v[164:165], off
	v_add_u32_e32 v164, 0xe000, v148
	s_add_i32 m0, s99, 0xe000
	v_lshl_add_u64 v[190:191], v[132:133], 0, s[24:25]
	global_load_lds_dwordx4 v[190:191], off
	s_waitcnt lgkmcnt(8)
	s_barrier
	s_waitcnt lgkmcnt(0)
	v_mfma_f32_16x16x32_bf16 v[124:127], v[182:185], v[166:169], v[124:127]
	v_mfma_f32_16x16x32_bf16 v[120:123], v[182:185], v[174:177], v[120:123]
	v_mfma_f32_16x16x32_bf16 v[116:119], v[194:197], v[166:169], v[116:119]
	v_mfma_f32_16x16x32_bf16 v[112:115], v[194:197], v[174:177], v[112:115]
	v_mfma_f32_16x16x32_bf16 v[108:111], v[208:211], v[166:169], v[108:111]
	v_mfma_f32_16x16x32_bf16 v[104:107], v[208:211], v[174:177], v[104:107]
	v_mfma_f32_16x16x32_bf16 v[100:103], v[216:219], v[166:169], v[100:103]
	v_mfma_f32_16x16x32_bf16 v[96:99], v[216:219], v[174:177], v[96:99]
	v_mfma_f32_16x16x32_bf16 v[124:127], v[186:189], v[170:173], v[124:127]
	v_mfma_f32_16x16x32_bf16 v[120:123], v[186:189], v[178:181], v[120:123]
	v_mfma_f32_16x16x32_bf16 v[116:119], v[202:205], v[170:173], v[116:119]
	v_mfma_f32_16x16x32_bf16 v[112:115], v[202:205], v[178:181], v[112:115]
	v_mfma_f32_16x16x32_bf16 v[108:111], v[212:215], v[170:173], v[108:111]
	v_mfma_f32_16x16x32_bf16 v[104:107], v[212:215], v[178:181], v[104:107]
	v_mfma_f32_16x16x32_bf16 v[100:103], v[220:223], v[170:173], v[100:103]
	v_mfma_f32_16x16x32_bf16 v[96:99], v[220:223], v[178:181], v[96:99]
	s_barrier
	v_lshl_add_u64 v[190:191], v[134:135], 0, s[26:27]
	s_add_i32 m0, s99, 0x10000
	ds_read_b128 v[224:227], v161
	ds_read_b128 v[228:231], v161 offset:1024
	ds_read_b128 v[232:235], v161 offset:2048
	ds_read_b128 v[236:239], v161 offset:3072
	global_load_lds_dwordx4 v[190:191], off
	s_add_i32 m0, s99, 0x12000
	v_lshl_add_u64 v[190:191], v[134:135], 0, s[28:29]
	global_load_lds_dwordx4 v[190:191], off
	s_barrier
	s_waitcnt lgkmcnt(0)
	v_mfma_f32_16x16x32_bf16 v[92:95], v[182:185], v[224:227], v[92:95]
	v_mfma_f32_16x16x32_bf16 v[88:91], v[182:185], v[232:235], v[88:91]
	v_mfma_f32_16x16x32_bf16 v[84:87], v[194:197], v[224:227], v[84:87]
	v_mfma_f32_16x16x32_bf16 v[80:83], v[194:197], v[232:235], v[80:83]
	v_mfma_f32_16x16x32_bf16 v[76:79], v[208:211], v[224:227], v[76:79]
	v_mfma_f32_16x16x32_bf16 v[72:75], v[208:211], v[232:235], v[72:75]
	v_mfma_f32_16x16x32_bf16 v[68:71], v[216:219], v[224:227], v[68:71]
	v_mfma_f32_16x16x32_bf16 v[64:67], v[216:219], v[232:235], v[64:67]
	v_mfma_f32_16x16x32_bf16 v[92:95], v[186:189], v[228:231], v[92:95]
	v_mfma_f32_16x16x32_bf16 v[88:91], v[186:189], v[236:239], v[88:91]
	v_mfma_f32_16x16x32_bf16 v[84:87], v[202:205], v[228:231], v[84:87]
	v_mfma_f32_16x16x32_bf16 v[80:83], v[202:205], v[236:239], v[80:83]
	v_mfma_f32_16x16x32_bf16 v[76:79], v[212:215], v[228:231], v[76:79]
	v_mfma_f32_16x16x32_bf16 v[72:75], v[212:215], v[236:239], v[72:75]
	v_mfma_f32_16x16x32_bf16 v[68:71], v[220:223], v[228:231], v[68:71]
	v_mfma_f32_16x16x32_bf16 v[64:67], v[220:223], v[236:239], v[64:67]
	v_lshl_add_u64 v[190:191], v[132:133], 0, s[30:31]
	s_add_i32 m0, s99, 0x0
	s_barrier
	ds_read_b128 v[182:185], v144 offset:16384
	ds_read_b128 v[186:189], v144 offset:17408
	ds_read_b128 v[194:197], v143 offset:16384
	ds_read_b128 v[202:205], v143 offset:17408
	ds_read_b128 v[208:211], v142 offset:16384
	ds_read_b128 v[212:215], v142 offset:17408
	ds_read_b128 v[216:219], v141 offset:16384
	ds_read_b128 v[220:223], v141 offset:17408
	global_load_lds_dwordx4 v[190:191], off
	s_add_i32 m0, s99, 0x2000
	v_lshl_add_u64 v[190:191], v[132:133], 0, s[34:35]
	global_load_lds_dwordx4 v[190:191], off
	s_barrier
	s_waitcnt lgkmcnt(0)
	v_mfma_f32_16x16x32_bf16 v[60:63], v[182:185], v[166:169], v[60:63]
	v_mfma_f32_16x16x32_bf16 v[56:59], v[182:185], v[174:177], v[56:59]
	v_mfma_f32_16x16x32_bf16 v[52:55], v[194:197], v[166:169], v[52:55]
	v_mfma_f32_16x16x32_bf16 v[48:51], v[194:197], v[174:177], v[48:51]
	v_mfma_f32_16x16x32_bf16 v[44:47], v[208:211], v[166:169], v[44:47]
	v_mfma_f32_16x16x32_bf16 v[40:43], v[208:211], v[174:177], v[40:43]
	v_mfma_f32_16x16x32_bf16 v[36:39], v[216:219], v[166:169], v[36:39]
	v_mfma_f32_16x16x32_bf16 v[32:35], v[216:219], v[174:177], v[32:35]
	v_mfma_f32_16x16x32_bf16 v[60:63], v[186:189], v[170:173], v[60:63]
	v_mfma_f32_16x16x32_bf16 v[56:59], v[186:189], v[178:181], v[56:59]
	v_mfma_f32_16x16x32_bf16 v[52:55], v[202:205], v[170:173], v[52:55]
	v_mfma_f32_16x16x32_bf16 v[48:51], v[202:205], v[178:181], v[48:51]
	v_mfma_f32_16x16x32_bf16 v[44:47], v[212:215], v[170:173], v[44:47]
	v_mfma_f32_16x16x32_bf16 v[40:43], v[212:215], v[178:181], v[40:43]
	v_mfma_f32_16x16x32_bf16 v[36:39], v[220:223], v[170:173], v[36:39]
	v_mfma_f32_16x16x32_bf16 v[32:35], v[220:223], v[178:181], v[32:35]
	s_barrier
	s_add_i32 m0, s99, 0x14000
	v_lshl_add_u64 v[166:167], v[134:135], 0, s[36:37]
	global_load_lds_dwordx4 v[166:167], off
	s_add_i32 m0, s99, 0x16000
	v_lshl_add_u64 v[166:167], v[134:135], 0, s[38:39]
	global_load_lds_dwordx4 v[166:167], off
	s_waitcnt vmcnt(6)
	s_barrier
; #define STAGE_A(P, hf, kt) do { if constexpr (ABLK) { const bf16* _gp = A + ((long)(brow >> 8) * nt + (kt)) * 16384 + (hf) * 8192; GLDS2(_gp, 4096, offA, P); } \
;     else { const bf16* _gp = A + (long)(brow + (hf) * HALF) * lda + (long)(kt) * BK; GLDS2(_gp, 64 * (long)lda, offA, P); } } while (0)
; #define STAGE_B(P, hf, kt) do { const bf16* _gp = Bt + (long)(bcol + (hf) * 2) * ldb + (long)(kt) * BK; GLDS2(_gp, 128 * (long)ldb, offB, P); } while (0)
; #define LDA(dst, b, h) for (int m = 0; m < 4; ++m) for (int k = 0; k < 2; ++k) \
;     dst[m][k] = *reinterpret_cast<const bf16x8*>((char*)SA(b, h) + lds_byte(wr * 64 + m * 16 + fr, k * 32 + fq * 8))
; #define LDB(dst, b, h) for (int n = 0; n < 2; ++n) for (int k = 0; k < 2; ++k) \
;     dst[n][k] = *reinterpret_cast<const bf16x8*>((char*)SB(b, h) + lds_byte(wc * 32 + n * 16 + fr, k * 32 + fq * 8))
; #define MMA(ai, bj, At, Bt_) do { __builtin_amdgcn_s_setprio(1); \
;     for (int m = 0; m < 4; ++m) for (int n = 0; n < 2; ++n) for (int k = 0; k < 2; ++k) \
;       acc[ai][bj][m][n] = __builtin_amdgcn_mfma_f32_16x16x32_bf16(At[m][k], Bt_[n][k], acc[ai][bj][m][n], 0, 0, 0); \
;     __builtin_amdgcn_s_setprio(0); } while (0)
; #define WAIT_V(n) asm volatile("s_waitcnt vmcnt(" #n ")" ::: "memory")
; #define WAIT_L(n) asm volatile("s_waitcnt lgkmcnt(" #n ")" ::: "memory")
; #define BAR __builtin_amdgcn_s_barrier()
; #define SCHED __builtin_amdgcn_sched_barrier(0)
; template <bool ABLK, class Epi>
; __device__ __forceinline__ void gemm_tile(const bf16* __restrict__ A, int lda, const bf16* __restrict__ Bt, int ldb, int K,
;                                           int brow, int bcol, bf16* shm, const Epi& epi, int wv) {
;     ...
;     WAIT_V(6); BAR; MMA(1, 1, At, B1); BAR;
;     LDB(B0, 1, 0); SCHED; LDA(At, 1, 0); STAGE_A(SA(0, 1), 1, t + 2);
;     WAIT_L(8); BAR; MMA(0, 0, At, B0); BAR; SCHED;
;     LDB(B1, 1, 1); STAGE_B(SB(1, 0), 0, t + 3);
;     BAR; MMA(0, 1, At, B1); BAR;
;     LDA(At, 1, 1); STAGE_A(SA(1, 0), 0, t + 3);
	v_mfma_f32_16x16x32_bf16 v[28:31], v[182:185], v[224:227], v[28:31]
	v_mfma_f32_16x16x32_bf16 v[24:27], v[182:185], v[232:235], v[24:27]
	v_mfma_f32_16x16x32_bf16 v[20:23], v[194:197], v[224:227], v[20:23]
	v_mfma_f32_16x16x32_bf16 v[16:19], v[194:197], v[232:235], v[16:19]
	v_mfma_f32_16x16x32_bf16 v[12:15], v[208:211], v[224:227], v[12:15]
	v_mfma_f32_16x16x32_bf16 v[8:11], v[208:211], v[232:235], v[8:11]
	v_mfma_f32_16x16x32_bf16 v[4:7], v[216:219], v[224:227], v[4:7]
	v_mfma_f32_16x16x32_bf16 v[0:3], v[216:219], v[232:235], v[0:3]
	v_mfma_f32_16x16x32_bf16 v[28:31], v[186:189], v[228:231], v[28:31]
	v_mfma_f32_16x16x32_bf16 v[24:27], v[186:189], v[236:239], v[24:27]
	v_mfma_f32_16x16x32_bf16 v[20:23], v[202:205], v[228:231], v[20:23]
	v_mfma_f32_16x16x32_bf16 v[16:19], v[202:205], v[236:239], v[16:19]
	v_mfma_f32_16x16x32_bf16 v[12:15], v[212:215], v[228:231], v[12:15]
	v_mfma_f32_16x16x32_bf16 v[8:11], v[212:215], v[236:239], v[8:11]
	v_mfma_f32_16x16x32_bf16 v[4:7], v[220:223], v[228:231], v[4:7]
	v_mfma_f32_16x16x32_bf16 v[0:3], v[220:223], v[236:239], v[0:3]
	s_barrier
	ds_read_b128 v[166:169], v151
	ds_read_b128 v[170:173], v151 offset:1024
	ds_read_b128 v[174:177], v151 offset:2048
	ds_read_b128 v[178:181], v151 offset:3072
	v_lshl_add_u64 v[190:191], v[132:133], 0, s[40:41]
	s_add_i32 m0, s99, 0x4000
	ds_read_b128 v[182:185], v144 offset:32768
	ds_read_b128 v[186:189], v144 offset:33792
	ds_read_b128 v[194:197], v143 offset:32768
	ds_read_b128 v[202:205], v143 offset:33792
	ds_read_b128 v[208:211], v142 offset:32768
	ds_read_b128 v[212:215], v142 offset:33792
	ds_read_b128 v[216:219], v141 offset:32768
	ds_read_b128 v[220:223], v141 offset:33792
	global_load_lds_dwordx4 v[190:191], off
	s_add_i32 m0, s99, 0x6000
	v_lshl_add_u64 v[190:191], v[132:133], 0, s[42:43]
	global_load_lds_dwordx4 v[190:191], off
	s_waitcnt lgkmcnt(8)
	s_barrier
	s_waitcnt lgkmcnt(0)
	v_mfma_f32_16x16x32_bf16 v[124:127], v[182:185], v[166:169], v[124:127]
	v_mfma_f32_16x16x32_bf16 v[120:123], v[182:185], v[174:177], v[120:123]
	v_mfma_f32_16x16x32_bf16 v[116:119], v[194:197], v[166:169], v[116:119]
	v_mfma_f32_16x16x32_bf16 v[112:115], v[194:197], v[174:177], v[112:115]
	v_mfma_f32_16x16x32_bf16 v[108:111], v[208:211], v[166:169], v[108:111]
	v_mfma_f32_16x16x32_bf16 v[104:107], v[208:211], v[174:177], v[104:107]
	v_mfma_f32_16x16x32_bf16 v[100:103], v[216:219], v[166:169], v[100:103]
	v_mfma_f32_16x16x32_bf16 v[96:99], v[216:219], v[174:177], v[96:99]
	v_mfma_f32_16x16x32_bf16 v[124:127], v[186:189], v[170:173], v[124:127]
	v_mfma_f32_16x16x32_bf16 v[120:123], v[186:189], v[178:181], v[120:123]
	v_mfma_f32_16x16x32_bf16 v[116:119], v[202:205], v[170:173], v[116:119]
	v_mfma_f32_16x16x32_bf16 v[112:115], v[202:205], v[178:181], v[112:115]
	v_mfma_f32_16x16x32_bf16 v[108:111], v[212:215], v[170:173], v[108:111]
	v_mfma_f32_16x16x32_bf16 v[104:107], v[212:215], v[178:181], v[104:107]
	v_mfma_f32_16x16x32_bf16 v[100:103], v[220:223], v[170:173], v[100:103]
	v_mfma_f32_16x16x32_bf16 v[96:99], v[220:223], v[178:181], v[96:99]
	s_barrier
	v_lshl_add_u64 v[190:191], v[134:135], 0, s[44:45]
	s_add_i32 m0, s99, 0x18000
	ds_read_b128 v[224:227], v147
	ds_read_b128 v[228:231], v147 offset:1024
	ds_read_b128 v[232:235], v147 offset:2048
	ds_read_b128 v[236:239], v147 offset:3072
	global_load_lds_dwordx4 v[190:191], off
	s_add_i32 m0, s99, 0x1a000
	v_lshl_add_u64 v[190:191], v[134:135], 0, s[46:47]
	global_load_lds_dwordx4 v[190:191], off
	s_barrier
	s_waitcnt lgkmcnt(0)
	v_mfma_f32_16x16x32_bf16 v[92:95], v[182:185], v[224:227], v[92:95]
	v_mfma_f32_16x16x32_bf16 v[88:91], v[182:185], v[232:235], v[88:91]
	v_mfma_f32_16x16x32_bf16 v[84:87], v[194:197], v[224:227], v[84:87]
	v_mfma_f32_16x16x32_bf16 v[80:83], v[194:197], v[232:235], v[80:83]
	v_mfma_f32_16x16x32_bf16 v[76:79], v[208:211], v[224:227], v[76:79]
	v_mfma_f32_16x16x32_bf16 v[72:75], v[208:211], v[232:235], v[72:75]
	v_mfma_f32_16x16x32_bf16 v[68:71], v[216:219], v[224:227], v[68:71]
	v_mfma_f32_16x16x32_bf16 v[64:67], v[216:219], v[232:235], v[64:67]
	v_mfma_f32_16x16x32_bf16 v[92:95], v[186:189], v[228:231], v[92:95]
	v_mfma_f32_16x16x32_bf16 v[88:91], v[186:189], v[236:239], v[88:91]
	v_mfma_f32_16x16x32_bf16 v[84:87], v[202:205], v[228:231], v[84:87]
	v_mfma_f32_16x16x32_bf16 v[80:83], v[202:205], v[236:239], v[80:83]
	v_mfma_f32_16x16x32_bf16 v[76:79], v[212:215], v[228:231], v[76:79]
	v_mfma_f32_16x16x32_bf16 v[72:75], v[212:215], v[236:239], v[72:75]
	v_mfma_f32_16x16x32_bf16 v[68:71], v[220:223], v[228:231], v[68:71]
	v_mfma_f32_16x16x32_bf16 v[64:67], v[220:223], v[236:239], v[64:67]
	v_lshl_add_u64 v[190:191], v[132:133], 0, s[46:47]
	s_add_i32 m0, s99, 0x8000
	s_barrier
	ds_read_b128 v[182:185], v144 offset:49152
	ds_read_b128 v[186:189], v144 offset:50176
	ds_read_b128 v[194:197], v143 offset:49152
	ds_read_b128 v[202:205], v143 offset:50176
	ds_read_b128 v[208:211], v142 offset:49152
	ds_read_b128 v[212:215], v142 offset:50176
	ds_read_b128 v[216:219], v141 offset:49152
	ds_read_b128 v[220:223], v141 offset:50176
	global_load_lds_dwordx4 v[190:191], off
	s_add_i32 m0, s99, 0xa000
	s_nop 0
	global_load_lds_dwordx4 v[132:133], off
	s_barrier
; #define STAGE_A(P, hf, kt) do { if constexpr (ABLK) { const bf16* _gp = A + ((long)(brow >> 8) * nt + (kt)) * 16384 + (hf) * 8192; GLDS2(_gp, 4096, offA, P); } \
;     else { const bf16* _gp = A + (long)(brow + (hf) * HALF) * lda + (long)(kt) * BK; GLDS2(_gp, 64 * (long)lda, offA, P); } } while (0)
; #define STAGE_B(P, hf, kt) do { const bf16* _gp = Bt + (long)(bcol + (hf) * 2) * ldb + (long)(kt) * BK; GLDS2(_gp, 128 * (long)ldb, offB, P); } while (0)
; #define LDA(dst, b, h) for (int m = 0; m < 4; ++m) for (int k = 0; k < 2; ++k) \
;     dst[m][k] = *reinterpret_cast<const bf16x8*>((char*)SA(b, h) + lds_byte(wr * 64 + m * 16 + fr, k * 32 + fq * 8))
; #define LDB(dst, b, h) for (int n = 0; n < 2; ++n) for (int k = 0; k < 2; ++k) \
;     dst[n][k] = *reinterpret_cast<const bf16x8*>((char*)SB(b, h) + lds_byte(wc * 32 + n * 16 + fr, k * 32 + fq * 8))
; #define MMA(ai, bj, At, Bt_) do { __builtin_amdgcn_s_setprio(1); \
;     for (int m = 0; m < 4; ++m) for (int n = 0; n < 2; ++n) for (int k = 0; k < 2; ++k) \
;       acc[ai][bj][m][n] = __builtin_amdgcn_mfma_f32_16x16x32_bf16(At[m][k], Bt_[n][k], acc[ai][bj][m][n], 0, 0, 0); \
;     __builtin_amdgcn_s_setprio(0); } while (0)
; #define WAIT_V(n) asm volatile("s_waitcnt vmcnt(" #n ")" ::: "memory")
; #define WAIT_L(n) asm volatile("s_waitcnt lgkmcnt(" #n ")" ::: "memory")
; #define BAR __builtin_amdgcn_s_barrier()
; #define SCHED __builtin_amdgcn_sched_barrier(0)
; template <bool ABLK, class Epi>
; __device__ __forceinline__ void gemm_tile(const bf16* __restrict__ A, int lda, const bf16* __restrict__ Bt, int ldb, int K,
;                                           int brow, int bcol, bf16* shm, const Epi& epi, int wv) {
;     ...
;     BAR; MMA(1, 0, At, B0); BAR; SCHED;
;     STAGE_B(SB(1, 1), 1, t + 3);
;     WAIT_V(6); BAR; MMA(1, 1, At, B1); BAR;
;   }
;   { LDB(B0, 0, 0); LDA(At, 0, 0); STAGE_A(SA(1, 1), 1, nt - 1);
;     BAR; WAIT_L(0); MMA(0, 0, At, B0); BAR;
;     LDB(B1, 0, 1); BAR; WAIT_L(0); MMA(0, 1, At, B1); BAR;
	s_waitcnt lgkmcnt(0)
	v_mfma_f32_16x16x32_bf16 v[60:63], v[182:185], v[166:169], v[60:63]
	v_mfma_f32_16x16x32_bf16 v[56:59], v[182:185], v[174:177], v[56:59]
	v_mfma_f32_16x16x32_bf16 v[52:55], v[194:197], v[166:169], v[52:55]
	v_mfma_f32_16x16x32_bf16 v[48:51], v[194:197], v[174:177], v[48:51]
	v_mfma_f32_16x16x32_bf16 v[44:47], v[208:211], v[166:169], v[44:47]
	v_mfma_f32_16x16x32_bf16 v[40:43], v[208:211], v[174:177], v[40:43]
	v_mfma_f32_16x16x32_bf16 v[36:39], v[216:219], v[166:169], v[36:39]
	v_mfma_f32_16x16x32_bf16 v[32:35], v[216:219], v[174:177], v[32:35]
	v_mfma_f32_16x16x32_bf16 v[60:63], v[186:189], v[170:173], v[60:63]
	v_mfma_f32_16x16x32_bf16 v[56:59], v[186:189], v[178:181], v[56:59]
	v_mfma_f32_16x16x32_bf16 v[52:55], v[202:205], v[170:173], v[52:55]
	v_mfma_f32_16x16x32_bf16 v[48:51], v[202:205], v[178:181], v[48:51]
	v_mfma_f32_16x16x32_bf16 v[44:47], v[212:215], v[170:173], v[44:47]
	v_mfma_f32_16x16x32_bf16 v[40:43], v[212:215], v[178:181], v[40:43]
	v_mfma_f32_16x16x32_bf16 v[36:39], v[220:223], v[170:173], v[36:39]
	v_mfma_f32_16x16x32_bf16 v[32:35], v[220:223], v[178:181], v[32:35]
	s_barrier
	s_add_i32 m0, s99, 0x1c000
	v_lshl_add_u64 v[166:167], v[134:135], 0, s[48:49]
	global_load_lds_dwordx4 v[166:167], off
	s_add_i32 m0, s99, 0x1e000
	s_nop 0
	global_load_lds_dwordx4 v[134:135], off
	s_waitcnt vmcnt(6)
	s_barrier
	v_mfma_f32_16x16x32_bf16 v[28:31], v[182:185], v[224:227], v[28:31]
	v_mfma_f32_16x16x32_bf16 v[24:27], v[182:185], v[232:235], v[24:27]
	v_mfma_f32_16x16x32_bf16 v[20:23], v[194:197], v[224:227], v[20:23]
	v_mfma_f32_16x16x32_bf16 v[16:19], v[194:197], v[232:235], v[16:19]
	v_mfma_f32_16x16x32_bf16 v[12:15], v[208:211], v[224:227], v[12:15]
	v_mfma_f32_16x16x32_bf16 v[8:11], v[208:211], v[232:235], v[8:11]
	v_mfma_f32_16x16x32_bf16 v[4:7], v[216:219], v[224:227], v[4:7]
	v_mfma_f32_16x16x32_bf16 v[0:3], v[216:219], v[232:235], v[0:3]
	v_mfma_f32_16x16x32_bf16 v[28:31], v[186:189], v[228:231], v[28:31]
	v_mfma_f32_16x16x32_bf16 v[24:27], v[186:189], v[236:239], v[24:27]
	v_mfma_f32_16x16x32_bf16 v[20:23], v[202:205], v[228:231], v[20:23]
	v_mfma_f32_16x16x32_bf16 v[16:19], v[202:205], v[236:239], v[16:19]
	v_mfma_f32_16x16x32_bf16 v[12:15], v[212:215], v[228:231], v[12:15]
	v_mfma_f32_16x16x32_bf16 v[8:11], v[212:215], v[236:239], v[8:11]
	v_mfma_f32_16x16x32_bf16 v[4:7], v[220:223], v[228:231], v[4:7]
	v_mfma_f32_16x16x32_bf16 v[0:3], v[220:223], v[236:239], v[0:3]
	s_add_i32 s33, s33, 2
	v_lshl_add_u64 v[132:133], v[132:133], 0, s[50:51]
	s_cmp_lt_u32 s33, 28
	v_lshl_add_u64 v[134:135], v[134:135], 0, s[52:53]
	s_barrier
	s_cbranch_scc1 .LBB0_370
	v_readfirstlane_b32 s2, v163
	v_lshl_add_u64 v[148:149], v[130:131], 0, s[54:55]
	s_mov_b32 m0, s2
	v_readfirstlane_b32 s2, v164
	ds_read_b128 v[132:135], v162
	ds_read_b128 v[152:155], v162 offset:1024
	ds_read_b128 v[156:159], v162 offset:2048
	ds_read_b128 v[166:169], v162 offset:3072
	ds_read_b128 v[170:173], v144
	ds_read_b128 v[174:177], v144 offset:1024
	ds_read_b128 v[178:181], v143
	ds_read_b128 v[182:185], v143 offset:1024
	ds_read_b128 v[186:189], v142
	ds_read_b128 v[194:197], v142 offset:1024
	ds_read_b128 v[202:205], v141
	ds_read_b128 v[208:211], v141 offset:1024
	global_load_lds_dwordx4 v[148:149], off
	v_lshl_add_u64 v[130:131], v[130:131], 0, s[56:57]
	s_mov_b32 m0, s2
	s_nop 0
	global_load_lds_dwordx4 v[130:131], off
	s_barrier
	s_waitcnt lgkmcnt(0)
	s_waitcnt lgkmcnt(0)
	v_mfma_f32_16x16x32_bf16 v[124:127], v[170:173], v[132:135], v[124:127]
	v_mfma_f32_16x16x32_bf16 v[120:123], v[170:173], v[156:159], v[120:123]
	v_mfma_f32_16x16x32_bf16 v[108:111], v[186:189], v[132:135], v[108:111]
	v_mfma_f32_16x16x32_bf16 v[104:107], v[186:189], v[156:159], v[104:107]
	v_mfma_f32_16x16x32_bf16 v[124:127], v[174:177], v[152:155], v[124:127]
	v_mfma_f32_16x16x32_bf16 v[120:123], v[174:177], v[166:169], v[120:123]
	v_mfma_f32_16x16x32_bf16 v[116:119], v[178:181], v[132:135], v[116:119]
	v_mfma_f32_16x16x32_bf16 v[112:115], v[178:181], v[156:159], v[112:115]
	v_mfma_f32_16x16x32_bf16 v[108:111], v[194:197], v[152:155], v[108:111]
	v_mfma_f32_16x16x32_bf16 v[104:107], v[194:197], v[166:169], v[104:107]
	v_mfma_f32_16x16x32_bf16 v[100:103], v[202:205], v[132:135], v[100:103]
	v_mfma_f32_16x16x32_bf16 v[96:99], v[202:205], v[156:159], v[96:99]
	v_mfma_f32_16x16x32_bf16 v[162:165], v[182:185], v[152:155], v[116:119]
	v_mfma_f32_16x16x32_bf16 v[212:215], v[182:185], v[166:169], v[112:115]
	v_mfma_f32_16x16x32_bf16 v[216:219], v[208:211], v[152:155], v[100:103]
	v_mfma_f32_16x16x32_bf16 v[220:223], v[208:211], v[166:169], v[96:99]
	s_barrier
	s_nop 1
	ds_read_b128 v[96:99], v161
	ds_read_b128 v[100:103], v161 offset:1024
	ds_read_b128 v[112:115], v161 offset:2048
	ds_read_b128 v[116:119], v161 offset:3072
	s_barrier
	s_waitcnt lgkmcnt(0)
	s_waitcnt lgkmcnt(0)
	v_mfma_f32_16x16x32_bf16 v[92:95], v[170:173], v[96:99], v[92:95]
	v_mfma_f32_16x16x32_bf16 v[88:91], v[170:173], v[112:115], v[88:91]
	v_mfma_f32_16x16x32_bf16 v[76:79], v[186:189], v[96:99], v[76:79]
	v_mfma_f32_16x16x32_bf16 v[72:75], v[186:189], v[112:115], v[72:75]
	v_mfma_f32_16x16x32_bf16 v[92:95], v[174:177], v[100:103], v[92:95]
	v_mfma_f32_16x16x32_bf16 v[88:91], v[174:177], v[116:119], v[88:91]
	v_mfma_f32_16x16x32_bf16 v[84:87], v[178:181], v[96:99], v[84:87]
	v_mfma_f32_16x16x32_bf16 v[80:83], v[178:181], v[112:115], v[80:83]
	v_mfma_f32_16x16x32_bf16 v[76:79], v[194:197], v[100:103], v[76:79]
	v_mfma_f32_16x16x32_bf16 v[72:75], v[194:197], v[116:119], v[72:75]
	v_mfma_f32_16x16x32_bf16 v[68:71], v[202:205], v[96:99], v[68:71]
	v_mfma_f32_16x16x32_bf16 v[64:67], v[202:205], v[112:115], v[64:67]
	v_mfma_f32_16x16x32_bf16 v[170:173], v[182:185], v[100:103], v[84:87]
	v_mfma_f32_16x16x32_bf16 v[174:177], v[182:185], v[116:119], v[80:83]
	v_mfma_f32_16x16x32_bf16 v[178:181], v[208:211], v[100:103], v[68:71]
	v_mfma_f32_16x16x32_bf16 v[182:185], v[208:211], v[116:119], v[64:67]
	s_barrier
; #define LDA(dst, b, h) for (int m = 0; m < 4; ++m) for (int k = 0; k < 2; ++k) \
;     dst[m][k] = *reinterpret_cast<const bf16x8*>((char*)SA(b, h) + lds_byte(wr * 64 + m * 16 + fr, k * 32 + fq * 8))
; #define LDB(dst, b, h) for (int n = 0; n < 2; ++n) for (int k = 0; k < 2; ++k) \
;     dst[n][k] = *reinterpret_cast<const bf16x8*>((char*)SB(b, h) + lds_byte(wc * 32 + n * 16 + fr, k * 32 + fq * 8))
; #define MMA(ai, bj, At, Bt_) do { __builtin_amdgcn_s_setprio(1); \
;     for (int m = 0; m < 4; ++m) for (int n = 0; n < 2; ++n) for (int k = 0; k < 2; ++k) \
;       acc[ai][bj][m][n] = __builtin_amdgcn_mfma_f32_16x16x32_bf16(At[m][k], Bt_[n][k], acc[ai][bj][m][n], 0, 0, 0); \
;     __builtin_amdgcn_s_setprio(0); } while (0)
; #define WAIT_V(n) asm volatile("s_waitcnt vmcnt(" #n ")" ::: "memory")
; #define WAIT_L(n) asm volatile("s_waitcnt lgkmcnt(" #n ")" ::: "memory")
; #define BAR __builtin_amdgcn_s_barrier()
; template <bool ABLK, class Epi>
; __device__ __forceinline__ void gemm_tile(const bf16* __restrict__ A, int lda, const bf16* __restrict__ Bt, int ldb, int K,
;                                           int brow, int bcol, bf16* shm, const Epi& epi, int wv) {
;     ...
;     LDA(At, 0, 1); WAIT_V(4); BAR; WAIT_L(0); MMA(1, 0, At, B0); MMA(1, 1, At, B1); BAR; }
;   { LDB(B0, 1, 0); LDA(At, 1, 0); WAIT_V(2); BAR; WAIT_L(0); MMA(0, 0, At, B0); BAR;
	s_nop 1
	ds_read_b128 v[64:67], v144 offset:16384
	ds_read_b128 v[68:71], v144 offset:17408
	ds_read_b128 v[80:83], v143 offset:16384
	ds_read_b128 v[84:87], v143 offset:17408
	ds_read_b128 v[186:189], v142 offset:16384
	ds_read_b128 v[194:197], v142 offset:17408
	ds_read_b128 v[202:205], v141 offset:16384
	ds_read_b128 v[208:211], v141 offset:17408
	s_waitcnt vmcnt(4)
	s_barrier
	s_waitcnt lgkmcnt(0)
	s_waitcnt lgkmcnt(0)
	v_mfma_f32_16x16x32_bf16 v[60:63], v[64:67], v[132:135], v[60:63]
	v_mfma_f32_16x16x32_bf16 v[56:59], v[64:67], v[156:159], v[56:59]
	v_mfma_f32_16x16x32_bf16 v[44:47], v[186:189], v[132:135], v[44:47]
	v_mfma_f32_16x16x32_bf16 v[40:43], v[186:189], v[156:159], v[40:43]
	v_mfma_f32_16x16x32_bf16 v[60:63], v[68:71], v[152:155], v[60:63]
	v_mfma_f32_16x16x32_bf16 v[56:59], v[68:71], v[166:169], v[56:59]
	v_mfma_f32_16x16x32_bf16 v[52:55], v[80:83], v[132:135], v[52:55]
	v_mfma_f32_16x16x32_bf16 v[48:51], v[80:83], v[156:159], v[48:51]
	v_mfma_f32_16x16x32_bf16 v[44:47], v[194:197], v[152:155], v[44:47]
	v_mfma_f32_16x16x32_bf16 v[40:43], v[194:197], v[166:169], v[40:43]
	v_mfma_f32_16x16x32_bf16 v[36:39], v[202:205], v[132:135], v[36:39]
	v_mfma_f32_16x16x32_bf16 v[32:35], v[202:205], v[156:159], v[32:35]
	v_mfma_f32_16x16x32_bf16 v[224:227], v[84:87], v[152:155], v[52:55]
	v_mfma_f32_16x16x32_bf16 v[228:231], v[84:87], v[166:169], v[48:51]
	v_mfma_f32_16x16x32_bf16 v[130:133], v[208:211], v[152:155], v[36:39]
	v_mfma_f32_16x16x32_bf16 v[152:155], v[208:211], v[166:169], v[32:35]
	v_mfma_f32_16x16x32_bf16 v[28:31], v[64:67], v[96:99], v[28:31]
	v_mfma_f32_16x16x32_bf16 v[24:27], v[64:67], v[112:115], v[24:27]
	v_mfma_f32_16x16x32_bf16 v[12:15], v[186:189], v[96:99], v[12:15]
	v_mfma_f32_16x16x32_bf16 v[8:11], v[186:189], v[112:115], v[8:11]
	v_mfma_f32_16x16x32_bf16 v[28:31], v[68:71], v[100:103], v[28:31]
	v_mfma_f32_16x16x32_bf16 v[24:27], v[68:71], v[116:119], v[24:27]
	v_mfma_f32_16x16x32_bf16 v[20:23], v[80:83], v[96:99], v[20:23]
	v_mfma_f32_16x16x32_bf16 v[16:19], v[80:83], v[112:115], v[16:19]
	v_mfma_f32_16x16x32_bf16 v[12:15], v[194:197], v[100:103], v[12:15]
	v_mfma_f32_16x16x32_bf16 v[8:11], v[194:197], v[116:119], v[8:11]
	v_mfma_f32_16x16x32_bf16 v[4:7], v[202:205], v[96:99], v[4:7]
	v_mfma_f32_16x16x32_bf16 v[0:3], v[202:205], v[112:115], v[0:3]
	v_mfma_f32_16x16x32_bf16 v[156:159], v[84:87], v[100:103], v[20:23]
	v_mfma_f32_16x16x32_bf16 v[166:169], v[84:87], v[116:119], v[16:19]
	v_mfma_f32_16x16x32_bf16 v[186:189], v[208:211], v[100:103], v[4:7]
	v_mfma_f32_16x16x32_bf16 v[194:197], v[208:211], v[116:119], v[0:3]
	s_barrier
	s_nop 1
	ds_read_b128 v[0:3], v151
	ds_read_b128 v[4:7], v151 offset:1024
	ds_read_b128 v[202:205], v151 offset:2048
	ds_read_b128 v[148:151], v151 offset:3072
	ds_read_b128 v[16:19], v144 offset:32768
	ds_read_b128 v[20:23], v144 offset:33792
	ds_read_b128 v[32:35], v143 offset:32768
	ds_read_b128 v[36:39], v143 offset:33792
	ds_read_b128 v[48:51], v142 offset:32768
	ds_read_b128 v[52:55], v142 offset:33792
	ds_read_b128 v[208:211], v141 offset:32768
	ds_read_b128 v[232:235], v141 offset:33792
	s_waitcnt vmcnt(2)
	s_barrier
	s_waitcnt lgkmcnt(0)
	s_waitcnt lgkmcnt(0)
	v_mfma_f32_16x16x32_bf16 v[64:67], v[16:19], v[0:3], v[124:127]
	v_mfma_f32_16x16x32_bf16 v[116:119], v[20:23], v[4:7], v[64:67]
	v_mfma_f32_16x16x32_bf16 v[64:67], v[16:19], v[202:205], v[120:123]
	v_mfma_f32_16x16x32_bf16 v[112:115], v[20:23], v[148:151], v[64:67]
	v_mfma_f32_16x16x32_bf16 v[64:67], v[32:35], v[0:3], v[162:165]
	v_mfma_f32_16x16x32_bf16 v[100:103], v[36:39], v[4:7], v[64:67]
	v_mfma_f32_16x16x32_bf16 v[64:67], v[32:35], v[202:205], v[212:215]
	v_mfma_f32_16x16x32_bf16 v[96:99], v[36:39], v[148:151], v[64:67]
	v_mfma_f32_16x16x32_bf16 v[64:67], v[48:51], v[0:3], v[108:111]
	v_mfma_f32_16x16x32_bf16 v[84:87], v[52:55], v[4:7], v[64:67]
	v_mfma_f32_16x16x32_bf16 v[64:67], v[48:51], v[202:205], v[104:107]
	v_mfma_f32_16x16x32_bf16 v[80:83], v[52:55], v[148:151], v[64:67]
	v_mfma_f32_16x16x32_bf16 v[64:67], v[208:211], v[0:3], v[216:219]
	v_mfma_f32_16x16x32_bf16 v[68:71], v[232:235], v[4:7], v[64:67]
	v_mfma_f32_16x16x32_bf16 v[64:67], v[208:211], v[202:205], v[220:223]
	v_mfma_f32_16x16x32_bf16 v[64:67], v[232:235], v[148:151], v[64:67]
	s_barrier
; #define LDA(dst, b, h) for (int m = 0; m < 4; ++m) for (int k = 0; k < 2; ++k) \
;     dst[m][k] = *reinterpret_cast<const bf16x8*>((char*)SA(b, h) + lds_byte(wr * 64 + m * 16 + fr, k * 32 + fq * 8))
; #define LDB(dst, b, h) for (int n = 0; n < 2; ++n) for (int k = 0; k < 2; ++k) \
;     dst[n][k] = *reinterpret_cast<const bf16x8*>((char*)SB(b, h) + lds_byte(wc * 32 + n * 16 + fr, k * 32 + fq * 8))
; #define MMA(ai, bj, At, Bt_) do { __builtin_amdgcn_s_setprio(1); \
;     for (int m = 0; m < 4; ++m) for (int n = 0; n < 2; ++n) for (int k = 0; k < 2; ++k) \
;       acc[ai][bj][m][n] = __builtin_amdgcn_mfma_f32_16x16x32_bf16(At[m][k], Bt_[n][k], acc[ai][bj][m][n], 0, 0, 0); \
;     __builtin_amdgcn_s_setprio(0); } while (0)
; #define WAIT_V(n) asm volatile("s_waitcnt vmcnt(" #n ")" ::: "memory")
; #define WAIT_L(n) asm volatile("s_waitcnt lgkmcnt(" #n ")" ::: "memory")
; #define BAR __builtin_amdgcn_s_barrier()
; template <bool ABLK, class Epi>
; __device__ __forceinline__ void gemm_tile(const bf16* __restrict__ A, int lda, const bf16* __restrict__ Bt, int ldb, int K,
;                                           int brow, int bcol, bf16* shm, const Epi& epi, int wv) {
;     ...
;     LDB(B1, 1, 1); WAIT_V(0); BAR; WAIT_L(0); MMA(0, 1, At, B1); BAR;
;     LDA(At, 1, 1); BAR; WAIT_L(0); MMA(1, 0, At, B0); MMA(1, 1, At, B1); BAR; }
;   if (wr == 0) BAR;
	ds_read_b128 v[160:163], v147
	ds_read_b128 v[212:215], v147 offset:1024
	ds_read_b128 v[216:219], v147 offset:2048
	ds_read_b128 v[220:223], v147 offset:3072
	s_waitcnt vmcnt(0)
	s_barrier
	s_waitcnt lgkmcnt(0)
	s_waitcnt lgkmcnt(0)
	v_mfma_f32_16x16x32_bf16 v[92:95], v[16:19], v[160:163], v[92:95]
	v_mfma_f32_16x16x32_bf16 v[16:19], v[16:19], v[216:219], v[88:91]
	v_mfma_f32_16x16x32_bf16 v[120:123], v[20:23], v[220:223], v[16:19]
	v_mfma_f32_16x16x32_bf16 v[16:19], v[32:35], v[160:163], v[170:173]
	v_mfma_f32_16x16x32_bf16 v[108:111], v[36:39], v[212:215], v[16:19]
	v_mfma_f32_16x16x32_bf16 v[16:19], v[32:35], v[216:219], v[174:177]
	v_mfma_f32_16x16x32_bf16 v[104:107], v[36:39], v[220:223], v[16:19]
	v_mfma_f32_16x16x32_bf16 v[16:19], v[48:51], v[160:163], v[76:79]
	v_mfma_f32_16x16x32_bf16 v[124:127], v[20:23], v[212:215], v[92:95]
	v_mfma_f32_16x16x32_bf16 v[92:95], v[52:55], v[212:215], v[16:19]
	v_mfma_f32_16x16x32_bf16 v[16:19], v[48:51], v[216:219], v[72:75]
	v_mfma_f32_16x16x32_bf16 v[88:91], v[52:55], v[220:223], v[16:19]
	v_mfma_f32_16x16x32_bf16 v[16:19], v[208:211], v[160:163], v[178:181]
	v_mfma_f32_16x16x32_bf16 v[76:79], v[232:235], v[212:215], v[16:19]
	v_mfma_f32_16x16x32_bf16 v[16:19], v[208:211], v[216:219], v[182:185]
	v_mfma_f32_16x16x32_bf16 v[72:75], v[232:235], v[220:223], v[16:19]
	s_barrier
	ds_read_b128 v[170:173], v144 offset:49152
	ds_read_b128 v[144:147], v144 offset:50176
	ds_read_b128 v[174:177], v143 offset:49152
	ds_read_b128 v[178:181], v143 offset:50176
	ds_read_b128 v[182:185], v142 offset:49152
	ds_read_b128 v[208:211], v142 offset:50176
	ds_read_b128 v[232:235], v141 offset:49152
	ds_read_b128 v[236:239], v141 offset:50176
	s_barrier
	s_waitcnt lgkmcnt(0)
	s_waitcnt lgkmcnt(0)
	v_mfma_f32_16x16x32_bf16 v[16:19], v[170:173], v[0:3], v[60:63]
	v_mfma_f32_16x16x32_bf16 v[52:55], v[144:147], v[4:7], v[16:19]
	v_mfma_f32_16x16x32_bf16 v[16:19], v[170:173], v[202:205], v[56:59]
	v_mfma_f32_16x16x32_bf16 v[48:51], v[144:147], v[148:151], v[16:19]
	v_mfma_f32_16x16x32_bf16 v[16:19], v[174:177], v[0:3], v[224:227]
	v_mfma_f32_16x16x32_bf16 v[36:39], v[178:181], v[4:7], v[16:19]
	v_mfma_f32_16x16x32_bf16 v[16:19], v[174:177], v[202:205], v[228:231]
	v_mfma_f32_16x16x32_bf16 v[32:35], v[178:181], v[148:151], v[16:19]
	v_mfma_f32_16x16x32_bf16 v[16:19], v[182:185], v[0:3], v[44:47]
	v_mfma_f32_16x16x32_bf16 v[0:3], v[232:235], v[0:3], v[130:133]
	v_mfma_f32_16x16x32_bf16 v[20:23], v[208:211], v[4:7], v[16:19]
	v_mfma_f32_16x16x32_bf16 v[16:19], v[182:185], v[202:205], v[40:43]
	v_mfma_f32_16x16x32_bf16 v[4:7], v[236:239], v[4:7], v[0:3]
	v_mfma_f32_16x16x32_bf16 v[0:3], v[232:235], v[202:205], v[152:155]
	v_mfma_f32_16x16x32_bf16 v[16:19], v[208:211], v[148:151], v[16:19]
	v_mfma_f32_16x16x32_bf16 v[0:3], v[236:239], v[148:151], v[0:3]
	v_mfma_f32_16x16x32_bf16 v[24:27], v[170:173], v[216:219], v[24:27]
	v_mfma_f32_16x16x32_bf16 v[56:59], v[144:147], v[220:223], v[24:27]
	v_mfma_f32_16x16x32_bf16 v[24:27], v[174:177], v[160:163], v[156:159]
	v_mfma_f32_16x16x32_bf16 v[44:47], v[178:181], v[212:215], v[24:27]
	v_mfma_f32_16x16x32_bf16 v[24:27], v[174:177], v[216:219], v[166:169]
	v_mfma_f32_16x16x32_bf16 v[8:11], v[182:185], v[216:219], v[8:11]
	v_mfma_f32_16x16x32_bf16 v[28:31], v[170:173], v[160:163], v[28:31]
	v_mfma_f32_16x16x32_bf16 v[40:43], v[178:181], v[220:223], v[24:27]
	v_mfma_f32_16x16x32_bf16 v[12:15], v[182:185], v[160:163], v[12:15]
	v_mfma_f32_16x16x32_bf16 v[24:27], v[208:211], v[220:223], v[8:11]
	v_mfma_f32_16x16x32_bf16 v[8:11], v[232:235], v[160:163], v[186:189]
	v_mfma_f32_16x16x32_bf16 v[60:63], v[144:147], v[212:215], v[28:31]
	v_mfma_f32_16x16x32_bf16 v[28:31], v[208:211], v[212:215], v[12:15]
	v_mfma_f32_16x16x32_bf16 v[12:15], v[236:239], v[212:215], v[8:11]
	v_mfma_f32_16x16x32_bf16 v[8:11], v[232:235], v[216:219], v[194:197]
	v_mfma_f32_16x16x32_bf16 v[8:11], v[236:239], v[220:223], v[8:11]
	v_cmp_gt_u32_e32 vcc, s78, v128
	s_barrier
	s_and_saveexec_b64 s[62:63], vcc
	s_cbranch_execz .LBB0_373
	s_barrier

; #define STAGE_A(P, hf, kt) do { if constexpr (ABLK) { const bf16* _gp = A + ((long)(brow >> 8) * nt + (kt)) * 16384 + (hf) * 8192; GLDS2(_gp, 4096, offA, P); } \
;     else { const bf16* _gp = A + (long)(brow + (hf) * HALF) * lda + (long)(kt) * BK; GLDS2(_gp, 64 * (long)lda, offA, P); } } while (0)
; #define STAGE_B(P, hf, kt) do { const bf16* _gp = Bt + (long)(bcol + (hf) * 2) * ldb + (long)(kt) * BK; GLDS2(_gp, 128 * (long)ldb, offB, P); } while (0)
; #define LDA(dst, b, h) for (int m = 0; m < 4; ++m) for (int k = 0; k < 2; ++k) \
;     dst[m][k] = *reinterpret_cast<const bf16x8*>((char*)SA(b, h) + lds_byte(wr * 64 + m * 16 + fr, k * 32 + fq * 8))
; #define LDB(dst, b, h) for (int n = 0; n < 2; ++n) for (int k = 0; k < 2; ++k) \
;     dst[n][k] = *reinterpret_cast<const bf16x8*>((char*)SB(b, h) + lds_byte(wc * 32 + n * 16 + fr, k * 32 + fq * 8))
; #define MMA(ai, bj, At, Bt_) do { __builtin_amdgcn_s_setprio(1); \
;     for (int m = 0; m < 4; ++m) for (int n = 0; n < 2; ++n) for (int k = 0; k < 2; ++k) \
;       acc[ai][bj][m][n] = __builtin_amdgcn_mfma_f32_16x16x32_bf16(At[m][k], Bt_[n][k], acc[ai][bj][m][n], 0, 0, 0); \
;     __builtin_amdgcn_s_setprio(0); } while (0)
; #define WAIT_V(n) asm volatile("s_waitcnt vmcnt(" #n ")" ::: "memory")
; #define WAIT_L(n) asm volatile("s_waitcnt lgkmcnt(" #n ")" ::: "memory")
; #define BAR __builtin_amdgcn_s_barrier()
; #define SCHED __builtin_amdgcn_sched_barrier(0)
; template <bool ABLK, class Epi>
; __device__ __forceinline__ void gemm_tile(const bf16* __restrict__ A, int lda, const bf16* __restrict__ Bt, int ldb, int K,
;                                           int brow, int bcol, bf16* shm, const Epi& epi, int wv) {
;     ...
;     LDB(B0, 0, 0); SCHED; LDA(At, 0, 0); STAGE_A(SA(1, 1), 1, t + 1);
;     WAIT_L(8); BAR; MMA(0, 0, At, B0); BAR; SCHED;
;     LDB(B1, 0, 1); STAGE_B(SB(0, 0), 0, t + 2);
;     BAR; MMA(0, 1, At, B1); BAR;
;     LDA(At, 0, 1); STAGE_A(SA(0, 0), 0, t + 2);
;     BAR; MMA(1, 0, At, B0); BAR; SCHED;
;     STAGE_B(SB(0, 1), 1, t + 2);
;     WAIT_V(6); BAR; MMA(1, 1, At, B1); BAR;
.LBB0_585:
	ds_read_b128 v[166:169], v162
	ds_read_b128 v[170:173], v162 offset:1024
	ds_read_b128 v[174:177], v162 offset:2048
	ds_read_b128 v[178:181], v162 offset:3072
	v_add_u32_e32 v163, 0xc000, v148
	v_lshl_add_u64 v[164:165], v[132:133], 0, s[22:23]
	s_add_i32 m0, s99, 0xc000
	ds_read_b128 v[182:185], v144
	ds_read_b128 v[186:189], v144 offset:1024
	ds_read_b128 v[194:197], v143
	ds_read_b128 v[202:205], v143 offset:1024
	ds_read_b128 v[208:211], v142
	ds_read_b128 v[212:215], v142 offset:1024
	ds_read_b128 v[216:219], v141
	ds_read_b128 v[220:223], v141 offset:1024
	global_load_lds_dwordx4 v[164:165], off
	v_add_u32_e32 v164, 0xe000, v148
	s_add_i32 m0, s99, 0xe000
	v_lshl_add_u64 v[190:191], v[132:133], 0, s[24:25]
	global_load_lds_dwordx4 v[190:191], off
	s_waitcnt lgkmcnt(8)
	s_barrier
	s_waitcnt lgkmcnt(0)
	v_mfma_f32_16x16x32_bf16 v[124:127], v[182:185], v[166:169], v[124:127]
	v_mfma_f32_16x16x32_bf16 v[120:123], v[182:185], v[174:177], v[120:123]
	v_mfma_f32_16x16x32_bf16 v[116:119], v[194:197], v[166:169], v[116:119]
	v_mfma_f32_16x16x32_bf16 v[112:115], v[194:197], v[174:177], v[112:115]
	v_mfma_f32_16x16x32_bf16 v[108:111], v[208:211], v[166:169], v[108:111]
	v_mfma_f32_16x16x32_bf16 v[104:107], v[208:211], v[174:177], v[104:107]
	v_mfma_f32_16x16x32_bf16 v[100:103], v[216:219], v[166:169], v[100:103]
	v_mfma_f32_16x16x32_bf16 v[96:99], v[216:219], v[174:177], v[96:99]
	v_mfma_f32_16x16x32_bf16 v[124:127], v[186:189], v[170:173], v[124:127]
	v_mfma_f32_16x16x32_bf16 v[120:123], v[186:189], v[178:181], v[120:123]
	v_mfma_f32_16x16x32_bf16 v[116:119], v[202:205], v[170:173], v[116:119]
	v_mfma_f32_16x16x32_bf16 v[112:115], v[202:205], v[178:181], v[112:115]
	v_mfma_f32_16x16x32_bf16 v[108:111], v[212:215], v[170:173], v[108:111]
	v_mfma_f32_16x16x32_bf16 v[104:107], v[212:215], v[178:181], v[104:107]
	v_mfma_f32_16x16x32_bf16 v[100:103], v[220:223], v[170:173], v[100:103]
	v_mfma_f32_16x16x32_bf16 v[96:99], v[220:223], v[178:181], v[96:99]
	s_barrier
	v_lshl_add_u64 v[190:191], v[134:135], 0, s[26:27]
	s_add_i32 m0, s99, 0x10000
	ds_read_b128 v[224:227], v161
	ds_read_b128 v[228:231], v161 offset:1024
	ds_read_b128 v[232:235], v161 offset:2048
	ds_read_b128 v[236:239], v161 offset:3072
	global_load_lds_dwordx4 v[190:191], off
	s_add_i32 m0, s99, 0x12000
	v_lshl_add_u64 v[190:191], v[134:135], 0, s[30:31]
	global_load_lds_dwordx4 v[190:191], off
	s_barrier
	s_waitcnt lgkmcnt(0)
	v_mfma_f32_16x16x32_bf16 v[92:95], v[182:185], v[224:227], v[92:95]
	v_mfma_f32_16x16x32_bf16 v[88:91], v[182:185], v[232:235], v[88:91]
	v_mfma_f32_16x16x32_bf16 v[84:87], v[194:197], v[224:227], v[84:87]
	v_mfma_f32_16x16x32_bf16 v[80:83], v[194:197], v[232:235], v[80:83]
	v_mfma_f32_16x16x32_bf16 v[76:79], v[208:211], v[224:227], v[76:79]
	v_mfma_f32_16x16x32_bf16 v[72:75], v[208:211], v[232:235], v[72:75]
	v_mfma_f32_16x16x32_bf16 v[68:71], v[216:219], v[224:227], v[68:71]
	v_mfma_f32_16x16x32_bf16 v[64:67], v[216:219], v[232:235], v[64:67]
	v_mfma_f32_16x16x32_bf16 v[92:95], v[186:189], v[228:231], v[92:95]
	v_mfma_f32_16x16x32_bf16 v[88:91], v[186:189], v[236:239], v[88:91]
	v_mfma_f32_16x16x32_bf16 v[84:87], v[202:205], v[228:231], v[84:87]
	v_mfma_f32_16x16x32_bf16 v[80:83], v[202:205], v[236:239], v[80:83]
	v_mfma_f32_16x16x32_bf16 v[76:79], v[212:215], v[228:231], v[76:79]
	v_mfma_f32_16x16x32_bf16 v[72:75], v[212:215], v[236:239], v[72:75]
	v_mfma_f32_16x16x32_bf16 v[68:71], v[220:223], v[228:231], v[68:71]
	v_mfma_f32_16x16x32_bf16 v[64:67], v[220:223], v[236:239], v[64:67]
	v_lshl_add_u64 v[190:191], v[132:133], 0, s[34:35]
	s_add_i32 m0, s99, 0x0
	s_barrier
	ds_read_b128 v[182:185], v144 offset:16384
	ds_read_b128 v[186:189], v144 offset:17408
	ds_read_b128 v[194:197], v143 offset:16384
	ds_read_b128 v[202:205], v143 offset:17408
	ds_read_b128 v[208:211], v142 offset:16384
	ds_read_b128 v[212:215], v142 offset:17408
	ds_read_b128 v[216:219], v141 offset:16384
	ds_read_b128 v[220:223], v141 offset:17408
	global_load_lds_dwordx4 v[190:191], off
	s_add_i32 m0, s99, 0x2000
	v_lshl_add_u64 v[190:191], v[132:133], 0, s[36:37]
	global_load_lds_dwordx4 v[190:191], off
	s_barrier
	s_waitcnt lgkmcnt(0)
	v_mfma_f32_16x16x32_bf16 v[60:63], v[182:185], v[166:169], v[60:63]
	v_mfma_f32_16x16x32_bf16 v[56:59], v[182:185], v[174:177], v[56:59]
	v_mfma_f32_16x16x32_bf16 v[52:55], v[194:197], v[166:169], v[52:55]
	v_mfma_f32_16x16x32_bf16 v[48:51], v[194:197], v[174:177], v[48:51]
	v_mfma_f32_16x16x32_bf16 v[44:47], v[208:211], v[166:169], v[44:47]
	v_mfma_f32_16x16x32_bf16 v[40:43], v[208:211], v[174:177], v[40:43]
	v_mfma_f32_16x16x32_bf16 v[36:39], v[216:219], v[166:169], v[36:39]
	v_mfma_f32_16x16x32_bf16 v[32:35], v[216:219], v[174:177], v[32:35]
	v_mfma_f32_16x16x32_bf16 v[60:63], v[186:189], v[170:173], v[60:63]
	v_mfma_f32_16x16x32_bf16 v[56:59], v[186:189], v[178:181], v[56:59]
	v_mfma_f32_16x16x32_bf16 v[52:55], v[202:205], v[170:173], v[52:55]
	v_mfma_f32_16x16x32_bf16 v[48:51], v[202:205], v[178:181], v[48:51]
	v_mfma_f32_16x16x32_bf16 v[44:47], v[212:215], v[170:173], v[44:47]
	v_mfma_f32_16x16x32_bf16 v[40:43], v[212:215], v[178:181], v[40:43]
	v_mfma_f32_16x16x32_bf16 v[36:39], v[220:223], v[170:173], v[36:39]
	v_mfma_f32_16x16x32_bf16 v[32:35], v[220:223], v[178:181], v[32:35]
	s_barrier
	s_add_i32 m0, s99, 0x14000
	v_lshl_add_u64 v[166:167], v[134:135], 0, s[38:39]
	global_load_lds_dwordx4 v[166:167], off
	s_add_i32 m0, s99, 0x16000
	v_lshl_add_u64 v[166:167], v[134:135], 0, s[40:41]
	global_load_lds_dwordx4 v[166:167], off
	s_waitcnt vmcnt(6)
	s_barrier
; #define STAGE_A(P, hf, kt) do { if constexpr (ABLK) { const bf16* _gp = A + ((long)(brow >> 8) * nt + (kt)) * 16384 + (hf) * 8192; GLDS2(_gp, 4096, offA, P); } \
;     else { const bf16* _gp = A + (long)(brow + (hf) * HALF) * lda + (long)(kt) * BK; GLDS2(_gp, 64 * (long)lda, offA, P); } } while (0)
; #define STAGE_B(P, hf, kt) do { const bf16* _gp = Bt + (long)(bcol + (hf) * 2) * ldb + (long)(kt) * BK; GLDS2(_gp, 128 * (long)ldb, offB, P); } while (0)
; #define LDA(dst, b, h) for (int m = 0; m < 4; ++m) for (int k = 0; k < 2; ++k) \
;     dst[m][k] = *reinterpret_cast<const bf16x8*>((char*)SA(b, h) + lds_byte(wr * 64 + m * 16 + fr, k * 32 + fq * 8))
; #define LDB(dst, b, h) for (int n = 0; n < 2; ++n) for (int k = 0; k < 2; ++k) \
;     dst[n][k] = *reinterpret_cast<const bf16x8*>((char*)SB(b, h) + lds_byte(wc * 32 + n * 16 + fr, k * 32 + fq * 8))
; #define MMA(ai, bj, At, Bt_) do { __builtin_amdgcn_s_setprio(1); \
;     for (int m = 0; m < 4; ++m) for (int n = 0; n < 2; ++n) for (int k = 0; k < 2; ++k) \
;       acc[ai][bj][m][n] = __builtin_amdgcn_mfma_f32_16x16x32_bf16(At[m][k], Bt_[n][k], acc[ai][bj][m][n], 0, 0, 0); \
;     __builtin_amdgcn_s_setprio(0); } while (0)
; #define WAIT_V(n) asm volatile("s_waitcnt vmcnt(" #n ")" ::: "memory")
; #define WAIT_L(n) asm volatile("s_waitcnt lgkmcnt(" #n ")" ::: "memory")
; #define BAR __builtin_amdgcn_s_barrier()
; #define SCHED __builtin_amdgcn_sched_barrier(0)
; template <bool ABLK, class Epi>
; __device__ __forceinline__ void gemm_tile(const bf16* __restrict__ A, int lda, const bf16* __restrict__ Bt, int ldb, int K,
;                                           int brow, int bcol, bf16* shm, const Epi& epi, int wv) {
;     ...
;     WAIT_V(6); BAR; MMA(1, 1, At, B1); BAR;
;     LDB(B0, 1, 0); SCHED; LDA(At, 1, 0); STAGE_A(SA(0, 1), 1, t + 2);
;     WAIT_L(8); BAR; MMA(0, 0, At, B0); BAR; SCHED;
;     LDB(B1, 1, 1); STAGE_B(SB(1, 0), 0, t + 3);
;     BAR; MMA(0, 1, At, B1); BAR;
;     LDA(At, 1, 1); STAGE_A(SA(1, 0), 0, t + 3);
	v_mfma_f32_16x16x32_bf16 v[28:31], v[182:185], v[224:227], v[28:31]
	v_mfma_f32_16x16x32_bf16 v[24:27], v[182:185], v[232:235], v[24:27]
	v_mfma_f32_16x16x32_bf16 v[20:23], v[194:197], v[224:227], v[20:23]
	v_mfma_f32_16x16x32_bf16 v[16:19], v[194:197], v[232:235], v[16:19]
	v_mfma_f32_16x16x32_bf16 v[12:15], v[208:211], v[224:227], v[12:15]
	v_mfma_f32_16x16x32_bf16 v[8:11], v[208:211], v[232:235], v[8:11]
	v_mfma_f32_16x16x32_bf16 v[4:7], v[216:219], v[224:227], v[4:7]
	v_mfma_f32_16x16x32_bf16 v[0:3], v[216:219], v[232:235], v[0:3]
	v_mfma_f32_16x16x32_bf16 v[28:31], v[186:189], v[228:231], v[28:31]
	v_mfma_f32_16x16x32_bf16 v[24:27], v[186:189], v[236:239], v[24:27]
	v_mfma_f32_16x16x32_bf16 v[20:23], v[202:205], v[228:231], v[20:23]
	v_mfma_f32_16x16x32_bf16 v[16:19], v[202:205], v[236:239], v[16:19]
	v_mfma_f32_16x16x32_bf16 v[12:15], v[212:215], v[228:231], v[12:15]
	v_mfma_f32_16x16x32_bf16 v[8:11], v[212:215], v[236:239], v[8:11]
	v_mfma_f32_16x16x32_bf16 v[4:7], v[220:223], v[228:231], v[4:7]
	v_mfma_f32_16x16x32_bf16 v[0:3], v[220:223], v[236:239], v[0:3]
	s_barrier
	ds_read_b128 v[166:169], v150
	ds_read_b128 v[170:173], v150 offset:1024
	ds_read_b128 v[174:177], v150 offset:2048
	ds_read_b128 v[178:181], v150 offset:3072
	v_lshl_add_u64 v[190:191], v[132:133], 0, s[42:43]
	s_add_i32 m0, s99, 0x4000
	ds_read_b128 v[182:185], v144 offset:32768
	ds_read_b128 v[186:189], v144 offset:33792
	ds_read_b128 v[194:197], v143 offset:32768
	ds_read_b128 v[202:205], v143 offset:33792
	ds_read_b128 v[208:211], v142 offset:32768
	ds_read_b128 v[212:215], v142 offset:33792
	ds_read_b128 v[216:219], v141 offset:32768
	ds_read_b128 v[220:223], v141 offset:33792
	global_load_lds_dwordx4 v[190:191], off
	s_add_i32 m0, s99, 0x6000
	v_lshl_add_u64 v[190:191], v[132:133], 0, s[44:45]
	global_load_lds_dwordx4 v[190:191], off
	s_waitcnt lgkmcnt(8)
	s_barrier
	s_waitcnt lgkmcnt(0)
	v_mfma_f32_16x16x32_bf16 v[124:127], v[182:185], v[166:169], v[124:127]
	v_mfma_f32_16x16x32_bf16 v[120:123], v[182:185], v[174:177], v[120:123]
	v_mfma_f32_16x16x32_bf16 v[116:119], v[194:197], v[166:169], v[116:119]
	v_mfma_f32_16x16x32_bf16 v[112:115], v[194:197], v[174:177], v[112:115]
	v_mfma_f32_16x16x32_bf16 v[108:111], v[208:211], v[166:169], v[108:111]
	v_mfma_f32_16x16x32_bf16 v[104:107], v[208:211], v[174:177], v[104:107]
	v_mfma_f32_16x16x32_bf16 v[100:103], v[216:219], v[166:169], v[100:103]
	v_mfma_f32_16x16x32_bf16 v[96:99], v[216:219], v[174:177], v[96:99]
	v_mfma_f32_16x16x32_bf16 v[124:127], v[186:189], v[170:173], v[124:127]
	v_mfma_f32_16x16x32_bf16 v[120:123], v[186:189], v[178:181], v[120:123]
	v_mfma_f32_16x16x32_bf16 v[116:119], v[202:205], v[170:173], v[116:119]
	v_mfma_f32_16x16x32_bf16 v[112:115], v[202:205], v[178:181], v[112:115]
	v_mfma_f32_16x16x32_bf16 v[108:111], v[212:215], v[170:173], v[108:111]
	v_mfma_f32_16x16x32_bf16 v[104:107], v[212:215], v[178:181], v[104:107]
	v_mfma_f32_16x16x32_bf16 v[100:103], v[220:223], v[170:173], v[100:103]
	v_mfma_f32_16x16x32_bf16 v[96:99], v[220:223], v[178:181], v[96:99]
	s_barrier
	v_lshl_add_u64 v[190:191], v[134:135], 0, s[46:47]
	s_add_i32 m0, s99, 0x18000
	ds_read_b128 v[224:227], v147
	ds_read_b128 v[228:231], v147 offset:1024
	ds_read_b128 v[232:235], v147 offset:2048
	ds_read_b128 v[236:239], v147 offset:3072
	global_load_lds_dwordx4 v[190:191], off
	s_add_i32 m0, s99, 0x1a000
	v_lshl_add_u64 v[190:191], v[134:135], 0, s[48:49]
	global_load_lds_dwordx4 v[190:191], off
	s_barrier
	s_waitcnt lgkmcnt(0)
	v_mfma_f32_16x16x32_bf16 v[92:95], v[182:185], v[224:227], v[92:95]
	v_mfma_f32_16x16x32_bf16 v[88:91], v[182:185], v[232:235], v[88:91]
	v_mfma_f32_16x16x32_bf16 v[84:87], v[194:197], v[224:227], v[84:87]
	v_mfma_f32_16x16x32_bf16 v[80:83], v[194:197], v[232:235], v[80:83]
	v_mfma_f32_16x16x32_bf16 v[76:79], v[208:211], v[224:227], v[76:79]
	v_mfma_f32_16x16x32_bf16 v[72:75], v[208:211], v[232:235], v[72:75]
	v_mfma_f32_16x16x32_bf16 v[68:71], v[216:219], v[224:227], v[68:71]
	v_mfma_f32_16x16x32_bf16 v[64:67], v[216:219], v[232:235], v[64:67]
	v_mfma_f32_16x16x32_bf16 v[92:95], v[186:189], v[228:231], v[92:95]
	v_mfma_f32_16x16x32_bf16 v[88:91], v[186:189], v[236:239], v[88:91]
	v_mfma_f32_16x16x32_bf16 v[84:87], v[202:205], v[228:231], v[84:87]
	v_mfma_f32_16x16x32_bf16 v[80:83], v[202:205], v[236:239], v[80:83]
	v_mfma_f32_16x16x32_bf16 v[76:79], v[212:215], v[228:231], v[76:79]
	v_mfma_f32_16x16x32_bf16 v[72:75], v[212:215], v[236:239], v[72:75]
	v_mfma_f32_16x16x32_bf16 v[68:71], v[220:223], v[228:231], v[68:71]
	v_mfma_f32_16x16x32_bf16 v[64:67], v[220:223], v[236:239], v[64:67]
	v_lshl_add_u64 v[190:191], v[132:133], 0, s[48:49]
	s_add_i32 m0, s99, 0x8000
	s_barrier
	ds_read_b128 v[182:185], v144 offset:49152
	ds_read_b128 v[186:189], v144 offset:50176
	ds_read_b128 v[194:197], v143 offset:49152
	ds_read_b128 v[202:205], v143 offset:50176
	ds_read_b128 v[208:211], v142 offset:49152
	ds_read_b128 v[212:215], v142 offset:50176
	ds_read_b128 v[216:219], v141 offset:49152
	ds_read_b128 v[220:223], v141 offset:50176
	global_load_lds_dwordx4 v[190:191], off
	s_add_i32 m0, s99, 0xa000
	s_nop 0
	global_load_lds_dwordx4 v[132:133], off
	s_barrier
; #define STAGE_A(P, hf, kt) do { if constexpr (ABLK) { const bf16* _gp = A + ((long)(brow >> 8) * nt + (kt)) * 16384 + (hf) * 8192; GLDS2(_gp, 4096, offA, P); } \
;     else { const bf16* _gp = A + (long)(brow + (hf) * HALF) * lda + (long)(kt) * BK; GLDS2(_gp, 64 * (long)lda, offA, P); } } while (0)
; #define STAGE_B(P, hf, kt) do { const bf16* _gp = Bt + (long)(bcol + (hf) * 2) * ldb + (long)(kt) * BK; GLDS2(_gp, 128 * (long)ldb, offB, P); } while (0)
; #define LDA(dst, b, h) for (int m = 0; m < 4; ++m) for (int k = 0; k < 2; ++k) \
;     dst[m][k] = *reinterpret_cast<const bf16x8*>((char*)SA(b, h) + lds_byte(wr * 64 + m * 16 + fr, k * 32 + fq * 8))
; #define LDB(dst, b, h) for (int n = 0; n < 2; ++n) for (int k = 0; k < 2; ++k) \
;     dst[n][k] = *reinterpret_cast<const bf16x8*>((char*)SB(b, h) + lds_byte(wc * 32 + n * 16 + fr, k * 32 + fq * 8))
; #define MMA(ai, bj, At, Bt_) do { __builtin_amdgcn_s_setprio(1); \
;     for (int m = 0; m < 4; ++m) for (int n = 0; n < 2; ++n) for (int k = 0; k < 2; ++k) \
;       acc[ai][bj][m][n] = __builtin_amdgcn_mfma_f32_16x16x32_bf16(At[m][k], Bt_[n][k], acc[ai][bj][m][n], 0, 0, 0); \
;     __builtin_amdgcn_s_setprio(0); } while (0)
; #define WAIT_V(n) asm volatile("s_waitcnt vmcnt(" #n ")" ::: "memory")
; #define WAIT_L(n) asm volatile("s_waitcnt lgkmcnt(" #n ")" ::: "memory")
; #define BAR __builtin_amdgcn_s_barrier()
; #define SCHED __builtin_amdgcn_sched_barrier(0)
; template <bool ABLK, class Epi>
; __device__ __forceinline__ void gemm_tile(const bf16* __restrict__ A, int lda, const bf16* __restrict__ Bt, int ldb, int K,
;                                           int brow, int bcol, bf16* shm, const Epi& epi, int wv) {
;     ...
;     BAR; MMA(1, 0, At, B0); BAR; SCHED;
;     STAGE_B(SB(1, 1), 1, t + 3);
;     WAIT_V(6); BAR; MMA(1, 1, At, B1); BAR;
;   }
;   { LDB(B0, 0, 0); LDA(At, 0, 0); STAGE_A(SA(1, 1), 1, nt - 1);
;     BAR; WAIT_L(0); MMA(0, 0, At, B0); BAR;
;     LDB(B1, 0, 1); BAR; WAIT_L(0); MMA(0, 1, At, B1); BAR;
	s_waitcnt lgkmcnt(0)
	v_mfma_f32_16x16x32_bf16 v[60:63], v[182:185], v[166:169], v[60:63]
	v_mfma_f32_16x16x32_bf16 v[56:59], v[182:185], v[174:177], v[56:59]
	v_mfma_f32_16x16x32_bf16 v[52:55], v[194:197], v[166:169], v[52:55]
	v_mfma_f32_16x16x32_bf16 v[48:51], v[194:197], v[174:177], v[48:51]
	v_mfma_f32_16x16x32_bf16 v[44:47], v[208:211], v[166:169], v[44:47]
	v_mfma_f32_16x16x32_bf16 v[40:43], v[208:211], v[174:177], v[40:43]
	v_mfma_f32_16x16x32_bf16 v[36:39], v[216:219], v[166:169], v[36:39]
	v_mfma_f32_16x16x32_bf16 v[32:35], v[216:219], v[174:177], v[32:35]
	v_mfma_f32_16x16x32_bf16 v[60:63], v[186:189], v[170:173], v[60:63]
	v_mfma_f32_16x16x32_bf16 v[56:59], v[186:189], v[178:181], v[56:59]
	v_mfma_f32_16x16x32_bf16 v[52:55], v[202:205], v[170:173], v[52:55]
	v_mfma_f32_16x16x32_bf16 v[48:51], v[202:205], v[178:181], v[48:51]
	v_mfma_f32_16x16x32_bf16 v[44:47], v[212:215], v[170:173], v[44:47]
	v_mfma_f32_16x16x32_bf16 v[40:43], v[212:215], v[178:181], v[40:43]
	v_mfma_f32_16x16x32_bf16 v[36:39], v[220:223], v[170:173], v[36:39]
	v_mfma_f32_16x16x32_bf16 v[32:35], v[220:223], v[178:181], v[32:35]
	s_barrier
	s_add_i32 m0, s99, 0x1c000
	v_lshl_add_u64 v[166:167], v[134:135], 0, s[50:51]
	global_load_lds_dwordx4 v[166:167], off
	s_add_i32 m0, s99, 0x1e000
	s_nop 0
	global_load_lds_dwordx4 v[134:135], off
	s_waitcnt vmcnt(6)
	s_barrier
	v_mfma_f32_16x16x32_bf16 v[28:31], v[182:185], v[224:227], v[28:31]
	v_mfma_f32_16x16x32_bf16 v[24:27], v[182:185], v[232:235], v[24:27]
	v_mfma_f32_16x16x32_bf16 v[20:23], v[194:197], v[224:227], v[20:23]
	v_mfma_f32_16x16x32_bf16 v[16:19], v[194:197], v[232:235], v[16:19]
	v_mfma_f32_16x16x32_bf16 v[12:15], v[208:211], v[224:227], v[12:15]
	v_mfma_f32_16x16x32_bf16 v[8:11], v[208:211], v[232:235], v[8:11]
	v_mfma_f32_16x16x32_bf16 v[4:7], v[216:219], v[224:227], v[4:7]
	v_mfma_f32_16x16x32_bf16 v[0:3], v[216:219], v[232:235], v[0:3]
	v_mfma_f32_16x16x32_bf16 v[28:31], v[186:189], v[228:231], v[28:31]
	v_mfma_f32_16x16x32_bf16 v[24:27], v[186:189], v[236:239], v[24:27]
	v_mfma_f32_16x16x32_bf16 v[20:23], v[202:205], v[228:231], v[20:23]
	v_mfma_f32_16x16x32_bf16 v[16:19], v[202:205], v[236:239], v[16:19]
	v_mfma_f32_16x16x32_bf16 v[12:15], v[212:215], v[228:231], v[12:15]
	v_mfma_f32_16x16x32_bf16 v[8:11], v[212:215], v[236:239], v[8:11]
	v_mfma_f32_16x16x32_bf16 v[4:7], v[220:223], v[228:231], v[4:7]
	v_mfma_f32_16x16x32_bf16 v[0:3], v[220:223], v[236:239], v[0:3]
	s_add_i32 s33, s33, 2
	v_lshl_add_u64 v[132:133], v[132:133], 0, s[52:53]
	s_cmp_lt_u32 s33, 28
	v_lshl_add_u64 v[134:135], v[134:135], 0, s[54:55]
	s_barrier
	s_cbranch_scc1 .LBB0_585
	v_readfirstlane_b32 s2, v163
	v_lshl_add_u64 v[148:149], v[130:131], 0, s[56:57]
	s_mov_b32 m0, s2
	v_readfirstlane_b32 s2, v164
	ds_read_b128 v[132:135], v162
	ds_read_b128 v[152:155], v162 offset:1024
	ds_read_b128 v[156:159], v162 offset:2048
	ds_read_b128 v[166:169], v162 offset:3072
	ds_read_b128 v[170:173], v144
	ds_read_b128 v[174:177], v144 offset:1024
	ds_read_b128 v[178:181], v143
	ds_read_b128 v[182:185], v143 offset:1024
	ds_read_b128 v[186:189], v142
	ds_read_b128 v[194:197], v142 offset:1024
	ds_read_b128 v[202:205], v141
	ds_read_b128 v[208:211], v141 offset:1024
	global_load_lds_dwordx4 v[148:149], off
	v_lshl_add_u64 v[130:131], v[130:131], 0, s[58:59]
	s_mov_b32 m0, s2
	s_nop 0
	global_load_lds_dwordx4 v[130:131], off
	s_barrier
	s_waitcnt lgkmcnt(0)
	s_waitcnt lgkmcnt(0)
	v_mfma_f32_16x16x32_bf16 v[124:127], v[170:173], v[132:135], v[124:127]
	v_mfma_f32_16x16x32_bf16 v[120:123], v[170:173], v[156:159], v[120:123]
	v_mfma_f32_16x16x32_bf16 v[108:111], v[186:189], v[132:135], v[108:111]
	v_mfma_f32_16x16x32_bf16 v[104:107], v[186:189], v[156:159], v[104:107]
	v_mfma_f32_16x16x32_bf16 v[124:127], v[174:177], v[152:155], v[124:127]
	v_mfma_f32_16x16x32_bf16 v[120:123], v[174:177], v[166:169], v[120:123]
	v_mfma_f32_16x16x32_bf16 v[116:119], v[178:181], v[132:135], v[116:119]
	v_mfma_f32_16x16x32_bf16 v[112:115], v[178:181], v[156:159], v[112:115]
	v_mfma_f32_16x16x32_bf16 v[108:111], v[194:197], v[152:155], v[108:111]
	v_mfma_f32_16x16x32_bf16 v[104:107], v[194:197], v[166:169], v[104:107]
	v_mfma_f32_16x16x32_bf16 v[100:103], v[202:205], v[132:135], v[100:103]
	v_mfma_f32_16x16x32_bf16 v[96:99], v[202:205], v[156:159], v[96:99]
	v_mfma_f32_16x16x32_bf16 v[162:165], v[182:185], v[152:155], v[116:119]
	v_mfma_f32_16x16x32_bf16 v[212:215], v[182:185], v[166:169], v[112:115]
	v_mfma_f32_16x16x32_bf16 v[216:219], v[208:211], v[152:155], v[100:103]
	v_mfma_f32_16x16x32_bf16 v[220:223], v[208:211], v[166:169], v[96:99]
	s_barrier
	s_nop 1
	ds_read_b128 v[96:99], v161
	ds_read_b128 v[100:103], v161 offset:1024
	ds_read_b128 v[112:115], v161 offset:2048
	ds_read_b128 v[116:119], v161 offset:3072
	s_barrier
	s_waitcnt lgkmcnt(0)
	s_waitcnt lgkmcnt(0)
	v_mfma_f32_16x16x32_bf16 v[92:95], v[170:173], v[96:99], v[92:95]
	v_mfma_f32_16x16x32_bf16 v[88:91], v[170:173], v[112:115], v[88:91]
	v_mfma_f32_16x16x32_bf16 v[76:79], v[186:189], v[96:99], v[76:79]
	v_mfma_f32_16x16x32_bf16 v[72:75], v[186:189], v[112:115], v[72:75]
	v_mfma_f32_16x16x32_bf16 v[92:95], v[174:177], v[100:103], v[92:95]
	v_mfma_f32_16x16x32_bf16 v[88:91], v[174:177], v[116:119], v[88:91]
	v_mfma_f32_16x16x32_bf16 v[84:87], v[178:181], v[96:99], v[84:87]
	v_mfma_f32_16x16x32_bf16 v[80:83], v[178:181], v[112:115], v[80:83]
	v_mfma_f32_16x16x32_bf16 v[76:79], v[194:197], v[100:103], v[76:79]
	v_mfma_f32_16x16x32_bf16 v[72:75], v[194:197], v[116:119], v[72:75]
	v_mfma_f32_16x16x32_bf16 v[68:71], v[202:205], v[96:99], v[68:71]
	v_mfma_f32_16x16x32_bf16 v[64:67], v[202:205], v[112:115], v[64:67]
	v_mfma_f32_16x16x32_bf16 v[170:173], v[182:185], v[100:103], v[84:87]
	v_mfma_f32_16x16x32_bf16 v[174:177], v[182:185], v[116:119], v[80:83]
	v_mfma_f32_16x16x32_bf16 v[178:181], v[208:211], v[100:103], v[68:71]
	v_mfma_f32_16x16x32_bf16 v[182:185], v[208:211], v[116:119], v[64:67]
	s_barrier
; #define LDA(dst, b, h) for (int m = 0; m < 4; ++m) for (int k = 0; k < 2; ++k) \
;     dst[m][k] = *reinterpret_cast<const bf16x8*>((char*)SA(b, h) + lds_byte(wr * 64 + m * 16 + fr, k * 32 + fq * 8))
; #define LDB(dst, b, h) for (int n = 0; n < 2; ++n) for (int k = 0; k < 2; ++k) \
;     dst[n][k] = *reinterpret_cast<const bf16x8*>((char*)SB(b, h) + lds_byte(wc * 32 + n * 16 + fr, k * 32 + fq * 8))
; #define MMA(ai, bj, At, Bt_) do { __builtin_amdgcn_s_setprio(1); \
;     for (int m = 0; m < 4; ++m) for (int n = 0; n < 2; ++n) for (int k = 0; k < 2; ++k) \
;       acc[ai][bj][m][n] = __builtin_amdgcn_mfma_f32_16x16x32_bf16(At[m][k], Bt_[n][k], acc[ai][bj][m][n], 0, 0, 0); \
;     __builtin_amdgcn_s_setprio(0); } while (0)
; #define WAIT_V(n) asm volatile("s_waitcnt vmcnt(" #n ")" ::: "memory")
; #define WAIT_L(n) asm volatile("s_waitcnt lgkmcnt(" #n ")" ::: "memory")
; #define BAR __builtin_amdgcn_s_barrier()
; template <bool ABLK, class Epi>
; __device__ __forceinline__ void gemm_tile(const bf16* __restrict__ A, int lda, const bf16* __restrict__ Bt, int ldb, int K,
;                                           int brow, int bcol, bf16* shm, const Epi& epi, int wv) {
;     ...
;     LDA(At, 0, 1); WAIT_V(4); BAR; WAIT_L(0); MMA(1, 0, At, B0); MMA(1, 1, At, B1); BAR; }
;   { LDB(B0, 1, 0); LDA(At, 1, 0); WAIT_V(2); BAR; WAIT_L(0); MMA(0, 0, At, B0); BAR;
	s_nop 1
	ds_read_b128 v[64:67], v144 offset:16384
	ds_read_b128 v[68:71], v144 offset:17408
	ds_read_b128 v[80:83], v143 offset:16384
	ds_read_b128 v[84:87], v143 offset:17408
	ds_read_b128 v[186:189], v142 offset:16384
	ds_read_b128 v[194:197], v142 offset:17408
	ds_read_b128 v[202:205], v141 offset:16384
	ds_read_b128 v[208:211], v141 offset:17408
	s_waitcnt vmcnt(4)
	s_barrier
	s_waitcnt lgkmcnt(0)
	s_waitcnt lgkmcnt(0)
	v_mfma_f32_16x16x32_bf16 v[60:63], v[64:67], v[132:135], v[60:63]
	v_mfma_f32_16x16x32_bf16 v[56:59], v[64:67], v[156:159], v[56:59]
	v_mfma_f32_16x16x32_bf16 v[44:47], v[186:189], v[132:135], v[44:47]
	v_mfma_f32_16x16x32_bf16 v[40:43], v[186:189], v[156:159], v[40:43]
	v_mfma_f32_16x16x32_bf16 v[60:63], v[68:71], v[152:155], v[60:63]
	v_mfma_f32_16x16x32_bf16 v[56:59], v[68:71], v[166:169], v[56:59]
	v_mfma_f32_16x16x32_bf16 v[52:55], v[80:83], v[132:135], v[52:55]
	v_mfma_f32_16x16x32_bf16 v[48:51], v[80:83], v[156:159], v[48:51]
	v_mfma_f32_16x16x32_bf16 v[44:47], v[194:197], v[152:155], v[44:47]
	v_mfma_f32_16x16x32_bf16 v[40:43], v[194:197], v[166:169], v[40:43]
	v_mfma_f32_16x16x32_bf16 v[36:39], v[202:205], v[132:135], v[36:39]
	v_mfma_f32_16x16x32_bf16 v[32:35], v[202:205], v[156:159], v[32:35]
	v_mfma_f32_16x16x32_bf16 v[224:227], v[84:87], v[152:155], v[52:55]
	v_mfma_f32_16x16x32_bf16 v[228:231], v[84:87], v[166:169], v[48:51]
	v_mfma_f32_16x16x32_bf16 v[130:133], v[208:211], v[152:155], v[36:39]
	v_mfma_f32_16x16x32_bf16 v[152:155], v[208:211], v[166:169], v[32:35]
	v_mfma_f32_16x16x32_bf16 v[28:31], v[64:67], v[96:99], v[28:31]
	v_mfma_f32_16x16x32_bf16 v[24:27], v[64:67], v[112:115], v[24:27]
	v_mfma_f32_16x16x32_bf16 v[12:15], v[186:189], v[96:99], v[12:15]
	v_mfma_f32_16x16x32_bf16 v[8:11], v[186:189], v[112:115], v[8:11]
	v_mfma_f32_16x16x32_bf16 v[28:31], v[68:71], v[100:103], v[28:31]
	v_mfma_f32_16x16x32_bf16 v[24:27], v[68:71], v[116:119], v[24:27]
	v_mfma_f32_16x16x32_bf16 v[20:23], v[80:83], v[96:99], v[20:23]
	v_mfma_f32_16x16x32_bf16 v[16:19], v[80:83], v[112:115], v[16:19]
	v_mfma_f32_16x16x32_bf16 v[12:15], v[194:197], v[100:103], v[12:15]
	v_mfma_f32_16x16x32_bf16 v[8:11], v[194:197], v[116:119], v[8:11]
	v_mfma_f32_16x16x32_bf16 v[4:7], v[202:205], v[96:99], v[4:7]
	v_mfma_f32_16x16x32_bf16 v[0:3], v[202:205], v[112:115], v[0:3]
	v_mfma_f32_16x16x32_bf16 v[156:159], v[84:87], v[100:103], v[20:23]
	v_mfma_f32_16x16x32_bf16 v[166:169], v[84:87], v[116:119], v[16:19]
	v_mfma_f32_16x16x32_bf16 v[186:189], v[208:211], v[100:103], v[4:7]
	v_mfma_f32_16x16x32_bf16 v[194:197], v[208:211], v[116:119], v[0:3]
	s_barrier
	s_nop 1
	ds_read_b128 v[0:3], v150
	ds_read_b128 v[4:7], v150 offset:1024
	ds_read_b128 v[202:205], v150 offset:2048
	ds_read_b128 v[148:151], v150 offset:3072
	ds_read_b128 v[16:19], v144 offset:32768
	ds_read_b128 v[20:23], v144 offset:33792
	ds_read_b128 v[32:35], v143 offset:32768
	ds_read_b128 v[36:39], v143 offset:33792
	ds_read_b128 v[48:51], v142 offset:32768
	ds_read_b128 v[52:55], v142 offset:33792
	ds_read_b128 v[208:211], v141 offset:32768
	ds_read_b128 v[232:235], v141 offset:33792
	s_waitcnt vmcnt(2)
	s_barrier
	s_waitcnt lgkmcnt(0)
	s_waitcnt lgkmcnt(0)
	v_mfma_f32_16x16x32_bf16 v[64:67], v[16:19], v[0:3], v[124:127]
	v_mfma_f32_16x16x32_bf16 v[112:115], v[20:23], v[4:7], v[64:67]
	v_mfma_f32_16x16x32_bf16 v[64:67], v[16:19], v[202:205], v[120:123]
	v_mfma_f32_16x16x32_bf16 v[116:119], v[20:23], v[148:151], v[64:67]
	v_mfma_f32_16x16x32_bf16 v[64:67], v[32:35], v[0:3], v[162:165]
	v_mfma_f32_16x16x32_bf16 v[96:99], v[36:39], v[4:7], v[64:67]
	v_mfma_f32_16x16x32_bf16 v[64:67], v[32:35], v[202:205], v[212:215]
	v_mfma_f32_16x16x32_bf16 v[100:103], v[36:39], v[148:151], v[64:67]
	v_mfma_f32_16x16x32_bf16 v[64:67], v[48:51], v[0:3], v[108:111]
	v_mfma_f32_16x16x32_bf16 v[80:83], v[52:55], v[4:7], v[64:67]
	v_mfma_f32_16x16x32_bf16 v[64:67], v[48:51], v[202:205], v[104:107]
	v_mfma_f32_16x16x32_bf16 v[84:87], v[52:55], v[148:151], v[64:67]
	v_mfma_f32_16x16x32_bf16 v[64:67], v[208:211], v[0:3], v[216:219]
	v_mfma_f32_16x16x32_bf16 v[68:71], v[208:211], v[202:205], v[220:223]
	v_mfma_f32_16x16x32_bf16 v[64:67], v[232:235], v[4:7], v[64:67]
	v_mfma_f32_16x16x32_bf16 v[68:71], v[232:235], v[148:151], v[68:71]
	s_barrier
; #define LDA(dst, b, h) for (int m = 0; m < 4; ++m) for (int k = 0; k < 2; ++k) \
;     dst[m][k] = *reinterpret_cast<const bf16x8*>((char*)SA(b, h) + lds_byte(wr * 64 + m * 16 + fr, k * 32 + fq * 8))
; #define LDB(dst, b, h) for (int n = 0; n < 2; ++n) for (int k = 0; k < 2; ++k) \
;     dst[n][k] = *reinterpret_cast<const bf16x8*>((char*)SB(b, h) + lds_byte(wc * 32 + n * 16 + fr, k * 32 + fq * 8))
; #define MMA(ai, bj, At, Bt_) do { __builtin_amdgcn_s_setprio(1); \
;     for (int m = 0; m < 4; ++m) for (int n = 0; n < 2; ++n) for (int k = 0; k < 2; ++k) \
;       acc[ai][bj][m][n] = __builtin_amdgcn_mfma_f32_16x16x32_bf16(At[m][k], Bt_[n][k], acc[ai][bj][m][n], 0, 0, 0); \
;     __builtin_amdgcn_s_setprio(0); } while (0)
; #define WAIT_V(n) asm volatile("s_waitcnt vmcnt(" #n ")" ::: "memory")
; #define WAIT_L(n) asm volatile("s_waitcnt lgkmcnt(" #n ")" ::: "memory")
; #define BAR __builtin_amdgcn_s_barrier()
; template <bool ABLK, class Epi>
; __device__ __forceinline__ void gemm_tile(const bf16* __restrict__ A, int lda, const bf16* __restrict__ Bt, int ldb, int K,
;                                           int brow, int bcol, bf16* shm, const Epi& epi, int wv) {
;     ...
;     LDB(B1, 1, 1); WAIT_V(0); BAR; WAIT_L(0); MMA(0, 1, At, B1); BAR;
;     LDA(At, 1, 1); BAR; WAIT_L(0); MMA(1, 0, At, B0); MMA(1, 1, At, B1); BAR; }
;   if (wr == 0) BAR;
	ds_read_b128 v[160:163], v147
	ds_read_b128 v[212:215], v147 offset:1024
	ds_read_b128 v[216:219], v147 offset:2048
	ds_read_b128 v[220:223], v147 offset:3072
	s_waitcnt vmcnt(0)
	s_barrier
	s_waitcnt lgkmcnt(0)
	s_waitcnt lgkmcnt(0)
	v_mfma_f32_16x16x32_bf16 v[92:95], v[16:19], v[160:163], v[92:95]
	v_mfma_f32_16x16x32_bf16 v[16:19], v[16:19], v[216:219], v[88:91]
	v_mfma_f32_16x16x32_bf16 v[124:127], v[20:23], v[220:223], v[16:19]
	v_mfma_f32_16x16x32_bf16 v[16:19], v[32:35], v[160:163], v[170:173]
	v_mfma_f32_16x16x32_bf16 v[104:107], v[36:39], v[212:215], v[16:19]
	v_mfma_f32_16x16x32_bf16 v[16:19], v[32:35], v[216:219], v[174:177]
	v_mfma_f32_16x16x32_bf16 v[108:111], v[36:39], v[220:223], v[16:19]
	v_mfma_f32_16x16x32_bf16 v[16:19], v[48:51], v[160:163], v[76:79]
	v_mfma_f32_16x16x32_bf16 v[88:91], v[52:55], v[212:215], v[16:19]
	v_mfma_f32_16x16x32_bf16 v[16:19], v[48:51], v[216:219], v[72:75]
	v_mfma_f32_16x16x32_bf16 v[120:123], v[20:23], v[212:215], v[92:95]
	v_mfma_f32_16x16x32_bf16 v[92:95], v[52:55], v[220:223], v[16:19]
	v_mfma_f32_16x16x32_bf16 v[16:19], v[208:211], v[160:163], v[178:181]
	v_mfma_f32_16x16x32_bf16 v[72:75], v[232:235], v[212:215], v[16:19]
	v_mfma_f32_16x16x32_bf16 v[16:19], v[208:211], v[216:219], v[182:185]
	v_mfma_f32_16x16x32_bf16 v[76:79], v[232:235], v[220:223], v[16:19]
	s_barrier
	ds_read_b128 v[170:173], v144 offset:49152
	ds_read_b128 v[144:147], v144 offset:50176
	ds_read_b128 v[174:177], v143 offset:49152
	ds_read_b128 v[178:181], v143 offset:50176
	ds_read_b128 v[182:185], v142 offset:49152
	ds_read_b128 v[208:211], v142 offset:50176
	ds_read_b128 v[232:235], v141 offset:49152
	ds_read_b128 v[236:239], v141 offset:50176
	s_barrier
	s_waitcnt lgkmcnt(0)
	s_waitcnt lgkmcnt(0)
	v_mfma_f32_16x16x32_bf16 v[16:19], v[170:173], v[0:3], v[60:63]
	v_mfma_f32_16x16x32_bf16 v[48:51], v[144:147], v[4:7], v[16:19]
	v_mfma_f32_16x16x32_bf16 v[16:19], v[170:173], v[202:205], v[56:59]
	v_mfma_f32_16x16x32_bf16 v[52:55], v[144:147], v[148:151], v[16:19]
	v_mfma_f32_16x16x32_bf16 v[16:19], v[174:177], v[0:3], v[224:227]
	v_mfma_f32_16x16x32_bf16 v[32:35], v[178:181], v[4:7], v[16:19]
	v_mfma_f32_16x16x32_bf16 v[16:19], v[174:177], v[202:205], v[228:231]
	v_mfma_f32_16x16x32_bf16 v[36:39], v[178:181], v[148:151], v[16:19]
	v_mfma_f32_16x16x32_bf16 v[16:19], v[182:185], v[0:3], v[44:47]
	v_mfma_f32_16x16x32_bf16 v[0:3], v[232:235], v[0:3], v[130:133]
	v_mfma_f32_16x16x32_bf16 v[16:19], v[208:211], v[4:7], v[16:19]
	v_mfma_f32_16x16x32_bf16 v[20:23], v[182:185], v[202:205], v[40:43]
	v_mfma_f32_16x16x32_bf16 v[0:3], v[236:239], v[4:7], v[0:3]
	v_mfma_f32_16x16x32_bf16 v[4:7], v[232:235], v[202:205], v[152:155]
	v_mfma_f32_16x16x32_bf16 v[20:23], v[208:211], v[148:151], v[20:23]
	v_mfma_f32_16x16x32_bf16 v[4:7], v[236:239], v[148:151], v[4:7]
	v_mfma_f32_16x16x32_bf16 v[24:27], v[170:173], v[216:219], v[24:27]
	v_mfma_f32_16x16x32_bf16 v[60:63], v[144:147], v[220:223], v[24:27]
	v_mfma_f32_16x16x32_bf16 v[24:27], v[174:177], v[160:163], v[156:159]
	v_mfma_f32_16x16x32_bf16 v[28:31], v[170:173], v[160:163], v[28:31]
	v_mfma_f32_16x16x32_bf16 v[40:43], v[178:181], v[212:215], v[24:27]
	v_mfma_f32_16x16x32_bf16 v[24:27], v[174:177], v[216:219], v[166:169]
	v_mfma_f32_16x16x32_bf16 v[12:15], v[182:185], v[160:163], v[12:15]
	v_mfma_f32_16x16x32_bf16 v[8:11], v[182:185], v[216:219], v[8:11]
	v_mfma_f32_16x16x32_bf16 v[56:59], v[144:147], v[212:215], v[28:31]
	v_mfma_f32_16x16x32_bf16 v[44:47], v[178:181], v[220:223], v[24:27]
	v_mfma_f32_16x16x32_bf16 v[24:27], v[208:211], v[212:215], v[12:15]
	v_mfma_f32_16x16x32_bf16 v[28:31], v[208:211], v[220:223], v[8:11]
	v_mfma_f32_16x16x32_bf16 v[8:11], v[232:235], v[160:163], v[186:189]
	v_mfma_f32_16x16x32_bf16 v[12:15], v[232:235], v[216:219], v[194:197]
	v_mfma_f32_16x16x32_bf16 v[8:11], v[236:239], v[212:215], v[8:11]
	v_mfma_f32_16x16x32_bf16 v[12:15], v[236:239], v[220:223], v[12:15]
	v_cmp_gt_u32_e32 vcc, s81, v128
	s_barrier
	s_and_saveexec_b64 s[64:65], vcc
	s_cbranch_execz .LBB0_581
	s_barrier
	s_branch .LBB0_581

; #define STAGE_A(P, hf, kt) do { if constexpr (ABLK) { const bf16* _gp = A + ((long)(brow >> 8) * nt + (kt)) * 16384 + (hf) * 8192; GLDS2(_gp, 4096, offA, P); } \
;     else { const bf16* _gp = A + (long)(brow + (hf) * HALF) * lda + (long)(kt) * BK; GLDS2(_gp, 64 * (long)lda, offA, P); } } while (0)
; #define STAGE_B(P, hf, kt) do { const bf16* _gp = Bt + (long)(bcol + (hf) * 2) * ldb + (long)(kt) * BK; GLDS2(_gp, 128 * (long)ldb, offB, P); } while (0)
; #define LDA(dst, b, h) for (int m = 0; m < 4; ++m) for (int k = 0; k < 2; ++k) \
;     dst[m][k] = *reinterpret_cast<const bf16x8*>((char*)SA(b, h) + lds_byte(wr * 64 + m * 16 + fr, k * 32 + fq * 8))
; #define LDB(dst, b, h) for (int n = 0; n < 2; ++n) for (int k = 0; k < 2; ++k) \
;     dst[n][k] = *reinterpret_cast<const bf16x8*>((char*)SB(b, h) + lds_byte(wc * 32 + n * 16 + fr, k * 32 + fq * 8))
; #define MMA(ai, bj, At, Bt_) do { __builtin_amdgcn_s_setprio(1); \
;     for (int m = 0; m < 4; ++m) for (int n = 0; n < 2; ++n) for (int k = 0; k < 2; ++k) \
;       acc[ai][bj][m][n] = __builtin_amdgcn_mfma_f32_16x16x32_bf16(At[m][k], Bt_[n][k], acc[ai][bj][m][n], 0, 0, 0); \
;     __builtin_amdgcn_s_setprio(0); } while (0)
; #define WAIT_V(n) asm volatile("s_waitcnt vmcnt(" #n ")" ::: "memory")
; #define WAIT_L(n) asm volatile("s_waitcnt lgkmcnt(" #n ")" ::: "memory")
; #define BAR __builtin_amdgcn_s_barrier()
; #define SCHED __builtin_amdgcn_sched_barrier(0)
; template <bool ABLK, class Epi>
; __device__ __forceinline__ void gemm_tile(const bf16* __restrict__ A, int lda, const bf16* __restrict__ Bt, int ldb, int K,
;                                           int brow, int bcol, bf16* shm, const Epi& epi, int wv) {
;     ...
;     LDB(B0, 0, 0); SCHED; LDA(At, 0, 0); STAGE_A(SA(1, 1), 1, t + 1);
;     WAIT_L(8); BAR; MMA(0, 0, At, B0); BAR; SCHED;
;     LDB(B1, 0, 1); STAGE_B(SB(0, 0), 0, t + 2);
;     BAR; MMA(0, 1, At, B1); BAR;
;     LDA(At, 0, 1); STAGE_A(SA(0, 0), 0, t + 2);
;     BAR; MMA(1, 0, At, B0); BAR; SCHED;
;     STAGE_B(SB(0, 1), 1, t + 2);
;     WAIT_V(6); BAR; MMA(1, 1, At, B1); BAR;
.LBB0_632:
	ds_read_b128 v[164:167], v160
	ds_read_b128 v[168:171], v160 offset:1024
	ds_read_b128 v[172:175], v160 offset:2048
	ds_read_b128 v[176:179], v160 offset:3072
	v_add_u32_e32 v161, 0xc000, v141
	v_lshl_add_u64 v[162:163], v[130:131], 0, s[22:23]
	s_add_i32 m0, s99, 0xc000
	ds_read_b128 v[180:183], v148
	ds_read_b128 v[184:187], v148 offset:1024
	ds_read_b128 v[194:197], v147
	ds_read_b128 v[202:205], v147 offset:1024
	ds_read_b128 v[208:211], v146
	ds_read_b128 v[212:215], v146 offset:1024
	ds_read_b128 v[216:219], v145
	ds_read_b128 v[220:223], v145 offset:1024
	global_load_lds_dwordx4 v[162:163], off
	v_add_u32_e32 v162, 0xe000, v141
	s_add_i32 m0, s99, 0xe000
	v_lshl_add_u64 v[190:191], v[130:131], 0, s[24:25]
	global_load_lds_dwordx4 v[190:191], off
	s_waitcnt lgkmcnt(8)
	s_barrier
	s_waitcnt lgkmcnt(0)
	v_mfma_f32_16x16x32_bf16 v[124:127], v[180:183], v[164:167], v[124:127]
	v_mfma_f32_16x16x32_bf16 v[120:123], v[180:183], v[172:175], v[120:123]
	v_mfma_f32_16x16x32_bf16 v[116:119], v[194:197], v[164:167], v[116:119]
	v_mfma_f32_16x16x32_bf16 v[112:115], v[194:197], v[172:175], v[112:115]
	v_mfma_f32_16x16x32_bf16 v[108:111], v[208:211], v[164:167], v[108:111]
	v_mfma_f32_16x16x32_bf16 v[104:107], v[208:211], v[172:175], v[104:107]
	v_mfma_f32_16x16x32_bf16 v[100:103], v[216:219], v[164:167], v[100:103]
	v_mfma_f32_16x16x32_bf16 v[96:99], v[216:219], v[172:175], v[96:99]
	v_mfma_f32_16x16x32_bf16 v[124:127], v[184:187], v[168:171], v[124:127]
	v_mfma_f32_16x16x32_bf16 v[120:123], v[184:187], v[176:179], v[120:123]
	v_mfma_f32_16x16x32_bf16 v[116:119], v[202:205], v[168:171], v[116:119]
	v_mfma_f32_16x16x32_bf16 v[112:115], v[202:205], v[176:179], v[112:115]
	v_mfma_f32_16x16x32_bf16 v[108:111], v[212:215], v[168:171], v[108:111]
	v_mfma_f32_16x16x32_bf16 v[104:107], v[212:215], v[176:179], v[104:107]
	v_mfma_f32_16x16x32_bf16 v[100:103], v[220:223], v[168:171], v[100:103]
	v_mfma_f32_16x16x32_bf16 v[96:99], v[220:223], v[176:179], v[96:99]
	s_barrier
	v_lshl_add_u64 v[190:191], v[132:133], 0, s[26:27]
	s_add_i32 m0, s99, 0x10000
	ds_read_b128 v[224:227], v159
	ds_read_b128 v[228:231], v159 offset:1024
	ds_read_b128 v[232:235], v159 offset:2048
	ds_read_b128 v[236:239], v159 offset:3072
	global_load_lds_dwordx4 v[190:191], off
	s_add_i32 m0, s99, 0x12000
	v_lshl_add_u64 v[190:191], v[132:133], 0, s[30:31]
	global_load_lds_dwordx4 v[190:191], off
	s_barrier
	s_waitcnt lgkmcnt(0)
	v_mfma_f32_16x16x32_bf16 v[92:95], v[180:183], v[224:227], v[92:95]
	v_mfma_f32_16x16x32_bf16 v[88:91], v[180:183], v[232:235], v[88:91]
	v_mfma_f32_16x16x32_bf16 v[84:87], v[194:197], v[224:227], v[84:87]
	v_mfma_f32_16x16x32_bf16 v[80:83], v[194:197], v[232:235], v[80:83]
	v_mfma_f32_16x16x32_bf16 v[76:79], v[208:211], v[224:227], v[76:79]
	v_mfma_f32_16x16x32_bf16 v[72:75], v[208:211], v[232:235], v[72:75]
	v_mfma_f32_16x16x32_bf16 v[68:71], v[216:219], v[224:227], v[68:71]
	v_mfma_f32_16x16x32_bf16 v[64:67], v[216:219], v[232:235], v[64:67]
	v_mfma_f32_16x16x32_bf16 v[92:95], v[184:187], v[228:231], v[92:95]
	v_mfma_f32_16x16x32_bf16 v[88:91], v[184:187], v[236:239], v[88:91]
	v_mfma_f32_16x16x32_bf16 v[84:87], v[202:205], v[228:231], v[84:87]
	v_mfma_f32_16x16x32_bf16 v[80:83], v[202:205], v[236:239], v[80:83]
	v_mfma_f32_16x16x32_bf16 v[76:79], v[212:215], v[228:231], v[76:79]
	v_mfma_f32_16x16x32_bf16 v[72:75], v[212:215], v[236:239], v[72:75]
	v_mfma_f32_16x16x32_bf16 v[68:71], v[220:223], v[228:231], v[68:71]
	v_mfma_f32_16x16x32_bf16 v[64:67], v[220:223], v[236:239], v[64:67]
	v_lshl_add_u64 v[190:191], v[130:131], 0, s[34:35]
	s_add_i32 m0, s99, 0x0
	s_barrier
	ds_read_b128 v[180:183], v148 offset:16384
	ds_read_b128 v[184:187], v148 offset:17408
	ds_read_b128 v[194:197], v147 offset:16384
	ds_read_b128 v[202:205], v147 offset:17408
	ds_read_b128 v[208:211], v146 offset:16384
	ds_read_b128 v[212:215], v146 offset:17408
	ds_read_b128 v[216:219], v145 offset:16384
	ds_read_b128 v[220:223], v145 offset:17408
	global_load_lds_dwordx4 v[190:191], off
	s_add_i32 m0, s99, 0x2000
	v_lshl_add_u64 v[190:191], v[130:131], 0, s[36:37]
	global_load_lds_dwordx4 v[190:191], off
	s_barrier
	s_waitcnt lgkmcnt(0)
	v_mfma_f32_16x16x32_bf16 v[60:63], v[180:183], v[164:167], v[60:63]
	v_mfma_f32_16x16x32_bf16 v[56:59], v[180:183], v[172:175], v[56:59]
	v_mfma_f32_16x16x32_bf16 v[52:55], v[194:197], v[164:167], v[52:55]
	v_mfma_f32_16x16x32_bf16 v[48:51], v[194:197], v[172:175], v[48:51]
	v_mfma_f32_16x16x32_bf16 v[44:47], v[208:211], v[164:167], v[44:47]
	v_mfma_f32_16x16x32_bf16 v[40:43], v[208:211], v[172:175], v[40:43]
	v_mfma_f32_16x16x32_bf16 v[36:39], v[216:219], v[164:167], v[36:39]
	v_mfma_f32_16x16x32_bf16 v[32:35], v[216:219], v[172:175], v[32:35]
	v_mfma_f32_16x16x32_bf16 v[60:63], v[184:187], v[168:171], v[60:63]
	v_mfma_f32_16x16x32_bf16 v[56:59], v[184:187], v[176:179], v[56:59]
	v_mfma_f32_16x16x32_bf16 v[52:55], v[202:205], v[168:171], v[52:55]
	v_mfma_f32_16x16x32_bf16 v[48:51], v[202:205], v[176:179], v[48:51]
	v_mfma_f32_16x16x32_bf16 v[44:47], v[212:215], v[168:171], v[44:47]
	v_mfma_f32_16x16x32_bf16 v[40:43], v[212:215], v[176:179], v[40:43]
	v_mfma_f32_16x16x32_bf16 v[36:39], v[220:223], v[168:171], v[36:39]
	v_mfma_f32_16x16x32_bf16 v[32:35], v[220:223], v[176:179], v[32:35]
	s_barrier
	s_add_i32 m0, s99, 0x14000
	v_lshl_add_u64 v[164:165], v[132:133], 0, s[38:39]
	global_load_lds_dwordx4 v[164:165], off
	s_add_i32 m0, s99, 0x16000
	v_lshl_add_u64 v[164:165], v[132:133], 0, s[40:41]
	global_load_lds_dwordx4 v[164:165], off
	s_waitcnt vmcnt(6)
	s_barrier
; #define STAGE_A(P, hf, kt) do { if constexpr (ABLK) { const bf16* _gp = A + ((long)(brow >> 8) * nt + (kt)) * 16384 + (hf) * 8192; GLDS2(_gp, 4096, offA, P); } \
;     else { const bf16* _gp = A + (long)(brow + (hf) * HALF) * lda + (long)(kt) * BK; GLDS2(_gp, 64 * (long)lda, offA, P); } } while (0)
; #define STAGE_B(P, hf, kt) do { const bf16* _gp = Bt + (long)(bcol + (hf) * 2) * ldb + (long)(kt) * BK; GLDS2(_gp, 128 * (long)ldb, offB, P); } while (0)
; #define LDA(dst, b, h) for (int m = 0; m < 4; ++m) for (int k = 0; k < 2; ++k) \
;     dst[m][k] = *reinterpret_cast<const bf16x8*>((char*)SA(b, h) + lds_byte(wr * 64 + m * 16 + fr, k * 32 + fq * 8))
; #define LDB(dst, b, h) for (int n = 0; n < 2; ++n) for (int k = 0; k < 2; ++k) \
;     dst[n][k] = *reinterpret_cast<const bf16x8*>((char*)SB(b, h) + lds_byte(wc * 32 + n * 16 + fr, k * 32 + fq * 8))
; #define MMA(ai, bj, At, Bt_) do { __builtin_amdgcn_s_setprio(1); \
;     for (int m = 0; m < 4; ++m) for (int n = 0; n < 2; ++n) for (int k = 0; k < 2; ++k) \
;       acc[ai][bj][m][n] = __builtin_amdgcn_mfma_f32_16x16x32_bf16(At[m][k], Bt_[n][k], acc[ai][bj][m][n], 0, 0, 0); \
;     __builtin_amdgcn_s_setprio(0); } while (0)
; #define WAIT_V(n) asm volatile("s_waitcnt vmcnt(" #n ")" ::: "memory")
; #define WAIT_L(n) asm volatile("s_waitcnt lgkmcnt(" #n ")" ::: "memory")
; #define BAR __builtin_amdgcn_s_barrier()
; #define SCHED __builtin_amdgcn_sched_barrier(0)
; template <bool ABLK, class Epi>
; __device__ __forceinline__ void gemm_tile(const bf16* __restrict__ A, int lda, const bf16* __restrict__ Bt, int ldb, int K,
;                                           int brow, int bcol, bf16* shm, const Epi& epi, int wv) {
;     ...
;     WAIT_V(6); BAR; MMA(1, 1, At, B1); BAR;
;     LDB(B0, 1, 0); SCHED; LDA(At, 1, 0); STAGE_A(SA(0, 1), 1, t + 2);
;     WAIT_L(8); BAR; MMA(0, 0, At, B0); BAR; SCHED;
;     LDB(B1, 1, 1); STAGE_B(SB(1, 0), 0, t + 3);
;     BAR; MMA(0, 1, At, B1); BAR;
;     LDA(At, 1, 1); STAGE_A(SA(1, 0), 0, t + 3);
	v_mfma_f32_16x16x32_bf16 v[28:31], v[180:183], v[224:227], v[28:31]
	v_mfma_f32_16x16x32_bf16 v[24:27], v[180:183], v[232:235], v[24:27]
	v_mfma_f32_16x16x32_bf16 v[20:23], v[194:197], v[224:227], v[20:23]
	v_mfma_f32_16x16x32_bf16 v[16:19], v[194:197], v[232:235], v[16:19]
	v_mfma_f32_16x16x32_bf16 v[12:15], v[208:211], v[224:227], v[12:15]
	v_mfma_f32_16x16x32_bf16 v[8:11], v[208:211], v[232:235], v[8:11]
	v_mfma_f32_16x16x32_bf16 v[4:7], v[216:219], v[224:227], v[4:7]
	v_mfma_f32_16x16x32_bf16 v[0:3], v[216:219], v[232:235], v[0:3]
	v_mfma_f32_16x16x32_bf16 v[28:31], v[184:187], v[228:231], v[28:31]
	v_mfma_f32_16x16x32_bf16 v[24:27], v[184:187], v[236:239], v[24:27]
	v_mfma_f32_16x16x32_bf16 v[20:23], v[202:205], v[228:231], v[20:23]
	v_mfma_f32_16x16x32_bf16 v[16:19], v[202:205], v[236:239], v[16:19]
	v_mfma_f32_16x16x32_bf16 v[12:15], v[212:215], v[228:231], v[12:15]
	v_mfma_f32_16x16x32_bf16 v[8:11], v[212:215], v[236:239], v[8:11]
	v_mfma_f32_16x16x32_bf16 v[4:7], v[220:223], v[228:231], v[4:7]
	v_mfma_f32_16x16x32_bf16 v[0:3], v[220:223], v[236:239], v[0:3]
	s_barrier
	ds_read_b128 v[164:167], v149
	ds_read_b128 v[168:171], v149 offset:1024
	ds_read_b128 v[172:175], v149 offset:2048
	ds_read_b128 v[176:179], v149 offset:3072
	v_lshl_add_u64 v[190:191], v[130:131], 0, s[42:43]
	s_add_i32 m0, s99, 0x4000
	ds_read_b128 v[180:183], v148 offset:32768
	ds_read_b128 v[184:187], v148 offset:33792
	ds_read_b128 v[194:197], v147 offset:32768
	ds_read_b128 v[202:205], v147 offset:33792
	ds_read_b128 v[208:211], v146 offset:32768
	ds_read_b128 v[212:215], v146 offset:33792
	ds_read_b128 v[216:219], v145 offset:32768
	ds_read_b128 v[220:223], v145 offset:33792
	global_load_lds_dwordx4 v[190:191], off
	s_add_i32 m0, s99, 0x6000
	v_lshl_add_u64 v[190:191], v[130:131], 0, s[44:45]
	global_load_lds_dwordx4 v[190:191], off
	s_waitcnt lgkmcnt(8)
	s_barrier
	s_waitcnt lgkmcnt(0)
	v_mfma_f32_16x16x32_bf16 v[124:127], v[180:183], v[164:167], v[124:127]
	v_mfma_f32_16x16x32_bf16 v[120:123], v[180:183], v[172:175], v[120:123]
	v_mfma_f32_16x16x32_bf16 v[116:119], v[194:197], v[164:167], v[116:119]
	v_mfma_f32_16x16x32_bf16 v[112:115], v[194:197], v[172:175], v[112:115]
	v_mfma_f32_16x16x32_bf16 v[108:111], v[208:211], v[164:167], v[108:111]
	v_mfma_f32_16x16x32_bf16 v[104:107], v[208:211], v[172:175], v[104:107]
	v_mfma_f32_16x16x32_bf16 v[100:103], v[216:219], v[164:167], v[100:103]
	v_mfma_f32_16x16x32_bf16 v[96:99], v[216:219], v[172:175], v[96:99]
	v_mfma_f32_16x16x32_bf16 v[124:127], v[184:187], v[168:171], v[124:127]
	v_mfma_f32_16x16x32_bf16 v[120:123], v[184:187], v[176:179], v[120:123]
	v_mfma_f32_16x16x32_bf16 v[116:119], v[202:205], v[168:171], v[116:119]
	v_mfma_f32_16x16x32_bf16 v[112:115], v[202:205], v[176:179], v[112:115]
	v_mfma_f32_16x16x32_bf16 v[108:111], v[212:215], v[168:171], v[108:111]
	v_mfma_f32_16x16x32_bf16 v[104:107], v[212:215], v[176:179], v[104:107]
	v_mfma_f32_16x16x32_bf16 v[100:103], v[220:223], v[168:171], v[100:103]
	v_mfma_f32_16x16x32_bf16 v[96:99], v[220:223], v[176:179], v[96:99]
	s_barrier
	v_lshl_add_u64 v[190:191], v[132:133], 0, s[46:47]
	s_add_i32 m0, s99, 0x18000
	ds_read_b128 v[224:227], v140
	ds_read_b128 v[228:231], v140 offset:1024
	ds_read_b128 v[232:235], v140 offset:2048
	ds_read_b128 v[236:239], v140 offset:3072
	global_load_lds_dwordx4 v[190:191], off
	s_add_i32 m0, s99, 0x1a000
	v_lshl_add_u64 v[190:191], v[132:133], 0, s[48:49]
	global_load_lds_dwordx4 v[190:191], off
	s_barrier
	s_waitcnt lgkmcnt(0)
	v_mfma_f32_16x16x32_bf16 v[92:95], v[180:183], v[224:227], v[92:95]
	v_mfma_f32_16x16x32_bf16 v[88:91], v[180:183], v[232:235], v[88:91]
	v_mfma_f32_16x16x32_bf16 v[84:87], v[194:197], v[224:227], v[84:87]
	v_mfma_f32_16x16x32_bf16 v[80:83], v[194:197], v[232:235], v[80:83]
	v_mfma_f32_16x16x32_bf16 v[76:79], v[208:211], v[224:227], v[76:79]
	v_mfma_f32_16x16x32_bf16 v[72:75], v[208:211], v[232:235], v[72:75]
	v_mfma_f32_16x16x32_bf16 v[68:71], v[216:219], v[224:227], v[68:71]
	v_mfma_f32_16x16x32_bf16 v[64:67], v[216:219], v[232:235], v[64:67]
	v_mfma_f32_16x16x32_bf16 v[92:95], v[184:187], v[228:231], v[92:95]
	v_mfma_f32_16x16x32_bf16 v[88:91], v[184:187], v[236:239], v[88:91]
	v_mfma_f32_16x16x32_bf16 v[84:87], v[202:205], v[228:231], v[84:87]
	v_mfma_f32_16x16x32_bf16 v[80:83], v[202:205], v[236:239], v[80:83]
	v_mfma_f32_16x16x32_bf16 v[76:79], v[212:215], v[228:231], v[76:79]
	v_mfma_f32_16x16x32_bf16 v[72:75], v[212:215], v[236:239], v[72:75]
	v_mfma_f32_16x16x32_bf16 v[68:71], v[220:223], v[228:231], v[68:71]
	v_mfma_f32_16x16x32_bf16 v[64:67], v[220:223], v[236:239], v[64:67]
	v_lshl_add_u64 v[190:191], v[130:131], 0, s[50:51]
	s_add_i32 m0, s99, 0x8000
	s_barrier
	ds_read_b128 v[180:183], v148 offset:49152
	ds_read_b128 v[184:187], v148 offset:50176
	ds_read_b128 v[194:197], v147 offset:49152
	ds_read_b128 v[202:205], v147 offset:50176
	ds_read_b128 v[208:211], v146 offset:49152
	ds_read_b128 v[212:215], v146 offset:50176
	ds_read_b128 v[216:219], v145 offset:49152
	ds_read_b128 v[220:223], v145 offset:50176
	global_load_lds_dwordx4 v[190:191], off
	s_add_i32 m0, s99, 0xa000
	s_nop 0
	global_load_lds_dwordx4 v[130:131], off
	s_barrier
; #define STAGE_A(P, hf, kt) do { if constexpr (ABLK) { const bf16* _gp = A + ((long)(brow >> 8) * nt + (kt)) * 16384 + (hf) * 8192; GLDS2(_gp, 4096, offA, P); } \
;     else { const bf16* _gp = A + (long)(brow + (hf) * HALF) * lda + (long)(kt) * BK; GLDS2(_gp, 64 * (long)lda, offA, P); } } while (0)
; #define STAGE_B(P, hf, kt) do { const bf16* _gp = Bt + (long)(bcol + (hf) * 2) * ldb + (long)(kt) * BK; GLDS2(_gp, 128 * (long)ldb, offB, P); } while (0)
; #define LDA(dst, b, h) for (int m = 0; m < 4; ++m) for (int k = 0; k < 2; ++k) \
;     dst[m][k] = *reinterpret_cast<const bf16x8*>((char*)SA(b, h) + lds_byte(wr * 64 + m * 16 + fr, k * 32 + fq * 8))
; #define LDB(dst, b, h) for (int n = 0; n < 2; ++n) for (int k = 0; k < 2; ++k) \
;     dst[n][k] = *reinterpret_cast<const bf16x8*>((char*)SB(b, h) + lds_byte(wc * 32 + n * 16 + fr, k * 32 + fq * 8))
; #define MMA(ai, bj, At, Bt_) do { __builtin_amdgcn_s_setprio(1); \
;     for (int m = 0; m < 4; ++m) for (int n = 0; n < 2; ++n) for (int k = 0; k < 2; ++k) \
;       acc[ai][bj][m][n] = __builtin_amdgcn_mfma_f32_16x16x32_bf16(At[m][k], Bt_[n][k], acc[ai][bj][m][n], 0, 0, 0); \
;     __builtin_amdgcn_s_setprio(0); } while (0)
; #define WAIT_V(n) asm volatile("s_waitcnt vmcnt(" #n ")" ::: "memory")
; #define WAIT_L(n) asm volatile("s_waitcnt lgkmcnt(" #n ")" ::: "memory")
; #define BAR __builtin_amdgcn_s_barrier()
; #define SCHED __builtin_amdgcn_sched_barrier(0)
; template <bool ABLK, class Epi>
; __device__ __forceinline__ void gemm_tile(const bf16* __restrict__ A, int lda, const bf16* __restrict__ Bt, int ldb, int K,
;                                           int brow, int bcol, bf16* shm, const Epi& epi, int wv) {
;     ...
;     BAR; MMA(1, 0, At, B0); BAR; SCHED;
;     STAGE_B(SB(1, 1), 1, t + 3);
;     WAIT_V(6); BAR; MMA(1, 1, At, B1); BAR;
;   }
;   { LDB(B0, 0, 0); LDA(At, 0, 0); STAGE_A(SA(1, 1), 1, nt - 1);
;     BAR; WAIT_L(0); MMA(0, 0, At, B0); BAR;
;     LDB(B1, 0, 1); BAR; WAIT_L(0); MMA(0, 1, At, B1); BAR;
	s_waitcnt lgkmcnt(0)
	v_mfma_f32_16x16x32_bf16 v[60:63], v[180:183], v[164:167], v[60:63]
	v_mfma_f32_16x16x32_bf16 v[56:59], v[180:183], v[172:175], v[56:59]
	v_mfma_f32_16x16x32_bf16 v[52:55], v[194:197], v[164:167], v[52:55]
	v_mfma_f32_16x16x32_bf16 v[48:51], v[194:197], v[172:175], v[48:51]
	v_mfma_f32_16x16x32_bf16 v[44:47], v[208:211], v[164:167], v[44:47]
	v_mfma_f32_16x16x32_bf16 v[40:43], v[208:211], v[172:175], v[40:43]
	v_mfma_f32_16x16x32_bf16 v[36:39], v[216:219], v[164:167], v[36:39]
	v_mfma_f32_16x16x32_bf16 v[32:35], v[216:219], v[172:175], v[32:35]
	v_mfma_f32_16x16x32_bf16 v[60:63], v[184:187], v[168:171], v[60:63]
	v_mfma_f32_16x16x32_bf16 v[56:59], v[184:187], v[176:179], v[56:59]
	v_mfma_f32_16x16x32_bf16 v[52:55], v[202:205], v[168:171], v[52:55]
	v_mfma_f32_16x16x32_bf16 v[48:51], v[202:205], v[176:179], v[48:51]
	v_mfma_f32_16x16x32_bf16 v[44:47], v[212:215], v[168:171], v[44:47]
	v_mfma_f32_16x16x32_bf16 v[40:43], v[212:215], v[176:179], v[40:43]
	v_mfma_f32_16x16x32_bf16 v[36:39], v[220:223], v[168:171], v[36:39]
	v_mfma_f32_16x16x32_bf16 v[32:35], v[220:223], v[176:179], v[32:35]
	s_barrier
	s_add_i32 m0, s99, 0x1c000
	v_lshl_add_u64 v[164:165], v[132:133], 0, s[52:53]
	global_load_lds_dwordx4 v[164:165], off
	s_add_i32 m0, s99, 0x1e000
	s_nop 0
	global_load_lds_dwordx4 v[132:133], off
	s_waitcnt vmcnt(6)
	s_barrier
	v_mfma_f32_16x16x32_bf16 v[28:31], v[180:183], v[224:227], v[28:31]
	v_mfma_f32_16x16x32_bf16 v[24:27], v[180:183], v[232:235], v[24:27]
	v_mfma_f32_16x16x32_bf16 v[20:23], v[194:197], v[224:227], v[20:23]
	v_mfma_f32_16x16x32_bf16 v[16:19], v[194:197], v[232:235], v[16:19]
	v_mfma_f32_16x16x32_bf16 v[12:15], v[208:211], v[224:227], v[12:15]
	v_mfma_f32_16x16x32_bf16 v[8:11], v[208:211], v[232:235], v[8:11]
	v_mfma_f32_16x16x32_bf16 v[4:7], v[216:219], v[224:227], v[4:7]
	v_mfma_f32_16x16x32_bf16 v[0:3], v[216:219], v[232:235], v[0:3]
	v_mfma_f32_16x16x32_bf16 v[28:31], v[184:187], v[228:231], v[28:31]
	v_mfma_f32_16x16x32_bf16 v[24:27], v[184:187], v[236:239], v[24:27]
	v_mfma_f32_16x16x32_bf16 v[20:23], v[202:205], v[228:231], v[20:23]
	v_mfma_f32_16x16x32_bf16 v[16:19], v[202:205], v[236:239], v[16:19]
	v_mfma_f32_16x16x32_bf16 v[12:15], v[212:215], v[228:231], v[12:15]
	v_mfma_f32_16x16x32_bf16 v[8:11], v[212:215], v[236:239], v[8:11]
	v_mfma_f32_16x16x32_bf16 v[4:7], v[220:223], v[228:231], v[4:7]
	v_mfma_f32_16x16x32_bf16 v[0:3], v[220:223], v[236:239], v[0:3]
	s_add_i32 s33, s33, 2
	v_lshl_add_u64 v[130:131], v[130:131], 0, s[54:55]
	s_cmpk_lt_u32 s33, 0x54
	v_lshl_add_u64 v[132:133], v[132:133], 0, s[56:57]
	s_barrier
	s_cbranch_scc1 .LBB0_632
	v_readfirstlane_b32 s2, v161
	v_lshl_add_u64 v[134:135], v[128:129], 0, s[58:59]
	s_mov_b32 m0, s2
	v_readfirstlane_b32 s2, v162
	ds_read_b128 v[130:133], v160
	ds_read_b128 v[150:153], v160 offset:1024
	ds_read_b128 v[154:157], v160 offset:2048
	ds_read_b128 v[164:167], v160 offset:3072
	ds_read_b128 v[168:171], v148
	ds_read_b128 v[172:175], v148 offset:1024
	ds_read_b128 v[176:179], v147
	ds_read_b128 v[180:183], v147 offset:1024
	ds_read_b128 v[184:187], v146
	ds_read_b128 v[194:197], v146 offset:1024
	ds_read_b128 v[202:205], v145
	ds_read_b128 v[208:211], v145 offset:1024
	global_load_lds_dwordx4 v[134:135], off
	v_lshl_add_u64 v[128:129], v[128:129], 0, s[60:61]
	s_mov_b32 m0, s2
	s_nop 0
	global_load_lds_dwordx4 v[128:129], off
	s_barrier
	s_waitcnt lgkmcnt(0)
	s_waitcnt lgkmcnt(0)
	v_mfma_f32_16x16x32_bf16 v[116:119], v[176:179], v[130:133], v[116:119]
	v_mfma_f32_16x16x32_bf16 v[108:111], v[184:187], v[130:133], v[108:111]
	v_mfma_f32_16x16x32_bf16 v[104:107], v[184:187], v[154:157], v[104:107]
	v_mfma_f32_16x16x32_bf16 v[100:103], v[202:205], v[130:133], v[100:103]
	v_mfma_f32_16x16x32_bf16 v[96:99], v[202:205], v[154:157], v[96:99]
	v_mfma_f32_16x16x32_bf16 v[124:127], v[168:171], v[130:133], v[124:127]
	v_mfma_f32_16x16x32_bf16 v[120:123], v[168:171], v[154:157], v[120:123]
	v_mfma_f32_16x16x32_bf16 v[116:119], v[180:183], v[150:153], v[116:119]
	v_mfma_f32_16x16x32_bf16 v[112:115], v[176:179], v[154:157], v[112:115]
	v_mfma_f32_16x16x32_bf16 v[108:111], v[194:197], v[150:153], v[108:111]
	v_mfma_f32_16x16x32_bf16 v[104:107], v[194:197], v[164:167], v[104:107]
	v_mfma_f32_16x16x32_bf16 v[100:103], v[208:211], v[150:153], v[100:103]
	v_mfma_f32_16x16x32_bf16 v[96:99], v[208:211], v[164:167], v[96:99]
	v_mfma_f32_16x16x32_bf16 v[124:127], v[172:175], v[150:153], v[124:127]
	v_mfma_f32_16x16x32_bf16 v[120:123], v[172:175], v[164:167], v[120:123]
	v_mfma_f32_16x16x32_bf16 v[160:163], v[180:183], v[164:167], v[112:115]
	s_barrier
	s_nop 0
	ds_read_b128 v[112:115], v159
	ds_read_b128 v[212:215], v159 offset:1024
	ds_read_b128 v[216:219], v159 offset:2048
	ds_read_b128 v[220:223], v159 offset:3072
	s_barrier
	s_waitcnt lgkmcnt(0)
	s_waitcnt lgkmcnt(0)
	v_mfma_f32_16x16x32_bf16 v[84:87], v[176:179], v[112:115], v[84:87]
	v_mfma_f32_16x16x32_bf16 v[80:83], v[176:179], v[216:219], v[80:83]
	v_mfma_f32_16x16x32_bf16 v[92:95], v[168:171], v[112:115], v[92:95]
	v_mfma_f32_16x16x32_bf16 v[88:91], v[168:171], v[216:219], v[88:91]
	v_mfma_f32_16x16x32_bf16 v[84:87], v[180:183], v[212:215], v[84:87]
	v_mfma_f32_16x16x32_bf16 v[80:83], v[180:183], v[220:223], v[80:83]
	v_mfma_f32_16x16x32_bf16 v[76:79], v[184:187], v[112:115], v[76:79]
	v_mfma_f32_16x16x32_bf16 v[72:75], v[184:187], v[216:219], v[72:75]
	v_mfma_f32_16x16x32_bf16 v[68:71], v[202:205], v[112:115], v[68:71]
	v_mfma_f32_16x16x32_bf16 v[64:67], v[202:205], v[216:219], v[64:67]
	v_mfma_f32_16x16x32_bf16 v[224:227], v[172:175], v[212:215], v[92:95]
	v_mfma_f32_16x16x32_bf16 v[168:171], v[172:175], v[220:223], v[88:91]
	v_mfma_f32_16x16x32_bf16 v[172:175], v[194:197], v[212:215], v[76:79]
	v_mfma_f32_16x16x32_bf16 v[176:179], v[194:197], v[220:223], v[72:75]
	v_mfma_f32_16x16x32_bf16 v[180:183], v[208:211], v[212:215], v[68:71]
	v_mfma_f32_16x16x32_bf16 v[184:187], v[208:211], v[220:223], v[64:67]
	s_barrier
; #define LDA(dst, b, h) for (int m = 0; m < 4; ++m) for (int k = 0; k < 2; ++k) \
;     dst[m][k] = *reinterpret_cast<const bf16x8*>((char*)SA(b, h) + lds_byte(wr * 64 + m * 16 + fr, k * 32 + fq * 8))
; #define LDB(dst, b, h) for (int n = 0; n < 2; ++n) for (int k = 0; k < 2; ++k) \
;     dst[n][k] = *reinterpret_cast<const bf16x8*>((char*)SB(b, h) + lds_byte(wc * 32 + n * 16 + fr, k * 32 + fq * 8))
; #define MMA(ai, bj, At, Bt_) do { __builtin_amdgcn_s_setprio(1); \
;     for (int m = 0; m < 4; ++m) for (int n = 0; n < 2; ++n) for (int k = 0; k < 2; ++k) \
;       acc[ai][bj][m][n] = __builtin_amdgcn_mfma_f32_16x16x32_bf16(At[m][k], Bt_[n][k], acc[ai][bj][m][n], 0, 0, 0); \
;     __builtin_amdgcn_s_setprio(0); } while (0)
; #define WAIT_V(n) asm volatile("s_waitcnt vmcnt(" #n ")" ::: "memory")
; #define WAIT_L(n) asm volatile("s_waitcnt lgkmcnt(" #n ")" ::: "memory")
; #define BAR __builtin_amdgcn_s_barrier()
; template <bool ABLK, class Epi>
; __device__ __forceinline__ void gemm_tile(const bf16* __restrict__ A, int lda, const bf16* __restrict__ Bt, int ldb, int K,
;                                           int brow, int bcol, bf16* shm, const Epi& epi, int wv) {
;     ...
;     LDA(At, 0, 1); WAIT_V(4); BAR; WAIT_L(0); MMA(1, 0, At, B0); MMA(1, 1, At, B1); BAR; }
;   { LDB(B0, 1, 0); LDA(At, 1, 0); WAIT_V(2); BAR; WAIT_L(0); MMA(0, 0, At, B0); BAR;
	s_nop 0
	ds_read_b128 v[64:67], v148 offset:16384
	ds_read_b128 v[68:71], v148 offset:17408
	ds_read_b128 v[72:75], v147 offset:16384
	ds_read_b128 v[76:79], v147 offset:17408
	ds_read_b128 v[88:91], v146 offset:16384
	ds_read_b128 v[92:95], v146 offset:17408
	ds_read_b128 v[194:197], v145 offset:16384
	ds_read_b128 v[202:205], v145 offset:17408
	s_waitcnt vmcnt(4)
	s_barrier
	s_waitcnt lgkmcnt(0)
	s_waitcnt lgkmcnt(0)
	v_mfma_f32_16x16x32_bf16 v[60:63], v[64:67], v[130:133], v[60:63]
	v_mfma_f32_16x16x32_bf16 v[56:59], v[64:67], v[154:157], v[56:59]
	v_mfma_f32_16x16x32_bf16 v[44:47], v[88:91], v[130:133], v[44:47]
	v_mfma_f32_16x16x32_bf16 v[40:43], v[88:91], v[154:157], v[40:43]
	v_mfma_f32_16x16x32_bf16 v[60:63], v[68:71], v[150:153], v[60:63]
	v_mfma_f32_16x16x32_bf16 v[56:59], v[68:71], v[164:167], v[56:59]
	v_mfma_f32_16x16x32_bf16 v[52:55], v[72:75], v[130:133], v[52:55]
	v_mfma_f32_16x16x32_bf16 v[48:51], v[72:75], v[154:157], v[48:51]
	v_mfma_f32_16x16x32_bf16 v[44:47], v[92:95], v[150:153], v[44:47]
	v_mfma_f32_16x16x32_bf16 v[40:43], v[92:95], v[164:167], v[40:43]
	v_mfma_f32_16x16x32_bf16 v[36:39], v[194:197], v[130:133], v[36:39]
	v_mfma_f32_16x16x32_bf16 v[32:35], v[194:197], v[154:157], v[32:35]
	v_mfma_f32_16x16x32_bf16 v[208:211], v[76:79], v[150:153], v[52:55]
	v_mfma_f32_16x16x32_bf16 v[228:231], v[76:79], v[164:167], v[48:51]
	v_mfma_f32_16x16x32_bf16 v[128:131], v[202:205], v[150:153], v[36:39]
	v_mfma_f32_16x16x32_bf16 v[150:153], v[202:205], v[164:167], v[32:35]
	v_mfma_f32_16x16x32_bf16 v[28:31], v[64:67], v[112:115], v[28:31]
	v_mfma_f32_16x16x32_bf16 v[24:27], v[64:67], v[216:219], v[24:27]
	v_mfma_f32_16x16x32_bf16 v[12:15], v[88:91], v[112:115], v[12:15]
	v_mfma_f32_16x16x32_bf16 v[8:11], v[88:91], v[216:219], v[8:11]
	v_mfma_f32_16x16x32_bf16 v[28:31], v[68:71], v[212:215], v[28:31]
	v_mfma_f32_16x16x32_bf16 v[24:27], v[68:71], v[220:223], v[24:27]
	v_mfma_f32_16x16x32_bf16 v[20:23], v[72:75], v[112:115], v[20:23]
	v_mfma_f32_16x16x32_bf16 v[16:19], v[72:75], v[216:219], v[16:19]
	v_mfma_f32_16x16x32_bf16 v[12:15], v[92:95], v[212:215], v[12:15]
	v_mfma_f32_16x16x32_bf16 v[8:11], v[92:95], v[220:223], v[8:11]
	v_mfma_f32_16x16x32_bf16 v[4:7], v[194:197], v[112:115], v[4:7]
	v_mfma_f32_16x16x32_bf16 v[0:3], v[194:197], v[216:219], v[0:3]
	v_mfma_f32_16x16x32_bf16 v[154:157], v[76:79], v[212:215], v[20:23]
	v_mfma_f32_16x16x32_bf16 v[164:167], v[76:79], v[220:223], v[16:19]
	v_mfma_f32_16x16x32_bf16 v[212:215], v[202:205], v[212:215], v[4:7]
	v_mfma_f32_16x16x32_bf16 v[194:197], v[202:205], v[220:223], v[0:3]
	s_barrier
	s_nop 1
	ds_read_b128 v[0:3], v149
	ds_read_b128 v[4:7], v149 offset:1024
	ds_read_b128 v[202:205], v149 offset:2048
	ds_read_b128 v[216:219], v149 offset:3072
	ds_read_b128 v[16:19], v148 offset:32768
	ds_read_b128 v[20:23], v148 offset:33792
	ds_read_b128 v[32:35], v147 offset:32768
	ds_read_b128 v[36:39], v147 offset:33792
	ds_read_b128 v[48:51], v146 offset:32768
	ds_read_b128 v[52:55], v146 offset:33792
	ds_read_b128 v[220:223], v145 offset:32768
	ds_read_b128 v[232:235], v145 offset:33792
	s_waitcnt vmcnt(2)
	s_barrier
	s_waitcnt lgkmcnt(0)
	s_waitcnt lgkmcnt(0)
	v_mfma_f32_16x16x32_bf16 v[64:67], v[16:19], v[0:3], v[124:127]
	v_mfma_f32_16x16x32_bf16 v[132:135], v[20:23], v[4:7], v[64:67]
	v_mfma_f32_16x16x32_bf16 v[64:67], v[16:19], v[202:205], v[120:123]
	v_mfma_f32_16x16x32_bf16 v[112:115], v[20:23], v[216:219], v[64:67]
	v_mfma_f32_16x16x32_bf16 v[64:67], v[32:35], v[0:3], v[116:119]
	v_mfma_f32_16x16x32_bf16 v[88:91], v[36:39], v[4:7], v[64:67]
	v_mfma_f32_16x16x32_bf16 v[64:67], v[32:35], v[202:205], v[160:163]
	v_mfma_f32_16x16x32_bf16 v[92:95], v[36:39], v[216:219], v[64:67]
	v_mfma_f32_16x16x32_bf16 v[64:67], v[48:51], v[0:3], v[108:111]
	v_mfma_f32_16x16x32_bf16 v[72:75], v[52:55], v[4:7], v[64:67]
	v_mfma_f32_16x16x32_bf16 v[64:67], v[48:51], v[202:205], v[104:107]
	v_mfma_f32_16x16x32_bf16 v[76:79], v[52:55], v[216:219], v[64:67]
	v_mfma_f32_16x16x32_bf16 v[64:67], v[220:223], v[0:3], v[100:103]
	v_mfma_f32_16x16x32_bf16 v[68:71], v[220:223], v[202:205], v[96:99]
	v_mfma_f32_16x16x32_bf16 v[64:67], v[232:235], v[4:7], v[64:67]
	v_mfma_f32_16x16x32_bf16 v[68:71], v[232:235], v[216:219], v[68:71]
	s_barrier
; #define LDA(dst, b, h) for (int m = 0; m < 4; ++m) for (int k = 0; k < 2; ++k) \
;     dst[m][k] = *reinterpret_cast<const bf16x8*>((char*)SA(b, h) + lds_byte(wr * 64 + m * 16 + fr, k * 32 + fq * 8))
; #define LDB(dst, b, h) for (int n = 0; n < 2; ++n) for (int k = 0; k < 2; ++k) \
;     dst[n][k] = *reinterpret_cast<const bf16x8*>((char*)SB(b, h) + lds_byte(wc * 32 + n * 16 + fr, k * 32 + fq * 8))
; #define MMA(ai, bj, At, Bt_) do { __builtin_amdgcn_s_setprio(1); \
;     for (int m = 0; m < 4; ++m) for (int n = 0; n < 2; ++n) for (int k = 0; k < 2; ++k) \
;       acc[ai][bj][m][n] = __builtin_amdgcn_mfma_f32_16x16x32_bf16(At[m][k], Bt_[n][k], acc[ai][bj][m][n], 0, 0, 0); \
;     __builtin_amdgcn_s_setprio(0); } while (0)
; #define WAIT_V(n) asm volatile("s_waitcnt vmcnt(" #n ")" ::: "memory")
; #define WAIT_L(n) asm volatile("s_waitcnt lgkmcnt(" #n ")" ::: "memory")
; #define BAR __builtin_amdgcn_s_barrier()
; template <bool ABLK, class Epi>
; __device__ __forceinline__ void gemm_tile(const bf16* __restrict__ A, int lda, const bf16* __restrict__ Bt, int ldb, int K,
;                                           int brow, int bcol, bf16* shm, const Epi& epi, int wv) {
;     ...
;     LDB(B1, 1, 1); WAIT_V(0); BAR; WAIT_L(0); MMA(0, 1, At, B1); BAR;
;     LDA(At, 1, 1); BAR; WAIT_L(0); MMA(1, 0, At, B0); MMA(1, 1, At, B1); BAR; }
;   if (wr == 0) BAR;
	ds_read_b128 v[120:123], v140
	ds_read_b128 v[124:127], v140 offset:1024
	ds_read_b128 v[158:161], v140 offset:2048
	ds_read_b128 v[236:239], v140 offset:3072
	s_waitcnt vmcnt(0)
	s_barrier
	s_waitcnt lgkmcnt(0)
	s_waitcnt lgkmcnt(0)
	v_mfma_f32_16x16x32_bf16 v[96:99], v[16:19], v[120:123], v[224:227]
	v_mfma_f32_16x16x32_bf16 v[16:19], v[16:19], v[158:161], v[168:171]
	v_mfma_f32_16x16x32_bf16 v[116:119], v[20:23], v[236:239], v[16:19]
	v_mfma_f32_16x16x32_bf16 v[16:19], v[32:35], v[120:123], v[84:87]
	v_mfma_f32_16x16x32_bf16 v[104:107], v[36:39], v[124:127], v[16:19]
	v_mfma_f32_16x16x32_bf16 v[16:19], v[32:35], v[158:161], v[80:83]
	v_mfma_f32_16x16x32_bf16 v[108:111], v[36:39], v[236:239], v[16:19]
	v_mfma_f32_16x16x32_bf16 v[16:19], v[48:51], v[120:123], v[172:175]
	v_mfma_f32_16x16x32_bf16 v[140:143], v[20:23], v[124:127], v[96:99]
	v_mfma_f32_16x16x32_bf16 v[96:99], v[52:55], v[124:127], v[16:19]
	v_mfma_f32_16x16x32_bf16 v[16:19], v[48:51], v[158:161], v[176:179]
	v_mfma_f32_16x16x32_bf16 v[100:103], v[52:55], v[236:239], v[16:19]
	v_mfma_f32_16x16x32_bf16 v[16:19], v[220:223], v[120:123], v[180:183]
	v_mfma_f32_16x16x32_bf16 v[80:83], v[232:235], v[124:127], v[16:19]
	v_mfma_f32_16x16x32_bf16 v[16:19], v[220:223], v[158:161], v[184:187]
	v_mfma_f32_16x16x32_bf16 v[84:87], v[232:235], v[236:239], v[16:19]
	s_barrier
	ds_read_b128 v[168:171], v148 offset:49152
	ds_read_b128 v[172:175], v148 offset:50176
	ds_read_b128 v[176:179], v147 offset:49152
	ds_read_b128 v[180:183], v147 offset:50176
	ds_read_b128 v[184:187], v146 offset:49152
	ds_read_b128 v[146:149], v146 offset:50176
	ds_read_b128 v[220:223], v145 offset:49152
	ds_read_b128 v[224:227], v145 offset:50176
	s_barrier
	s_waitcnt lgkmcnt(0)
	s_waitcnt lgkmcnt(0)
	v_mfma_f32_16x16x32_bf16 v[16:19], v[168:171], v[0:3], v[60:63]
	v_mfma_f32_16x16x32_bf16 v[48:51], v[172:175], v[4:7], v[16:19]
	v_mfma_f32_16x16x32_bf16 v[16:19], v[168:171], v[202:205], v[56:59]
	v_mfma_f32_16x16x32_bf16 v[52:55], v[172:175], v[216:219], v[16:19]
	v_mfma_f32_16x16x32_bf16 v[16:19], v[176:179], v[0:3], v[208:211]
	v_mfma_f32_16x16x32_bf16 v[32:35], v[180:183], v[4:7], v[16:19]
	v_mfma_f32_16x16x32_bf16 v[16:19], v[176:179], v[202:205], v[228:231]
	v_mfma_f32_16x16x32_bf16 v[36:39], v[180:183], v[216:219], v[16:19]
	v_mfma_f32_16x16x32_bf16 v[16:19], v[184:187], v[0:3], v[44:47]
	v_mfma_f32_16x16x32_bf16 v[0:3], v[220:223], v[0:3], v[128:131]
	v_mfma_f32_16x16x32_bf16 v[16:19], v[146:149], v[4:7], v[16:19]
	v_mfma_f32_16x16x32_bf16 v[20:23], v[184:187], v[202:205], v[40:43]
	v_mfma_f32_16x16x32_bf16 v[0:3], v[224:227], v[4:7], v[0:3]
	v_mfma_f32_16x16x32_bf16 v[4:7], v[220:223], v[202:205], v[150:153]
	v_mfma_f32_16x16x32_bf16 v[20:23], v[146:149], v[216:219], v[20:23]
	v_mfma_f32_16x16x32_bf16 v[4:7], v[224:227], v[216:219], v[4:7]
	v_mfma_f32_16x16x32_bf16 v[24:27], v[168:171], v[158:161], v[24:27]
	v_mfma_f32_16x16x32_bf16 v[28:31], v[168:171], v[120:123], v[28:31]
	v_mfma_f32_16x16x32_bf16 v[60:63], v[172:175], v[236:239], v[24:27]
	v_mfma_f32_16x16x32_bf16 v[24:27], v[176:179], v[120:123], v[154:157]
	v_mfma_f32_16x16x32_bf16 v[8:11], v[184:187], v[158:161], v[8:11]
	v_mfma_f32_16x16x32_bf16 v[56:59], v[172:175], v[124:127], v[28:31]
	v_mfma_f32_16x16x32_bf16 v[40:43], v[180:183], v[124:127], v[24:27]
	v_mfma_f32_16x16x32_bf16 v[24:27], v[176:179], v[158:161], v[164:167]
	v_mfma_f32_16x16x32_bf16 v[12:15], v[184:187], v[120:123], v[12:15]
	v_mfma_f32_16x16x32_bf16 v[28:31], v[146:149], v[236:239], v[8:11]
	v_mfma_f32_16x16x32_bf16 v[8:11], v[220:223], v[120:123], v[212:215]
	v_mfma_f32_16x16x32_bf16 v[44:47], v[180:183], v[236:239], v[24:27]
	v_mfma_f32_16x16x32_bf16 v[24:27], v[146:149], v[124:127], v[12:15]
	v_mfma_f32_16x16x32_bf16 v[12:15], v[224:227], v[124:127], v[8:11]
	v_mfma_f32_16x16x32_bf16 v[8:11], v[220:223], v[158:161], v[194:197]
	v_mfma_f32_16x16x32_bf16 v[8:11], v[224:227], v[236:239], v[8:11]
	v_cmp_gt_u32_e32 vcc, s77, v136
	s_barrier
	s_and_saveexec_b64 s[62:63], vcc
	s_cbranch_execz .LBB0_628
	s_barrier
	s_branch .LBB0_628

; #define STAGE_A(P, hf, kt) do { if constexpr (ABLK) { const bf16* _gp = A + ((long)(brow >> 8) * nt + (kt)) * 16384 + (hf) * 8192; GLDS2(_gp, 4096, offA, P); } \
;     else { const bf16* _gp = A + (long)(brow + (hf) * HALF) * lda + (long)(kt) * BK; GLDS2(_gp, 64 * (long)lda, offA, P); } } while (0)
; #define STAGE_B(P, hf, kt) do { const bf16* _gp = Bt + (long)(bcol + (hf) * 2) * ldb + (long)(kt) * BK; GLDS2(_gp, 128 * (long)ldb, offB, P); } while (0)
; #define LDA(dst, b, h) for (int m = 0; m < 4; ++m) for (int k = 0; k < 2; ++k) \
;     dst[m][k] = *reinterpret_cast<const bf16x8*>((char*)SA(b, h) + lds_byte(wr * 64 + m * 16 + fr, k * 32 + fq * 8))
; #define LDB(dst, b, h) for (int n = 0; n < 2; ++n) for (int k = 0; k < 2; ++k) \
;     dst[n][k] = *reinterpret_cast<const bf16x8*>((char*)SB(b, h) + lds_byte(wc * 32 + n * 16 + fr, k * 32 + fq * 8))
; #define MMA(ai, bj, At, Bt_) do { __builtin_amdgcn_s_setprio(1); \
;     for (int m = 0; m < 4; ++m) for (int n = 0; n < 2; ++n) for (int k = 0; k < 2; ++k) \
;       acc[ai][bj][m][n] = __builtin_amdgcn_mfma_f32_16x16x32_bf16(At[m][k], Bt_[n][k], acc[ai][bj][m][n], 0, 0, 0); \
;     __builtin_amdgcn_s_setprio(0); } while (0)
; #define WAIT_V(n) asm volatile("s_waitcnt vmcnt(" #n ")" ::: "memory")
; #define WAIT_L(n) asm volatile("s_waitcnt lgkmcnt(" #n ")" ::: "memory")
; #define BAR __builtin_amdgcn_s_barrier()
; #define SCHED __builtin_amdgcn_sched_barrier(0)
; template <bool ABLK, class Epi>
; __device__ __forceinline__ void gemm_tile(const bf16* __restrict__ A, int lda, const bf16* __restrict__ Bt, int ldb, int K,
;                                           int brow, int bcol, bf16* shm, const Epi& epi, int wv) {
;     ...
;     LDB(B0, 0, 0); SCHED; LDA(At, 0, 0); STAGE_A(SA(1, 1), 1, t + 1);
;     WAIT_L(8); BAR; MMA(0, 0, At, B0); BAR; SCHED;
;     LDB(B1, 0, 1); STAGE_B(SB(0, 0), 0, t + 2);
;     BAR; MMA(0, 1, At, B1); BAR;
;     LDA(At, 0, 1); STAGE_A(SA(0, 0), 0, t + 2);
;     BAR; MMA(1, 0, At, B0); BAR; SCHED;
;     STAGE_B(SB(0, 1), 1, t + 2);
;     WAIT_V(6); BAR; MMA(1, 1, At, B1); BAR;
.LBB0_719:
	ds_read_b128 v[164:167], v161
	ds_read_b128 v[168:171], v161 offset:1024
	ds_read_b128 v[172:175], v161 offset:2048
	ds_read_b128 v[176:179], v161 offset:3072
	v_add_u32_e32 v162, 0xc000, v147
	v_add_u32_e32 v163, 0xe000, v147
	v_lshl_add_u64 v[198:199], v[130:131], 0, s[24:25]
	s_add_i32 m0, s99, 0xc000
	ds_read_b128 v[180:183], v143
	ds_read_b128 v[184:187], v143 offset:1024
	ds_read_b128 v[188:191], v142
	ds_read_b128 v[194:197], v142 offset:1024
	ds_read_b128 v[202:205], v141
	ds_read_b128 v[208:211], v141 offset:1024
	ds_read_b128 v[212:215], v140
	ds_read_b128 v[216:219], v140 offset:1024
	global_load_lds_dwordx4 v[198:199], off
	s_add_i32 m0, s99, 0xe000
	v_lshl_add_u64 v[198:199], v[130:131], 0, s[26:27]
	global_load_lds_dwordx4 v[198:199], off
	s_waitcnt lgkmcnt(8)
	s_barrier
	s_waitcnt lgkmcnt(0)
	v_mfma_f32_16x16x32_bf16 v[124:127], v[180:183], v[164:167], v[124:127]
	v_mfma_f32_16x16x32_bf16 v[120:123], v[180:183], v[172:175], v[120:123]
	v_mfma_f32_16x16x32_bf16 v[116:119], v[188:191], v[164:167], v[116:119]
	v_mfma_f32_16x16x32_bf16 v[112:115], v[188:191], v[172:175], v[112:115]
	v_mfma_f32_16x16x32_bf16 v[108:111], v[202:205], v[164:167], v[108:111]
	v_mfma_f32_16x16x32_bf16 v[104:107], v[202:205], v[172:175], v[104:107]
	v_mfma_f32_16x16x32_bf16 v[100:103], v[212:215], v[164:167], v[100:103]
	v_mfma_f32_16x16x32_bf16 v[96:99], v[212:215], v[172:175], v[96:99]
	v_mfma_f32_16x16x32_bf16 v[124:127], v[184:187], v[168:171], v[124:127]
	v_mfma_f32_16x16x32_bf16 v[120:123], v[184:187], v[176:179], v[120:123]
	v_mfma_f32_16x16x32_bf16 v[116:119], v[194:197], v[168:171], v[116:119]
	v_mfma_f32_16x16x32_bf16 v[112:115], v[194:197], v[176:179], v[112:115]
	v_mfma_f32_16x16x32_bf16 v[108:111], v[208:211], v[168:171], v[108:111]
	v_mfma_f32_16x16x32_bf16 v[104:107], v[208:211], v[176:179], v[104:107]
	v_mfma_f32_16x16x32_bf16 v[100:103], v[216:219], v[168:171], v[100:103]
	v_mfma_f32_16x16x32_bf16 v[96:99], v[216:219], v[176:179], v[96:99]
	s_barrier
	v_lshl_add_u64 v[198:199], v[132:133], 0, s[30:31]
	s_add_i32 m0, s99, 0x10000
	ds_read_b128 v[220:223], v160
	ds_read_b128 v[224:227], v160 offset:1024
	ds_read_b128 v[228:231], v160 offset:2048
	ds_read_b128 v[232:235], v160 offset:3072
	global_load_lds_dwordx4 v[198:199], off
	s_add_i32 m0, s99, 0x12000
	v_lshl_add_u64 v[198:199], v[132:133], 0, s[34:35]
	global_load_lds_dwordx4 v[198:199], off
	s_barrier
	s_waitcnt lgkmcnt(0)
	v_mfma_f32_16x16x32_bf16 v[92:95], v[180:183], v[220:223], v[92:95]
	v_mfma_f32_16x16x32_bf16 v[88:91], v[180:183], v[228:231], v[88:91]
	v_mfma_f32_16x16x32_bf16 v[84:87], v[188:191], v[220:223], v[84:87]
	v_mfma_f32_16x16x32_bf16 v[80:83], v[188:191], v[228:231], v[80:83]
	v_mfma_f32_16x16x32_bf16 v[76:79], v[202:205], v[220:223], v[76:79]
	v_mfma_f32_16x16x32_bf16 v[72:75], v[202:205], v[228:231], v[72:75]
	v_mfma_f32_16x16x32_bf16 v[68:71], v[212:215], v[220:223], v[68:71]
	v_mfma_f32_16x16x32_bf16 v[64:67], v[212:215], v[228:231], v[64:67]
	v_mfma_f32_16x16x32_bf16 v[92:95], v[184:187], v[224:227], v[92:95]
	v_mfma_f32_16x16x32_bf16 v[88:91], v[184:187], v[232:235], v[88:91]
	v_mfma_f32_16x16x32_bf16 v[84:87], v[194:197], v[224:227], v[84:87]
	v_mfma_f32_16x16x32_bf16 v[80:83], v[194:197], v[232:235], v[80:83]
	v_mfma_f32_16x16x32_bf16 v[76:79], v[208:211], v[224:227], v[76:79]
	v_mfma_f32_16x16x32_bf16 v[72:75], v[208:211], v[232:235], v[72:75]
	v_mfma_f32_16x16x32_bf16 v[68:71], v[216:219], v[224:227], v[68:71]
	v_mfma_f32_16x16x32_bf16 v[64:67], v[216:219], v[232:235], v[64:67]
	v_lshl_add_u64 v[198:199], v[130:131], 0, s[36:37]
	s_add_i32 m0, s99, 0x0
	s_barrier
	ds_read_b128 v[180:183], v143 offset:16384
	ds_read_b128 v[184:187], v143 offset:17408
	ds_read_b128 v[188:191], v142 offset:16384
	ds_read_b128 v[194:197], v142 offset:17408
	ds_read_b128 v[202:205], v141 offset:16384
	ds_read_b128 v[208:211], v141 offset:17408
	ds_read_b128 v[212:215], v140 offset:16384
	ds_read_b128 v[216:219], v140 offset:17408
	global_load_lds_dwordx4 v[198:199], off
	s_add_i32 m0, s99, 0x2000
	v_lshl_add_u64 v[198:199], v[130:131], 0, s[38:39]
	global_load_lds_dwordx4 v[198:199], off
	s_barrier
	s_waitcnt lgkmcnt(0)
	v_mfma_f32_16x16x32_bf16 v[60:63], v[180:183], v[164:167], v[60:63]
	v_mfma_f32_16x16x32_bf16 v[56:59], v[180:183], v[172:175], v[56:59]
	v_mfma_f32_16x16x32_bf16 v[52:55], v[188:191], v[164:167], v[52:55]
	v_mfma_f32_16x16x32_bf16 v[48:51], v[188:191], v[172:175], v[48:51]
	v_mfma_f32_16x16x32_bf16 v[44:47], v[202:205], v[164:167], v[44:47]
	v_mfma_f32_16x16x32_bf16 v[40:43], v[202:205], v[172:175], v[40:43]
	v_mfma_f32_16x16x32_bf16 v[36:39], v[212:215], v[164:167], v[36:39]
	v_mfma_f32_16x16x32_bf16 v[32:35], v[212:215], v[172:175], v[32:35]
	v_mfma_f32_16x16x32_bf16 v[60:63], v[184:187], v[168:171], v[60:63]
	v_mfma_f32_16x16x32_bf16 v[56:59], v[184:187], v[176:179], v[56:59]
	v_mfma_f32_16x16x32_bf16 v[52:55], v[194:197], v[168:171], v[52:55]
	v_mfma_f32_16x16x32_bf16 v[48:51], v[194:197], v[176:179], v[48:51]
	v_mfma_f32_16x16x32_bf16 v[44:47], v[208:211], v[168:171], v[44:47]
	v_mfma_f32_16x16x32_bf16 v[40:43], v[208:211], v[176:179], v[40:43]
	v_mfma_f32_16x16x32_bf16 v[36:39], v[216:219], v[168:171], v[36:39]
	v_mfma_f32_16x16x32_bf16 v[32:35], v[216:219], v[176:179], v[32:35]
	s_barrier
	s_add_i32 m0, s99, 0x14000
	v_lshl_add_u64 v[164:165], v[132:133], 0, s[40:41]
	global_load_lds_dwordx4 v[164:165], off
	s_add_i32 m0, s99, 0x16000
	v_lshl_add_u64 v[164:165], v[132:133], 0, s[42:43]
	global_load_lds_dwordx4 v[164:165], off
	s_waitcnt vmcnt(6)
	s_barrier
; #define STAGE_A(P, hf, kt) do { if constexpr (ABLK) { const bf16* _gp = A + ((long)(brow >> 8) * nt + (kt)) * 16384 + (hf) * 8192; GLDS2(_gp, 4096, offA, P); } \
;     else { const bf16* _gp = A + (long)(brow + (hf) * HALF) * lda + (long)(kt) * BK; GLDS2(_gp, 64 * (long)lda, offA, P); } } while (0)
; #define STAGE_B(P, hf, kt) do { const bf16* _gp = Bt + (long)(bcol + (hf) * 2) * ldb + (long)(kt) * BK; GLDS2(_gp, 128 * (long)ldb, offB, P); } while (0)
; #define LDA(dst, b, h) for (int m = 0; m < 4; ++m) for (int k = 0; k < 2; ++k) \
;     dst[m][k] = *reinterpret_cast<const bf16x8*>((char*)SA(b, h) + lds_byte(wr * 64 + m * 16 + fr, k * 32 + fq * 8))
; #define LDB(dst, b, h) for (int n = 0; n < 2; ++n) for (int k = 0; k < 2; ++k) \
;     dst[n][k] = *reinterpret_cast<const bf16x8*>((char*)SB(b, h) + lds_byte(wc * 32 + n * 16 + fr, k * 32 + fq * 8))
; #define MMA(ai, bj, At, Bt_) do { __builtin_amdgcn_s_setprio(1); \
;     for (int m = 0; m < 4; ++m) for (int n = 0; n < 2; ++n) for (int k = 0; k < 2; ++k) \
;       acc[ai][bj][m][n] = __builtin_amdgcn_mfma_f32_16x16x32_bf16(At[m][k], Bt_[n][k], acc[ai][bj][m][n], 0, 0, 0); \
;     __builtin_amdgcn_s_setprio(0); } while (0)
; #define WAIT_V(n) asm volatile("s_waitcnt vmcnt(" #n ")" ::: "memory")
; #define WAIT_L(n) asm volatile("s_waitcnt lgkmcnt(" #n ")" ::: "memory")
; #define BAR __builtin_amdgcn_s_barrier()
; #define SCHED __builtin_amdgcn_sched_barrier(0)
; template <bool ABLK, class Epi>
; __device__ __forceinline__ void gemm_tile(const bf16* __restrict__ A, int lda, const bf16* __restrict__ Bt, int ldb, int K,
;                                           int brow, int bcol, bf16* shm, const Epi& epi, int wv) {
;     ...
;     WAIT_V(6); BAR; MMA(1, 1, At, B1); BAR;
;     LDB(B0, 1, 0); SCHED; LDA(At, 1, 0); STAGE_A(SA(0, 1), 1, t + 2);
;     WAIT_L(8); BAR; MMA(0, 0, At, B0); BAR; SCHED;
;     LDB(B1, 1, 1); STAGE_B(SB(1, 0), 0, t + 3);
;     BAR; MMA(0, 1, At, B1); BAR;
;     LDA(At, 1, 1); STAGE_A(SA(1, 0), 0, t + 3);
	v_mfma_f32_16x16x32_bf16 v[28:31], v[180:183], v[220:223], v[28:31]
	v_mfma_f32_16x16x32_bf16 v[24:27], v[180:183], v[228:231], v[24:27]
	v_mfma_f32_16x16x32_bf16 v[20:23], v[188:191], v[220:223], v[20:23]
	v_mfma_f32_16x16x32_bf16 v[16:19], v[188:191], v[228:231], v[16:19]
	v_mfma_f32_16x16x32_bf16 v[12:15], v[202:205], v[220:223], v[12:15]
	v_mfma_f32_16x16x32_bf16 v[8:11], v[202:205], v[228:231], v[8:11]
	v_mfma_f32_16x16x32_bf16 v[4:7], v[212:215], v[220:223], v[4:7]
	v_mfma_f32_16x16x32_bf16 v[0:3], v[212:215], v[228:231], v[0:3]
	v_mfma_f32_16x16x32_bf16 v[28:31], v[184:187], v[224:227], v[28:31]
	v_mfma_f32_16x16x32_bf16 v[24:27], v[184:187], v[232:235], v[24:27]
	v_mfma_f32_16x16x32_bf16 v[20:23], v[194:197], v[224:227], v[20:23]
	v_mfma_f32_16x16x32_bf16 v[16:19], v[194:197], v[232:235], v[16:19]
	v_mfma_f32_16x16x32_bf16 v[12:15], v[208:211], v[224:227], v[12:15]
	v_mfma_f32_16x16x32_bf16 v[8:11], v[208:211], v[232:235], v[8:11]
	v_mfma_f32_16x16x32_bf16 v[4:7], v[216:219], v[224:227], v[4:7]
	v_mfma_f32_16x16x32_bf16 v[0:3], v[216:219], v[232:235], v[0:3]
	s_barrier
	ds_read_b128 v[164:167], v149
	ds_read_b128 v[168:171], v149 offset:1024
	ds_read_b128 v[172:175], v149 offset:2048
	ds_read_b128 v[176:179], v149 offset:3072
	v_lshl_add_u64 v[198:199], v[130:131], 0, s[44:45]
	s_add_i32 m0, s99, 0x4000
	ds_read_b128 v[180:183], v143 offset:32768
	ds_read_b128 v[184:187], v143 offset:33792
	ds_read_b128 v[188:191], v142 offset:32768
	ds_read_b128 v[194:197], v142 offset:33792
	ds_read_b128 v[202:205], v141 offset:32768
	ds_read_b128 v[208:211], v141 offset:33792
	ds_read_b128 v[212:215], v140 offset:32768
	ds_read_b128 v[216:219], v140 offset:33792
	global_load_lds_dwordx4 v[198:199], off
	s_add_i32 m0, s99, 0x6000
	v_lshl_add_u64 v[198:199], v[130:131], 0, s[46:47]
	global_load_lds_dwordx4 v[198:199], off
	s_waitcnt lgkmcnt(8)
	s_barrier
	s_waitcnt lgkmcnt(0)
	v_mfma_f32_16x16x32_bf16 v[124:127], v[180:183], v[164:167], v[124:127]
	v_mfma_f32_16x16x32_bf16 v[120:123], v[180:183], v[172:175], v[120:123]
	v_mfma_f32_16x16x32_bf16 v[116:119], v[188:191], v[164:167], v[116:119]
	v_mfma_f32_16x16x32_bf16 v[112:115], v[188:191], v[172:175], v[112:115]
	v_mfma_f32_16x16x32_bf16 v[108:111], v[202:205], v[164:167], v[108:111]
	v_mfma_f32_16x16x32_bf16 v[104:107], v[202:205], v[172:175], v[104:107]
	v_mfma_f32_16x16x32_bf16 v[100:103], v[212:215], v[164:167], v[100:103]
	v_mfma_f32_16x16x32_bf16 v[96:99], v[212:215], v[172:175], v[96:99]
	v_mfma_f32_16x16x32_bf16 v[124:127], v[184:187], v[168:171], v[124:127]
	v_mfma_f32_16x16x32_bf16 v[120:123], v[184:187], v[176:179], v[120:123]
	v_mfma_f32_16x16x32_bf16 v[116:119], v[194:197], v[168:171], v[116:119]
	v_mfma_f32_16x16x32_bf16 v[112:115], v[194:197], v[176:179], v[112:115]
	v_mfma_f32_16x16x32_bf16 v[108:111], v[208:211], v[168:171], v[108:111]
	v_mfma_f32_16x16x32_bf16 v[104:107], v[208:211], v[176:179], v[104:107]
	v_mfma_f32_16x16x32_bf16 v[100:103], v[216:219], v[168:171], v[100:103]
	v_mfma_f32_16x16x32_bf16 v[96:99], v[216:219], v[176:179], v[96:99]
	s_barrier
	v_lshl_add_u64 v[198:199], v[132:133], 0, s[48:49]
	s_add_i32 m0, s99, 0x18000
	ds_read_b128 v[220:223], v146
	ds_read_b128 v[224:227], v146 offset:1024
	ds_read_b128 v[228:231], v146 offset:2048
	ds_read_b128 v[232:235], v146 offset:3072
	global_load_lds_dwordx4 v[198:199], off
	s_add_i32 m0, s99, 0x1a000
	v_lshl_add_u64 v[198:199], v[132:133], 0, s[50:51]
	global_load_lds_dwordx4 v[198:199], off
	s_barrier
	s_waitcnt lgkmcnt(0)
	v_mfma_f32_16x16x32_bf16 v[92:95], v[180:183], v[220:223], v[92:95]
	v_mfma_f32_16x16x32_bf16 v[88:91], v[180:183], v[228:231], v[88:91]
	v_mfma_f32_16x16x32_bf16 v[84:87], v[188:191], v[220:223], v[84:87]
	v_mfma_f32_16x16x32_bf16 v[80:83], v[188:191], v[228:231], v[80:83]
	v_mfma_f32_16x16x32_bf16 v[76:79], v[202:205], v[220:223], v[76:79]
	v_mfma_f32_16x16x32_bf16 v[72:75], v[202:205], v[228:231], v[72:75]
	v_mfma_f32_16x16x32_bf16 v[68:71], v[212:215], v[220:223], v[68:71]
	v_mfma_f32_16x16x32_bf16 v[64:67], v[212:215], v[228:231], v[64:67]
	v_mfma_f32_16x16x32_bf16 v[92:95], v[184:187], v[224:227], v[92:95]
	v_mfma_f32_16x16x32_bf16 v[88:91], v[184:187], v[232:235], v[88:91]
	v_mfma_f32_16x16x32_bf16 v[84:87], v[194:197], v[224:227], v[84:87]
	v_mfma_f32_16x16x32_bf16 v[80:83], v[194:197], v[232:235], v[80:83]
	v_mfma_f32_16x16x32_bf16 v[76:79], v[208:211], v[224:227], v[76:79]
	v_mfma_f32_16x16x32_bf16 v[72:75], v[208:211], v[232:235], v[72:75]
	v_mfma_f32_16x16x32_bf16 v[68:71], v[216:219], v[224:227], v[68:71]
	v_mfma_f32_16x16x32_bf16 v[64:67], v[216:219], v[232:235], v[64:67]
	v_lshl_add_u64 v[198:199], v[130:131], 0, s[50:51]
	s_add_i32 m0, s99, 0x8000
	s_barrier
	ds_read_b128 v[180:183], v143 offset:49152
	ds_read_b128 v[184:187], v143 offset:50176
	ds_read_b128 v[188:191], v142 offset:49152
	ds_read_b128 v[194:197], v142 offset:50176
	ds_read_b128 v[202:205], v141 offset:49152
	ds_read_b128 v[208:211], v141 offset:50176
	ds_read_b128 v[212:215], v140 offset:49152
	ds_read_b128 v[216:219], v140 offset:50176
	global_load_lds_dwordx4 v[198:199], off
	s_add_i32 m0, s99, 0xa000
	s_nop 0
	global_load_lds_dwordx4 v[130:131], off
	s_barrier
; #define STAGE_A(P, hf, kt) do { if constexpr (ABLK) { const bf16* _gp = A + ((long)(brow >> 8) * nt + (kt)) * 16384 + (hf) * 8192; GLDS2(_gp, 4096, offA, P); } \
;     else { const bf16* _gp = A + (long)(brow + (hf) * HALF) * lda + (long)(kt) * BK; GLDS2(_gp, 64 * (long)lda, offA, P); } } while (0)
; #define STAGE_B(P, hf, kt) do { const bf16* _gp = Bt + (long)(bcol + (hf) * 2) * ldb + (long)(kt) * BK; GLDS2(_gp, 128 * (long)ldb, offB, P); } while (0)
; #define LDA(dst, b, h) for (int m = 0; m < 4; ++m) for (int k = 0; k < 2; ++k) \
;     dst[m][k] = *reinterpret_cast<const bf16x8*>((char*)SA(b, h) + lds_byte(wr * 64 + m * 16 + fr, k * 32 + fq * 8))
; #define LDB(dst, b, h) for (int n = 0; n < 2; ++n) for (int k = 0; k < 2; ++k) \
;     dst[n][k] = *reinterpret_cast<const bf16x8*>((char*)SB(b, h) + lds_byte(wc * 32 + n * 16 + fr, k * 32 + fq * 8))
; #define MMA(ai, bj, At, Bt_) do { __builtin_amdgcn_s_setprio(1); \
;     for (int m = 0; m < 4; ++m) for (int n = 0; n < 2; ++n) for (int k = 0; k < 2; ++k) \
;       acc[ai][bj][m][n] = __builtin_amdgcn_mfma_f32_16x16x32_bf16(At[m][k], Bt_[n][k], acc[ai][bj][m][n], 0, 0, 0); \
;     __builtin_amdgcn_s_setprio(0); } while (0)
; #define WAIT_V(n) asm volatile("s_waitcnt vmcnt(" #n ")" ::: "memory")
; #define WAIT_L(n) asm volatile("s_waitcnt lgkmcnt(" #n ")" ::: "memory")
; #define BAR __builtin_amdgcn_s_barrier()
; #define SCHED __builtin_amdgcn_sched_barrier(0)
; template <bool ABLK, class Epi>
; __device__ __forceinline__ void gemm_tile(const bf16* __restrict__ A, int lda, const bf16* __restrict__ Bt, int ldb, int K,
;                                           int brow, int bcol, bf16* shm, const Epi& epi, int wv) {
;     ...
;     LDA(At, 1, 1); STAGE_A(SA(1, 0), 0, t + 3);
;     BAR; MMA(1, 0, At, B0); BAR; SCHED;
;     STAGE_B(SB(1, 1), 1, t + 3);
;     WAIT_V(6); BAR; MMA(1, 1, At, B1); BAR;
;   }
;   { LDB(B0, 0, 0); LDA(At, 0, 0); STAGE_A(SA(1, 1), 1, nt - 1);
;     BAR; WAIT_L(0); MMA(0, 0, At, B0); BAR;
;     LDB(B1, 0, 1); BAR; WAIT_L(0); MMA(0, 1, At, B1); BAR;
	s_waitcnt lgkmcnt(0)
	v_mfma_f32_16x16x32_bf16 v[60:63], v[180:183], v[164:167], v[60:63]
	v_mfma_f32_16x16x32_bf16 v[56:59], v[180:183], v[172:175], v[56:59]
	v_mfma_f32_16x16x32_bf16 v[52:55], v[188:191], v[164:167], v[52:55]
	v_mfma_f32_16x16x32_bf16 v[48:51], v[188:191], v[172:175], v[48:51]
	v_mfma_f32_16x16x32_bf16 v[44:47], v[202:205], v[164:167], v[44:47]
	v_mfma_f32_16x16x32_bf16 v[40:43], v[202:205], v[172:175], v[40:43]
	v_mfma_f32_16x16x32_bf16 v[36:39], v[212:215], v[164:167], v[36:39]
	v_mfma_f32_16x16x32_bf16 v[32:35], v[212:215], v[172:175], v[32:35]
	v_mfma_f32_16x16x32_bf16 v[60:63], v[184:187], v[168:171], v[60:63]
	v_mfma_f32_16x16x32_bf16 v[56:59], v[184:187], v[176:179], v[56:59]
	v_mfma_f32_16x16x32_bf16 v[52:55], v[194:197], v[168:171], v[52:55]
	v_mfma_f32_16x16x32_bf16 v[48:51], v[194:197], v[176:179], v[48:51]
	v_mfma_f32_16x16x32_bf16 v[44:47], v[208:211], v[168:171], v[44:47]
	v_mfma_f32_16x16x32_bf16 v[40:43], v[208:211], v[176:179], v[40:43]
	v_mfma_f32_16x16x32_bf16 v[36:39], v[216:219], v[168:171], v[36:39]
	v_mfma_f32_16x16x32_bf16 v[32:35], v[216:219], v[176:179], v[32:35]
	s_barrier
	s_add_i32 m0, s99, 0x1c000
	v_lshl_add_u64 v[164:165], v[132:133], 0, s[52:53]
	global_load_lds_dwordx4 v[164:165], off
	s_add_i32 m0, s99, 0x1e000
	s_nop 0
	global_load_lds_dwordx4 v[132:133], off
	s_waitcnt vmcnt(6)
	s_barrier
	v_mfma_f32_16x16x32_bf16 v[28:31], v[180:183], v[220:223], v[28:31]
	v_mfma_f32_16x16x32_bf16 v[24:27], v[180:183], v[228:231], v[24:27]
	v_mfma_f32_16x16x32_bf16 v[20:23], v[188:191], v[220:223], v[20:23]
	v_mfma_f32_16x16x32_bf16 v[16:19], v[188:191], v[228:231], v[16:19]
	v_mfma_f32_16x16x32_bf16 v[12:15], v[202:205], v[220:223], v[12:15]
	v_mfma_f32_16x16x32_bf16 v[8:11], v[202:205], v[228:231], v[8:11]
	v_mfma_f32_16x16x32_bf16 v[4:7], v[212:215], v[220:223], v[4:7]
	v_mfma_f32_16x16x32_bf16 v[0:3], v[212:215], v[228:231], v[0:3]
	v_mfma_f32_16x16x32_bf16 v[28:31], v[184:187], v[224:227], v[28:31]
	v_mfma_f32_16x16x32_bf16 v[24:27], v[184:187], v[232:235], v[24:27]
	v_mfma_f32_16x16x32_bf16 v[20:23], v[194:197], v[224:227], v[20:23]
	v_mfma_f32_16x16x32_bf16 v[16:19], v[194:197], v[232:235], v[16:19]
	v_mfma_f32_16x16x32_bf16 v[12:15], v[208:211], v[224:227], v[12:15]
	v_mfma_f32_16x16x32_bf16 v[8:11], v[208:211], v[232:235], v[8:11]
	v_mfma_f32_16x16x32_bf16 v[4:7], v[216:219], v[224:227], v[4:7]
	v_mfma_f32_16x16x32_bf16 v[0:3], v[216:219], v[232:235], v[0:3]
	s_add_i32 s33, s33, 2
	v_lshl_add_u64 v[130:131], v[130:131], 0, s[54:55]
	s_cmp_lt_u32 s33, 28
	v_lshl_add_u64 v[132:133], v[132:133], 0, s[56:57]
	s_barrier
	s_cbranch_scc1 .LBB0_719
	v_readfirstlane_b32 s2, v162
	v_lshl_add_u64 v[144:145], v[128:129], 0, s[58:59]
	s_mov_b32 m0, s2
	v_readfirstlane_b32 s2, v163
	ds_read_b128 v[130:133], v161
	ds_read_b128 v[150:153], v161 offset:1024
	ds_read_b128 v[154:157], v161 offset:2048
	ds_read_b128 v[164:167], v161 offset:3072
	ds_read_b128 v[168:171], v143
	ds_read_b128 v[172:175], v143 offset:1024
	ds_read_b128 v[176:179], v142
	ds_read_b128 v[180:183], v142 offset:1024
	ds_read_b128 v[184:187], v141
	ds_read_b128 v[188:191], v141 offset:1024
	ds_read_b128 v[194:197], v140
	ds_read_b128 v[202:205], v140 offset:1024
	global_load_lds_dwordx4 v[144:145], off
	v_lshl_add_u64 v[128:129], v[128:129], 0, s[60:61]
	s_mov_b32 m0, s2
	s_nop 0
	global_load_lds_dwordx4 v[128:129], off
	s_barrier
	s_waitcnt lgkmcnt(0)
	s_waitcnt lgkmcnt(0)
	v_mfma_f32_16x16x32_bf16 v[124:127], v[168:171], v[130:133], v[124:127]
	v_mfma_f32_16x16x32_bf16 v[120:123], v[168:171], v[154:157], v[120:123]
	v_mfma_f32_16x16x32_bf16 v[108:111], v[184:187], v[130:133], v[108:111]
	v_mfma_f32_16x16x32_bf16 v[104:107], v[184:187], v[154:157], v[104:107]
	v_mfma_f32_16x16x32_bf16 v[124:127], v[172:175], v[150:153], v[124:127]
	v_mfma_f32_16x16x32_bf16 v[120:123], v[172:175], v[164:167], v[120:123]
	v_mfma_f32_16x16x32_bf16 v[116:119], v[176:179], v[130:133], v[116:119]
	v_mfma_f32_16x16x32_bf16 v[112:115], v[176:179], v[154:157], v[112:115]
	v_mfma_f32_16x16x32_bf16 v[108:111], v[188:191], v[150:153], v[108:111]
	v_mfma_f32_16x16x32_bf16 v[104:107], v[188:191], v[164:167], v[104:107]
	v_mfma_f32_16x16x32_bf16 v[100:103], v[194:197], v[130:133], v[100:103]
	v_mfma_f32_16x16x32_bf16 v[96:99], v[194:197], v[154:157], v[96:99]
	v_mfma_f32_16x16x32_bf16 v[208:211], v[180:183], v[150:153], v[116:119]
	v_mfma_f32_16x16x32_bf16 v[212:215], v[180:183], v[164:167], v[112:115]
	v_mfma_f32_16x16x32_bf16 v[216:219], v[202:205], v[150:153], v[100:103]
	v_mfma_f32_16x16x32_bf16 v[220:223], v[202:205], v[164:167], v[96:99]
	s_barrier
	s_nop 1
	ds_read_b128 v[96:99], v160
	ds_read_b128 v[100:103], v160 offset:1024
	ds_read_b128 v[112:115], v160 offset:2048
	ds_read_b128 v[116:119], v160 offset:3072
	s_barrier
	s_waitcnt lgkmcnt(0)
	s_waitcnt lgkmcnt(0)
	v_mfma_f32_16x16x32_bf16 v[92:95], v[168:171], v[96:99], v[92:95]
	v_mfma_f32_16x16x32_bf16 v[88:91], v[168:171], v[112:115], v[88:91]
	v_mfma_f32_16x16x32_bf16 v[76:79], v[184:187], v[96:99], v[76:79]
	v_mfma_f32_16x16x32_bf16 v[72:75], v[184:187], v[112:115], v[72:75]
	v_mfma_f32_16x16x32_bf16 v[68:71], v[194:197], v[96:99], v[68:71]
	v_mfma_f32_16x16x32_bf16 v[64:67], v[194:197], v[112:115], v[64:67]
	v_mfma_f32_16x16x32_bf16 v[92:95], v[172:175], v[100:103], v[92:95]
	v_mfma_f32_16x16x32_bf16 v[88:91], v[172:175], v[116:119], v[88:91]
	v_mfma_f32_16x16x32_bf16 v[84:87], v[176:179], v[96:99], v[84:87]
	v_mfma_f32_16x16x32_bf16 v[80:83], v[176:179], v[112:115], v[80:83]
	v_mfma_f32_16x16x32_bf16 v[76:79], v[188:191], v[100:103], v[76:79]
	v_mfma_f32_16x16x32_bf16 v[72:75], v[188:191], v[116:119], v[72:75]
	v_mfma_f32_16x16x32_bf16 v[68:71], v[202:205], v[100:103], v[68:71]
	v_mfma_f32_16x16x32_bf16 v[64:67], v[202:205], v[116:119], v[64:67]
	v_mfma_f32_16x16x32_bf16 v[158:161], v[180:183], v[100:103], v[84:87]
	v_mfma_f32_16x16x32_bf16 v[168:171], v[180:183], v[116:119], v[80:83]
	s_barrier
; #define LDA(dst, b, h) for (int m = 0; m < 4; ++m) for (int k = 0; k < 2; ++k) \
;     dst[m][k] = *reinterpret_cast<const bf16x8*>((char*)SA(b, h) + lds_byte(wr * 64 + m * 16 + fr, k * 32 + fq * 8))
; #define LDB(dst, b, h) for (int n = 0; n < 2; ++n) for (int k = 0; k < 2; ++k) \
;     dst[n][k] = *reinterpret_cast<const bf16x8*>((char*)SB(b, h) + lds_byte(wc * 32 + n * 16 + fr, k * 32 + fq * 8))
; #define MMA(ai, bj, At, Bt_) do { __builtin_amdgcn_s_setprio(1); \
;     for (int m = 0; m < 4; ++m) for (int n = 0; n < 2; ++n) for (int k = 0; k < 2; ++k) \
;       acc[ai][bj][m][n] = __builtin_amdgcn_mfma_f32_16x16x32_bf16(At[m][k], Bt_[n][k], acc[ai][bj][m][n], 0, 0, 0); \
;     __builtin_amdgcn_s_setprio(0); } while (0)
; #define WAIT_V(n) asm volatile("s_waitcnt vmcnt(" #n ")" ::: "memory")
; #define WAIT_L(n) asm volatile("s_waitcnt lgkmcnt(" #n ")" ::: "memory")
; #define BAR __builtin_amdgcn_s_barrier()
; template <bool ABLK, class Epi>
; __device__ __forceinline__ void gemm_tile(const bf16* __restrict__ A, int lda, const bf16* __restrict__ Bt, int ldb, int K,
;                                           int brow, int bcol, bf16* shm, const Epi& epi, int wv) {
;     ...
;     LDA(At, 0, 1); WAIT_V(4); BAR; WAIT_L(0); MMA(1, 0, At, B0); MMA(1, 1, At, B1); BAR; }
;   { LDB(B0, 1, 0); LDA(At, 1, 0); WAIT_V(2); BAR; WAIT_L(0); MMA(0, 0, At, B0); BAR;
;     LDB(B1, 1, 1); WAIT_V(0); BAR; WAIT_L(0); MMA(0, 1, At, B1); BAR;
	s_nop 0
	ds_read_b128 v[80:83], v143 offset:16384
	ds_read_b128 v[84:87], v143 offset:17408
	ds_read_b128 v[172:175], v142 offset:16384
	ds_read_b128 v[176:179], v142 offset:17408
	ds_read_b128 v[180:183], v141 offset:16384
	ds_read_b128 v[184:187], v141 offset:17408
	ds_read_b128 v[188:191], v140 offset:16384
	ds_read_b128 v[194:197], v140 offset:17408
	s_waitcnt vmcnt(4)
	s_barrier
	s_waitcnt lgkmcnt(0)
	s_waitcnt lgkmcnt(0)
	v_mfma_f32_16x16x32_bf16 v[44:47], v[180:183], v[130:133], v[44:47]
	v_mfma_f32_16x16x32_bf16 v[40:43], v[180:183], v[154:157], v[40:43]
	v_mfma_f32_16x16x32_bf16 v[60:63], v[80:83], v[130:133], v[60:63]
	v_mfma_f32_16x16x32_bf16 v[56:59], v[80:83], v[154:157], v[56:59]
	v_mfma_f32_16x16x32_bf16 v[52:55], v[172:175], v[130:133], v[52:55]
	v_mfma_f32_16x16x32_bf16 v[48:51], v[172:175], v[154:157], v[48:51]
	v_mfma_f32_16x16x32_bf16 v[44:47], v[184:187], v[150:153], v[44:47]
	v_mfma_f32_16x16x32_bf16 v[40:43], v[184:187], v[164:167], v[40:43]
	v_mfma_f32_16x16x32_bf16 v[36:39], v[188:191], v[130:133], v[36:39]
	v_mfma_f32_16x16x32_bf16 v[32:35], v[188:191], v[154:157], v[32:35]
	v_mfma_f32_16x16x32_bf16 v[202:205], v[84:87], v[150:153], v[60:63]
	v_mfma_f32_16x16x32_bf16 v[224:227], v[84:87], v[164:167], v[56:59]
	v_mfma_f32_16x16x32_bf16 v[228:231], v[176:179], v[150:153], v[52:55]
	v_mfma_f32_16x16x32_bf16 v[232:235], v[176:179], v[164:167], v[48:51]
	v_mfma_f32_16x16x32_bf16 v[128:131], v[194:197], v[150:153], v[36:39]
	v_mfma_f32_16x16x32_bf16 v[150:153], v[194:197], v[164:167], v[32:35]
	v_mfma_f32_16x16x32_bf16 v[28:31], v[80:83], v[96:99], v[28:31]
	v_mfma_f32_16x16x32_bf16 v[24:27], v[80:83], v[112:115], v[24:27]
	v_mfma_f32_16x16x32_bf16 v[12:15], v[180:183], v[96:99], v[12:15]
	v_mfma_f32_16x16x32_bf16 v[8:11], v[180:183], v[112:115], v[8:11]
	v_mfma_f32_16x16x32_bf16 v[28:31], v[84:87], v[100:103], v[28:31]
	v_mfma_f32_16x16x32_bf16 v[24:27], v[84:87], v[116:119], v[24:27]
	v_mfma_f32_16x16x32_bf16 v[20:23], v[172:175], v[96:99], v[20:23]
	v_mfma_f32_16x16x32_bf16 v[16:19], v[172:175], v[112:115], v[16:19]
	v_mfma_f32_16x16x32_bf16 v[12:15], v[184:187], v[100:103], v[12:15]
	v_mfma_f32_16x16x32_bf16 v[8:11], v[184:187], v[116:119], v[8:11]
	v_mfma_f32_16x16x32_bf16 v[4:7], v[188:191], v[96:99], v[4:7]
	v_mfma_f32_16x16x32_bf16 v[0:3], v[188:191], v[112:115], v[0:3]
	v_mfma_f32_16x16x32_bf16 v[154:157], v[176:179], v[100:103], v[20:23]
	v_mfma_f32_16x16x32_bf16 v[162:165], v[176:179], v[116:119], v[16:19]
	v_mfma_f32_16x16x32_bf16 v[172:175], v[194:197], v[100:103], v[4:7]
	v_mfma_f32_16x16x32_bf16 v[176:179], v[194:197], v[116:119], v[0:3]
	s_barrier
	s_nop 1
	ds_read_b128 v[0:3], v149
	ds_read_b128 v[4:7], v149 offset:1024
	ds_read_b128 v[180:183], v149 offset:2048
	ds_read_b128 v[184:187], v149 offset:3072
	ds_read_b128 v[16:19], v143 offset:32768
	ds_read_b128 v[20:23], v143 offset:33792
	ds_read_b128 v[32:35], v142 offset:32768
	ds_read_b128 v[36:39], v142 offset:33792
	ds_read_b128 v[48:51], v141 offset:32768
	ds_read_b128 v[52:55], v141 offset:33792
	ds_read_b128 v[188:191], v140 offset:32768
	ds_read_b128 v[194:197], v140 offset:33792
	s_waitcnt vmcnt(2)
	s_barrier
	s_waitcnt lgkmcnt(0)
	s_waitcnt lgkmcnt(0)
	v_mfma_f32_16x16x32_bf16 v[56:59], v[16:19], v[0:3], v[124:127]
	v_mfma_f32_16x16x32_bf16 v[112:115], v[20:23], v[4:7], v[56:59]
	v_mfma_f32_16x16x32_bf16 v[56:59], v[16:19], v[180:183], v[120:123]
	v_mfma_f32_16x16x32_bf16 v[116:119], v[20:23], v[184:187], v[56:59]
	v_mfma_f32_16x16x32_bf16 v[56:59], v[32:35], v[0:3], v[208:211]
	v_mfma_f32_16x16x32_bf16 v[96:99], v[36:39], v[4:7], v[56:59]
	v_mfma_f32_16x16x32_bf16 v[56:59], v[32:35], v[180:183], v[212:215]
	v_mfma_f32_16x16x32_bf16 v[100:103], v[36:39], v[184:187], v[56:59]
	v_mfma_f32_16x16x32_bf16 v[56:59], v[48:51], v[0:3], v[108:111]
	v_mfma_f32_16x16x32_bf16 v[80:83], v[52:55], v[4:7], v[56:59]
	v_mfma_f32_16x16x32_bf16 v[56:59], v[48:51], v[180:183], v[104:107]
	v_mfma_f32_16x16x32_bf16 v[84:87], v[52:55], v[184:187], v[56:59]
	v_mfma_f32_16x16x32_bf16 v[56:59], v[188:191], v[0:3], v[216:219]
	v_mfma_f32_16x16x32_bf16 v[60:63], v[188:191], v[180:183], v[220:223]
	v_mfma_f32_16x16x32_bf16 v[56:59], v[194:197], v[4:7], v[56:59]
	v_mfma_f32_16x16x32_bf16 v[60:63], v[194:197], v[184:187], v[60:63]
	s_barrier
; #define LDA(dst, b, h) for (int m = 0; m < 4; ++m) for (int k = 0; k < 2; ++k) \
;     dst[m][k] = *reinterpret_cast<const bf16x8*>((char*)SA(b, h) + lds_byte(wr * 64 + m * 16 + fr, k * 32 + fq * 8))
; #define LDB(dst, b, h) for (int n = 0; n < 2; ++n) for (int k = 0; k < 2; ++k) \
;     dst[n][k] = *reinterpret_cast<const bf16x8*>((char*)SB(b, h) + lds_byte(wc * 32 + n * 16 + fr, k * 32 + fq * 8))
; #define MMA(ai, bj, At, Bt_) do { __builtin_amdgcn_s_setprio(1); \
;     for (int m = 0; m < 4; ++m) for (int n = 0; n < 2; ++n) for (int k = 0; k < 2; ++k) \
;       acc[ai][bj][m][n] = __builtin_amdgcn_mfma_f32_16x16x32_bf16(At[m][k], Bt_[n][k], acc[ai][bj][m][n], 0, 0, 0); \
;     __builtin_amdgcn_s_setprio(0); } while (0)
; #define WAIT_V(n) asm volatile("s_waitcnt vmcnt(" #n ")" ::: "memory")
; #define WAIT_L(n) asm volatile("s_waitcnt lgkmcnt(" #n ")" ::: "memory")
; #define BAR __builtin_amdgcn_s_barrier()
; template <bool ABLK, class Epi>
; __device__ __forceinline__ void gemm_tile(const bf16* __restrict__ A, int lda, const bf16* __restrict__ Bt, int ldb, int K,
;                                           int brow, int bcol, bf16* shm, const Epi& epi, int wv) {
;     ...
;     LDB(B1, 1, 1); WAIT_V(0); BAR; WAIT_L(0); MMA(0, 1, At, B1); BAR;
;     LDA(At, 1, 1); BAR; WAIT_L(0); MMA(1, 0, At, B0); MMA(1, 1, At, B1); BAR; }
;   if (wr == 0) BAR;
	ds_read_b128 v[208:211], v146
	ds_read_b128 v[212:215], v146 offset:1024
	ds_read_b128 v[216:219], v146 offset:2048
	ds_read_b128 v[144:147], v146 offset:3072
	s_waitcnt vmcnt(0)
	s_barrier
	s_waitcnt lgkmcnt(0)
	s_waitcnt lgkmcnt(0)
	v_mfma_f32_16x16x32_bf16 v[92:95], v[16:19], v[208:211], v[92:95]
	v_mfma_f32_16x16x32_bf16 v[16:19], v[16:19], v[216:219], v[88:91]
	v_mfma_f32_16x16x32_bf16 v[124:127], v[20:23], v[144:147], v[16:19]
	v_mfma_f32_16x16x32_bf16 v[16:19], v[32:35], v[208:211], v[158:161]
	v_mfma_f32_16x16x32_bf16 v[104:107], v[36:39], v[212:215], v[16:19]
	v_mfma_f32_16x16x32_bf16 v[16:19], v[32:35], v[216:219], v[168:171]
	v_mfma_f32_16x16x32_bf16 v[108:111], v[36:39], v[144:147], v[16:19]
	v_mfma_f32_16x16x32_bf16 v[16:19], v[48:51], v[208:211], v[76:79]
	v_mfma_f32_16x16x32_bf16 v[88:91], v[52:55], v[212:215], v[16:19]
	v_mfma_f32_16x16x32_bf16 v[16:19], v[48:51], v[216:219], v[72:75]
	v_mfma_f32_16x16x32_bf16 v[120:123], v[20:23], v[212:215], v[92:95]
	v_mfma_f32_16x16x32_bf16 v[92:95], v[52:55], v[144:147], v[16:19]
	v_mfma_f32_16x16x32_bf16 v[16:19], v[188:191], v[208:211], v[68:71]
	v_mfma_f32_16x16x32_bf16 v[72:75], v[194:197], v[212:215], v[16:19]
	v_mfma_f32_16x16x32_bf16 v[16:19], v[188:191], v[216:219], v[64:67]
	v_mfma_f32_16x16x32_bf16 v[76:79], v[194:197], v[144:147], v[16:19]
	s_barrier
	ds_read_b128 v[68:71], v143 offset:49152
	ds_read_b128 v[158:161], v143 offset:50176
	ds_read_b128 v[166:169], v142 offset:49152
	ds_read_b128 v[188:191], v142 offset:50176
	ds_read_b128 v[194:197], v141 offset:49152
	ds_read_b128 v[220:223], v141 offset:50176
	ds_read_b128 v[236:239], v140 offset:49152
	ds_read_b128 v[140:143], v140 offset:50176
	s_barrier
	s_waitcnt lgkmcnt(0)
	s_waitcnt lgkmcnt(0)
	v_mfma_f32_16x16x32_bf16 v[16:19], v[68:71], v[0:3], v[202:205]
	v_mfma_f32_16x16x32_bf16 v[48:51], v[158:161], v[4:7], v[16:19]
	v_mfma_f32_16x16x32_bf16 v[16:19], v[68:71], v[180:183], v[224:227]
	v_mfma_f32_16x16x32_bf16 v[52:55], v[158:161], v[184:187], v[16:19]
	v_mfma_f32_16x16x32_bf16 v[16:19], v[166:169], v[0:3], v[228:231]
	v_mfma_f32_16x16x32_bf16 v[32:35], v[188:191], v[4:7], v[16:19]
	v_mfma_f32_16x16x32_bf16 v[16:19], v[166:169], v[180:183], v[232:235]
	v_mfma_f32_16x16x32_bf16 v[36:39], v[188:191], v[184:187], v[16:19]
	v_mfma_f32_16x16x32_bf16 v[16:19], v[194:197], v[0:3], v[44:47]
	v_mfma_f32_16x16x32_bf16 v[0:3], v[236:239], v[0:3], v[128:131]
	v_mfma_f32_16x16x32_bf16 v[16:19], v[220:223], v[4:7], v[16:19]
	v_mfma_f32_16x16x32_bf16 v[20:23], v[194:197], v[180:183], v[40:43]
	v_mfma_f32_16x16x32_bf16 v[0:3], v[140:143], v[4:7], v[0:3]
	v_mfma_f32_16x16x32_bf16 v[4:7], v[236:239], v[180:183], v[150:153]
	v_mfma_f32_16x16x32_bf16 v[20:23], v[220:223], v[184:187], v[20:23]
	v_mfma_f32_16x16x32_bf16 v[4:7], v[140:143], v[184:187], v[4:7]
	v_mfma_f32_16x16x32_bf16 v[24:27], v[68:71], v[216:219], v[24:27]
	v_mfma_f32_16x16x32_bf16 v[28:31], v[68:71], v[208:211], v[28:31]
	v_mfma_f32_16x16x32_bf16 v[68:71], v[158:161], v[144:147], v[24:27]
	v_mfma_f32_16x16x32_bf16 v[24:27], v[166:169], v[208:211], v[154:157]
	v_mfma_f32_16x16x32_bf16 v[8:11], v[194:197], v[216:219], v[8:11]
	v_mfma_f32_16x16x32_bf16 v[64:67], v[158:161], v[212:215], v[28:31]
	v_mfma_f32_16x16x32_bf16 v[40:43], v[188:191], v[212:215], v[24:27]
	v_mfma_f32_16x16x32_bf16 v[24:27], v[166:169], v[216:219], v[162:165]
	v_mfma_f32_16x16x32_bf16 v[12:15], v[194:197], v[208:211], v[12:15]
	v_mfma_f32_16x16x32_bf16 v[28:31], v[220:223], v[144:147], v[8:11]
	v_mfma_f32_16x16x32_bf16 v[8:11], v[236:239], v[208:211], v[172:175]
	v_mfma_f32_16x16x32_bf16 v[44:47], v[188:191], v[144:147], v[24:27]
	v_mfma_f32_16x16x32_bf16 v[24:27], v[220:223], v[212:215], v[12:15]
	v_mfma_f32_16x16x32_bf16 v[12:15], v[140:143], v[212:215], v[8:11]
	v_mfma_f32_16x16x32_bf16 v[8:11], v[236:239], v[216:219], v[176:179]
	v_mfma_f32_16x16x32_bf16 v[8:11], v[140:143], v[144:147], v[8:11]
	v_cmp_gt_u32_e32 vcc, s83, v135
	s_barrier
	s_and_saveexec_b64 s[66:67], vcc
	s_cbranch_execz .LBB0_715
	s_barrier
	s_branch .LBB0_715

; #define STAGE_A(P, hf, kt) do { if constexpr (ABLK) { const bf16* _gp = A + ((long)(brow >> 8) * nt + (kt)) * 16384 + (hf) * 8192; GLDS2(_gp, 4096, offA, P); } \
;     else { const bf16* _gp = A + (long)(brow + (hf) * HALF) * lda + (long)(kt) * BK; GLDS2(_gp, 64 * (long)lda, offA, P); } } while (0)
; #define STAGE_B(P, hf, kt) do { const bf16* _gp = Bt + (long)(bcol + (hf) * 2) * ldb + (long)(kt) * BK; GLDS2(_gp, 128 * (long)ldb, offB, P); } while (0)
; #define LDA(dst, b, h) for (int m = 0; m < 4; ++m) for (int k = 0; k < 2; ++k) \
;     dst[m][k] = *reinterpret_cast<const bf16x8*>((char*)SA(b, h) + lds_byte(wr * 64 + m * 16 + fr, k * 32 + fq * 8))
; #define LDB(dst, b, h) for (int n = 0; n < 2; ++n) for (int k = 0; k < 2; ++k) \
;     dst[n][k] = *reinterpret_cast<const bf16x8*>((char*)SB(b, h) + lds_byte(wc * 32 + n * 16 + fr, k * 32 + fq * 8))
; #define MMA(ai, bj, At, Bt_) do { __builtin_amdgcn_s_setprio(1); \
;     for (int m = 0; m < 4; ++m) for (int n = 0; n < 2; ++n) for (int k = 0; k < 2; ++k) \
;       acc[ai][bj][m][n] = __builtin_amdgcn_mfma_f32_16x16x32_bf16(At[m][k], Bt_[n][k], acc[ai][bj][m][n], 0, 0, 0); \
;     __builtin_amdgcn_s_setprio(0); } while (0)
; #define WAIT_V(n) asm volatile("s_waitcnt vmcnt(" #n ")" ::: "memory")
; #define WAIT_L(n) asm volatile("s_waitcnt lgkmcnt(" #n ")" ::: "memory")
; #define BAR __builtin_amdgcn_s_barrier()
; #define SCHED __builtin_amdgcn_sched_barrier(0)
; template <bool ABLK, class Epi>
; __device__ __forceinline__ void gemm_tile(const bf16* __restrict__ A, int lda, const bf16* __restrict__ Bt, int ldb, int K,
;                                           int brow, int bcol, bf16* shm, const Epi& epi, int wv) {
;     ...
;   STAGE_B(SB(0, 0), 0, 0); STAGE_A(SA(0, 0), 0, 0);
;   STAGE_B(SB(0, 1), 1, 0); STAGE_A(SA(0, 1), 1, 0);
;   if (wr == 1) BAR;
;   WAIT_V(4); BAR;
;   STAGE_B(SB(1, 0), 0, 1); STAGE_A(SA(1, 0), 0, 1); STAGE_B(SB(1, 1), 1, 1);
;   WAIT_V(6); BAR;
;   for (int t = 0; t < nt - 2; t += 2) {
;     LDB(B0, 0, 0); SCHED; LDA(At, 0, 0); STAGE_A(SA(1, 1), 1, t + 1);
;     WAIT_L(8); BAR; MMA(0, 0, At, B0); BAR; SCHED;
;     LDB(B1, 0, 1); STAGE_B(SB(0, 0), 0, t + 2);
;     BAR; MMA(0, 1, At, B1); BAR;
;     LDA(At, 0, 1); STAGE_A(SA(0, 0), 0, t + 2);
.LBB0_805:
	s_or_b64 exec, exec, s[60:61]
	v_add_u32_e32 v18, s66, v6
	v_add_u32_e32 v19, 0x2000, v18
	v_readfirstlane_b32 s85, v18
	v_lshl_add_u64 v[8:9], v[0:1], 0, s[10:11]
	s_mov_b32 m0, s85
	s_mov_b64 s[60:61], 0x18080
	v_readfirstlane_b32 s84, v19
	v_add_u32_e32 v14, 0x8000, v22
	s_waitcnt vmcnt(4)
	s_barrier
	global_load_lds_dwordx4 v[8:9], off
	v_lshl_add_u64 v[8:9], v[0:1], 0, s[60:61]
	s_mov_b32 m0, s84
	v_readfirstlane_b32 s83, v14
	v_add_u32_e32 v15, 0xa000, v22
	global_load_lds_dwordx4 v[8:9], off
	v_lshl_add_u64 v[8:9], v[4:5], 0, s[10:11]
	s_mov_b32 m0, s83
	v_readfirstlane_b32 s82, v15
	global_load_lds_dwordx4 v[8:9], off
	v_lshl_add_u64 v[8:9], v[4:5], 0, s[12:13]
	s_mov_b32 m0, s82
	s_mov_b64 s[60:61], 0x680
	global_load_lds_dwordx4 v[8:9], off
	v_add_u32_e32 v9, s67, v6
	v_add_u32_e32 v12, 0x2000, v9
	v_readfirstlane_b32 s72, v9
	v_lshl_add_u64 v[10:11], v[0:1], 0, s[60:61]
	s_mov_b32 m0, s72
	v_readfirstlane_b32 s61, v12
	global_load_lds_dwordx4 v[10:11], off
	v_lshl_add_u64 v[6:7], v[0:1], 0, s[14:15]
	s_mov_b32 m0, s61
	v_bfe_u32 v131, v128, 4, 2
	global_load_lds_dwordx4 v[6:7], off
	v_and_b32_e32 v6, 15, v128
	v_lshlrev_b32_e32 v133, 2, v6
	v_bfe_u32 v130, v128, 6, 2
	v_lshlrev_b32_e32 v7, 4, v131
	v_lshlrev_b32_e32 v8, 6, v6
	v_and_b32_e32 v10, 32, v133
	v_lshlrev_b32_e32 v190, 12, v130
	v_bitop3_b32 v191, v7, v10, v8 bitop3:0x36
	v_add3_u32 v8, s64, v191, v190
	s_waitcnt vmcnt(6)
	s_barrier
	ds_read_b128 v[26:29], v8
	ds_read_b128 v[30:33], v8 offset:1024
	ds_read_b128 v[34:37], v8 offset:2048
	ds_read_b128 v[38:41], v8 offset:3072
	v_lshlrev_b32_e32 v13, 6, v128
	v_and_b32_e32 v13, 0x3c0, v13
	v_bitop3_b32 v7, v13, v10, v7 bitop3:0x36
	v_add_u32_e32 v10, 0xc000, v22
	v_lshlrev_b32_e32 v11, 13, v129
	v_readfirstlane_b32 s79, v10
	v_add_u32_e32 v13, 0xe000, v22
	v_add3_u32 v6, 0, v191, v11
	v_add3_u32 v7, 0, v7, v11
	v_lshl_add_u64 v[74:75], v[2:3], 0, s[10:11]
	s_mov_b32 m0, s79
	v_readfirstlane_b32 s60, v13
	ds_read_b128 v[42:45], v6
	ds_read_b128 v[46:49], v6 offset:1024
	ds_read_b128 v[50:53], v7 offset:2048
	ds_read_b128 v[54:57], v7 offset:3072
	ds_read_b128 v[58:61], v7 offset:4096
	ds_read_b128 v[62:65], v7 offset:5120
	ds_read_b128 v[66:69], v7 offset:6144
	ds_read_b128 v[70:73], v7 offset:7168
	global_load_lds_dwordx4 v[74:75], off
	v_lshl_add_u64 v[74:75], v[2:3], 0, s[12:13]
	s_mov_b32 m0, s60
	s_nop 0
	global_load_lds_dwordx4 v[74:75], off
	s_waitcnt lgkmcnt(8)
	s_barrier
	s_waitcnt lgkmcnt(0)
	v_mfma_f32_16x16x32_bf16 v[74:77], v[42:45], v[26:29], 0
	v_mfma_f32_16x16x32_bf16 v[78:81], v[42:45], v[34:37], 0
	v_mfma_f32_16x16x32_bf16 v[82:85], v[50:53], v[26:29], 0
	v_mfma_f32_16x16x32_bf16 v[86:89], v[50:53], v[34:37], 0
	v_mfma_f32_16x16x32_bf16 v[90:93], v[58:61], v[26:29], 0
	v_mfma_f32_16x16x32_bf16 v[94:97], v[58:61], v[34:37], 0
	v_mfma_f32_16x16x32_bf16 v[98:101], v[66:69], v[26:29], 0
	v_mfma_f32_16x16x32_bf16 v[102:105], v[66:69], v[34:37], 0
	v_mfma_f32_16x16x32_bf16 v[74:77], v[46:49], v[30:33], v[74:77]
	v_mfma_f32_16x16x32_bf16 v[78:81], v[46:49], v[38:41], v[78:81]
	v_mfma_f32_16x16x32_bf16 v[82:85], v[54:57], v[30:33], v[82:85]
	v_mfma_f32_16x16x32_bf16 v[86:89], v[54:57], v[38:41], v[86:89]
	v_mfma_f32_16x16x32_bf16 v[90:93], v[62:65], v[30:33], v[90:93]
	v_mfma_f32_16x16x32_bf16 v[94:97], v[62:65], v[38:41], v[94:97]
	v_mfma_f32_16x16x32_bf16 v[98:101], v[70:73], v[30:33], v[98:101]
	v_mfma_f32_16x16x32_bf16 v[102:105], v[70:73], v[38:41], v[102:105]
	s_barrier
	v_readfirstlane_b32 s78, v24
	v_add3_u32 v11, s65, v191, v190
	v_lshl_add_u64 v[122:123], v[0:1], 0, s[16:17]
	s_mov_b32 m0, s78
	v_readfirstlane_b32 s73, v25
	ds_read_b128 v[106:109], v11
	ds_read_b128 v[110:113], v11 offset:1024
	ds_read_b128 v[114:117], v11 offset:2048
	ds_read_b128 v[118:121], v11 offset:3072
	global_load_lds_dwordx4 v[122:123], off
	v_lshl_add_u64 v[122:123], v[0:1], 0, s[18:19]
	s_mov_b32 m0, s73
	s_nop 0
	global_load_lds_dwordx4 v[122:123], off
	s_barrier
	s_waitcnt lgkmcnt(0)
	v_mfma_f32_16x16x32_bf16 v[122:125], v[42:45], v[106:109], 0
	v_mfma_f32_16x16x32_bf16 v[42:45], v[42:45], v[114:117], 0
	v_mfma_f32_16x16x32_bf16 v[122:125], v[46:49], v[110:113], v[122:125]
	v_mfma_f32_16x16x32_bf16 v[42:45], v[46:49], v[118:121], v[42:45]
	v_mfma_f32_16x16x32_bf16 v[46:49], v[50:53], v[106:109], 0
	v_mfma_f32_16x16x32_bf16 v[50:53], v[50:53], v[114:117], 0
	v_mfma_f32_16x16x32_bf16 v[46:49], v[54:57], v[110:113], v[46:49]
	v_mfma_f32_16x16x32_bf16 v[50:53], v[54:57], v[118:121], v[50:53]
	v_mfma_f32_16x16x32_bf16 v[54:57], v[58:61], v[106:109], 0
	v_mfma_f32_16x16x32_bf16 v[58:61], v[58:61], v[114:117], 0
	v_mfma_f32_16x16x32_bf16 v[54:57], v[62:65], v[110:113], v[54:57]
	v_mfma_f32_16x16x32_bf16 v[58:61], v[62:65], v[118:121], v[58:61]
	v_mfma_f32_16x16x32_bf16 v[62:65], v[66:69], v[106:109], 0
	v_mfma_f32_16x16x32_bf16 v[66:69], v[66:69], v[114:117], 0
	v_mfma_f32_16x16x32_bf16 v[62:65], v[70:73], v[110:113], v[62:65]
	v_mfma_f32_16x16x32_bf16 v[66:69], v[70:73], v[118:121], v[66:69]
	v_readfirstlane_b32 s80, v22
	v_lshl_add_u64 v[24:25], v[4:5], 0, s[16:17]
	s_mov_b32 m0, s80
	v_readfirstlane_b32 s74, v23
	s_barrier
	ds_read_b128 v[70:73], v6 offset:16384
	ds_read_b128 v[134:137], v6 offset:17408
	ds_read_b128 v[138:141], v7 offset:18432
	ds_read_b128 v[142:145], v7 offset:19456
	ds_read_b128 v[146:149], v7 offset:20480
	ds_read_b128 v[150:153], v7 offset:21504
	ds_read_b128 v[154:157], v7 offset:22528
	ds_read_b128 v[158:161], v7 offset:23552
	global_load_lds_dwordx4 v[24:25], off
	v_lshl_add_u64 v[24:25], v[4:5], 0, s[20:21]
	s_mov_b32 m0, s74
	s_nop 0
	global_load_lds_dwordx4 v[24:25], off
	s_barrier
; #define STAGE_A(P, hf, kt) do { if constexpr (ABLK) { const bf16* _gp = A + ((long)(brow >> 8) * nt + (kt)) * 16384 + (hf) * 8192; GLDS2(_gp, 4096, offA, P); } \
;     else { const bf16* _gp = A + (long)(brow + (hf) * HALF) * lda + (long)(kt) * BK; GLDS2(_gp, 64 * (long)lda, offA, P); } } while (0)
; #define STAGE_B(P, hf, kt) do { const bf16* _gp = Bt + (long)(bcol + (hf) * 2) * ldb + (long)(kt) * BK; GLDS2(_gp, 128 * (long)ldb, offB, P); } while (0)
; #define LDA(dst, b, h) for (int m = 0; m < 4; ++m) for (int k = 0; k < 2; ++k) \
;     dst[m][k] = *reinterpret_cast<const bf16x8*>((char*)SA(b, h) + lds_byte(wr * 64 + m * 16 + fr, k * 32 + fq * 8))
; #define LDB(dst, b, h) for (int n = 0; n < 2; ++n) for (int k = 0; k < 2; ++k) \
;     dst[n][k] = *reinterpret_cast<const bf16x8*>((char*)SB(b, h) + lds_byte(wc * 32 + n * 16 + fr, k * 32 + fq * 8))
; #define MMA(ai, bj, At, Bt_) do { __builtin_amdgcn_s_setprio(1); \
;     for (int m = 0; m < 4; ++m) for (int n = 0; n < 2; ++n) for (int k = 0; k < 2; ++k) \
;       acc[ai][bj][m][n] = __builtin_amdgcn_mfma_f32_16x16x32_bf16(At[m][k], Bt_[n][k], acc[ai][bj][m][n], 0, 0, 0); \
;     __builtin_amdgcn_s_setprio(0); } while (0)
; #define WAIT_V(n) asm volatile("s_waitcnt vmcnt(" #n ")" ::: "memory")
; #define WAIT_L(n) asm volatile("s_waitcnt lgkmcnt(" #n ")" ::: "memory")
; #define BAR __builtin_amdgcn_s_barrier()
; #define SCHED __builtin_amdgcn_sched_barrier(0)
; template <bool ABLK, class Epi>
; __device__ __forceinline__ void gemm_tile(const bf16* __restrict__ A, int lda, const bf16* __restrict__ Bt, int ldb, int K,
;                                           int brow, int bcol, bf16* shm, const Epi& epi, int wv) {
;     ...
;     LDA(At, 0, 1); STAGE_A(SA(0, 0), 0, t + 2);
;     BAR; MMA(1, 0, At, B0); BAR; SCHED;
;     STAGE_B(SB(0, 1), 1, t + 2);
;     WAIT_V(6); BAR; MMA(1, 1, At, B1); BAR;
;     LDB(B0, 1, 0); SCHED; LDA(At, 1, 0); STAGE_A(SA(0, 1), 1, t + 2);
;     WAIT_L(8); BAR; MMA(0, 0, At, B0); BAR; SCHED;
;     LDB(B1, 1, 1); STAGE_B(SB(1, 0), 0, t + 3);
	s_waitcnt lgkmcnt(0)
	v_mfma_f32_16x16x32_bf16 v[22:25], v[70:73], v[26:29], 0
	v_mfma_f32_16x16x32_bf16 v[166:169], v[138:141], v[26:29], 0
	v_mfma_f32_16x16x32_bf16 v[174:177], v[146:149], v[26:29], 0
	v_mfma_f32_16x16x32_bf16 v[26:29], v[154:157], v[26:29], 0
	v_mfma_f32_16x16x32_bf16 v[22:25], v[134:137], v[30:33], v[22:25]
	v_mfma_f32_16x16x32_bf16 v[166:169], v[142:145], v[30:33], v[166:169]
	v_mfma_f32_16x16x32_bf16 v[174:177], v[150:153], v[30:33], v[174:177]
	v_mfma_f32_16x16x32_bf16 v[26:29], v[158:161], v[30:33], v[26:29]
	v_mfma_f32_16x16x32_bf16 v[30:33], v[154:157], v[34:37], 0
	v_mfma_f32_16x16x32_bf16 v[162:165], v[70:73], v[34:37], 0
	v_mfma_f32_16x16x32_bf16 v[170:173], v[138:141], v[34:37], 0
	v_mfma_f32_16x16x32_bf16 v[178:181], v[146:149], v[34:37], 0
	v_mfma_f32_16x16x32_bf16 v[30:33], v[158:161], v[38:41], v[30:33]
	v_mfma_f32_16x16x32_bf16 v[162:165], v[134:137], v[38:41], v[162:165]
	v_mfma_f32_16x16x32_bf16 v[170:173], v[142:145], v[38:41], v[170:173]
	v_mfma_f32_16x16x32_bf16 v[178:181], v[150:153], v[38:41], v[178:181]
	s_barrier
	v_readfirstlane_b32 s76, v16
	v_lshl_add_u64 v[34:35], v[0:1], 0, s[22:23]
	s_mov_b32 m0, s76
	v_readfirstlane_b32 s75, v21
	global_load_lds_dwordx4 v[34:35], off
	v_lshl_add_u64 v[34:35], v[0:1], 0, s[24:25]
	s_mov_b32 m0, s75
	s_nop 0
	global_load_lds_dwordx4 v[34:35], off
	s_waitcnt vmcnt(6)
	s_barrier
	v_mfma_f32_16x16x32_bf16 v[34:37], v[70:73], v[106:109], 0
	v_mfma_f32_16x16x32_bf16 v[38:41], v[70:73], v[114:117], 0
	v_mfma_f32_16x16x32_bf16 v[34:37], v[134:137], v[110:113], v[34:37]
	v_mfma_f32_16x16x32_bf16 v[38:41], v[134:137], v[118:121], v[38:41]
	v_mfma_f32_16x16x32_bf16 v[70:73], v[138:141], v[106:109], 0
	v_mfma_f32_16x16x32_bf16 v[134:137], v[138:141], v[114:117], 0
	v_mfma_f32_16x16x32_bf16 v[138:141], v[146:149], v[106:109], 0
	v_mfma_f32_16x16x32_bf16 v[106:109], v[154:157], v[106:109], 0
	v_mfma_f32_16x16x32_bf16 v[70:73], v[142:145], v[110:113], v[70:73]
	v_mfma_f32_16x16x32_bf16 v[138:141], v[150:153], v[110:113], v[138:141]
	v_mfma_f32_16x16x32_bf16 v[106:109], v[158:161], v[110:113], v[106:109]
	v_mfma_f32_16x16x32_bf16 v[110:113], v[154:157], v[114:117], 0
	v_mfma_f32_16x16x32_bf16 v[134:137], v[142:145], v[118:121], v[134:137]
	v_mfma_f32_16x16x32_bf16 v[142:145], v[146:149], v[114:117], 0
	v_mfma_f32_16x16x32_bf16 v[110:113], v[158:161], v[118:121], v[110:113]
	v_mfma_f32_16x16x32_bf16 v[142:145], v[150:153], v[118:121], v[142:145]
	v_add3_u32 v16, s66, v191, v190
	s_barrier
	ds_read_b128 v[114:117], v16
	ds_read_b128 v[118:121], v16 offset:1024
	ds_read_b128 v[146:149], v16 offset:2048
	ds_read_b128 v[150:153], v16 offset:3072
	v_readfirstlane_b32 s81, v17
	v_lshl_add_u64 v[126:127], v[2:3], 0, s[16:17]
	s_mov_b32 m0, s81
	v_readfirstlane_b32 s77, v20
	ds_read_b128 v[154:157], v6 offset:32768
	ds_read_b128 v[158:161], v6 offset:33792
	ds_read_b128 v[182:185], v7 offset:34816
	ds_read_b128 v[186:189], v7 offset:35840
	ds_read_b128 v[194:197], v7 offset:36864
	ds_read_b128 v[202:205], v7 offset:37888
	ds_read_b128 v[208:211], v7 offset:38912
	ds_read_b128 v[212:215], v7 offset:39936
	global_load_lds_dwordx4 v[126:127], off
	v_lshl_add_u64 v[126:127], v[2:3], 0, s[20:21]
	s_mov_b32 m0, s77
	s_nop 0
	global_load_lds_dwordx4 v[126:127], off
	s_waitcnt lgkmcnt(8)
	s_barrier
	s_waitcnt lgkmcnt(0)
	v_mfma_f32_16x16x32_bf16 v[74:77], v[154:157], v[114:117], v[74:77]
	v_mfma_f32_16x16x32_bf16 v[78:81], v[154:157], v[146:149], v[78:81]
	v_mfma_f32_16x16x32_bf16 v[82:85], v[182:185], v[114:117], v[82:85]
	v_mfma_f32_16x16x32_bf16 v[86:89], v[182:185], v[146:149], v[86:89]
	v_mfma_f32_16x16x32_bf16 v[90:93], v[194:197], v[114:117], v[90:93]
	v_mfma_f32_16x16x32_bf16 v[94:97], v[194:197], v[146:149], v[94:97]
	v_mfma_f32_16x16x32_bf16 v[98:101], v[208:211], v[114:117], v[98:101]
	v_mfma_f32_16x16x32_bf16 v[102:105], v[208:211], v[146:149], v[102:105]
	v_mfma_f32_16x16x32_bf16 v[74:77], v[158:161], v[118:121], v[74:77]
	v_mfma_f32_16x16x32_bf16 v[78:81], v[158:161], v[150:153], v[78:81]
	v_mfma_f32_16x16x32_bf16 v[82:85], v[186:189], v[118:121], v[82:85]
	v_mfma_f32_16x16x32_bf16 v[86:89], v[186:189], v[150:153], v[86:89]
	v_mfma_f32_16x16x32_bf16 v[90:93], v[202:205], v[118:121], v[90:93]
	v_mfma_f32_16x16x32_bf16 v[94:97], v[202:205], v[150:153], v[94:97]
	v_mfma_f32_16x16x32_bf16 v[98:101], v[212:215], v[118:121], v[98:101]
	v_mfma_f32_16x16x32_bf16 v[102:105], v[212:215], v[150:153], v[102:105]
	s_barrier
	s_mov_b32 m0, s85
	v_add3_u32 v17, s67, v191, v190
	v_lshl_add_u64 v[20:21], v[0:1], 0, s[26:27]
	ds_read_b128 v[216:219], v17
	ds_read_b128 v[220:223], v17 offset:1024
	ds_read_b128 v[224:227], v17 offset:2048
	ds_read_b128 v[228:231], v17 offset:3072
	global_load_lds_dwordx4 v[20:21], off
	v_lshl_add_u64 v[20:21], v[0:1], 0, s[30:31]
	s_mov_b32 m0, s84
	s_nop 0
	global_load_lds_dwordx4 v[20:21], off
	s_barrier
	s_waitcnt lgkmcnt(0)
	v_mfma_f32_16x16x32_bf16 v[122:125], v[154:157], v[216:219], v[122:125]
	v_mfma_f32_16x16x32_bf16 v[42:45], v[154:157], v[224:227], v[42:45]
	v_mfma_f32_16x16x32_bf16 v[46:49], v[182:185], v[216:219], v[46:49]
	v_mfma_f32_16x16x32_bf16 v[50:53], v[182:185], v[224:227], v[50:53]
	v_mfma_f32_16x16x32_bf16 v[54:57], v[194:197], v[216:219], v[54:57]
	v_mfma_f32_16x16x32_bf16 v[58:61], v[194:197], v[224:227], v[58:61]
	v_mfma_f32_16x16x32_bf16 v[62:65], v[208:211], v[216:219], v[62:65]
	v_mfma_f32_16x16x32_bf16 v[66:69], v[208:211], v[224:227], v[66:69]
	v_mfma_f32_16x16x32_bf16 v[122:125], v[158:161], v[220:223], v[122:125]
	v_mfma_f32_16x16x32_bf16 v[42:45], v[158:161], v[228:231], v[42:45]
	v_mfma_f32_16x16x32_bf16 v[46:49], v[186:189], v[220:223], v[46:49]
	v_mfma_f32_16x16x32_bf16 v[50:53], v[186:189], v[228:231], v[50:53]
	v_mfma_f32_16x16x32_bf16 v[54:57], v[202:205], v[220:223], v[54:57]
	v_mfma_f32_16x16x32_bf16 v[58:61], v[202:205], v[228:231], v[58:61]
	v_mfma_f32_16x16x32_bf16 v[62:65], v[212:215], v[220:223], v[62:65]
	v_mfma_f32_16x16x32_bf16 v[66:69], v[212:215], v[228:231], v[66:69]
	s_mov_b32 m0, s83
	v_lshl_add_u64 v[20:21], v[4:5], 0, s[26:27]
	s_barrier
; #define STAGE_A(P, hf, kt) do { if constexpr (ABLK) { const bf16* _gp = A + ((long)(brow >> 8) * nt + (kt)) * 16384 + (hf) * 8192; GLDS2(_gp, 4096, offA, P); } \
;     else { const bf16* _gp = A + (long)(brow + (hf) * HALF) * lda + (long)(kt) * BK; GLDS2(_gp, 64 * (long)lda, offA, P); } } while (0)
; #define STAGE_B(P, hf, kt) do { const bf16* _gp = Bt + (long)(bcol + (hf) * 2) * ldb + (long)(kt) * BK; GLDS2(_gp, 128 * (long)ldb, offB, P); } while (0)
; #define LDA(dst, b, h) for (int m = 0; m < 4; ++m) for (int k = 0; k < 2; ++k) \
;     dst[m][k] = *reinterpret_cast<const bf16x8*>((char*)SA(b, h) + lds_byte(wr * 64 + m * 16 + fr, k * 32 + fq * 8))
; #define LDB(dst, b, h) for (int n = 0; n < 2; ++n) for (int k = 0; k < 2; ++k) \
;     dst[n][k] = *reinterpret_cast<const bf16x8*>((char*)SB(b, h) + lds_byte(wc * 32 + n * 16 + fr, k * 32 + fq * 8))
; #define MMA(ai, bj, At, Bt_) do { __builtin_amdgcn_s_setprio(1); \
;     for (int m = 0; m < 4; ++m) for (int n = 0; n < 2; ++n) for (int k = 0; k < 2; ++k) \
;       acc[ai][bj][m][n] = __builtin_amdgcn_mfma_f32_16x16x32_bf16(At[m][k], Bt_[n][k], acc[ai][bj][m][n], 0, 0, 0); \
;     __builtin_amdgcn_s_setprio(0); } while (0)
; #define WAIT_V(n) asm volatile("s_waitcnt vmcnt(" #n ")" ::: "memory")
; #define WAIT_L(n) asm volatile("s_waitcnt lgkmcnt(" #n ")" ::: "memory")
; #define BAR __builtin_amdgcn_s_barrier()
; #define SCHED __builtin_amdgcn_sched_barrier(0)
; template <bool ABLK, class Epi>
; __device__ __forceinline__ void gemm_tile(const bf16* __restrict__ A, int lda, const bf16* __restrict__ Bt, int ldb, int K,
;                                           int brow, int bcol, bf16* shm, const Epi& epi, int wv) {
;     ...
;     LDB(B0, 1, 0); SCHED; LDA(At, 1, 0); STAGE_A(SA(0, 1), 1, t + 2);
;     WAIT_L(8); BAR; MMA(0, 0, At, B0); BAR; SCHED;
;     LDB(B1, 1, 1); STAGE_B(SB(1, 0), 0, t + 3);
;     BAR; MMA(0, 1, At, B1); BAR;
;     LDA(At, 1, 1); STAGE_A(SA(1, 0), 0, t + 3);
;     BAR; MMA(1, 0, At, B0); BAR; SCHED;
;     STAGE_B(SB(1, 1), 1, t + 3);
;     WAIT_V(6); BAR; MMA(1, 1, At, B1); BAR;
	ds_read_b128 v[154:157], v6 offset:49152
	ds_read_b128 v[158:161], v6 offset:50176
	ds_read_b128 v[182:185], v7 offset:51200
	ds_read_b128 v[186:189], v7 offset:52224
	ds_read_b128 v[194:197], v7 offset:53248
	ds_read_b128 v[202:205], v7 offset:54272
	ds_read_b128 v[208:211], v7 offset:55296
	ds_read_b128 v[212:215], v7 offset:56320
	global_load_lds_dwordx4 v[20:21], off
	v_lshl_add_u64 v[20:21], v[4:5], 0, s[34:35]
	s_mov_b32 m0, s82
	s_nop 0
	global_load_lds_dwordx4 v[20:21], off
	s_barrier
	s_waitcnt lgkmcnt(0)
	v_mfma_f32_16x16x32_bf16 v[20:23], v[154:157], v[114:117], v[22:25]
	v_mfma_f32_16x16x32_bf16 v[24:27], v[208:211], v[114:117], v[26:29]
	v_mfma_f32_16x16x32_bf16 v[28:31], v[208:211], v[146:149], v[30:33]
	v_mfma_f32_16x16x32_bf16 v[20:23], v[158:161], v[118:121], v[20:23]
	v_mfma_f32_16x16x32_bf16 v[162:165], v[154:157], v[146:149], v[162:165]
	v_mfma_f32_16x16x32_bf16 v[166:169], v[182:185], v[114:117], v[166:169]
	v_mfma_f32_16x16x32_bf16 v[170:173], v[182:185], v[146:149], v[170:173]
	v_mfma_f32_16x16x32_bf16 v[174:177], v[194:197], v[114:117], v[174:177]
	v_mfma_f32_16x16x32_bf16 v[178:181], v[194:197], v[146:149], v[178:181]
	v_mfma_f32_16x16x32_bf16 v[24:27], v[212:215], v[118:121], v[24:27]
	v_mfma_f32_16x16x32_bf16 v[28:31], v[212:215], v[150:153], v[28:31]
	v_mfma_f32_16x16x32_bf16 v[162:165], v[158:161], v[150:153], v[162:165]
	v_mfma_f32_16x16x32_bf16 v[166:169], v[186:189], v[118:121], v[166:169]
	v_mfma_f32_16x16x32_bf16 v[170:173], v[186:189], v[150:153], v[170:173]
	v_mfma_f32_16x16x32_bf16 v[174:177], v[202:205], v[118:121], v[174:177]
	v_mfma_f32_16x16x32_bf16 v[178:181], v[202:205], v[150:153], v[178:181]
	s_barrier
	s_mov_b32 m0, s72
	v_lshl_add_u64 v[32:33], v[0:1], 0, s[36:37]
	global_load_lds_dwordx4 v[32:33], off
	v_lshl_add_u64 v[32:33], v[0:1], 0, s[38:39]
	s_mov_b32 m0, s61
	s_nop 0
	global_load_lds_dwordx4 v[32:33], off
	s_waitcnt vmcnt(6)
	s_barrier
	v_mfma_f32_16x16x32_bf16 v[32:35], v[154:157], v[216:219], v[34:37]
	v_mfma_f32_16x16x32_bf16 v[36:39], v[154:157], v[224:227], v[38:41]
	v_mfma_f32_16x16x32_bf16 v[70:73], v[182:185], v[216:219], v[70:73]
	v_mfma_f32_16x16x32_bf16 v[114:117], v[182:185], v[224:227], v[134:137]
	v_mfma_f32_16x16x32_bf16 v[118:121], v[194:197], v[216:219], v[138:141]
	v_mfma_f32_16x16x32_bf16 v[106:109], v[208:211], v[216:219], v[106:109]
	v_mfma_f32_16x16x32_bf16 v[110:113], v[208:211], v[224:227], v[110:113]
	v_mfma_f32_16x16x32_bf16 v[32:35], v[158:161], v[220:223], v[32:35]
	v_mfma_f32_16x16x32_bf16 v[36:39], v[158:161], v[228:231], v[36:39]
	v_mfma_f32_16x16x32_bf16 v[70:73], v[186:189], v[220:223], v[70:73]
	v_mfma_f32_16x16x32_bf16 v[114:117], v[186:189], v[228:231], v[114:117]
	v_mfma_f32_16x16x32_bf16 v[118:121], v[202:205], v[220:223], v[118:121]
	v_mfma_f32_16x16x32_bf16 v[134:137], v[194:197], v[224:227], v[142:145]
	v_mfma_f32_16x16x32_bf16 v[106:109], v[212:215], v[220:223], v[106:109]
	v_mfma_f32_16x16x32_bf16 v[110:113], v[212:215], v[228:231], v[110:113]
	v_mfma_f32_16x16x32_bf16 v[134:137], v[202:205], v[228:231], v[134:137]
	s_barrier
	ds_read_b128 v[138:141], v8
	ds_read_b128 v[142:145], v8 offset:1024
	ds_read_b128 v[146:149], v8 offset:2048
	ds_read_b128 v[150:153], v8 offset:3072
	s_mov_b32 m0, s79
	v_lshl_add_u64 v[40:41], v[2:3], 0, s[26:27]
	ds_read_b128 v[154:157], v6
	ds_read_b128 v[158:161], v6 offset:1024
	ds_read_b128 v[182:185], v7 offset:2048
	ds_read_b128 v[186:189], v7 offset:3072
	ds_read_b128 v[194:197], v7 offset:4096
	ds_read_b128 v[202:205], v7 offset:5120
	ds_read_b128 v[208:211], v7 offset:6144
	ds_read_b128 v[212:215], v7 offset:7168
	global_load_lds_dwordx4 v[40:41], off
	v_lshl_add_u64 v[40:41], v[2:3], 0, s[34:35]
	s_mov_b32 m0, s60
	s_nop 0
	global_load_lds_dwordx4 v[40:41], off
	s_waitcnt lgkmcnt(8)
	s_barrier
	s_waitcnt lgkmcnt(0)
	v_mfma_f32_16x16x32_bf16 v[74:77], v[154:157], v[138:141], v[74:77]
	v_mfma_f32_16x16x32_bf16 v[78:81], v[154:157], v[146:149], v[78:81]
	v_mfma_f32_16x16x32_bf16 v[82:85], v[182:185], v[138:141], v[82:85]
	v_mfma_f32_16x16x32_bf16 v[86:89], v[182:185], v[146:149], v[86:89]
	v_mfma_f32_16x16x32_bf16 v[90:93], v[194:197], v[138:141], v[90:93]
	v_mfma_f32_16x16x32_bf16 v[94:97], v[194:197], v[146:149], v[94:97]
	v_mfma_f32_16x16x32_bf16 v[98:101], v[208:211], v[138:141], v[98:101]
	v_mfma_f32_16x16x32_bf16 v[102:105], v[208:211], v[146:149], v[102:105]
	v_mfma_f32_16x16x32_bf16 v[74:77], v[158:161], v[142:145], v[74:77]
	v_mfma_f32_16x16x32_bf16 v[78:81], v[158:161], v[150:153], v[78:81]
	v_mfma_f32_16x16x32_bf16 v[82:85], v[186:189], v[142:145], v[82:85]
	v_mfma_f32_16x16x32_bf16 v[86:89], v[186:189], v[150:153], v[86:89]
	v_mfma_f32_16x16x32_bf16 v[90:93], v[202:205], v[142:145], v[90:93]
	v_mfma_f32_16x16x32_bf16 v[94:97], v[202:205], v[150:153], v[94:97]
	v_mfma_f32_16x16x32_bf16 v[98:101], v[212:215], v[142:145], v[98:101]
	v_mfma_f32_16x16x32_bf16 v[102:105], v[212:215], v[150:153], v[102:105]
	s_barrier
	s_mov_b32 m0, s78
	v_lshl_add_u64 v[40:41], v[0:1], 0, s[40:41]
	ds_read_b128 v[216:219], v11
	ds_read_b128 v[220:223], v11 offset:1024
	ds_read_b128 v[224:227], v11 offset:2048
	ds_read_b128 v[228:231], v11 offset:3072
	global_load_lds_dwordx4 v[40:41], off
	v_lshl_add_u64 v[40:41], v[0:1], 0, s[42:43]
	s_mov_b32 m0, s73
	s_nop 0
	global_load_lds_dwordx4 v[40:41], off
	s_barrier
; #define STAGE_A(P, hf, kt) do { if constexpr (ABLK) { const bf16* _gp = A + ((long)(brow >> 8) * nt + (kt)) * 16384 + (hf) * 8192; GLDS2(_gp, 4096, offA, P); } \
;     else { const bf16* _gp = A + (long)(brow + (hf) * HALF) * lda + (long)(kt) * BK; GLDS2(_gp, 64 * (long)lda, offA, P); } } while (0)
; #define STAGE_B(P, hf, kt) do { const bf16* _gp = Bt + (long)(bcol + (hf) * 2) * ldb + (long)(kt) * BK; GLDS2(_gp, 128 * (long)ldb, offB, P); } while (0)
; #define LDA(dst, b, h) for (int m = 0; m < 4; ++m) for (int k = 0; k < 2; ++k) \
;     dst[m][k] = *reinterpret_cast<const bf16x8*>((char*)SA(b, h) + lds_byte(wr * 64 + m * 16 + fr, k * 32 + fq * 8))
; #define LDB(dst, b, h) for (int n = 0; n < 2; ++n) for (int k = 0; k < 2; ++k) \
;     dst[n][k] = *reinterpret_cast<const bf16x8*>((char*)SB(b, h) + lds_byte(wc * 32 + n * 16 + fr, k * 32 + fq * 8))
; #define MMA(ai, bj, At, Bt_) do { __builtin_amdgcn_s_setprio(1); \
;     for (int m = 0; m < 4; ++m) for (int n = 0; n < 2; ++n) for (int k = 0; k < 2; ++k) \
;       acc[ai][bj][m][n] = __builtin_amdgcn_mfma_f32_16x16x32_bf16(At[m][k], Bt_[n][k], acc[ai][bj][m][n], 0, 0, 0); \
;     __builtin_amdgcn_s_setprio(0); } while (0)
; #define WAIT_V(n) asm volatile("s_waitcnt vmcnt(" #n ")" ::: "memory")
; #define WAIT_L(n) asm volatile("s_waitcnt lgkmcnt(" #n ")" ::: "memory")
; #define BAR __builtin_amdgcn_s_barrier()
; #define SCHED __builtin_amdgcn_sched_barrier(0)
; template <bool ABLK, class Epi>
; __device__ __forceinline__ void gemm_tile(const bf16* __restrict__ A, int lda, const bf16* __restrict__ Bt, int ldb, int K,
;                                           int brow, int bcol, bf16* shm, const Epi& epi, int wv) {
;     ...
;     LDB(B0, 0, 0); SCHED; LDA(At, 0, 0); STAGE_A(SA(1, 1), 1, t + 1);
;     WAIT_L(8); BAR; MMA(0, 0, At, B0); BAR; SCHED;
;     LDB(B1, 0, 1); STAGE_B(SB(0, 0), 0, t + 2);
;     BAR; MMA(0, 1, At, B1); BAR;
;     LDA(At, 0, 1); STAGE_A(SA(0, 0), 0, t + 2);
;     BAR; MMA(1, 0, At, B0); BAR; SCHED;
;     STAGE_B(SB(0, 1), 1, t + 2);
;     WAIT_V(6); BAR; MMA(1, 1, At, B1); BAR;
	s_waitcnt lgkmcnt(0)
	v_mfma_f32_16x16x32_bf16 v[122:125], v[154:157], v[216:219], v[122:125]
	v_mfma_f32_16x16x32_bf16 v[40:43], v[154:157], v[224:227], v[42:45]
	v_mfma_f32_16x16x32_bf16 v[44:47], v[182:185], v[216:219], v[46:49]
	v_mfma_f32_16x16x32_bf16 v[48:51], v[182:185], v[224:227], v[50:53]
	v_mfma_f32_16x16x32_bf16 v[52:55], v[194:197], v[216:219], v[54:57]
	v_mfma_f32_16x16x32_bf16 v[56:59], v[194:197], v[224:227], v[58:61]
	v_mfma_f32_16x16x32_bf16 v[60:63], v[208:211], v[216:219], v[62:65]
	v_mfma_f32_16x16x32_bf16 v[64:67], v[208:211], v[224:227], v[66:69]
	v_mfma_f32_16x16x32_bf16 v[122:125], v[158:161], v[220:223], v[122:125]
	v_mfma_f32_16x16x32_bf16 v[40:43], v[158:161], v[228:231], v[40:43]
	v_mfma_f32_16x16x32_bf16 v[44:47], v[186:189], v[220:223], v[44:47]
	v_mfma_f32_16x16x32_bf16 v[48:51], v[186:189], v[228:231], v[48:51]
	v_mfma_f32_16x16x32_bf16 v[52:55], v[202:205], v[220:223], v[52:55]
	v_mfma_f32_16x16x32_bf16 v[56:59], v[202:205], v[228:231], v[56:59]
	v_mfma_f32_16x16x32_bf16 v[60:63], v[212:215], v[220:223], v[60:63]
	v_mfma_f32_16x16x32_bf16 v[64:67], v[212:215], v[228:231], v[64:67]
	s_mov_b32 m0, s80
	v_lshl_add_u64 v[68:69], v[4:5], 0, s[40:41]
	s_barrier
	ds_read_b128 v[154:157], v6 offset:16384
	ds_read_b128 v[158:161], v6 offset:17408
	ds_read_b128 v[182:185], v7 offset:18432
	ds_read_b128 v[186:189], v7 offset:19456
	ds_read_b128 v[194:197], v7 offset:20480
	ds_read_b128 v[202:205], v7 offset:21504
	ds_read_b128 v[208:211], v7 offset:22528
	ds_read_b128 v[212:215], v7 offset:23552
	global_load_lds_dwordx4 v[68:69], off
	v_lshl_add_u64 v[68:69], v[4:5], 0, s[44:45]
	s_mov_b32 m0, s74
	s_nop 0
	global_load_lds_dwordx4 v[68:69], off
	s_barrier
	s_waitcnt lgkmcnt(0)
	v_mfma_f32_16x16x32_bf16 v[20:23], v[154:157], v[138:141], v[20:23]
	v_mfma_f32_16x16x32_bf16 v[24:27], v[208:211], v[138:141], v[24:27]
	v_mfma_f32_16x16x32_bf16 v[28:31], v[208:211], v[146:149], v[28:31]
	v_mfma_f32_16x16x32_bf16 v[20:23], v[158:161], v[142:145], v[20:23]
	v_mfma_f32_16x16x32_bf16 v[162:165], v[154:157], v[146:149], v[162:165]
	v_mfma_f32_16x16x32_bf16 v[166:169], v[182:185], v[138:141], v[166:169]
	v_mfma_f32_16x16x32_bf16 v[170:173], v[182:185], v[146:149], v[170:173]
	v_mfma_f32_16x16x32_bf16 v[174:177], v[194:197], v[138:141], v[174:177]
	v_mfma_f32_16x16x32_bf16 v[178:181], v[194:197], v[146:149], v[178:181]
	v_mfma_f32_16x16x32_bf16 v[24:27], v[212:215], v[142:145], v[24:27]
	v_mfma_f32_16x16x32_bf16 v[28:31], v[212:215], v[150:153], v[28:31]
	v_mfma_f32_16x16x32_bf16 v[162:165], v[158:161], v[150:153], v[162:165]
	v_mfma_f32_16x16x32_bf16 v[166:169], v[186:189], v[142:145], v[166:169]
	v_mfma_f32_16x16x32_bf16 v[170:173], v[186:189], v[150:153], v[170:173]
	v_mfma_f32_16x16x32_bf16 v[174:177], v[202:205], v[142:145], v[174:177]
	v_mfma_f32_16x16x32_bf16 v[178:181], v[202:205], v[150:153], v[178:181]
	s_barrier
	s_mov_b32 m0, s76
	v_lshl_add_u64 v[68:69], v[0:1], 0, s[46:47]
	global_load_lds_dwordx4 v[68:69], off
	v_lshl_add_u64 v[68:69], v[0:1], 0, s[48:49]
	s_mov_b32 m0, s75
	s_nop 0
	global_load_lds_dwordx4 v[68:69], off
	s_waitcnt vmcnt(6)
	s_barrier
	v_mfma_f32_16x16x32_bf16 v[32:35], v[154:157], v[216:219], v[32:35]
	v_mfma_f32_16x16x32_bf16 v[36:39], v[154:157], v[224:227], v[36:39]
	v_mfma_f32_16x16x32_bf16 v[68:71], v[182:185], v[216:219], v[70:73]
	v_mfma_f32_16x16x32_bf16 v[114:117], v[182:185], v[224:227], v[114:117]
	v_mfma_f32_16x16x32_bf16 v[118:121], v[194:197], v[216:219], v[118:121]
	v_mfma_f32_16x16x32_bf16 v[106:109], v[208:211], v[216:219], v[106:109]
	v_mfma_f32_16x16x32_bf16 v[110:113], v[208:211], v[224:227], v[110:113]
	v_mfma_f32_16x16x32_bf16 v[32:35], v[158:161], v[220:223], v[32:35]
	v_mfma_f32_16x16x32_bf16 v[36:39], v[158:161], v[228:231], v[36:39]
	v_mfma_f32_16x16x32_bf16 v[68:71], v[186:189], v[220:223], v[68:71]
	v_mfma_f32_16x16x32_bf16 v[114:117], v[186:189], v[228:231], v[114:117]
	v_mfma_f32_16x16x32_bf16 v[118:121], v[202:205], v[220:223], v[118:121]
	v_mfma_f32_16x16x32_bf16 v[134:137], v[194:197], v[224:227], v[134:137]
	v_mfma_f32_16x16x32_bf16 v[106:109], v[212:215], v[220:223], v[106:109]
	v_mfma_f32_16x16x32_bf16 v[110:113], v[212:215], v[228:231], v[110:113]
	v_mfma_f32_16x16x32_bf16 v[134:137], v[202:205], v[228:231], v[134:137]
	s_barrier
	ds_read_b128 v[138:141], v16
	ds_read_b128 v[142:145], v16 offset:1024
	ds_read_b128 v[146:149], v16 offset:2048
	ds_read_b128 v[150:153], v16 offset:3072
	s_mov_b32 m0, s81
	v_lshl_add_u64 v[72:73], v[2:3], 0, s[40:41]
	ds_read_b128 v[154:157], v6 offset:32768
	ds_read_b128 v[158:161], v6 offset:33792
	ds_read_b128 v[182:185], v7 offset:34816
	ds_read_b128 v[186:189], v7 offset:35840
	ds_read_b128 v[194:197], v7 offset:36864
	ds_read_b128 v[202:205], v7 offset:37888
	ds_read_b128 v[208:211], v7 offset:38912
	ds_read_b128 v[212:215], v7 offset:39936
	global_load_lds_dwordx4 v[72:73], off
	v_lshl_add_u64 v[72:73], v[2:3], 0, s[44:45]
	s_mov_b32 m0, s77
	s_nop 0
	global_load_lds_dwordx4 v[72:73], off
	s_waitcnt lgkmcnt(8)
	s_barrier
	s_waitcnt lgkmcnt(0)
	v_mfma_f32_16x16x32_bf16 v[72:75], v[154:157], v[138:141], v[74:77]
	v_mfma_f32_16x16x32_bf16 v[76:79], v[154:157], v[146:149], v[78:81]
	v_mfma_f32_16x16x32_bf16 v[80:83], v[182:185], v[138:141], v[82:85]
	v_mfma_f32_16x16x32_bf16 v[84:87], v[182:185], v[146:149], v[86:89]
	v_mfma_f32_16x16x32_bf16 v[88:91], v[194:197], v[138:141], v[90:93]
	v_mfma_f32_16x16x32_bf16 v[92:95], v[194:197], v[146:149], v[94:97]
	v_mfma_f32_16x16x32_bf16 v[96:99], v[208:211], v[138:141], v[98:101]
	v_mfma_f32_16x16x32_bf16 v[100:103], v[208:211], v[146:149], v[102:105]
	v_mfma_f32_16x16x32_bf16 v[72:75], v[158:161], v[142:145], v[72:75]
	v_mfma_f32_16x16x32_bf16 v[76:79], v[158:161], v[150:153], v[76:79]
	v_mfma_f32_16x16x32_bf16 v[80:83], v[186:189], v[142:145], v[80:83]
	v_mfma_f32_16x16x32_bf16 v[84:87], v[186:189], v[150:153], v[84:87]
	v_mfma_f32_16x16x32_bf16 v[88:91], v[202:205], v[142:145], v[88:91]
	v_mfma_f32_16x16x32_bf16 v[92:95], v[202:205], v[150:153], v[92:95]
	v_mfma_f32_16x16x32_bf16 v[96:99], v[212:215], v[142:145], v[96:99]
	v_mfma_f32_16x16x32_bf16 v[100:103], v[212:215], v[150:153], v[100:103]
	s_barrier
; #define STAGE_A(P, hf, kt) do { if constexpr (ABLK) { const bf16* _gp = A + ((long)(brow >> 8) * nt + (kt)) * 16384 + (hf) * 8192; GLDS2(_gp, 4096, offA, P); } \
;     else { const bf16* _gp = A + (long)(brow + (hf) * HALF) * lda + (long)(kt) * BK; GLDS2(_gp, 64 * (long)lda, offA, P); } } while (0)
; #define STAGE_B(P, hf, kt) do { const bf16* _gp = Bt + (long)(bcol + (hf) * 2) * ldb + (long)(kt) * BK; GLDS2(_gp, 128 * (long)ldb, offB, P); } while (0)
; #define LDA(dst, b, h) for (int m = 0; m < 4; ++m) for (int k = 0; k < 2; ++k) \
;     dst[m][k] = *reinterpret_cast<const bf16x8*>((char*)SA(b, h) + lds_byte(wr * 64 + m * 16 + fr, k * 32 + fq * 8))
; #define LDB(dst, b, h) for (int n = 0; n < 2; ++n) for (int k = 0; k < 2; ++k) \
;     dst[n][k] = *reinterpret_cast<const bf16x8*>((char*)SB(b, h) + lds_byte(wc * 32 + n * 16 + fr, k * 32 + fq * 8))
; #define MMA(ai, bj, At, Bt_) do { __builtin_amdgcn_s_setprio(1); \
;     for (int m = 0; m < 4; ++m) for (int n = 0; n < 2; ++n) for (int k = 0; k < 2; ++k) \
;       acc[ai][bj][m][n] = __builtin_amdgcn_mfma_f32_16x16x32_bf16(At[m][k], Bt_[n][k], acc[ai][bj][m][n], 0, 0, 0); \
;     __builtin_amdgcn_s_setprio(0); } while (0)
; #define WAIT_V(n) asm volatile("s_waitcnt vmcnt(" #n ")" ::: "memory")
; #define WAIT_L(n) asm volatile("s_waitcnt lgkmcnt(" #n ")" ::: "memory")
; #define BAR __builtin_amdgcn_s_barrier()
; #define SCHED __builtin_amdgcn_sched_barrier(0)
; template <bool ABLK, class Epi>
; __device__ __forceinline__ void gemm_tile(const bf16* __restrict__ A, int lda, const bf16* __restrict__ Bt, int ldb, int K,
;                                           int brow, int bcol, bf16* shm, const Epi& epi, int wv) {
;     ...
;     WAIT_V(6); BAR; MMA(1, 1, At, B1); BAR;
;     LDB(B0, 1, 0); SCHED; LDA(At, 1, 0); STAGE_A(SA(0, 1), 1, t + 2);
;     WAIT_L(8); BAR; MMA(0, 0, At, B0); BAR; SCHED;
;     LDB(B1, 1, 1); STAGE_B(SB(1, 0), 0, t + 3);
;     BAR; MMA(0, 1, At, B1); BAR;
;     LDA(At, 1, 1); STAGE_A(SA(1, 0), 0, t + 3);
;     BAR; MMA(1, 0, At, B0); BAR; SCHED;
;     STAGE_B(SB(1, 1), 1, t + 3);
;     WAIT_V(6); BAR; MMA(1, 1, At, B1); BAR;
;   }
;   { LDB(B0, 0, 0); LDA(At, 0, 0); STAGE_A(SA(1, 1), 1, nt - 1);
	v_readfirstlane_b32 s2, v18
	v_lshl_add_u64 v[104:105], v[0:1], 0, s[50:51]
	s_mov_b32 m0, s2
	v_readfirstlane_b32 s2, v19
	ds_read_b128 v[216:219], v17
	ds_read_b128 v[220:223], v17 offset:1024
	ds_read_b128 v[224:227], v17 offset:2048
	ds_read_b128 v[228:231], v17 offset:3072
	global_load_lds_dwordx4 v[104:105], off
	v_lshl_add_u64 v[104:105], v[0:1], 0, s[52:53]
	s_mov_b32 m0, s2
	s_nop 0
	global_load_lds_dwordx4 v[104:105], off
	s_barrier
	s_waitcnt lgkmcnt(0)
	v_mfma_f32_16x16x32_bf16 v[122:125], v[154:157], v[216:219], v[122:125]
	v_mfma_f32_16x16x32_bf16 v[40:43], v[154:157], v[224:227], v[40:43]
	v_mfma_f32_16x16x32_bf16 v[44:47], v[182:185], v[216:219], v[44:47]
	v_mfma_f32_16x16x32_bf16 v[48:51], v[182:185], v[224:227], v[48:51]
	v_mfma_f32_16x16x32_bf16 v[52:55], v[194:197], v[216:219], v[52:55]
	v_mfma_f32_16x16x32_bf16 v[56:59], v[194:197], v[224:227], v[56:59]
	v_mfma_f32_16x16x32_bf16 v[60:63], v[208:211], v[216:219], v[60:63]
	v_mfma_f32_16x16x32_bf16 v[64:67], v[208:211], v[224:227], v[64:67]
	v_mfma_f32_16x16x32_bf16 v[122:125], v[158:161], v[220:223], v[122:125]
	v_mfma_f32_16x16x32_bf16 v[40:43], v[158:161], v[228:231], v[40:43]
	v_mfma_f32_16x16x32_bf16 v[44:47], v[186:189], v[220:223], v[44:47]
	v_mfma_f32_16x16x32_bf16 v[48:51], v[186:189], v[228:231], v[48:51]
	v_mfma_f32_16x16x32_bf16 v[52:55], v[202:205], v[220:223], v[52:55]
	v_mfma_f32_16x16x32_bf16 v[56:59], v[202:205], v[228:231], v[56:59]
	v_mfma_f32_16x16x32_bf16 v[60:63], v[212:215], v[220:223], v[60:63]
	v_mfma_f32_16x16x32_bf16 v[64:67], v[212:215], v[228:231], v[64:67]
	v_readfirstlane_b32 s2, v14
	v_lshl_add_u64 v[18:19], v[4:5], 0, s[50:51]
	s_mov_b32 m0, s2
	v_readfirstlane_b32 s2, v15
	s_barrier
	ds_read_b128 v[154:157], v6 offset:49152
	ds_read_b128 v[158:161], v6 offset:50176
	ds_read_b128 v[182:185], v7 offset:51200
	ds_read_b128 v[186:189], v7 offset:52224
	ds_read_b128 v[194:197], v7 offset:53248
	ds_read_b128 v[202:205], v7 offset:54272
	ds_read_b128 v[208:211], v7 offset:55296
	ds_read_b128 v[212:215], v7 offset:56320
	global_load_lds_dwordx4 v[18:19], off
	v_lshl_add_u64 v[4:5], v[4:5], 0, s[54:55]
	s_mov_b32 m0, s2
	s_nop 0
	global_load_lds_dwordx4 v[4:5], off
	s_barrier
	s_waitcnt lgkmcnt(0)
	v_mfma_f32_16x16x32_bf16 v[18:21], v[154:157], v[138:141], v[20:23]
	v_mfma_f32_16x16x32_bf16 v[22:25], v[208:211], v[138:141], v[24:27]
	v_mfma_f32_16x16x32_bf16 v[26:29], v[208:211], v[146:149], v[28:31]
	v_mfma_f32_16x16x32_bf16 v[18:21], v[158:161], v[142:145], v[18:21]
	v_mfma_f32_16x16x32_bf16 v[162:165], v[154:157], v[146:149], v[162:165]
	v_mfma_f32_16x16x32_bf16 v[166:169], v[182:185], v[138:141], v[166:169]
	v_mfma_f32_16x16x32_bf16 v[170:173], v[182:185], v[146:149], v[170:173]
	v_mfma_f32_16x16x32_bf16 v[174:177], v[194:197], v[138:141], v[174:177]
	v_mfma_f32_16x16x32_bf16 v[178:181], v[194:197], v[146:149], v[178:181]
	v_mfma_f32_16x16x32_bf16 v[22:25], v[212:215], v[142:145], v[22:25]
	v_mfma_f32_16x16x32_bf16 v[26:29], v[212:215], v[150:153], v[26:29]
	v_mfma_f32_16x16x32_bf16 v[162:165], v[158:161], v[150:153], v[162:165]
	v_mfma_f32_16x16x32_bf16 v[166:169], v[186:189], v[142:145], v[166:169]
	v_mfma_f32_16x16x32_bf16 v[170:173], v[186:189], v[150:153], v[170:173]
	v_mfma_f32_16x16x32_bf16 v[174:177], v[202:205], v[142:145], v[174:177]
	v_mfma_f32_16x16x32_bf16 v[178:181], v[202:205], v[150:153], v[178:181]
	s_barrier
	v_readfirstlane_b32 s2, v9
	v_lshl_add_u64 v[4:5], v[0:1], 0, s[56:57]
	s_mov_b32 m0, s2
	v_readfirstlane_b32 s2, v12
	global_load_lds_dwordx4 v[4:5], off
	v_lshl_add_u64 v[0:1], v[0:1], 0, s[58:59]
	s_mov_b32 m0, s2
	s_nop 0
	global_load_lds_dwordx4 v[0:1], off
	s_waitcnt vmcnt(6)
	s_barrier
	v_mfma_f32_16x16x32_bf16 v[30:33], v[154:157], v[216:219], v[32:35]
	v_mfma_f32_16x16x32_bf16 v[34:37], v[154:157], v[224:227], v[36:39]
	v_mfma_f32_16x16x32_bf16 v[68:71], v[182:185], v[216:219], v[68:71]
	v_mfma_f32_16x16x32_bf16 v[114:117], v[182:185], v[224:227], v[114:117]
	v_mfma_f32_16x16x32_bf16 v[118:121], v[194:197], v[216:219], v[118:121]
	v_mfma_f32_16x16x32_bf16 v[104:107], v[208:211], v[216:219], v[106:109]
	v_mfma_f32_16x16x32_bf16 v[108:111], v[208:211], v[224:227], v[110:113]
	v_mfma_f32_16x16x32_bf16 v[30:33], v[158:161], v[220:223], v[30:33]
	v_mfma_f32_16x16x32_bf16 v[34:37], v[158:161], v[228:231], v[34:37]
	v_mfma_f32_16x16x32_bf16 v[68:71], v[186:189], v[220:223], v[68:71]
	v_mfma_f32_16x16x32_bf16 v[114:117], v[186:189], v[228:231], v[114:117]
	v_mfma_f32_16x16x32_bf16 v[118:121], v[202:205], v[220:223], v[118:121]
	v_mfma_f32_16x16x32_bf16 v[134:137], v[194:197], v[224:227], v[134:137]
	v_mfma_f32_16x16x32_bf16 v[104:107], v[212:215], v[220:223], v[104:107]
	v_mfma_f32_16x16x32_bf16 v[108:111], v[212:215], v[228:231], v[108:111]
	v_mfma_f32_16x16x32_bf16 v[134:137], v[202:205], v[228:231], v[134:137]
	v_readfirstlane_b32 s2, v10
	v_lshl_add_u64 v[0:1], v[2:3], 0, s[50:51]
	s_mov_b32 m0, s2
	v_readfirstlane_b32 s2, v13
	s_barrier
	ds_read_b128 v[138:141], v8
	ds_read_b128 v[142:145], v8 offset:1024
	ds_read_b128 v[146:149], v8 offset:2048
	ds_read_b128 v[150:153], v8 offset:3072
	ds_read_b128 v[154:157], v6
	ds_read_b128 v[158:161], v6 offset:1024
	ds_read_b128 v[182:185], v7 offset:2048
	ds_read_b128 v[186:189], v7 offset:3072
	ds_read_b128 v[194:197], v7 offset:4096
	ds_read_b128 v[202:205], v7 offset:5120
	ds_read_b128 v[208:211], v7 offset:6144
	ds_read_b128 v[212:215], v7 offset:7168
	global_load_lds_dwordx4 v[0:1], off
	v_lshl_add_u64 v[0:1], v[2:3], 0, s[54:55]
	s_mov_b32 m0, s2
	s_nop 0
	global_load_lds_dwordx4 v[0:1], off
	s_barrier
; #define STAGE_A(P, hf, kt) do { if constexpr (ABLK) { const bf16* _gp = A + ((long)(brow >> 8) * nt + (kt)) * 16384 + (hf) * 8192; GLDS2(_gp, 4096, offA, P); } \
;     else { const bf16* _gp = A + (long)(brow + (hf) * HALF) * lda + (long)(kt) * BK; GLDS2(_gp, 64 * (long)lda, offA, P); } } while (0)
; #define LDA(dst, b, h) for (int m = 0; m < 4; ++m) for (int k = 0; k < 2; ++k) \
;     dst[m][k] = *reinterpret_cast<const bf16x8*>((char*)SA(b, h) + lds_byte(wr * 64 + m * 16 + fr, k * 32 + fq * 8))
; #define LDB(dst, b, h) for (int n = 0; n < 2; ++n) for (int k = 0; k < 2; ++k) \
;     dst[n][k] = *reinterpret_cast<const bf16x8*>((char*)SB(b, h) + lds_byte(wc * 32 + n * 16 + fr, k * 32 + fq * 8))
; #define MMA(ai, bj, At, Bt_) do { __builtin_amdgcn_s_setprio(1); \
;     for (int m = 0; m < 4; ++m) for (int n = 0; n < 2; ++n) for (int k = 0; k < 2; ++k) \
;       acc[ai][bj][m][n] = __builtin_amdgcn_mfma_f32_16x16x32_bf16(At[m][k], Bt_[n][k], acc[ai][bj][m][n], 0, 0, 0); \
;     __builtin_amdgcn_s_setprio(0); } while (0)
; #define WAIT_V(n) asm volatile("s_waitcnt vmcnt(" #n ")" ::: "memory")
; #define WAIT_L(n) asm volatile("s_waitcnt lgkmcnt(" #n ")" ::: "memory")
; #define BAR __builtin_amdgcn_s_barrier()
; template <bool ABLK, class Epi>
; __device__ __forceinline__ void gemm_tile(const bf16* __restrict__ A, int lda, const bf16* __restrict__ Bt, int ldb, int K,
;                                           int brow, int bcol, bf16* shm, const Epi& epi, int wv) {
;     ...
;   { LDB(B0, 0, 0); LDA(At, 0, 0); STAGE_A(SA(1, 1), 1, nt - 1);
;     BAR; WAIT_L(0); MMA(0, 0, At, B0); BAR;
;     LDB(B1, 0, 1); BAR; WAIT_L(0); MMA(0, 1, At, B1); BAR;
;     LDA(At, 0, 1); WAIT_V(4); BAR; WAIT_L(0); MMA(1, 0, At, B0); MMA(1, 1, At, B1); BAR; }
;   { LDB(B0, 1, 0); LDA(At, 1, 0); WAIT_V(2); BAR; WAIT_L(0); MMA(0, 0, At, B0); BAR;
	s_waitcnt lgkmcnt(0)
	s_waitcnt lgkmcnt(0)
	v_mfma_f32_16x16x32_bf16 v[0:3], v[154:157], v[138:141], v[72:75]
	v_mfma_f32_16x16x32_bf16 v[12:15], v[154:157], v[146:149], v[76:79]
	v_mfma_f32_16x16x32_bf16 v[72:75], v[182:185], v[138:141], v[80:83]
	v_mfma_f32_16x16x32_bf16 v[76:79], v[182:185], v[146:149], v[84:87]
	v_mfma_f32_16x16x32_bf16 v[80:83], v[194:197], v[138:141], v[88:91]
	v_mfma_f32_16x16x32_bf16 v[84:87], v[194:197], v[146:149], v[92:95]
	v_mfma_f32_16x16x32_bf16 v[88:91], v[208:211], v[138:141], v[96:99]
	v_mfma_f32_16x16x32_bf16 v[92:95], v[208:211], v[146:149], v[100:103]
	v_mfma_f32_16x16x32_bf16 v[0:3], v[158:161], v[142:145], v[0:3]
	v_mfma_f32_16x16x32_bf16 v[12:15], v[158:161], v[150:153], v[12:15]
	v_mfma_f32_16x16x32_bf16 v[72:75], v[186:189], v[142:145], v[72:75]
	v_mfma_f32_16x16x32_bf16 v[76:79], v[186:189], v[150:153], v[76:79]
	v_mfma_f32_16x16x32_bf16 v[80:83], v[202:205], v[142:145], v[80:83]
	v_mfma_f32_16x16x32_bf16 v[84:87], v[202:205], v[150:153], v[84:87]
	v_mfma_f32_16x16x32_bf16 v[88:91], v[212:215], v[142:145], v[88:91]
	v_mfma_f32_16x16x32_bf16 v[92:95], v[212:215], v[150:153], v[92:95]
	s_barrier
	ds_read_b128 v[96:99], v11
	ds_read_b128 v[100:103], v11 offset:1024
	ds_read_b128 v[216:219], v11 offset:2048
	ds_read_b128 v[8:11], v11 offset:3072
	s_barrier
	s_waitcnt lgkmcnt(0)
	s_waitcnt lgkmcnt(0)
	v_mfma_f32_16x16x32_bf16 v[38:41], v[154:157], v[216:219], v[40:43]
	v_mfma_f32_16x16x32_bf16 v[42:45], v[182:185], v[96:99], v[44:47]
	v_mfma_f32_16x16x32_bf16 v[46:49], v[182:185], v[216:219], v[48:51]
	v_mfma_f32_16x16x32_bf16 v[50:53], v[194:197], v[96:99], v[52:55]
	v_mfma_f32_16x16x32_bf16 v[54:57], v[194:197], v[216:219], v[56:59]
	v_mfma_f32_16x16x32_bf16 v[122:125], v[154:157], v[96:99], v[122:125]
	v_mfma_f32_16x16x32_bf16 v[154:157], v[202:205], v[8:11], v[54:57]
	v_mfma_f32_16x16x32_bf16 v[54:57], v[208:211], v[96:99], v[60:63]
	v_mfma_f32_16x16x32_bf16 v[122:125], v[158:161], v[100:103], v[122:125]
	v_mfma_f32_16x16x32_bf16 v[38:41], v[158:161], v[8:11], v[38:41]
	v_mfma_f32_16x16x32_bf16 v[158:161], v[212:215], v[100:103], v[54:57]
	v_mfma_f32_16x16x32_bf16 v[54:57], v[208:211], v[216:219], v[64:67]
	v_mfma_f32_16x16x32_bf16 v[42:45], v[186:189], v[100:103], v[42:45]
	v_mfma_f32_16x16x32_bf16 v[46:49], v[186:189], v[8:11], v[46:49]
	v_mfma_f32_16x16x32_bf16 v[50:53], v[202:205], v[100:103], v[50:53]
	v_mfma_f32_16x16x32_bf16 v[64:67], v[212:215], v[8:11], v[54:57]
	s_barrier
	s_nop 1
	ds_read_b128 v[54:57], v6 offset:16384
	ds_read_b128 v[58:61], v6 offset:17408
	ds_read_b128 v[182:185], v7 offset:18432
	ds_read_b128 v[186:189], v7 offset:19456
	ds_read_b128 v[194:197], v7 offset:20480
	ds_read_b128 v[202:205], v7 offset:21504
	ds_read_b128 v[208:211], v7 offset:22528
	ds_read_b128 v[212:215], v7 offset:23552
	s_waitcnt vmcnt(4)
	s_barrier
	s_waitcnt lgkmcnt(0)
	s_waitcnt lgkmcnt(0)
	v_mfma_f32_16x16x32_bf16 v[22:25], v[208:211], v[138:141], v[22:25]
	v_mfma_f32_16x16x32_bf16 v[18:21], v[54:57], v[138:141], v[18:21]
	v_mfma_f32_16x16x32_bf16 v[166:169], v[182:185], v[138:141], v[166:169]
	v_mfma_f32_16x16x32_bf16 v[174:177], v[194:197], v[138:141], v[174:177]
	v_mfma_f32_16x16x32_bf16 v[138:141], v[212:215], v[142:145], v[22:25]
	v_mfma_f32_16x16x32_bf16 v[22:25], v[208:211], v[146:149], v[26:29]
	v_mfma_f32_16x16x32_bf16 v[18:21], v[58:61], v[142:145], v[18:21]
	v_mfma_f32_16x16x32_bf16 v[162:165], v[54:57], v[146:149], v[162:165]
	v_mfma_f32_16x16x32_bf16 v[170:173], v[182:185], v[146:149], v[170:173]
	v_mfma_f32_16x16x32_bf16 v[178:181], v[194:197], v[146:149], v[178:181]
	v_mfma_f32_16x16x32_bf16 v[24:27], v[212:215], v[150:153], v[22:25]
	v_mfma_f32_16x16x32_bf16 v[162:165], v[58:61], v[150:153], v[162:165]
	v_mfma_f32_16x16x32_bf16 v[166:169], v[186:189], v[142:145], v[166:169]
	v_mfma_f32_16x16x32_bf16 v[170:173], v[186:189], v[150:153], v[170:173]
	v_mfma_f32_16x16x32_bf16 v[174:177], v[202:205], v[142:145], v[174:177]
	v_mfma_f32_16x16x32_bf16 v[178:181], v[202:205], v[150:153], v[178:181]
	v_mfma_f32_16x16x32_bf16 v[28:31], v[54:57], v[96:99], v[30:33]
	v_mfma_f32_16x16x32_bf16 v[32:35], v[54:57], v[216:219], v[34:37]
	v_mfma_f32_16x16x32_bf16 v[142:145], v[58:61], v[8:11], v[32:35]
	v_mfma_f32_16x16x32_bf16 v[32:35], v[182:185], v[96:99], v[68:71]
	v_mfma_f32_16x16x32_bf16 v[146:149], v[186:189], v[100:103], v[32:35]
	v_mfma_f32_16x16x32_bf16 v[32:35], v[182:185], v[216:219], v[114:117]
	v_mfma_f32_16x16x32_bf16 v[150:153], v[186:189], v[8:11], v[32:35]
	v_mfma_f32_16x16x32_bf16 v[32:35], v[194:197], v[96:99], v[118:121]
	v_mfma_f32_16x16x32_bf16 v[182:185], v[202:205], v[100:103], v[32:35]
	v_mfma_f32_16x16x32_bf16 v[32:35], v[194:197], v[216:219], v[134:137]
	v_mfma_f32_16x16x32_bf16 v[134:137], v[202:205], v[8:11], v[32:35]
	v_mfma_f32_16x16x32_bf16 v[32:35], v[208:211], v[96:99], v[104:107]
	v_mfma_f32_16x16x32_bf16 v[28:31], v[58:61], v[100:103], v[28:31]
	v_mfma_f32_16x16x32_bf16 v[186:189], v[212:215], v[100:103], v[32:35]
	v_mfma_f32_16x16x32_bf16 v[32:35], v[208:211], v[216:219], v[108:111]
	v_mfma_f32_16x16x32_bf16 v[194:197], v[212:215], v[8:11], v[32:35]
	s_barrier
; #define LDA(dst, b, h) for (int m = 0; m < 4; ++m) for (int k = 0; k < 2; ++k) \
;     dst[m][k] = *reinterpret_cast<const bf16x8*>((char*)SA(b, h) + lds_byte(wr * 64 + m * 16 + fr, k * 32 + fq * 8))
; #define LDB(dst, b, h) for (int n = 0; n < 2; ++n) for (int k = 0; k < 2; ++k) \
;     dst[n][k] = *reinterpret_cast<const bf16x8*>((char*)SB(b, h) + lds_byte(wc * 32 + n * 16 + fr, k * 32 + fq * 8))
; #define MMA(ai, bj, At, Bt_) do { __builtin_amdgcn_s_setprio(1); \
;     for (int m = 0; m < 4; ++m) for (int n = 0; n < 2; ++n) for (int k = 0; k < 2; ++k) \
;       acc[ai][bj][m][n] = __builtin_amdgcn_mfma_f32_16x16x32_bf16(At[m][k], Bt_[n][k], acc[ai][bj][m][n], 0, 0, 0); \
;     __builtin_amdgcn_s_setprio(0); } while (0)
; #define WAIT_V(n) asm volatile("s_waitcnt vmcnt(" #n ")" ::: "memory")
; #define WAIT_L(n) asm volatile("s_waitcnt lgkmcnt(" #n ")" ::: "memory")
; #define BAR __builtin_amdgcn_s_barrier()
; template <bool ABLK, class Epi>
; __device__ __forceinline__ void gemm_tile(const bf16* __restrict__ A, int lda, const bf16* __restrict__ Bt, int ldb, int K,
;                                           int brow, int bcol, bf16* shm, const Epi& epi, int wv) {
;     ...
;   { LDB(B0, 1, 0); LDA(At, 1, 0); WAIT_V(2); BAR; WAIT_L(0); MMA(0, 0, At, B0); BAR;
;     LDB(B1, 1, 1); WAIT_V(0); BAR; WAIT_L(0); MMA(0, 1, At, B1); BAR;
;     LDA(At, 1, 1); BAR; WAIT_L(0); MMA(1, 0, At, B0); MMA(1, 1, At, B1); BAR; }
;   if (wr == 0) BAR;
	ds_read_b128 v[8:11], v16
	ds_read_b128 v[68:71], v16 offset:1024
	ds_read_b128 v[202:205], v16 offset:2048
	ds_read_b128 v[208:211], v16 offset:3072
	s_nop 0
	ds_read_b128 v[32:35], v6 offset:32768
	ds_read_b128 v[104:107], v6 offset:33792
	ds_read_b128 v[108:111], v7 offset:34816
	ds_read_b128 v[212:215], v7 offset:35840
	ds_read_b128 v[216:219], v7 offset:36864
	ds_read_b128 v[220:223], v7 offset:37888
	ds_read_b128 v[224:227], v7 offset:38912
	ds_read_b128 v[228:231], v7 offset:39936
	s_waitcnt vmcnt(2)
	s_barrier
	s_waitcnt lgkmcnt(0)
	s_waitcnt lgkmcnt(0)
	v_mfma_f32_16x16x32_bf16 v[0:3], v[32:35], v[8:11], v[0:3]
	v_mfma_f32_16x16x32_bf16 v[112:115], v[104:107], v[68:71], v[0:3]
	v_mfma_f32_16x16x32_bf16 v[0:3], v[32:35], v[202:205], v[12:15]
	v_mfma_f32_16x16x32_bf16 v[116:119], v[104:107], v[208:211], v[0:3]
	v_mfma_f32_16x16x32_bf16 v[0:3], v[108:111], v[8:11], v[72:75]
	v_mfma_f32_16x16x32_bf16 v[96:99], v[212:215], v[68:71], v[0:3]
	v_mfma_f32_16x16x32_bf16 v[0:3], v[108:111], v[202:205], v[76:79]
	v_mfma_f32_16x16x32_bf16 v[100:103], v[212:215], v[208:211], v[0:3]
	v_mfma_f32_16x16x32_bf16 v[0:3], v[216:219], v[8:11], v[80:83]
	v_mfma_f32_16x16x32_bf16 v[80:83], v[220:223], v[68:71], v[0:3]
	v_mfma_f32_16x16x32_bf16 v[0:3], v[216:219], v[202:205], v[84:87]
	v_mfma_f32_16x16x32_bf16 v[84:87], v[220:223], v[208:211], v[0:3]
	v_mfma_f32_16x16x32_bf16 v[0:3], v[224:227], v[8:11], v[88:91]
	v_mfma_f32_16x16x32_bf16 v[56:59], v[228:231], v[68:71], v[0:3]
	v_mfma_f32_16x16x32_bf16 v[0:3], v[224:227], v[202:205], v[92:95]
	v_mfma_f32_16x16x32_bf16 v[60:63], v[228:231], v[208:211], v[0:3]
	s_barrier
	ds_read_b128 v[12:15], v17
	ds_read_b128 v[232:235], v17 offset:1024
	ds_read_b128 v[236:239], v17 offset:2048
	ds_read_b128 v[240:243], v17 offset:3072
	s_waitcnt vmcnt(0)
	s_barrier
	s_waitcnt lgkmcnt(0)
	s_waitcnt lgkmcnt(0)
	v_mfma_f32_16x16x32_bf16 v[0:3], v[32:35], v[12:15], v[122:125]
	v_mfma_f32_16x16x32_bf16 v[120:123], v[104:107], v[232:235], v[0:3]
	v_mfma_f32_16x16x32_bf16 v[0:3], v[32:35], v[236:239], v[38:41]
	v_mfma_f32_16x16x32_bf16 v[124:127], v[104:107], v[240:243], v[0:3]
	v_mfma_f32_16x16x32_bf16 v[0:3], v[108:111], v[12:15], v[42:45]
	v_mfma_f32_16x16x32_bf16 v[104:107], v[212:215], v[232:235], v[0:3]
	v_mfma_f32_16x16x32_bf16 v[0:3], v[108:111], v[236:239], v[46:49]
	v_mfma_f32_16x16x32_bf16 v[108:111], v[212:215], v[240:243], v[0:3]
	v_mfma_f32_16x16x32_bf16 v[0:3], v[216:219], v[12:15], v[50:53]
	v_mfma_f32_16x16x32_bf16 v[88:91], v[220:223], v[232:235], v[0:3]
	v_mfma_f32_16x16x32_bf16 v[0:3], v[216:219], v[236:239], v[154:157]
	v_mfma_f32_16x16x32_bf16 v[92:95], v[220:223], v[240:243], v[0:3]
	v_mfma_f32_16x16x32_bf16 v[0:3], v[224:227], v[12:15], v[158:161]
	v_mfma_f32_16x16x32_bf16 v[72:75], v[228:231], v[232:235], v[0:3]
	v_mfma_f32_16x16x32_bf16 v[0:3], v[224:227], v[236:239], v[64:67]
	v_mfma_f32_16x16x32_bf16 v[76:79], v[228:231], v[240:243], v[0:3]
	s_barrier
	ds_read_b128 v[40:43], v6 offset:49152
	ds_read_b128 v[44:47], v6 offset:50176
	ds_read_b128 v[154:157], v7 offset:51200
	ds_read_b128 v[158:161], v7 offset:52224
	ds_read_b128 v[212:215], v7 offset:53248
	ds_read_b128 v[216:219], v7 offset:54272
	ds_read_b128 v[220:223], v7 offset:55296
	ds_read_b128 v[224:227], v7 offset:56320
	s_barrier
	s_waitcnt lgkmcnt(0)
	s_waitcnt lgkmcnt(0)
	v_mfma_f32_16x16x32_bf16 v[0:3], v[40:43], v[8:11], v[18:21]
	v_mfma_f32_16x16x32_bf16 v[48:51], v[44:47], v[68:71], v[0:3]
	v_mfma_f32_16x16x32_bf16 v[0:3], v[40:43], v[202:205], v[162:165]
	v_mfma_f32_16x16x32_bf16 v[52:55], v[44:47], v[208:211], v[0:3]
	v_mfma_f32_16x16x32_bf16 v[0:3], v[154:157], v[8:11], v[166:169]
	v_mfma_f32_16x16x32_bf16 v[32:35], v[158:161], v[68:71], v[0:3]
	v_mfma_f32_16x16x32_bf16 v[0:3], v[154:157], v[202:205], v[170:173]
	v_mfma_f32_16x16x32_bf16 v[36:39], v[158:161], v[208:211], v[0:3]
	v_mfma_f32_16x16x32_bf16 v[0:3], v[212:215], v[8:11], v[174:177]
	v_mfma_f32_16x16x32_bf16 v[16:19], v[216:219], v[68:71], v[0:3]
	v_mfma_f32_16x16x32_bf16 v[0:3], v[212:215], v[202:205], v[178:181]
	v_mfma_f32_16x16x32_bf16 v[20:23], v[216:219], v[208:211], v[0:3]
	v_mfma_f32_16x16x32_bf16 v[0:3], v[220:223], v[8:11], v[138:141]
	v_mfma_f32_16x16x32_bf16 v[4:7], v[220:223], v[202:205], v[24:27]
	v_mfma_f32_16x16x32_bf16 v[0:3], v[224:227], v[68:71], v[0:3]
	v_mfma_f32_16x16x32_bf16 v[4:7], v[224:227], v[208:211], v[4:7]
	v_mfma_f32_16x16x32_bf16 v[8:11], v[40:43], v[12:15], v[28:31]
	v_mfma_f32_16x16x32_bf16 v[64:67], v[44:47], v[232:235], v[8:11]
	v_mfma_f32_16x16x32_bf16 v[8:11], v[40:43], v[236:239], v[142:145]
	v_mfma_f32_16x16x32_bf16 v[68:71], v[44:47], v[240:243], v[8:11]
	v_mfma_f32_16x16x32_bf16 v[8:11], v[154:157], v[12:15], v[146:149]
	v_mfma_f32_16x16x32_bf16 v[40:43], v[158:161], v[232:235], v[8:11]
	v_mfma_f32_16x16x32_bf16 v[8:11], v[154:157], v[236:239], v[150:153]
	v_mfma_f32_16x16x32_bf16 v[44:47], v[158:161], v[240:243], v[8:11]
	v_mfma_f32_16x16x32_bf16 v[8:11], v[212:215], v[12:15], v[182:185]
	v_mfma_f32_16x16x32_bf16 v[24:27], v[216:219], v[232:235], v[8:11]
	v_mfma_f32_16x16x32_bf16 v[8:11], v[212:215], v[236:239], v[134:137]
	v_mfma_f32_16x16x32_bf16 v[28:31], v[216:219], v[240:243], v[8:11]
	v_mfma_f32_16x16x32_bf16 v[8:11], v[220:223], v[12:15], v[186:189]
	v_mfma_f32_16x16x32_bf16 v[12:15], v[220:223], v[236:239], v[194:197]
	v_mfma_f32_16x16x32_bf16 v[8:11], v[224:227], v[232:235], v[8:11]
	v_mfma_f32_16x16x32_bf16 v[12:15], v[224:227], v[240:243], v[12:15]
	v_cmp_gt_u32_e32 vcc, s68, v128
	s_barrier
	s_and_saveexec_b64 s[60:61], vcc
	s_cbranch_execz .LBB0_802
	s_barrier
	s_branch .LBB0_802

; #define STAGE_A(P, hf, kt) do { if constexpr (ABLK) { const bf16* _gp = A + ((long)(brow >> 8) * nt + (kt)) * 16384 + (hf) * 8192; GLDS2(_gp, 4096, offA, P); } \
;     else { const bf16* _gp = A + (long)(brow + (hf) * HALF) * lda + (long)(kt) * BK; GLDS2(_gp, 64 * (long)lda, offA, P); } } while (0)
; #define STAGE_B(P, hf, kt) do { const bf16* _gp = Bt + (long)(bcol + (hf) * 2) * ldb + (long)(kt) * BK; GLDS2(_gp, 128 * (long)ldb, offB, P); } while (0)
; #define LDA(dst, b, h) for (int m = 0; m < 4; ++m) for (int k = 0; k < 2; ++k) \
;     dst[m][k] = *reinterpret_cast<const bf16x8*>((char*)SA(b, h) + lds_byte(wr * 64 + m * 16 + fr, k * 32 + fq * 8))
; #define LDB(dst, b, h) for (int n = 0; n < 2; ++n) for (int k = 0; k < 2; ++k) \
;     dst[n][k] = *reinterpret_cast<const bf16x8*>((char*)SB(b, h) + lds_byte(wc * 32 + n * 16 + fr, k * 32 + fq * 8))
; #define MMA(ai, bj, At, Bt_) do { __builtin_amdgcn_s_setprio(1); \
;     for (int m = 0; m < 4; ++m) for (int n = 0; n < 2; ++n) for (int k = 0; k < 2; ++k) \
;       acc[ai][bj][m][n] = __builtin_amdgcn_mfma_f32_16x16x32_bf16(At[m][k], Bt_[n][k], acc[ai][bj][m][n], 0, 0, 0); \
;     __builtin_amdgcn_s_setprio(0); } while (0)
; #define WAIT_V(n) asm volatile("s_waitcnt vmcnt(" #n ")" ::: "memory")
; #define BAR __builtin_amdgcn_s_barrier()
; template <bool ABLK, class Epi>
; __device__ __forceinline__ void gemm_tile(const bf16* __restrict__ A, int lda, const bf16* __restrict__ Bt, int ldb, int K,
;                                           int brow, int bcol, bf16* shm, const Epi& epi, int wv) {
;     ...
;   for (int t = 0; t < nt - 2; t += 2) {
;     LDB(B0, 0, 0); SCHED; LDA(At, 0, 0); STAGE_A(SA(1, 1), 1, t + 1);
;     WAIT_L(8); BAR; MMA(0, 0, At, B0); BAR; SCHED;
;     LDB(B1, 0, 1); STAGE_B(SB(0, 0), 0, t + 2);
;     BAR; MMA(0, 1, At, B1); BAR;
;     LDA(At, 0, 1); STAGE_A(SA(0, 0), 0, t + 2);
;     BAR; MMA(1, 0, At, B0); BAR; SCHED;
;     STAGE_B(SB(0, 1), 1, t + 2);
;     WAIT_V(6); BAR; MMA(1, 1, At, B1); BAR;
;     LDB(B0, 1, 0); SCHED; LDA(At, 1, 0); STAGE_A(SA(0, 1), 1, t + 2);
;     WAIT_L(8); BAR; MMA(0, 0, At, B0); BAR; SCHED;
;     LDB(B1, 1, 1); STAGE_B(SB(1, 0), 0, t + 3);
;     BAR; MMA(0, 1, At, B1); BAR;
;     LDA(At, 1, 1); STAGE_A(SA(1, 0), 0, t + 3);
;     BAR; MMA(1, 0, At, B0); BAR; SCHED;
;     STAGE_B(SB(1, 1), 1, t + 3);
;     WAIT_V(6); BAR; MMA(1, 1, At, B1); BAR;
;   }
.LBB0_814:
	ds_read_b128 v[168:171], v165
	ds_read_b128 v[172:175], v165 offset:1024
	ds_read_b128 v[176:179], v165 offset:2048
	ds_read_b128 v[180:183], v165 offset:3072
	v_add_u32_e32 v166, 0xc000, v150
	v_lshl_add_u64 v[198:199], v[136:137], 0, s[66:67]
	s_mov_b64 s[68:69], 0x22e60080
	v_add_u32_e32 v167, 0xe000, v150
	v_lshl_add_u64 v[224:225], v[198:199], 0, s[68:69]
	s_add_i32 m0, s99, 0xc000
	ds_read_b128 v[184:187], v147
	ds_read_b128 v[188:191], v147 offset:1024
	ds_read_b128 v[194:197], v146
	ds_read_b128 v[202:205], v146 offset:1024
	ds_read_b128 v[208:211], v145
	ds_read_b128 v[212:215], v145 offset:1024
	ds_read_b128 v[216:219], v144
	ds_read_b128 v[220:223], v144 offset:1024
	global_load_lds_dwordx4 v[224:225], off
	s_add_i32 m0, s99, 0xe000
	v_lshl_add_u64 v[224:225], v[198:199], 0, s[26:27]
	global_load_lds_dwordx4 v[224:225], off
	s_waitcnt lgkmcnt(8)
	s_barrier
	s_waitcnt lgkmcnt(0)
	v_mfma_f32_16x16x32_bf16 v[124:127], v[184:187], v[168:171], v[124:127]
	v_mfma_f32_16x16x32_bf16 v[120:123], v[184:187], v[176:179], v[120:123]
	v_mfma_f32_16x16x32_bf16 v[116:119], v[194:197], v[168:171], v[116:119]
	v_mfma_f32_16x16x32_bf16 v[112:115], v[194:197], v[176:179], v[112:115]
	v_mfma_f32_16x16x32_bf16 v[108:111], v[208:211], v[168:171], v[108:111]
	v_mfma_f32_16x16x32_bf16 v[104:107], v[208:211], v[176:179], v[104:107]
	v_mfma_f32_16x16x32_bf16 v[100:103], v[216:219], v[168:171], v[100:103]
	v_mfma_f32_16x16x32_bf16 v[96:99], v[216:219], v[176:179], v[96:99]
	v_mfma_f32_16x16x32_bf16 v[124:127], v[188:191], v[172:175], v[124:127]
	v_mfma_f32_16x16x32_bf16 v[120:123], v[188:191], v[180:183], v[120:123]
	v_mfma_f32_16x16x32_bf16 v[116:119], v[202:205], v[172:175], v[116:119]
	v_mfma_f32_16x16x32_bf16 v[112:115], v[202:205], v[180:183], v[112:115]
	v_mfma_f32_16x16x32_bf16 v[108:111], v[212:215], v[172:175], v[108:111]
	v_mfma_f32_16x16x32_bf16 v[104:107], v[212:215], v[180:183], v[104:107]
	v_mfma_f32_16x16x32_bf16 v[100:103], v[220:223], v[172:175], v[100:103]
	v_mfma_f32_16x16x32_bf16 v[96:99], v[220:223], v[180:183], v[96:99]
	s_barrier
	v_lshl_add_u64 v[240:241], v[134:135], 0, s[66:67]
	v_lshl_add_u64 v[242:243], v[240:241], 0, s[30:31]
	s_add_i32 m0, s99, 0x10000
	ds_read_b128 v[224:227], v164
	ds_read_b128 v[228:231], v164 offset:1024
	ds_read_b128 v[232:235], v164 offset:2048
	ds_read_b128 v[236:239], v164 offset:3072
	global_load_lds_dwordx4 v[242:243], off
	s_add_i32 m0, s99, 0x12000
	v_lshl_add_u64 v[242:243], v[240:241], 0, s[34:35]
	global_load_lds_dwordx4 v[242:243], off
	s_barrier
	s_waitcnt lgkmcnt(0)
	v_mfma_f32_16x16x32_bf16 v[92:95], v[184:187], v[224:227], v[92:95]
	v_mfma_f32_16x16x32_bf16 v[88:91], v[184:187], v[232:235], v[88:91]
	v_mfma_f32_16x16x32_bf16 v[84:87], v[194:197], v[224:227], v[84:87]
	v_mfma_f32_16x16x32_bf16 v[80:83], v[194:197], v[232:235], v[80:83]
	v_mfma_f32_16x16x32_bf16 v[76:79], v[208:211], v[224:227], v[76:79]
	v_mfma_f32_16x16x32_bf16 v[72:75], v[208:211], v[232:235], v[72:75]
	v_mfma_f32_16x16x32_bf16 v[68:71], v[216:219], v[224:227], v[68:71]
	v_mfma_f32_16x16x32_bf16 v[64:67], v[216:219], v[232:235], v[64:67]
	v_mfma_f32_16x16x32_bf16 v[92:95], v[188:191], v[228:231], v[92:95]
	v_mfma_f32_16x16x32_bf16 v[88:91], v[188:191], v[236:239], v[88:91]
	v_mfma_f32_16x16x32_bf16 v[84:87], v[202:205], v[228:231], v[84:87]
	v_mfma_f32_16x16x32_bf16 v[80:83], v[202:205], v[236:239], v[80:83]
	v_mfma_f32_16x16x32_bf16 v[76:79], v[212:215], v[228:231], v[76:79]
	v_mfma_f32_16x16x32_bf16 v[72:75], v[212:215], v[236:239], v[72:75]
	v_mfma_f32_16x16x32_bf16 v[68:71], v[220:223], v[228:231], v[68:71]
	v_mfma_f32_16x16x32_bf16 v[64:67], v[220:223], v[236:239], v[64:67]
	v_lshl_add_u64 v[242:243], v[198:199], 0, s[36:37]
	s_add_i32 m0, s99, 0x0
	s_barrier
	ds_read_b128 v[184:187], v147 offset:16384
	ds_read_b128 v[188:191], v147 offset:17408
	ds_read_b128 v[194:197], v146 offset:16384
	ds_read_b128 v[202:205], v146 offset:17408
	ds_read_b128 v[208:211], v145 offset:16384
	ds_read_b128 v[212:215], v145 offset:17408
	ds_read_b128 v[216:219], v144 offset:16384
	ds_read_b128 v[220:223], v144 offset:17408
	global_load_lds_dwordx4 v[242:243], off
	s_add_i32 m0, s99, 0x2000
	v_lshl_add_u64 v[242:243], v[198:199], 0, s[38:39]
	global_load_lds_dwordx4 v[242:243], off
	s_barrier
	s_waitcnt lgkmcnt(0)
	v_mfma_f32_16x16x32_bf16 v[60:63], v[184:187], v[168:171], v[60:63]
	v_mfma_f32_16x16x32_bf16 v[56:59], v[184:187], v[176:179], v[56:59]
	v_mfma_f32_16x16x32_bf16 v[52:55], v[194:197], v[168:171], v[52:55]
	v_mfma_f32_16x16x32_bf16 v[48:51], v[194:197], v[176:179], v[48:51]
	v_mfma_f32_16x16x32_bf16 v[44:47], v[208:211], v[168:171], v[44:47]
	v_mfma_f32_16x16x32_bf16 v[40:43], v[208:211], v[176:179], v[40:43]
	v_mfma_f32_16x16x32_bf16 v[36:39], v[216:219], v[168:171], v[36:39]
	v_mfma_f32_16x16x32_bf16 v[32:35], v[216:219], v[176:179], v[32:35]
	v_mfma_f32_16x16x32_bf16 v[60:63], v[188:191], v[172:175], v[60:63]
	v_mfma_f32_16x16x32_bf16 v[56:59], v[188:191], v[180:183], v[56:59]
	v_mfma_f32_16x16x32_bf16 v[52:55], v[202:205], v[172:175], v[52:55]
	v_mfma_f32_16x16x32_bf16 v[48:51], v[202:205], v[180:183], v[48:51]
	v_mfma_f32_16x16x32_bf16 v[44:47], v[212:215], v[172:175], v[44:47]
	v_mfma_f32_16x16x32_bf16 v[40:43], v[212:215], v[180:183], v[40:43]
	v_mfma_f32_16x16x32_bf16 v[36:39], v[220:223], v[172:175], v[36:39]
	v_mfma_f32_16x16x32_bf16 v[32:35], v[220:223], v[180:183], v[32:35]
	s_barrier
	s_add_i32 m0, s99, 0x14000
	v_lshl_add_u64 v[168:169], v[240:241], 0, s[40:41]
	global_load_lds_dwordx4 v[168:169], off
	s_add_i32 m0, s99, 0x16000
	v_lshl_add_u64 v[168:169], v[240:241], 0, s[42:43]
	global_load_lds_dwordx4 v[168:169], off
	s_waitcnt vmcnt(6)
	s_barrier
; #define STAGE_A(P, hf, kt) do { if constexpr (ABLK) { const bf16* _gp = A + ((long)(brow >> 8) * nt + (kt)) * 16384 + (hf) * 8192; GLDS2(_gp, 4096, offA, P); } \
;     else { const bf16* _gp = A + (long)(brow + (hf) * HALF) * lda + (long)(kt) * BK; GLDS2(_gp, 64 * (long)lda, offA, P); } } while (0)
; #define STAGE_B(P, hf, kt) do { const bf16* _gp = Bt + (long)(bcol + (hf) * 2) * ldb + (long)(kt) * BK; GLDS2(_gp, 128 * (long)ldb, offB, P); } while (0)
; #define LDA(dst, b, h) for (int m = 0; m < 4; ++m) for (int k = 0; k < 2; ++k) \
;     dst[m][k] = *reinterpret_cast<const bf16x8*>((char*)SA(b, h) + lds_byte(wr * 64 + m * 16 + fr, k * 32 + fq * 8))
; #define LDB(dst, b, h) for (int n = 0; n < 2; ++n) for (int k = 0; k < 2; ++k) \
;     dst[n][k] = *reinterpret_cast<const bf16x8*>((char*)SB(b, h) + lds_byte(wc * 32 + n * 16 + fr, k * 32 + fq * 8))
; #define MMA(ai, bj, At, Bt_) do { __builtin_amdgcn_s_setprio(1); \
;     for (int m = 0; m < 4; ++m) for (int n = 0; n < 2; ++n) for (int k = 0; k < 2; ++k) \
;       acc[ai][bj][m][n] = __builtin_amdgcn_mfma_f32_16x16x32_bf16(At[m][k], Bt_[n][k], acc[ai][bj][m][n], 0, 0, 0); \
;     __builtin_amdgcn_s_setprio(0); } while (0)
; #define WAIT_V(n) asm volatile("s_waitcnt vmcnt(" #n ")" ::: "memory")
; #define BAR __builtin_amdgcn_s_barrier()
; template <bool ABLK, class Epi>
; __device__ __forceinline__ void gemm_tile(const bf16* __restrict__ A, int lda, const bf16* __restrict__ Bt, int ldb, int K,
;                                           int brow, int bcol, bf16* shm, const Epi& epi, int wv) {
;     ...
;   for (int t = 0; t < nt - 2; t += 2) {
;     LDB(B0, 0, 0); SCHED; LDA(At, 0, 0); STAGE_A(SA(1, 1), 1, t + 1);
;     WAIT_L(8); BAR; MMA(0, 0, At, B0); BAR; SCHED;
;     LDB(B1, 0, 1); STAGE_B(SB(0, 0), 0, t + 2);
;     BAR; MMA(0, 1, At, B1); BAR;
;     LDA(At, 0, 1); STAGE_A(SA(0, 0), 0, t + 2);
;     BAR; MMA(1, 0, At, B0); BAR; SCHED;
;     STAGE_B(SB(0, 1), 1, t + 2);
;     WAIT_V(6); BAR; MMA(1, 1, At, B1); BAR;
;     LDB(B0, 1, 0); SCHED; LDA(At, 1, 0); STAGE_A(SA(0, 1), 1, t + 2);
;     WAIT_L(8); BAR; MMA(0, 0, At, B0); BAR; SCHED;
;     LDB(B1, 1, 1); STAGE_B(SB(1, 0), 0, t + 3);
;     BAR; MMA(0, 1, At, B1); BAR;
;     LDA(At, 1, 1); STAGE_A(SA(1, 0), 0, t + 3);
;     BAR; MMA(1, 0, At, B0); BAR; SCHED;
;     STAGE_B(SB(1, 1), 1, t + 3);
;     WAIT_V(6); BAR; MMA(1, 1, At, B1); BAR;
;   }
	v_mfma_f32_16x16x32_bf16 v[28:31], v[184:187], v[224:227], v[28:31]
	v_mfma_f32_16x16x32_bf16 v[24:27], v[184:187], v[232:235], v[24:27]
	v_mfma_f32_16x16x32_bf16 v[20:23], v[194:197], v[224:227], v[20:23]
	v_mfma_f32_16x16x32_bf16 v[16:19], v[194:197], v[232:235], v[16:19]
	v_mfma_f32_16x16x32_bf16 v[12:15], v[208:211], v[224:227], v[12:15]
	v_mfma_f32_16x16x32_bf16 v[8:11], v[208:211], v[232:235], v[8:11]
	v_mfma_f32_16x16x32_bf16 v[4:7], v[216:219], v[224:227], v[4:7]
	v_mfma_f32_16x16x32_bf16 v[0:3], v[216:219], v[232:235], v[0:3]
	v_mfma_f32_16x16x32_bf16 v[28:31], v[188:191], v[228:231], v[28:31]
	v_mfma_f32_16x16x32_bf16 v[24:27], v[188:191], v[236:239], v[24:27]
	v_mfma_f32_16x16x32_bf16 v[20:23], v[202:205], v[228:231], v[20:23]
	v_mfma_f32_16x16x32_bf16 v[16:19], v[202:205], v[236:239], v[16:19]
	v_mfma_f32_16x16x32_bf16 v[12:15], v[212:215], v[228:231], v[12:15]
	v_mfma_f32_16x16x32_bf16 v[8:11], v[212:215], v[236:239], v[8:11]
	v_mfma_f32_16x16x32_bf16 v[4:7], v[220:223], v[228:231], v[4:7]
	v_mfma_f32_16x16x32_bf16 v[0:3], v[220:223], v[236:239], v[0:3]
	s_barrier
	ds_read_b128 v[168:171], v155
	ds_read_b128 v[172:175], v155 offset:1024
	ds_read_b128 v[176:179], v155 offset:2048
	ds_read_b128 v[180:183], v155 offset:3072
	v_lshl_add_u64 v[224:225], v[198:199], 0, s[44:45]
	s_add_i32 m0, s99, 0x4000
	ds_read_b128 v[184:187], v147 offset:32768
	ds_read_b128 v[188:191], v147 offset:33792
	ds_read_b128 v[194:197], v146 offset:32768
	ds_read_b128 v[202:205], v146 offset:33792
	ds_read_b128 v[208:211], v145 offset:32768
	ds_read_b128 v[212:215], v145 offset:33792
	ds_read_b128 v[216:219], v144 offset:32768
	ds_read_b128 v[220:223], v144 offset:33792
	global_load_lds_dwordx4 v[224:225], off
	s_add_i32 m0, s99, 0x6000
	v_lshl_add_u64 v[224:225], v[198:199], 0, s[46:47]
	global_load_lds_dwordx4 v[224:225], off
	s_waitcnt lgkmcnt(8)
	s_barrier
	s_waitcnt lgkmcnt(0)
	v_mfma_f32_16x16x32_bf16 v[124:127], v[184:187], v[168:171], v[124:127]
	v_mfma_f32_16x16x32_bf16 v[120:123], v[184:187], v[176:179], v[120:123]
	v_mfma_f32_16x16x32_bf16 v[116:119], v[194:197], v[168:171], v[116:119]
	v_mfma_f32_16x16x32_bf16 v[112:115], v[194:197], v[176:179], v[112:115]
	v_mfma_f32_16x16x32_bf16 v[108:111], v[208:211], v[168:171], v[108:111]
	v_mfma_f32_16x16x32_bf16 v[104:107], v[208:211], v[176:179], v[104:107]
	v_mfma_f32_16x16x32_bf16 v[100:103], v[216:219], v[168:171], v[100:103]
	v_mfma_f32_16x16x32_bf16 v[96:99], v[216:219], v[176:179], v[96:99]
	v_mfma_f32_16x16x32_bf16 v[124:127], v[188:191], v[172:175], v[124:127]
	v_mfma_f32_16x16x32_bf16 v[120:123], v[188:191], v[180:183], v[120:123]
	v_mfma_f32_16x16x32_bf16 v[116:119], v[202:205], v[172:175], v[116:119]
	v_mfma_f32_16x16x32_bf16 v[112:115], v[202:205], v[180:183], v[112:115]
	v_mfma_f32_16x16x32_bf16 v[108:111], v[212:215], v[172:175], v[108:111]
	v_mfma_f32_16x16x32_bf16 v[104:107], v[212:215], v[180:183], v[104:107]
	v_mfma_f32_16x16x32_bf16 v[100:103], v[220:223], v[172:175], v[100:103]
	v_mfma_f32_16x16x32_bf16 v[96:99], v[220:223], v[180:183], v[96:99]
	s_barrier
	v_lshl_add_u64 v[242:243], v[240:241], 0, s[48:49]
	s_add_i32 m0, s99, 0x18000
	ds_read_b128 v[224:227], v151
	ds_read_b128 v[228:231], v151 offset:1024
	ds_read_b128 v[232:235], v151 offset:2048
	ds_read_b128 v[236:239], v151 offset:3072
	global_load_lds_dwordx4 v[242:243], off
	s_add_i32 m0, s99, 0x1a000
	v_lshl_add_u64 v[242:243], v[240:241], 0, s[50:51]
	global_load_lds_dwordx4 v[242:243], off
	s_barrier
	s_waitcnt lgkmcnt(0)
	v_mfma_f32_16x16x32_bf16 v[92:95], v[184:187], v[224:227], v[92:95]
	v_mfma_f32_16x16x32_bf16 v[88:91], v[184:187], v[232:235], v[88:91]
	v_mfma_f32_16x16x32_bf16 v[84:87], v[194:197], v[224:227], v[84:87]
	v_mfma_f32_16x16x32_bf16 v[80:83], v[194:197], v[232:235], v[80:83]
	v_mfma_f32_16x16x32_bf16 v[76:79], v[208:211], v[224:227], v[76:79]
	v_mfma_f32_16x16x32_bf16 v[72:75], v[208:211], v[232:235], v[72:75]
	v_mfma_f32_16x16x32_bf16 v[68:71], v[216:219], v[224:227], v[68:71]
	v_mfma_f32_16x16x32_bf16 v[64:67], v[216:219], v[232:235], v[64:67]
	v_mfma_f32_16x16x32_bf16 v[92:95], v[188:191], v[228:231], v[92:95]
	v_mfma_f32_16x16x32_bf16 v[88:91], v[188:191], v[236:239], v[88:91]
	v_mfma_f32_16x16x32_bf16 v[84:87], v[202:205], v[228:231], v[84:87]
	v_mfma_f32_16x16x32_bf16 v[80:83], v[202:205], v[236:239], v[80:83]
	v_mfma_f32_16x16x32_bf16 v[76:79], v[212:215], v[228:231], v[76:79]
	v_mfma_f32_16x16x32_bf16 v[72:75], v[212:215], v[236:239], v[72:75]
	v_mfma_f32_16x16x32_bf16 v[68:71], v[220:223], v[228:231], v[68:71]
	v_mfma_f32_16x16x32_bf16 v[64:67], v[220:223], v[236:239], v[64:67]
	v_lshl_add_u64 v[242:243], v[198:199], 0, s[52:53]
	s_add_i32 m0, s99, 0x8000
	s_barrier
	ds_read_b128 v[184:187], v147 offset:49152
	ds_read_b128 v[188:191], v147 offset:50176
	ds_read_b128 v[194:197], v146 offset:49152
	ds_read_b128 v[202:205], v146 offset:50176
	ds_read_b128 v[208:211], v145 offset:49152
	ds_read_b128 v[212:215], v145 offset:50176
	ds_read_b128 v[216:219], v144 offset:49152
	ds_read_b128 v[220:223], v144 offset:50176
	global_load_lds_dwordx4 v[242:243], off
	s_add_i32 m0, s99, 0xa000
	v_lshl_add_u64 v[198:199], v[198:199], 0, s[54:55]
	global_load_lds_dwordx4 v[198:199], off
	s_barrier
; #define STAGE_A(P, hf, kt) do { if constexpr (ABLK) { const bf16* _gp = A + ((long)(brow >> 8) * nt + (kt)) * 16384 + (hf) * 8192; GLDS2(_gp, 4096, offA, P); } \
;     else { const bf16* _gp = A + (long)(brow + (hf) * HALF) * lda + (long)(kt) * BK; GLDS2(_gp, 64 * (long)lda, offA, P); } } while (0)
; #define STAGE_B(P, hf, kt) do { const bf16* _gp = Bt + (long)(bcol + (hf) * 2) * ldb + (long)(kt) * BK; GLDS2(_gp, 128 * (long)ldb, offB, P); } while (0)
; #define LDA(dst, b, h) for (int m = 0; m < 4; ++m) for (int k = 0; k < 2; ++k) \
;     dst[m][k] = *reinterpret_cast<const bf16x8*>((char*)SA(b, h) + lds_byte(wr * 64 + m * 16 + fr, k * 32 + fq * 8))
; #define LDB(dst, b, h) for (int n = 0; n < 2; ++n) for (int k = 0; k < 2; ++k) \
;     dst[n][k] = *reinterpret_cast<const bf16x8*>((char*)SB(b, h) + lds_byte(wc * 32 + n * 16 + fr, k * 32 + fq * 8))
; #define MMA(ai, bj, At, Bt_) do { __builtin_amdgcn_s_setprio(1); \
;     for (int m = 0; m < 4; ++m) for (int n = 0; n < 2; ++n) for (int k = 0; k < 2; ++k) \
;       acc[ai][bj][m][n] = __builtin_amdgcn_mfma_f32_16x16x32_bf16(At[m][k], Bt_[n][k], acc[ai][bj][m][n], 0, 0, 0); \
;     __builtin_amdgcn_s_setprio(0); } while (0)
; #define WAIT_V(n) asm volatile("s_waitcnt vmcnt(" #n ")" ::: "memory")
; #define WAIT_L(n) asm volatile("s_waitcnt lgkmcnt(" #n ")" ::: "memory")
; #define BAR __builtin_amdgcn_s_barrier()
; #define SCHED __builtin_amdgcn_sched_barrier(0)
; template <bool ABLK, class Epi>
; __device__ __forceinline__ void gemm_tile(const bf16* __restrict__ A, int lda, const bf16* __restrict__ Bt, int ldb, int K,
;                                           int brow, int bcol, bf16* shm, const Epi& epi, int wv) {
;     ...
;     WAIT_L(8); BAR; MMA(0, 0, At, B0); BAR; SCHED;
;     LDB(B1, 1, 1); STAGE_B(SB(1, 0), 0, t + 3);
;     BAR; MMA(0, 1, At, B1); BAR;
;     LDA(At, 1, 1); STAGE_A(SA(1, 0), 0, t + 3);
;     BAR; MMA(1, 0, At, B0); BAR; SCHED;
;     STAGE_B(SB(1, 1), 1, t + 3);
;     WAIT_V(6); BAR; MMA(1, 1, At, B1); BAR;
;   }
;   { LDB(B0, 0, 0); LDA(At, 0, 0); STAGE_A(SA(1, 1), 1, nt - 1);
;     BAR; WAIT_L(0); MMA(0, 0, At, B0); BAR;
;     LDB(B1, 0, 1); BAR; WAIT_L(0); MMA(0, 1, At, B1); BAR;
;     LDA(At, 0, 1); WAIT_V(4); BAR; WAIT_L(0); MMA(1, 0, At, B0); MMA(1, 1, At, B1); BAR; }
	s_waitcnt lgkmcnt(0)
	v_mfma_f32_16x16x32_bf16 v[60:63], v[184:187], v[168:171], v[60:63]
	v_mfma_f32_16x16x32_bf16 v[56:59], v[184:187], v[176:179], v[56:59]
	v_mfma_f32_16x16x32_bf16 v[52:55], v[194:197], v[168:171], v[52:55]
	v_mfma_f32_16x16x32_bf16 v[48:51], v[194:197], v[176:179], v[48:51]
	v_mfma_f32_16x16x32_bf16 v[44:47], v[208:211], v[168:171], v[44:47]
	v_mfma_f32_16x16x32_bf16 v[40:43], v[208:211], v[176:179], v[40:43]
	v_mfma_f32_16x16x32_bf16 v[36:39], v[216:219], v[168:171], v[36:39]
	v_mfma_f32_16x16x32_bf16 v[32:35], v[216:219], v[176:179], v[32:35]
	v_mfma_f32_16x16x32_bf16 v[60:63], v[188:191], v[172:175], v[60:63]
	v_mfma_f32_16x16x32_bf16 v[56:59], v[188:191], v[180:183], v[56:59]
	v_mfma_f32_16x16x32_bf16 v[52:55], v[202:205], v[172:175], v[52:55]
	v_mfma_f32_16x16x32_bf16 v[48:51], v[202:205], v[180:183], v[48:51]
	v_mfma_f32_16x16x32_bf16 v[44:47], v[212:215], v[172:175], v[44:47]
	v_mfma_f32_16x16x32_bf16 v[40:43], v[212:215], v[180:183], v[40:43]
	v_mfma_f32_16x16x32_bf16 v[36:39], v[220:223], v[172:175], v[36:39]
	v_mfma_f32_16x16x32_bf16 v[32:35], v[220:223], v[180:183], v[32:35]
	s_barrier
	s_add_i32 m0, s99, 0x1c000
	v_lshl_add_u64 v[168:169], v[240:241], 0, s[56:57]
	global_load_lds_dwordx4 v[168:169], off
	s_add_i32 m0, s99, 0x1e000
	v_lshl_add_u64 v[168:169], v[240:241], 0, s[58:59]
	global_load_lds_dwordx4 v[168:169], off
	s_waitcnt vmcnt(6)
	s_barrier
	v_mfma_f32_16x16x32_bf16 v[28:31], v[184:187], v[224:227], v[28:31]
	v_mfma_f32_16x16x32_bf16 v[24:27], v[184:187], v[232:235], v[24:27]
	v_mfma_f32_16x16x32_bf16 v[20:23], v[194:197], v[224:227], v[20:23]
	v_mfma_f32_16x16x32_bf16 v[16:19], v[194:197], v[232:235], v[16:19]
	v_mfma_f32_16x16x32_bf16 v[12:15], v[208:211], v[224:227], v[12:15]
	v_mfma_f32_16x16x32_bf16 v[8:11], v[208:211], v[232:235], v[8:11]
	v_mfma_f32_16x16x32_bf16 v[4:7], v[216:219], v[224:227], v[4:7]
	v_mfma_f32_16x16x32_bf16 v[0:3], v[216:219], v[232:235], v[0:3]
	v_mfma_f32_16x16x32_bf16 v[28:31], v[188:191], v[228:231], v[28:31]
	v_mfma_f32_16x16x32_bf16 v[24:27], v[188:191], v[236:239], v[24:27]
	v_mfma_f32_16x16x32_bf16 v[20:23], v[202:205], v[228:231], v[20:23]
	v_mfma_f32_16x16x32_bf16 v[16:19], v[202:205], v[236:239], v[16:19]
	v_mfma_f32_16x16x32_bf16 v[12:15], v[212:215], v[228:231], v[12:15]
	v_mfma_f32_16x16x32_bf16 v[8:11], v[212:215], v[236:239], v[8:11]
	v_mfma_f32_16x16x32_bf16 v[4:7], v[220:223], v[228:231], v[4:7]
	v_mfma_f32_16x16x32_bf16 v[0:3], v[220:223], v[236:239], v[0:3]
	s_add_i32 s9, s9, 2
	s_add_u32 s66, s66, 0x100
	s_addc_u32 s67, s67, 0
	s_cmp_lt_u32 s9, 4
	s_barrier
	s_cbranch_scc1 .LBB0_814
	v_readfirstlane_b32 s2, v166
	v_lshl_add_u64 v[132:133], v[132:133], 0, s[60:61]
	s_mov_b32 m0, s2
	v_lshl_add_u64 v[130:131], v[130:131], 1, s[64:65]
	v_readfirstlane_b32 s2, v167
	ds_read_b128 v[134:137], v165
	ds_read_b128 v[156:159], v165 offset:1024
	ds_read_b128 v[160:163], v165 offset:2048
	ds_read_b128 v[168:171], v165 offset:3072
	ds_read_b128 v[172:175], v147
	ds_read_b128 v[176:179], v147 offset:1024
	ds_read_b128 v[180:183], v146
	ds_read_b128 v[184:187], v146 offset:1024
	ds_read_b128 v[188:191], v145
	ds_read_b128 v[194:197], v145 offset:1024
	ds_read_b128 v[202:205], v144
	ds_read_b128 v[208:211], v144 offset:1024
	global_load_lds_dwordx4 v[132:133], off
	v_lshl_add_u64 v[130:131], v[130:131], 0, s[62:63]
	s_mov_b32 m0, s2
	s_nop 0
	global_load_lds_dwordx4 v[130:131], off
	s_barrier
	s_waitcnt lgkmcnt(0)
	s_waitcnt lgkmcnt(0)
	v_mfma_f32_16x16x32_bf16 v[124:127], v[172:175], v[134:137], v[124:127]
	v_mfma_f32_16x16x32_bf16 v[120:123], v[172:175], v[160:163], v[120:123]
	v_mfma_f32_16x16x32_bf16 v[108:111], v[188:191], v[134:137], v[108:111]
	v_mfma_f32_16x16x32_bf16 v[104:107], v[188:191], v[160:163], v[104:107]
	v_mfma_f32_16x16x32_bf16 v[124:127], v[176:179], v[156:159], v[124:127]
	v_mfma_f32_16x16x32_bf16 v[120:123], v[176:179], v[168:171], v[120:123]
	v_mfma_f32_16x16x32_bf16 v[116:119], v[180:183], v[134:137], v[116:119]
	v_mfma_f32_16x16x32_bf16 v[112:115], v[180:183], v[160:163], v[112:115]
	v_mfma_f32_16x16x32_bf16 v[108:111], v[194:197], v[156:159], v[108:111]
	v_mfma_f32_16x16x32_bf16 v[104:107], v[194:197], v[168:171], v[104:107]
	v_mfma_f32_16x16x32_bf16 v[100:103], v[202:205], v[134:137], v[100:103]
	v_mfma_f32_16x16x32_bf16 v[96:99], v[202:205], v[160:163], v[96:99]
	v_mfma_f32_16x16x32_bf16 v[130:133], v[184:187], v[156:159], v[116:119]
	v_mfma_f32_16x16x32_bf16 v[212:215], v[184:187], v[168:171], v[112:115]
	v_mfma_f32_16x16x32_bf16 v[216:219], v[208:211], v[156:159], v[100:103]
	v_mfma_f32_16x16x32_bf16 v[220:223], v[208:211], v[168:171], v[96:99]
	s_barrier
	s_nop 1
	ds_read_b128 v[96:99], v164
	ds_read_b128 v[100:103], v164 offset:1024
	ds_read_b128 v[112:115], v164 offset:2048
	ds_read_b128 v[116:119], v164 offset:3072
	s_barrier
	s_waitcnt lgkmcnt(0)
	s_waitcnt lgkmcnt(0)
	v_mfma_f32_16x16x32_bf16 v[92:95], v[172:175], v[96:99], v[92:95]
	v_mfma_f32_16x16x32_bf16 v[88:91], v[172:175], v[112:115], v[88:91]
	v_mfma_f32_16x16x32_bf16 v[76:79], v[188:191], v[96:99], v[76:79]
	v_mfma_f32_16x16x32_bf16 v[72:75], v[188:191], v[112:115], v[72:75]
	v_mfma_f32_16x16x32_bf16 v[92:95], v[176:179], v[100:103], v[92:95]
	v_mfma_f32_16x16x32_bf16 v[88:91], v[176:179], v[116:119], v[88:91]
	v_mfma_f32_16x16x32_bf16 v[84:87], v[180:183], v[96:99], v[84:87]
	v_mfma_f32_16x16x32_bf16 v[80:83], v[180:183], v[112:115], v[80:83]
	v_mfma_f32_16x16x32_bf16 v[76:79], v[194:197], v[100:103], v[76:79]
	v_mfma_f32_16x16x32_bf16 v[72:75], v[194:197], v[116:119], v[72:75]
	v_mfma_f32_16x16x32_bf16 v[68:71], v[202:205], v[96:99], v[68:71]
	v_mfma_f32_16x16x32_bf16 v[64:67], v[202:205], v[112:115], v[64:67]
	v_mfma_f32_16x16x32_bf16 v[164:167], v[184:187], v[100:103], v[84:87]
	v_mfma_f32_16x16x32_bf16 v[172:175], v[184:187], v[116:119], v[80:83]
	v_mfma_f32_16x16x32_bf16 v[176:179], v[208:211], v[100:103], v[68:71]
	v_mfma_f32_16x16x32_bf16 v[180:183], v[208:211], v[116:119], v[64:67]
	s_barrier
; #define LDA(dst, b, h) for (int m = 0; m < 4; ++m) for (int k = 0; k < 2; ++k) \
;     dst[m][k] = *reinterpret_cast<const bf16x8*>((char*)SA(b, h) + lds_byte(wr * 64 + m * 16 + fr, k * 32 + fq * 8))
; #define LDB(dst, b, h) for (int n = 0; n < 2; ++n) for (int k = 0; k < 2; ++k) \
;     dst[n][k] = *reinterpret_cast<const bf16x8*>((char*)SB(b, h) + lds_byte(wc * 32 + n * 16 + fr, k * 32 + fq * 8))
; #define MMA(ai, bj, At, Bt_) do { __builtin_amdgcn_s_setprio(1); \
;     for (int m = 0; m < 4; ++m) for (int n = 0; n < 2; ++n) for (int k = 0; k < 2; ++k) \
;       acc[ai][bj][m][n] = __builtin_amdgcn_mfma_f32_16x16x32_bf16(At[m][k], Bt_[n][k], acc[ai][bj][m][n], 0, 0, 0); \
;     __builtin_amdgcn_s_setprio(0); } while (0)
; #define WAIT_V(n) asm volatile("s_waitcnt vmcnt(" #n ")" ::: "memory")
; #define WAIT_L(n) asm volatile("s_waitcnt lgkmcnt(" #n ")" ::: "memory")
; #define BAR __builtin_amdgcn_s_barrier()
; template <bool ABLK, class Epi>
; __device__ __forceinline__ void gemm_tile(const bf16* __restrict__ A, int lda, const bf16* __restrict__ Bt, int ldb, int K,
;                                           int brow, int bcol, bf16* shm, const Epi& epi, int wv) {
;     ...
;     LDA(At, 0, 1); WAIT_V(4); BAR; WAIT_L(0); MMA(1, 0, At, B0); MMA(1, 1, At, B1); BAR; }
;   { LDB(B0, 1, 0); LDA(At, 1, 0); WAIT_V(2); BAR; WAIT_L(0); MMA(0, 0, At, B0); BAR;
;     LDB(B1, 1, 1); WAIT_V(0); BAR; WAIT_L(0); MMA(0, 1, At, B1); BAR;
	s_nop 1
	ds_read_b128 v[64:67], v147 offset:16384
	ds_read_b128 v[68:71], v147 offset:17408
	ds_read_b128 v[80:83], v146 offset:16384
	ds_read_b128 v[84:87], v146 offset:17408
	ds_read_b128 v[184:187], v145 offset:16384
	ds_read_b128 v[188:191], v145 offset:17408
	ds_read_b128 v[194:197], v144 offset:16384
	ds_read_b128 v[202:205], v144 offset:17408
	s_waitcnt vmcnt(4)
	s_barrier
	s_waitcnt lgkmcnt(0)
	s_waitcnt lgkmcnt(0)
	v_mfma_f32_16x16x32_bf16 v[60:63], v[64:67], v[134:137], v[60:63]
	v_mfma_f32_16x16x32_bf16 v[56:59], v[64:67], v[160:163], v[56:59]
	v_mfma_f32_16x16x32_bf16 v[44:47], v[184:187], v[134:137], v[44:47]
	v_mfma_f32_16x16x32_bf16 v[40:43], v[184:187], v[160:163], v[40:43]
	v_mfma_f32_16x16x32_bf16 v[60:63], v[68:71], v[156:159], v[60:63]
	v_mfma_f32_16x16x32_bf16 v[56:59], v[68:71], v[168:171], v[56:59]
	v_mfma_f32_16x16x32_bf16 v[52:55], v[80:83], v[134:137], v[52:55]
	v_mfma_f32_16x16x32_bf16 v[48:51], v[80:83], v[160:163], v[48:51]
	v_mfma_f32_16x16x32_bf16 v[44:47], v[188:191], v[156:159], v[44:47]
	v_mfma_f32_16x16x32_bf16 v[40:43], v[188:191], v[168:171], v[40:43]
	v_mfma_f32_16x16x32_bf16 v[36:39], v[194:197], v[134:137], v[36:39]
	v_mfma_f32_16x16x32_bf16 v[32:35], v[194:197], v[160:163], v[32:35]
	v_mfma_f32_16x16x32_bf16 v[208:211], v[84:87], v[156:159], v[52:55]
	v_mfma_f32_16x16x32_bf16 v[224:227], v[84:87], v[168:171], v[48:51]
	v_mfma_f32_16x16x32_bf16 v[134:137], v[202:205], v[156:159], v[36:39]
	v_mfma_f32_16x16x32_bf16 v[156:159], v[202:205], v[168:171], v[32:35]
	v_mfma_f32_16x16x32_bf16 v[28:31], v[64:67], v[96:99], v[28:31]
	v_mfma_f32_16x16x32_bf16 v[24:27], v[64:67], v[112:115], v[24:27]
	v_mfma_f32_16x16x32_bf16 v[12:15], v[184:187], v[96:99], v[12:15]
	v_mfma_f32_16x16x32_bf16 v[8:11], v[184:187], v[112:115], v[8:11]
	v_mfma_f32_16x16x32_bf16 v[28:31], v[68:71], v[100:103], v[28:31]
	v_mfma_f32_16x16x32_bf16 v[24:27], v[68:71], v[116:119], v[24:27]
	v_mfma_f32_16x16x32_bf16 v[20:23], v[80:83], v[96:99], v[20:23]
	v_mfma_f32_16x16x32_bf16 v[16:19], v[80:83], v[112:115], v[16:19]
	v_mfma_f32_16x16x32_bf16 v[12:15], v[188:191], v[100:103], v[12:15]
	v_mfma_f32_16x16x32_bf16 v[8:11], v[188:191], v[116:119], v[8:11]
	v_mfma_f32_16x16x32_bf16 v[4:7], v[194:197], v[96:99], v[4:7]
	v_mfma_f32_16x16x32_bf16 v[0:3], v[194:197], v[112:115], v[0:3]
	v_mfma_f32_16x16x32_bf16 v[160:163], v[84:87], v[100:103], v[20:23]
	v_mfma_f32_16x16x32_bf16 v[168:171], v[84:87], v[116:119], v[16:19]
	v_mfma_f32_16x16x32_bf16 v[184:187], v[202:205], v[100:103], v[4:7]
	v_mfma_f32_16x16x32_bf16 v[188:191], v[202:205], v[116:119], v[0:3]
	s_barrier
	s_nop 1
	ds_read_b128 v[0:3], v155
	ds_read_b128 v[4:7], v155 offset:1024
	ds_read_b128 v[194:197], v155 offset:2048
	ds_read_b128 v[152:155], v155 offset:3072
	ds_read_b128 v[16:19], v147 offset:32768
	ds_read_b128 v[20:23], v147 offset:33792
	ds_read_b128 v[32:35], v146 offset:32768
	ds_read_b128 v[36:39], v146 offset:33792
	ds_read_b128 v[48:51], v145 offset:32768
	ds_read_b128 v[52:55], v145 offset:33792
	ds_read_b128 v[202:205], v144 offset:32768
	ds_read_b128 v[228:231], v144 offset:33792
	s_waitcnt vmcnt(2)
	s_barrier
	s_waitcnt lgkmcnt(0)
	s_waitcnt lgkmcnt(0)
	v_mfma_f32_16x16x32_bf16 v[64:67], v[16:19], v[0:3], v[124:127]
	v_mfma_f32_16x16x32_bf16 v[112:115], v[20:23], v[4:7], v[64:67]
	v_mfma_f32_16x16x32_bf16 v[64:67], v[16:19], v[194:197], v[120:123]
	v_mfma_f32_16x16x32_bf16 v[116:119], v[20:23], v[152:155], v[64:67]
	v_mfma_f32_16x16x32_bf16 v[64:67], v[32:35], v[0:3], v[130:133]
	v_mfma_f32_16x16x32_bf16 v[96:99], v[36:39], v[4:7], v[64:67]
	v_mfma_f32_16x16x32_bf16 v[64:67], v[32:35], v[194:197], v[212:215]
	v_mfma_f32_16x16x32_bf16 v[100:103], v[36:39], v[152:155], v[64:67]
	v_mfma_f32_16x16x32_bf16 v[64:67], v[48:51], v[0:3], v[108:111]
	v_mfma_f32_16x16x32_bf16 v[80:83], v[52:55], v[4:7], v[64:67]
	v_mfma_f32_16x16x32_bf16 v[64:67], v[48:51], v[194:197], v[104:107]
	v_mfma_f32_16x16x32_bf16 v[84:87], v[52:55], v[152:155], v[64:67]
	v_mfma_f32_16x16x32_bf16 v[64:67], v[202:205], v[0:3], v[216:219]
	v_mfma_f32_16x16x32_bf16 v[68:71], v[202:205], v[194:197], v[220:223]
	v_mfma_f32_16x16x32_bf16 v[64:67], v[228:231], v[4:7], v[64:67]
	v_mfma_f32_16x16x32_bf16 v[68:71], v[228:231], v[152:155], v[68:71]
	s_barrier
; #define LDA(dst, b, h) for (int m = 0; m < 4; ++m) for (int k = 0; k < 2; ++k) \
;     dst[m][k] = *reinterpret_cast<const bf16x8*>((char*)SA(b, h) + lds_byte(wr * 64 + m * 16 + fr, k * 32 + fq * 8))
; #define LDB(dst, b, h) for (int n = 0; n < 2; ++n) for (int k = 0; k < 2; ++k) \
;     dst[n][k] = *reinterpret_cast<const bf16x8*>((char*)SB(b, h) + lds_byte(wc * 32 + n * 16 + fr, k * 32 + fq * 8))
; #define MMA(ai, bj, At, Bt_) do { __builtin_amdgcn_s_setprio(1); \
;     for (int m = 0; m < 4; ++m) for (int n = 0; n < 2; ++n) for (int k = 0; k < 2; ++k) \
;       acc[ai][bj][m][n] = __builtin_amdgcn_mfma_f32_16x16x32_bf16(At[m][k], Bt_[n][k], acc[ai][bj][m][n], 0, 0, 0); \
;     __builtin_amdgcn_s_setprio(0); } while (0)
; #define WAIT_V(n) asm volatile("s_waitcnt vmcnt(" #n ")" ::: "memory")
; #define WAIT_L(n) asm volatile("s_waitcnt lgkmcnt(" #n ")" ::: "memory")
; #define BAR __builtin_amdgcn_s_barrier()
; template <bool ABLK, class Epi>
; __device__ __forceinline__ void gemm_tile(const bf16* __restrict__ A, int lda, const bf16* __restrict__ Bt, int ldb, int K,
;                                           int brow, int bcol, bf16* shm, const Epi& epi, int wv) {
;     ...
;     LDB(B1, 1, 1); WAIT_V(0); BAR; WAIT_L(0); MMA(0, 1, At, B1); BAR;
;     LDA(At, 1, 1); BAR; WAIT_L(0); MMA(1, 0, At, B0); MMA(1, 1, At, B1); BAR; }
;   if (wr == 0) BAR;
	ds_read_b128 v[130:133], v151
	ds_read_b128 v[212:215], v151 offset:1024
	ds_read_b128 v[216:219], v151 offset:2048
	ds_read_b128 v[148:151], v151 offset:3072
	s_waitcnt vmcnt(0)
	s_barrier
	s_waitcnt lgkmcnt(0)
	s_waitcnt lgkmcnt(0)
	v_mfma_f32_16x16x32_bf16 v[92:95], v[16:19], v[130:133], v[92:95]
	v_mfma_f32_16x16x32_bf16 v[16:19], v[16:19], v[216:219], v[88:91]
	v_mfma_f32_16x16x32_bf16 v[124:127], v[20:23], v[148:151], v[16:19]
	v_mfma_f32_16x16x32_bf16 v[16:19], v[32:35], v[130:133], v[164:167]
	v_mfma_f32_16x16x32_bf16 v[104:107], v[36:39], v[212:215], v[16:19]
	v_mfma_f32_16x16x32_bf16 v[16:19], v[32:35], v[216:219], v[172:175]
	v_mfma_f32_16x16x32_bf16 v[108:111], v[36:39], v[148:151], v[16:19]
	v_mfma_f32_16x16x32_bf16 v[16:19], v[48:51], v[130:133], v[76:79]
	v_mfma_f32_16x16x32_bf16 v[88:91], v[52:55], v[212:215], v[16:19]
	v_mfma_f32_16x16x32_bf16 v[16:19], v[48:51], v[216:219], v[72:75]
	v_mfma_f32_16x16x32_bf16 v[120:123], v[20:23], v[212:215], v[92:95]
	v_mfma_f32_16x16x32_bf16 v[92:95], v[52:55], v[148:151], v[16:19]
	v_mfma_f32_16x16x32_bf16 v[16:19], v[202:205], v[130:133], v[176:179]
	v_mfma_f32_16x16x32_bf16 v[72:75], v[228:231], v[212:215], v[16:19]
	v_mfma_f32_16x16x32_bf16 v[16:19], v[202:205], v[216:219], v[180:183]
	v_mfma_f32_16x16x32_bf16 v[76:79], v[228:231], v[148:151], v[16:19]
	s_barrier
	ds_read_b128 v[164:167], v147 offset:49152
	ds_read_b128 v[172:175], v147 offset:50176
	ds_read_b128 v[176:179], v146 offset:49152
	ds_read_b128 v[180:183], v146 offset:50176
	ds_read_b128 v[202:205], v145 offset:49152
	ds_read_b128 v[220:223], v145 offset:50176
	ds_read_b128 v[228:231], v144 offset:49152
	ds_read_b128 v[144:147], v144 offset:50176
	s_barrier
	s_waitcnt lgkmcnt(0)
	s_waitcnt lgkmcnt(0)
	v_mfma_f32_16x16x32_bf16 v[16:19], v[164:167], v[0:3], v[60:63]
	v_mfma_f32_16x16x32_bf16 v[48:51], v[172:175], v[4:7], v[16:19]
	v_mfma_f32_16x16x32_bf16 v[16:19], v[164:167], v[194:197], v[56:59]
	v_mfma_f32_16x16x32_bf16 v[52:55], v[172:175], v[152:155], v[16:19]
	v_mfma_f32_16x16x32_bf16 v[16:19], v[176:179], v[0:3], v[208:211]
	v_mfma_f32_16x16x32_bf16 v[32:35], v[180:183], v[4:7], v[16:19]
	v_mfma_f32_16x16x32_bf16 v[16:19], v[176:179], v[194:197], v[224:227]
	v_mfma_f32_16x16x32_bf16 v[36:39], v[180:183], v[152:155], v[16:19]
	v_mfma_f32_16x16x32_bf16 v[16:19], v[202:205], v[0:3], v[44:47]
	v_mfma_f32_16x16x32_bf16 v[0:3], v[228:231], v[0:3], v[134:137]
	v_mfma_f32_16x16x32_bf16 v[16:19], v[220:223], v[4:7], v[16:19]
	v_mfma_f32_16x16x32_bf16 v[20:23], v[202:205], v[194:197], v[40:43]
	v_mfma_f32_16x16x32_bf16 v[0:3], v[144:147], v[4:7], v[0:3]
	v_mfma_f32_16x16x32_bf16 v[4:7], v[228:231], v[194:197], v[156:159]
	v_mfma_f32_16x16x32_bf16 v[20:23], v[220:223], v[152:155], v[20:23]
	v_mfma_f32_16x16x32_bf16 v[4:7], v[144:147], v[152:155], v[4:7]
	v_mfma_f32_16x16x32_bf16 v[24:27], v[164:167], v[216:219], v[24:27]
	v_mfma_f32_16x16x32_bf16 v[60:63], v[172:175], v[148:151], v[24:27]
	v_mfma_f32_16x16x32_bf16 v[24:27], v[176:179], v[130:133], v[160:163]
	v_mfma_f32_16x16x32_bf16 v[28:31], v[164:167], v[130:133], v[28:31]
	v_mfma_f32_16x16x32_bf16 v[40:43], v[180:183], v[212:215], v[24:27]
	v_mfma_f32_16x16x32_bf16 v[24:27], v[176:179], v[216:219], v[168:171]
	v_mfma_f32_16x16x32_bf16 v[12:15], v[202:205], v[130:133], v[12:15]
	v_mfma_f32_16x16x32_bf16 v[8:11], v[202:205], v[216:219], v[8:11]
	v_mfma_f32_16x16x32_bf16 v[56:59], v[172:175], v[212:215], v[28:31]
	v_mfma_f32_16x16x32_bf16 v[44:47], v[180:183], v[148:151], v[24:27]
	v_mfma_f32_16x16x32_bf16 v[24:27], v[220:223], v[212:215], v[12:15]
	v_mfma_f32_16x16x32_bf16 v[28:31], v[220:223], v[148:151], v[8:11]
	v_mfma_f32_16x16x32_bf16 v[8:11], v[228:231], v[130:133], v[184:187]
	v_mfma_f32_16x16x32_bf16 v[12:15], v[228:231], v[216:219], v[188:191]
	v_mfma_f32_16x16x32_bf16 v[8:11], v[144:147], v[212:215], v[8:11]
	v_mfma_f32_16x16x32_bf16 v[12:15], v[144:147], v[148:151], v[12:15]
	v_cmp_gt_u32_e32 vcc, s79, v128
	s_barrier
	s_and_saveexec_b64 s[64:65], vcc
	s_cbranch_execz .LBB0_817
	s_barrier

; #define STAGE_A(P, hf, kt) do { if constexpr (ABLK) { const bf16* _gp = A + ((long)(brow >> 8) * nt + (kt)) * 16384 + (hf) * 8192; GLDS2(_gp, 4096, offA, P); } \
;     else { const bf16* _gp = A + (long)(brow + (hf) * HALF) * lda + (long)(kt) * BK; GLDS2(_gp, 64 * (long)lda, offA, P); } } while (0)
; #define STAGE_B(P, hf, kt) do { const bf16* _gp = Bt + (long)(bcol + (hf) * 2) * ldb + (long)(kt) * BK; GLDS2(_gp, 128 * (long)ldb, offB, P); } while (0)
; #define LDA(dst, b, h) for (int m = 0; m < 4; ++m) for (int k = 0; k < 2; ++k) \
;     dst[m][k] = *reinterpret_cast<const bf16x8*>((char*)SA(b, h) + lds_byte(wr * 64 + m * 16 + fr, k * 32 + fq * 8))
; #define LDB(dst, b, h) for (int n = 0; n < 2; ++n) for (int k = 0; k < 2; ++k) \
;     dst[n][k] = *reinterpret_cast<const bf16x8*>((char*)SB(b, h) + lds_byte(wc * 32 + n * 16 + fr, k * 32 + fq * 8))
; #define MMA(ai, bj, At, Bt_) do { __builtin_amdgcn_s_setprio(1); \
;     for (int m = 0; m < 4; ++m) for (int n = 0; n < 2; ++n) for (int k = 0; k < 2; ++k) \
;       acc[ai][bj][m][n] = __builtin_amdgcn_mfma_f32_16x16x32_bf16(At[m][k], Bt_[n][k], acc[ai][bj][m][n], 0, 0, 0); \
;     __builtin_amdgcn_s_setprio(0); } while (0)
; #define WAIT_V(n) asm volatile("s_waitcnt vmcnt(" #n ")" ::: "memory")
; #define BAR __builtin_amdgcn_s_barrier()
; template <bool ABLK, class Epi>
; __device__ __forceinline__ void gemm_tile(const bf16* __restrict__ A, int lda, const bf16* __restrict__ Bt, int ldb, int K,
;                                           int brow, int bcol, bf16* shm, const Epi& epi, int wv) {
;     ...
;   for (int t = 0; t < nt - 2; t += 2) {
;     LDB(B0, 0, 0); SCHED; LDA(At, 0, 0); STAGE_A(SA(1, 1), 1, t + 1);
;     WAIT_L(8); BAR; MMA(0, 0, At, B0); BAR; SCHED;
;     LDB(B1, 0, 1); STAGE_B(SB(0, 0), 0, t + 2);
;     BAR; MMA(0, 1, At, B1); BAR;
;     LDA(At, 0, 1); STAGE_A(SA(0, 0), 0, t + 2);
;     BAR; MMA(1, 0, At, B0); BAR; SCHED;
;     STAGE_B(SB(0, 1), 1, t + 2);
;     WAIT_V(6); BAR; MMA(1, 1, At, B1); BAR;
;     LDB(B0, 1, 0); SCHED; LDA(At, 1, 0); STAGE_A(SA(0, 1), 1, t + 2);
;     WAIT_L(8); BAR; MMA(0, 0, At, B0); BAR; SCHED;
;     LDB(B1, 1, 1); STAGE_B(SB(1, 0), 0, t + 3);
;     BAR; MMA(0, 1, At, B1); BAR;
;     LDA(At, 1, 1); STAGE_A(SA(1, 0), 0, t + 3);
;     BAR; MMA(1, 0, At, B0); BAR; SCHED;
;     STAGE_B(SB(1, 1), 1, t + 3);
;     WAIT_V(6); BAR; MMA(1, 1, At, B1); BAR;
;   }
.LBB0_977:
	ds_read_b128 v[164:167], v161
	ds_read_b128 v[168:171], v161 offset:1024
	ds_read_b128 v[172:175], v161 offset:2048
	ds_read_b128 v[176:179], v161 offset:3072
	v_add_u32_e32 v162, 0xc000, v147
	v_add_u32_e32 v163, 0xe000, v147
	v_lshl_add_u64 v[198:199], v[130:131], 0, s[24:25]
	s_add_i32 m0, s99, 0xc000
	ds_read_b128 v[180:183], v143
	ds_read_b128 v[184:187], v143 offset:1024
	ds_read_b128 v[188:191], v142
	ds_read_b128 v[194:197], v142 offset:1024
	ds_read_b128 v[202:205], v141
	ds_read_b128 v[208:211], v141 offset:1024
	ds_read_b128 v[212:215], v140
	ds_read_b128 v[216:219], v140 offset:1024
	global_load_lds_dwordx4 v[198:199], off
	s_add_i32 m0, s99, 0xe000
	v_lshl_add_u64 v[198:199], v[130:131], 0, s[26:27]
	global_load_lds_dwordx4 v[198:199], off
	s_waitcnt lgkmcnt(8)
	s_barrier
	s_waitcnt lgkmcnt(0)
	v_mfma_f32_16x16x32_bf16 v[124:127], v[180:183], v[164:167], v[124:127]
	v_mfma_f32_16x16x32_bf16 v[120:123], v[180:183], v[172:175], v[120:123]
	v_mfma_f32_16x16x32_bf16 v[116:119], v[188:191], v[164:167], v[116:119]
	v_mfma_f32_16x16x32_bf16 v[112:115], v[188:191], v[172:175], v[112:115]
	v_mfma_f32_16x16x32_bf16 v[108:111], v[202:205], v[164:167], v[108:111]
	v_mfma_f32_16x16x32_bf16 v[104:107], v[202:205], v[172:175], v[104:107]
	v_mfma_f32_16x16x32_bf16 v[100:103], v[212:215], v[164:167], v[100:103]
	v_mfma_f32_16x16x32_bf16 v[96:99], v[212:215], v[172:175], v[96:99]
	v_mfma_f32_16x16x32_bf16 v[124:127], v[184:187], v[168:171], v[124:127]
	v_mfma_f32_16x16x32_bf16 v[120:123], v[184:187], v[176:179], v[120:123]
	v_mfma_f32_16x16x32_bf16 v[116:119], v[194:197], v[168:171], v[116:119]
	v_mfma_f32_16x16x32_bf16 v[112:115], v[194:197], v[176:179], v[112:115]
	v_mfma_f32_16x16x32_bf16 v[108:111], v[208:211], v[168:171], v[108:111]
	v_mfma_f32_16x16x32_bf16 v[104:107], v[208:211], v[176:179], v[104:107]
	v_mfma_f32_16x16x32_bf16 v[100:103], v[216:219], v[168:171], v[100:103]
	v_mfma_f32_16x16x32_bf16 v[96:99], v[216:219], v[176:179], v[96:99]
	s_barrier
	v_lshl_add_u64 v[198:199], v[132:133], 0, s[30:31]
	s_add_i32 m0, s99, 0x10000
	ds_read_b128 v[220:223], v160
	ds_read_b128 v[224:227], v160 offset:1024
	ds_read_b128 v[228:231], v160 offset:2048
	ds_read_b128 v[232:235], v160 offset:3072
	global_load_lds_dwordx4 v[198:199], off
	s_add_i32 m0, s99, 0x12000
	v_lshl_add_u64 v[198:199], v[132:133], 0, s[34:35]
	global_load_lds_dwordx4 v[198:199], off
	s_barrier
	s_waitcnt lgkmcnt(0)
	v_mfma_f32_16x16x32_bf16 v[92:95], v[180:183], v[220:223], v[92:95]
	v_mfma_f32_16x16x32_bf16 v[88:91], v[180:183], v[228:231], v[88:91]
	v_mfma_f32_16x16x32_bf16 v[84:87], v[188:191], v[220:223], v[84:87]
	v_mfma_f32_16x16x32_bf16 v[80:83], v[188:191], v[228:231], v[80:83]
	v_mfma_f32_16x16x32_bf16 v[76:79], v[202:205], v[220:223], v[76:79]
	v_mfma_f32_16x16x32_bf16 v[72:75], v[202:205], v[228:231], v[72:75]
	v_mfma_f32_16x16x32_bf16 v[68:71], v[212:215], v[220:223], v[68:71]
	v_mfma_f32_16x16x32_bf16 v[64:67], v[212:215], v[228:231], v[64:67]
	v_mfma_f32_16x16x32_bf16 v[92:95], v[184:187], v[224:227], v[92:95]
	v_mfma_f32_16x16x32_bf16 v[88:91], v[184:187], v[232:235], v[88:91]
	v_mfma_f32_16x16x32_bf16 v[84:87], v[194:197], v[224:227], v[84:87]
	v_mfma_f32_16x16x32_bf16 v[80:83], v[194:197], v[232:235], v[80:83]
	v_mfma_f32_16x16x32_bf16 v[76:79], v[208:211], v[224:227], v[76:79]
	v_mfma_f32_16x16x32_bf16 v[72:75], v[208:211], v[232:235], v[72:75]
	v_mfma_f32_16x16x32_bf16 v[68:71], v[216:219], v[224:227], v[68:71]
	v_mfma_f32_16x16x32_bf16 v[64:67], v[216:219], v[232:235], v[64:67]
	v_lshl_add_u64 v[198:199], v[130:131], 0, s[36:37]
	s_add_i32 m0, s99, 0x0
	s_barrier
	ds_read_b128 v[180:183], v143 offset:16384
	ds_read_b128 v[184:187], v143 offset:17408
	ds_read_b128 v[188:191], v142 offset:16384
	ds_read_b128 v[194:197], v142 offset:17408
	ds_read_b128 v[202:205], v141 offset:16384
	ds_read_b128 v[208:211], v141 offset:17408
	ds_read_b128 v[212:215], v140 offset:16384
	ds_read_b128 v[216:219], v140 offset:17408
	global_load_lds_dwordx4 v[198:199], off
	s_add_i32 m0, s99, 0x2000
	v_lshl_add_u64 v[198:199], v[130:131], 0, s[38:39]
	global_load_lds_dwordx4 v[198:199], off
	s_barrier
	s_waitcnt lgkmcnt(0)
	v_mfma_f32_16x16x32_bf16 v[60:63], v[180:183], v[164:167], v[60:63]
	v_mfma_f32_16x16x32_bf16 v[56:59], v[180:183], v[172:175], v[56:59]
	v_mfma_f32_16x16x32_bf16 v[52:55], v[188:191], v[164:167], v[52:55]
	v_mfma_f32_16x16x32_bf16 v[48:51], v[188:191], v[172:175], v[48:51]
	v_mfma_f32_16x16x32_bf16 v[44:47], v[202:205], v[164:167], v[44:47]
	v_mfma_f32_16x16x32_bf16 v[40:43], v[202:205], v[172:175], v[40:43]
	v_mfma_f32_16x16x32_bf16 v[36:39], v[212:215], v[164:167], v[36:39]
	v_mfma_f32_16x16x32_bf16 v[32:35], v[212:215], v[172:175], v[32:35]
	v_mfma_f32_16x16x32_bf16 v[60:63], v[184:187], v[168:171], v[60:63]
	v_mfma_f32_16x16x32_bf16 v[56:59], v[184:187], v[176:179], v[56:59]
	v_mfma_f32_16x16x32_bf16 v[52:55], v[194:197], v[168:171], v[52:55]
	v_mfma_f32_16x16x32_bf16 v[48:51], v[194:197], v[176:179], v[48:51]
	v_mfma_f32_16x16x32_bf16 v[44:47], v[208:211], v[168:171], v[44:47]
	v_mfma_f32_16x16x32_bf16 v[40:43], v[208:211], v[176:179], v[40:43]
	v_mfma_f32_16x16x32_bf16 v[36:39], v[216:219], v[168:171], v[36:39]
	v_mfma_f32_16x16x32_bf16 v[32:35], v[216:219], v[176:179], v[32:35]
	s_barrier
	s_add_i32 m0, s99, 0x14000
	v_lshl_add_u64 v[164:165], v[132:133], 0, s[40:41]
	global_load_lds_dwordx4 v[164:165], off
	s_add_i32 m0, s99, 0x16000
	v_lshl_add_u64 v[164:165], v[132:133], 0, s[42:43]
	global_load_lds_dwordx4 v[164:165], off
	s_waitcnt vmcnt(6)
	s_barrier
; #define STAGE_A(P, hf, kt) do { if constexpr (ABLK) { const bf16* _gp = A + ((long)(brow >> 8) * nt + (kt)) * 16384 + (hf) * 8192; GLDS2(_gp, 4096, offA, P); } \
;     else { const bf16* _gp = A + (long)(brow + (hf) * HALF) * lda + (long)(kt) * BK; GLDS2(_gp, 64 * (long)lda, offA, P); } } while (0)
; #define STAGE_B(P, hf, kt) do { const bf16* _gp = Bt + (long)(bcol + (hf) * 2) * ldb + (long)(kt) * BK; GLDS2(_gp, 128 * (long)ldb, offB, P); } while (0)
; #define LDA(dst, b, h) for (int m = 0; m < 4; ++m) for (int k = 0; k < 2; ++k) \
;     dst[m][k] = *reinterpret_cast<const bf16x8*>((char*)SA(b, h) + lds_byte(wr * 64 + m * 16 + fr, k * 32 + fq * 8))
; #define LDB(dst, b, h) for (int n = 0; n < 2; ++n) for (int k = 0; k < 2; ++k) \
;     dst[n][k] = *reinterpret_cast<const bf16x8*>((char*)SB(b, h) + lds_byte(wc * 32 + n * 16 + fr, k * 32 + fq * 8))
; #define MMA(ai, bj, At, Bt_) do { __builtin_amdgcn_s_setprio(1); \
;     for (int m = 0; m < 4; ++m) for (int n = 0; n < 2; ++n) for (int k = 0; k < 2; ++k) \
;       acc[ai][bj][m][n] = __builtin_amdgcn_mfma_f32_16x16x32_bf16(At[m][k], Bt_[n][k], acc[ai][bj][m][n], 0, 0, 0); \
;     __builtin_amdgcn_s_setprio(0); } while (0)
; #define WAIT_V(n) asm volatile("s_waitcnt vmcnt(" #n ")" ::: "memory")
; #define BAR __builtin_amdgcn_s_barrier()
; template <bool ABLK, class Epi>
; __device__ __forceinline__ void gemm_tile(const bf16* __restrict__ A, int lda, const bf16* __restrict__ Bt, int ldb, int K,
;                                           int brow, int bcol, bf16* shm, const Epi& epi, int wv) {
;     ...
;   for (int t = 0; t < nt - 2; t += 2) {
;     LDB(B0, 0, 0); SCHED; LDA(At, 0, 0); STAGE_A(SA(1, 1), 1, t + 1);
;     WAIT_L(8); BAR; MMA(0, 0, At, B0); BAR; SCHED;
;     LDB(B1, 0, 1); STAGE_B(SB(0, 0), 0, t + 2);
;     BAR; MMA(0, 1, At, B1); BAR;
;     LDA(At, 0, 1); STAGE_A(SA(0, 0), 0, t + 2);
;     BAR; MMA(1, 0, At, B0); BAR; SCHED;
;     STAGE_B(SB(0, 1), 1, t + 2);
;     WAIT_V(6); BAR; MMA(1, 1, At, B1); BAR;
;     LDB(B0, 1, 0); SCHED; LDA(At, 1, 0); STAGE_A(SA(0, 1), 1, t + 2);
;     WAIT_L(8); BAR; MMA(0, 0, At, B0); BAR; SCHED;
;     LDB(B1, 1, 1); STAGE_B(SB(1, 0), 0, t + 3);
;     BAR; MMA(0, 1, At, B1); BAR;
;     LDA(At, 1, 1); STAGE_A(SA(1, 0), 0, t + 3);
;     BAR; MMA(1, 0, At, B0); BAR; SCHED;
;     STAGE_B(SB(1, 1), 1, t + 3);
;     WAIT_V(6); BAR; MMA(1, 1, At, B1); BAR;
;   }
	v_mfma_f32_16x16x32_bf16 v[28:31], v[180:183], v[220:223], v[28:31]
	v_mfma_f32_16x16x32_bf16 v[24:27], v[180:183], v[228:231], v[24:27]
	v_mfma_f32_16x16x32_bf16 v[20:23], v[188:191], v[220:223], v[20:23]
	v_mfma_f32_16x16x32_bf16 v[16:19], v[188:191], v[228:231], v[16:19]
	v_mfma_f32_16x16x32_bf16 v[12:15], v[202:205], v[220:223], v[12:15]
	v_mfma_f32_16x16x32_bf16 v[8:11], v[202:205], v[228:231], v[8:11]
	v_mfma_f32_16x16x32_bf16 v[4:7], v[212:215], v[220:223], v[4:7]
	v_mfma_f32_16x16x32_bf16 v[0:3], v[212:215], v[228:231], v[0:3]
	v_mfma_f32_16x16x32_bf16 v[28:31], v[184:187], v[224:227], v[28:31]
	v_mfma_f32_16x16x32_bf16 v[24:27], v[184:187], v[232:235], v[24:27]
	v_mfma_f32_16x16x32_bf16 v[20:23], v[194:197], v[224:227], v[20:23]
	v_mfma_f32_16x16x32_bf16 v[16:19], v[194:197], v[232:235], v[16:19]
	v_mfma_f32_16x16x32_bf16 v[12:15], v[208:211], v[224:227], v[12:15]
	v_mfma_f32_16x16x32_bf16 v[8:11], v[208:211], v[232:235], v[8:11]
	v_mfma_f32_16x16x32_bf16 v[4:7], v[216:219], v[224:227], v[4:7]
	v_mfma_f32_16x16x32_bf16 v[0:3], v[216:219], v[232:235], v[0:3]
	s_barrier
	ds_read_b128 v[164:167], v149
	ds_read_b128 v[168:171], v149 offset:1024
	ds_read_b128 v[172:175], v149 offset:2048
	ds_read_b128 v[176:179], v149 offset:3072
	v_lshl_add_u64 v[198:199], v[130:131], 0, s[44:45]
	s_add_i32 m0, s99, 0x4000
	ds_read_b128 v[180:183], v143 offset:32768
	ds_read_b128 v[184:187], v143 offset:33792
	ds_read_b128 v[188:191], v142 offset:32768
	ds_read_b128 v[194:197], v142 offset:33792
	ds_read_b128 v[202:205], v141 offset:32768
	ds_read_b128 v[208:211], v141 offset:33792
	ds_read_b128 v[212:215], v140 offset:32768
	ds_read_b128 v[216:219], v140 offset:33792
	global_load_lds_dwordx4 v[198:199], off
	s_add_i32 m0, s99, 0x6000
	v_lshl_add_u64 v[198:199], v[130:131], 0, s[46:47]
	global_load_lds_dwordx4 v[198:199], off
	s_waitcnt lgkmcnt(8)
	s_barrier
	s_waitcnt lgkmcnt(0)
	v_mfma_f32_16x16x32_bf16 v[124:127], v[180:183], v[164:167], v[124:127]
	v_mfma_f32_16x16x32_bf16 v[120:123], v[180:183], v[172:175], v[120:123]
	v_mfma_f32_16x16x32_bf16 v[116:119], v[188:191], v[164:167], v[116:119]
	v_mfma_f32_16x16x32_bf16 v[112:115], v[188:191], v[172:175], v[112:115]
	v_mfma_f32_16x16x32_bf16 v[108:111], v[202:205], v[164:167], v[108:111]
	v_mfma_f32_16x16x32_bf16 v[104:107], v[202:205], v[172:175], v[104:107]
	v_mfma_f32_16x16x32_bf16 v[100:103], v[212:215], v[164:167], v[100:103]
	v_mfma_f32_16x16x32_bf16 v[96:99], v[212:215], v[172:175], v[96:99]
	v_mfma_f32_16x16x32_bf16 v[124:127], v[184:187], v[168:171], v[124:127]
	v_mfma_f32_16x16x32_bf16 v[120:123], v[184:187], v[176:179], v[120:123]
	v_mfma_f32_16x16x32_bf16 v[116:119], v[194:197], v[168:171], v[116:119]
	v_mfma_f32_16x16x32_bf16 v[112:115], v[194:197], v[176:179], v[112:115]
	v_mfma_f32_16x16x32_bf16 v[108:111], v[208:211], v[168:171], v[108:111]
	v_mfma_f32_16x16x32_bf16 v[104:107], v[208:211], v[176:179], v[104:107]
	v_mfma_f32_16x16x32_bf16 v[100:103], v[216:219], v[168:171], v[100:103]
	v_mfma_f32_16x16x32_bf16 v[96:99], v[216:219], v[176:179], v[96:99]
	s_barrier
	v_lshl_add_u64 v[198:199], v[132:133], 0, s[48:49]
	s_add_i32 m0, s99, 0x18000
	ds_read_b128 v[220:223], v146
	ds_read_b128 v[224:227], v146 offset:1024
	ds_read_b128 v[228:231], v146 offset:2048
	ds_read_b128 v[232:235], v146 offset:3072
	global_load_lds_dwordx4 v[198:199], off
	s_add_i32 m0, s99, 0x1a000
	v_lshl_add_u64 v[198:199], v[132:133], 0, s[50:51]
	global_load_lds_dwordx4 v[198:199], off
	s_barrier
	s_waitcnt lgkmcnt(0)
	v_mfma_f32_16x16x32_bf16 v[92:95], v[180:183], v[220:223], v[92:95]
	v_mfma_f32_16x16x32_bf16 v[88:91], v[180:183], v[228:231], v[88:91]
	v_mfma_f32_16x16x32_bf16 v[84:87], v[188:191], v[220:223], v[84:87]
	v_mfma_f32_16x16x32_bf16 v[80:83], v[188:191], v[228:231], v[80:83]
	v_mfma_f32_16x16x32_bf16 v[76:79], v[202:205], v[220:223], v[76:79]
	v_mfma_f32_16x16x32_bf16 v[72:75], v[202:205], v[228:231], v[72:75]
	v_mfma_f32_16x16x32_bf16 v[68:71], v[212:215], v[220:223], v[68:71]
	v_mfma_f32_16x16x32_bf16 v[64:67], v[212:215], v[228:231], v[64:67]
	v_mfma_f32_16x16x32_bf16 v[92:95], v[184:187], v[224:227], v[92:95]
	v_mfma_f32_16x16x32_bf16 v[88:91], v[184:187], v[232:235], v[88:91]
	v_mfma_f32_16x16x32_bf16 v[84:87], v[194:197], v[224:227], v[84:87]
	v_mfma_f32_16x16x32_bf16 v[80:83], v[194:197], v[232:235], v[80:83]
	v_mfma_f32_16x16x32_bf16 v[76:79], v[208:211], v[224:227], v[76:79]
	v_mfma_f32_16x16x32_bf16 v[72:75], v[208:211], v[232:235], v[72:75]
	v_mfma_f32_16x16x32_bf16 v[68:71], v[216:219], v[224:227], v[68:71]
	v_mfma_f32_16x16x32_bf16 v[64:67], v[216:219], v[232:235], v[64:67]
	v_lshl_add_u64 v[198:199], v[130:131], 0, s[50:51]
	s_add_i32 m0, s99, 0x8000
	s_barrier
	ds_read_b128 v[180:183], v143 offset:49152
	ds_read_b128 v[184:187], v143 offset:50176
	ds_read_b128 v[188:191], v142 offset:49152
	ds_read_b128 v[194:197], v142 offset:50176
	ds_read_b128 v[202:205], v141 offset:49152
	ds_read_b128 v[208:211], v141 offset:50176
	ds_read_b128 v[212:215], v140 offset:49152
	ds_read_b128 v[216:219], v140 offset:50176
	global_load_lds_dwordx4 v[198:199], off
	s_add_i32 m0, s99, 0xa000
	s_nop 0
	global_load_lds_dwordx4 v[130:131], off
	s_barrier
; #define STAGE_A(P, hf, kt) do { if constexpr (ABLK) { const bf16* _gp = A + ((long)(brow >> 8) * nt + (kt)) * 16384 + (hf) * 8192; GLDS2(_gp, 4096, offA, P); } \
;     else { const bf16* _gp = A + (long)(brow + (hf) * HALF) * lda + (long)(kt) * BK; GLDS2(_gp, 64 * (long)lda, offA, P); } } while (0)
; #define STAGE_B(P, hf, kt) do { const bf16* _gp = Bt + (long)(bcol + (hf) * 2) * ldb + (long)(kt) * BK; GLDS2(_gp, 128 * (long)ldb, offB, P); } while (0)
; #define LDA(dst, b, h) for (int m = 0; m < 4; ++m) for (int k = 0; k < 2; ++k) \
;     dst[m][k] = *reinterpret_cast<const bf16x8*>((char*)SA(b, h) + lds_byte(wr * 64 + m * 16 + fr, k * 32 + fq * 8))
; #define LDB(dst, b, h) for (int n = 0; n < 2; ++n) for (int k = 0; k < 2; ++k) \
;     dst[n][k] = *reinterpret_cast<const bf16x8*>((char*)SB(b, h) + lds_byte(wc * 32 + n * 16 + fr, k * 32 + fq * 8))
; #define MMA(ai, bj, At, Bt_) do { __builtin_amdgcn_s_setprio(1); \
;     for (int m = 0; m < 4; ++m) for (int n = 0; n < 2; ++n) for (int k = 0; k < 2; ++k) \
;       acc[ai][bj][m][n] = __builtin_amdgcn_mfma_f32_16x16x32_bf16(At[m][k], Bt_[n][k], acc[ai][bj][m][n], 0, 0, 0); \
;     __builtin_amdgcn_s_setprio(0); } while (0)
; #define WAIT_V(n) asm volatile("s_waitcnt vmcnt(" #n ")" ::: "memory")
; #define WAIT_L(n) asm volatile("s_waitcnt lgkmcnt(" #n ")" ::: "memory")
; #define BAR __builtin_amdgcn_s_barrier()
; #define SCHED __builtin_amdgcn_sched_barrier(0)
; template <bool ABLK, class Epi>
; __device__ __forceinline__ void gemm_tile(const bf16* __restrict__ A, int lda, const bf16* __restrict__ Bt, int ldb, int K,
;                                           int brow, int bcol, bf16* shm, const Epi& epi, int wv) {
;     ...
;     WAIT_L(8); BAR; MMA(0, 0, At, B0); BAR; SCHED;
;     LDB(B1, 1, 1); STAGE_B(SB(1, 0), 0, t + 3);
;     BAR; MMA(0, 1, At, B1); BAR;
;     LDA(At, 1, 1); STAGE_A(SA(1, 0), 0, t + 3);
;     BAR; MMA(1, 0, At, B0); BAR; SCHED;
;     STAGE_B(SB(1, 1), 1, t + 3);
;     WAIT_V(6); BAR; MMA(1, 1, At, B1); BAR;
;   }
;   { LDB(B0, 0, 0); LDA(At, 0, 0); STAGE_A(SA(1, 1), 1, nt - 1);
;     BAR; WAIT_L(0); MMA(0, 0, At, B0); BAR;
;     LDB(B1, 0, 1); BAR; WAIT_L(0); MMA(0, 1, At, B1); BAR;
;     LDA(At, 0, 1); WAIT_V(4); BAR; WAIT_L(0); MMA(1, 0, At, B0); MMA(1, 1, At, B1); BAR; }
	s_waitcnt lgkmcnt(0)
	v_mfma_f32_16x16x32_bf16 v[60:63], v[180:183], v[164:167], v[60:63]
	v_mfma_f32_16x16x32_bf16 v[56:59], v[180:183], v[172:175], v[56:59]
	v_mfma_f32_16x16x32_bf16 v[52:55], v[188:191], v[164:167], v[52:55]
	v_mfma_f32_16x16x32_bf16 v[48:51], v[188:191], v[172:175], v[48:51]
	v_mfma_f32_16x16x32_bf16 v[44:47], v[202:205], v[164:167], v[44:47]
	v_mfma_f32_16x16x32_bf16 v[40:43], v[202:205], v[172:175], v[40:43]
	v_mfma_f32_16x16x32_bf16 v[36:39], v[212:215], v[164:167], v[36:39]
	v_mfma_f32_16x16x32_bf16 v[32:35], v[212:215], v[172:175], v[32:35]
	v_mfma_f32_16x16x32_bf16 v[60:63], v[184:187], v[168:171], v[60:63]
	v_mfma_f32_16x16x32_bf16 v[56:59], v[184:187], v[176:179], v[56:59]
	v_mfma_f32_16x16x32_bf16 v[52:55], v[194:197], v[168:171], v[52:55]
	v_mfma_f32_16x16x32_bf16 v[48:51], v[194:197], v[176:179], v[48:51]
	v_mfma_f32_16x16x32_bf16 v[44:47], v[208:211], v[168:171], v[44:47]
	v_mfma_f32_16x16x32_bf16 v[40:43], v[208:211], v[176:179], v[40:43]
	v_mfma_f32_16x16x32_bf16 v[36:39], v[216:219], v[168:171], v[36:39]
	v_mfma_f32_16x16x32_bf16 v[32:35], v[216:219], v[176:179], v[32:35]
	s_barrier
	s_add_i32 m0, s99, 0x1c000
	v_lshl_add_u64 v[164:165], v[132:133], 0, s[52:53]
	global_load_lds_dwordx4 v[164:165], off
	s_add_i32 m0, s99, 0x1e000
	s_nop 0
	global_load_lds_dwordx4 v[132:133], off
	s_waitcnt vmcnt(6)
	s_barrier
	v_mfma_f32_16x16x32_bf16 v[28:31], v[180:183], v[220:223], v[28:31]
	v_mfma_f32_16x16x32_bf16 v[24:27], v[180:183], v[228:231], v[24:27]
	v_mfma_f32_16x16x32_bf16 v[20:23], v[188:191], v[220:223], v[20:23]
	v_mfma_f32_16x16x32_bf16 v[16:19], v[188:191], v[228:231], v[16:19]
	v_mfma_f32_16x16x32_bf16 v[12:15], v[202:205], v[220:223], v[12:15]
	v_mfma_f32_16x16x32_bf16 v[8:11], v[202:205], v[228:231], v[8:11]
	v_mfma_f32_16x16x32_bf16 v[4:7], v[212:215], v[220:223], v[4:7]
	v_mfma_f32_16x16x32_bf16 v[0:3], v[212:215], v[228:231], v[0:3]
	v_mfma_f32_16x16x32_bf16 v[28:31], v[184:187], v[224:227], v[28:31]
	v_mfma_f32_16x16x32_bf16 v[24:27], v[184:187], v[232:235], v[24:27]
	v_mfma_f32_16x16x32_bf16 v[20:23], v[194:197], v[224:227], v[20:23]
	v_mfma_f32_16x16x32_bf16 v[16:19], v[194:197], v[232:235], v[16:19]
	v_mfma_f32_16x16x32_bf16 v[12:15], v[208:211], v[224:227], v[12:15]
	v_mfma_f32_16x16x32_bf16 v[8:11], v[208:211], v[232:235], v[8:11]
	v_mfma_f32_16x16x32_bf16 v[4:7], v[216:219], v[224:227], v[4:7]
	v_mfma_f32_16x16x32_bf16 v[0:3], v[216:219], v[232:235], v[0:3]
	s_add_i32 s33, s33, 2
	v_lshl_add_u64 v[130:131], v[130:131], 0, s[54:55]
	s_cmp_lt_u32 s33, 28
	v_lshl_add_u64 v[132:133], v[132:133], 0, s[56:57]
	s_barrier
	s_cbranch_scc1 .LBB0_977
	v_readfirstlane_b32 s2, v162
	v_lshl_add_u64 v[144:145], v[128:129], 0, s[58:59]
	s_mov_b32 m0, s2
	v_readfirstlane_b32 s2, v163
	ds_read_b128 v[130:133], v161
	ds_read_b128 v[150:153], v161 offset:1024
	ds_read_b128 v[154:157], v161 offset:2048
	ds_read_b128 v[164:167], v161 offset:3072
	ds_read_b128 v[168:171], v143
	ds_read_b128 v[172:175], v143 offset:1024
	ds_read_b128 v[176:179], v142
	ds_read_b128 v[180:183], v142 offset:1024
	ds_read_b128 v[184:187], v141
	ds_read_b128 v[188:191], v141 offset:1024
	ds_read_b128 v[194:197], v140
	ds_read_b128 v[202:205], v140 offset:1024
	global_load_lds_dwordx4 v[144:145], off
	v_lshl_add_u64 v[128:129], v[128:129], 0, s[60:61]
	s_mov_b32 m0, s2
	s_nop 0
	global_load_lds_dwordx4 v[128:129], off
	s_barrier
	s_waitcnt lgkmcnt(0)
	s_waitcnt lgkmcnt(0)
	v_mfma_f32_16x16x32_bf16 v[124:127], v[168:171], v[130:133], v[124:127]
	v_mfma_f32_16x16x32_bf16 v[116:119], v[176:179], v[130:133], v[116:119]
	v_mfma_f32_16x16x32_bf16 v[108:111], v[184:187], v[130:133], v[108:111]
	v_mfma_f32_16x16x32_bf16 v[104:107], v[184:187], v[154:157], v[104:107]
	v_mfma_f32_16x16x32_bf16 v[100:103], v[194:197], v[130:133], v[100:103]
	v_mfma_f32_16x16x32_bf16 v[96:99], v[194:197], v[154:157], v[96:99]
	v_mfma_f32_16x16x32_bf16 v[124:127], v[172:175], v[150:153], v[124:127]
	v_mfma_f32_16x16x32_bf16 v[120:123], v[168:171], v[154:157], v[120:123]
	v_mfma_f32_16x16x32_bf16 v[116:119], v[180:183], v[150:153], v[116:119]
	v_mfma_f32_16x16x32_bf16 v[112:115], v[176:179], v[154:157], v[112:115]
	v_mfma_f32_16x16x32_bf16 v[108:111], v[188:191], v[150:153], v[108:111]
	v_mfma_f32_16x16x32_bf16 v[104:107], v[188:191], v[164:167], v[104:107]
	v_mfma_f32_16x16x32_bf16 v[100:103], v[202:205], v[150:153], v[100:103]
	v_mfma_f32_16x16x32_bf16 v[96:99], v[202:205], v[164:167], v[96:99]
	v_mfma_f32_16x16x32_bf16 v[208:211], v[172:175], v[164:167], v[120:123]
	v_mfma_f32_16x16x32_bf16 v[212:215], v[180:183], v[164:167], v[112:115]
	s_barrier
	s_nop 0
	ds_read_b128 v[112:115], v160
	ds_read_b128 v[120:123], v160 offset:1024
	ds_read_b128 v[216:219], v160 offset:2048
	ds_read_b128 v[158:161], v160 offset:3072
	s_barrier
	s_waitcnt lgkmcnt(0)
	s_waitcnt lgkmcnt(0)
	v_mfma_f32_16x16x32_bf16 v[84:87], v[176:179], v[112:115], v[84:87]
	v_mfma_f32_16x16x32_bf16 v[80:83], v[176:179], v[216:219], v[80:83]
	v_mfma_f32_16x16x32_bf16 v[92:95], v[168:171], v[112:115], v[92:95]
	v_mfma_f32_16x16x32_bf16 v[88:91], v[168:171], v[216:219], v[88:91]
	v_mfma_f32_16x16x32_bf16 v[84:87], v[180:183], v[120:123], v[84:87]
	v_mfma_f32_16x16x32_bf16 v[80:83], v[180:183], v[158:161], v[80:83]
	v_mfma_f32_16x16x32_bf16 v[76:79], v[184:187], v[112:115], v[76:79]
	v_mfma_f32_16x16x32_bf16 v[72:75], v[184:187], v[216:219], v[72:75]
	v_mfma_f32_16x16x32_bf16 v[68:71], v[194:197], v[112:115], v[68:71]
	v_mfma_f32_16x16x32_bf16 v[64:67], v[194:197], v[216:219], v[64:67]
	v_mfma_f32_16x16x32_bf16 v[220:223], v[172:175], v[120:123], v[92:95]
	v_mfma_f32_16x16x32_bf16 v[168:171], v[172:175], v[158:161], v[88:91]
	v_mfma_f32_16x16x32_bf16 v[172:175], v[188:191], v[120:123], v[76:79]
	v_mfma_f32_16x16x32_bf16 v[176:179], v[188:191], v[158:161], v[72:75]
	v_mfma_f32_16x16x32_bf16 v[180:183], v[202:205], v[120:123], v[68:71]
	v_mfma_f32_16x16x32_bf16 v[184:187], v[202:205], v[158:161], v[64:67]
	s_barrier
; #define LDA(dst, b, h) for (int m = 0; m < 4; ++m) for (int k = 0; k < 2; ++k) \
;     dst[m][k] = *reinterpret_cast<const bf16x8*>((char*)SA(b, h) + lds_byte(wr * 64 + m * 16 + fr, k * 32 + fq * 8))
; #define LDB(dst, b, h) for (int n = 0; n < 2; ++n) for (int k = 0; k < 2; ++k) \
;     dst[n][k] = *reinterpret_cast<const bf16x8*>((char*)SB(b, h) + lds_byte(wc * 32 + n * 16 + fr, k * 32 + fq * 8))
; #define MMA(ai, bj, At, Bt_) do { __builtin_amdgcn_s_setprio(1); \
;     for (int m = 0; m < 4; ++m) for (int n = 0; n < 2; ++n) for (int k = 0; k < 2; ++k) \
;       acc[ai][bj][m][n] = __builtin_amdgcn_mfma_f32_16x16x32_bf16(At[m][k], Bt_[n][k], acc[ai][bj][m][n], 0, 0, 0); \
;     __builtin_amdgcn_s_setprio(0); } while (0)
; #define WAIT_V(n) asm volatile("s_waitcnt vmcnt(" #n ")" ::: "memory")
; #define WAIT_L(n) asm volatile("s_waitcnt lgkmcnt(" #n ")" ::: "memory")
; #define BAR __builtin_amdgcn_s_barrier()
; template <bool ABLK, class Epi>
; __device__ __forceinline__ void gemm_tile(const bf16* __restrict__ A, int lda, const bf16* __restrict__ Bt, int ldb, int K,
;                                           int brow, int bcol, bf16* shm, const Epi& epi, int wv) {
;     ...
;     LDA(At, 0, 1); WAIT_V(4); BAR; WAIT_L(0); MMA(1, 0, At, B0); MMA(1, 1, At, B1); BAR; }
;   { LDB(B0, 1, 0); LDA(At, 1, 0); WAIT_V(2); BAR; WAIT_L(0); MMA(0, 0, At, B0); BAR;
;     LDB(B1, 1, 1); WAIT_V(0); BAR; WAIT_L(0); MMA(0, 1, At, B1); BAR;
	s_nop 0
	ds_read_b128 v[64:67], v143 offset:16384
	ds_read_b128 v[68:71], v143 offset:17408
	ds_read_b128 v[72:75], v142 offset:16384
	ds_read_b128 v[76:79], v142 offset:17408
	ds_read_b128 v[88:91], v141 offset:16384
	ds_read_b128 v[92:95], v141 offset:17408
	ds_read_b128 v[188:191], v140 offset:16384
	ds_read_b128 v[194:197], v140 offset:17408
	s_waitcnt vmcnt(4)
	s_barrier
	s_waitcnt lgkmcnt(0)
	s_waitcnt lgkmcnt(0)
	v_mfma_f32_16x16x32_bf16 v[60:63], v[64:67], v[130:133], v[60:63]
	v_mfma_f32_16x16x32_bf16 v[56:59], v[64:67], v[154:157], v[56:59]
	v_mfma_f32_16x16x32_bf16 v[44:47], v[88:91], v[130:133], v[44:47]
	v_mfma_f32_16x16x32_bf16 v[40:43], v[88:91], v[154:157], v[40:43]
	v_mfma_f32_16x16x32_bf16 v[60:63], v[68:71], v[150:153], v[60:63]
	v_mfma_f32_16x16x32_bf16 v[56:59], v[68:71], v[164:167], v[56:59]
	v_mfma_f32_16x16x32_bf16 v[52:55], v[72:75], v[130:133], v[52:55]
	v_mfma_f32_16x16x32_bf16 v[48:51], v[72:75], v[154:157], v[48:51]
	v_mfma_f32_16x16x32_bf16 v[44:47], v[92:95], v[150:153], v[44:47]
	v_mfma_f32_16x16x32_bf16 v[40:43], v[92:95], v[164:167], v[40:43]
	v_mfma_f32_16x16x32_bf16 v[36:39], v[188:191], v[130:133], v[36:39]
	v_mfma_f32_16x16x32_bf16 v[32:35], v[188:191], v[154:157], v[32:35]
	v_mfma_f32_16x16x32_bf16 v[202:205], v[76:79], v[150:153], v[52:55]
	v_mfma_f32_16x16x32_bf16 v[224:227], v[76:79], v[164:167], v[48:51]
	v_mfma_f32_16x16x32_bf16 v[128:131], v[194:197], v[150:153], v[36:39]
	v_mfma_f32_16x16x32_bf16 v[150:153], v[194:197], v[164:167], v[32:35]
	v_mfma_f32_16x16x32_bf16 v[28:31], v[64:67], v[112:115], v[28:31]
	v_mfma_f32_16x16x32_bf16 v[24:27], v[64:67], v[216:219], v[24:27]
	v_mfma_f32_16x16x32_bf16 v[12:15], v[88:91], v[112:115], v[12:15]
	v_mfma_f32_16x16x32_bf16 v[8:11], v[88:91], v[216:219], v[8:11]
	v_mfma_f32_16x16x32_bf16 v[28:31], v[68:71], v[120:123], v[28:31]
	v_mfma_f32_16x16x32_bf16 v[24:27], v[68:71], v[158:161], v[24:27]
	v_mfma_f32_16x16x32_bf16 v[20:23], v[72:75], v[112:115], v[20:23]
	v_mfma_f32_16x16x32_bf16 v[16:19], v[72:75], v[216:219], v[16:19]
	v_mfma_f32_16x16x32_bf16 v[12:15], v[92:95], v[120:123], v[12:15]
	v_mfma_f32_16x16x32_bf16 v[8:11], v[92:95], v[158:161], v[8:11]
	v_mfma_f32_16x16x32_bf16 v[4:7], v[188:191], v[112:115], v[4:7]
	v_mfma_f32_16x16x32_bf16 v[0:3], v[188:191], v[216:219], v[0:3]
	v_mfma_f32_16x16x32_bf16 v[154:157], v[76:79], v[120:123], v[20:23]
	v_mfma_f32_16x16x32_bf16 v[162:165], v[76:79], v[158:161], v[16:19]
	v_mfma_f32_16x16x32_bf16 v[228:231], v[194:197], v[120:123], v[4:7]
	v_mfma_f32_16x16x32_bf16 v[158:161], v[194:197], v[158:161], v[0:3]
	s_barrier
	s_nop 1
	ds_read_b128 v[0:3], v149
	ds_read_b128 v[4:7], v149 offset:1024
	ds_read_b128 v[188:191], v149 offset:2048
	ds_read_b128 v[194:197], v149 offset:3072
	ds_read_b128 v[16:19], v143 offset:32768
	ds_read_b128 v[20:23], v143 offset:33792
	ds_read_b128 v[32:35], v142 offset:32768
	ds_read_b128 v[36:39], v142 offset:33792
	ds_read_b128 v[48:51], v141 offset:32768
	ds_read_b128 v[52:55], v141 offset:33792
	ds_read_b128 v[216:219], v140 offset:32768
	ds_read_b128 v[232:235], v140 offset:33792
	s_waitcnt vmcnt(2)
	s_barrier
	s_waitcnt lgkmcnt(0)
	s_waitcnt lgkmcnt(0)
	v_mfma_f32_16x16x32_bf16 v[64:67], v[16:19], v[0:3], v[124:127]
	v_mfma_f32_16x16x32_bf16 v[120:123], v[20:23], v[4:7], v[64:67]
	v_mfma_f32_16x16x32_bf16 v[64:67], v[16:19], v[188:191], v[208:211]
	v_mfma_f32_16x16x32_bf16 v[112:115], v[20:23], v[194:197], v[64:67]
	v_mfma_f32_16x16x32_bf16 v[64:67], v[32:35], v[0:3], v[116:119]
	v_mfma_f32_16x16x32_bf16 v[88:91], v[36:39], v[4:7], v[64:67]
	v_mfma_f32_16x16x32_bf16 v[64:67], v[32:35], v[188:191], v[212:215]
	v_mfma_f32_16x16x32_bf16 v[92:95], v[36:39], v[194:197], v[64:67]
	v_mfma_f32_16x16x32_bf16 v[64:67], v[48:51], v[0:3], v[108:111]
	v_mfma_f32_16x16x32_bf16 v[72:75], v[52:55], v[4:7], v[64:67]
	v_mfma_f32_16x16x32_bf16 v[64:67], v[48:51], v[188:191], v[104:107]
	v_mfma_f32_16x16x32_bf16 v[76:79], v[52:55], v[194:197], v[64:67]
	v_mfma_f32_16x16x32_bf16 v[64:67], v[216:219], v[0:3], v[100:103]
	v_mfma_f32_16x16x32_bf16 v[68:71], v[216:219], v[188:191], v[96:99]
	v_mfma_f32_16x16x32_bf16 v[64:67], v[232:235], v[4:7], v[64:67]
	v_mfma_f32_16x16x32_bf16 v[68:71], v[232:235], v[194:197], v[68:71]
	s_barrier
; #define LDA(dst, b, h) for (int m = 0; m < 4; ++m) for (int k = 0; k < 2; ++k) \
;     dst[m][k] = *reinterpret_cast<const bf16x8*>((char*)SA(b, h) + lds_byte(wr * 64 + m * 16 + fr, k * 32 + fq * 8))
; #define LDB(dst, b, h) for (int n = 0; n < 2; ++n) for (int k = 0; k < 2; ++k) \
;     dst[n][k] = *reinterpret_cast<const bf16x8*>((char*)SB(b, h) + lds_byte(wc * 32 + n * 16 + fr, k * 32 + fq * 8))
; #define MMA(ai, bj, At, Bt_) do { __builtin_amdgcn_s_setprio(1); \
;     for (int m = 0; m < 4; ++m) for (int n = 0; n < 2; ++n) for (int k = 0; k < 2; ++k) \
;       acc[ai][bj][m][n] = __builtin_amdgcn_mfma_f32_16x16x32_bf16(At[m][k], Bt_[n][k], acc[ai][bj][m][n], 0, 0, 0); \
;     __builtin_amdgcn_s_setprio(0); } while (0)
; #define WAIT_V(n) asm volatile("s_waitcnt vmcnt(" #n ")" ::: "memory")
; #define WAIT_L(n) asm volatile("s_waitcnt lgkmcnt(" #n ")" ::: "memory")
; #define BAR __builtin_amdgcn_s_barrier()
; template <bool ABLK, class Epi>
; __device__ __forceinline__ void gemm_tile(const bf16* __restrict__ A, int lda, const bf16* __restrict__ Bt, int ldb, int K,
;                                           int brow, int bcol, bf16* shm, const Epi& epi, int wv) {
;     ...
;     LDB(B1, 1, 1); WAIT_V(0); BAR; WAIT_L(0); MMA(0, 1, At, B1); BAR;
;     LDA(At, 1, 1); BAR; WAIT_L(0); MMA(1, 0, At, B0); MMA(1, 1, At, B1); BAR; }
;   if (wr == 0) BAR;
	ds_read_b128 v[208:211], v146
	ds_read_b128 v[212:215], v146 offset:1024
	ds_read_b128 v[236:239], v146 offset:2048
	ds_read_b128 v[144:147], v146 offset:3072
	s_waitcnt vmcnt(0)
	s_barrier
	s_waitcnt lgkmcnt(0)
	s_waitcnt lgkmcnt(0)
	v_mfma_f32_16x16x32_bf16 v[96:99], v[16:19], v[208:211], v[220:223]
	v_mfma_f32_16x16x32_bf16 v[16:19], v[16:19], v[236:239], v[168:171]
	v_mfma_f32_16x16x32_bf16 v[116:119], v[20:23], v[144:147], v[16:19]
	v_mfma_f32_16x16x32_bf16 v[16:19], v[32:35], v[208:211], v[84:87]
	v_mfma_f32_16x16x32_bf16 v[104:107], v[36:39], v[212:215], v[16:19]
	v_mfma_f32_16x16x32_bf16 v[16:19], v[32:35], v[236:239], v[80:83]
	v_mfma_f32_16x16x32_bf16 v[108:111], v[36:39], v[144:147], v[16:19]
	v_mfma_f32_16x16x32_bf16 v[16:19], v[48:51], v[208:211], v[172:175]
	v_mfma_f32_16x16x32_bf16 v[124:127], v[20:23], v[212:215], v[96:99]
	v_mfma_f32_16x16x32_bf16 v[96:99], v[52:55], v[212:215], v[16:19]
	v_mfma_f32_16x16x32_bf16 v[16:19], v[48:51], v[236:239], v[176:179]
	v_mfma_f32_16x16x32_bf16 v[100:103], v[52:55], v[144:147], v[16:19]
	v_mfma_f32_16x16x32_bf16 v[16:19], v[216:219], v[208:211], v[180:183]
	v_mfma_f32_16x16x32_bf16 v[80:83], v[232:235], v[212:215], v[16:19]
	v_mfma_f32_16x16x32_bf16 v[16:19], v[216:219], v[236:239], v[184:187]
	v_mfma_f32_16x16x32_bf16 v[84:87], v[232:235], v[144:147], v[16:19]
	s_barrier
	ds_read_b128 v[166:169], v143 offset:49152
	ds_read_b128 v[170:173], v143 offset:50176
	ds_read_b128 v[174:177], v142 offset:49152
	ds_read_b128 v[178:181], v142 offset:50176
	ds_read_b128 v[182:185], v141 offset:49152
	ds_read_b128 v[216:219], v141 offset:50176
	ds_read_b128 v[220:223], v140 offset:49152
	ds_read_b128 v[140:143], v140 offset:50176
	s_barrier
	s_waitcnt lgkmcnt(0)
	s_waitcnt lgkmcnt(0)
	v_mfma_f32_16x16x32_bf16 v[16:19], v[166:169], v[0:3], v[60:63]
	v_mfma_f32_16x16x32_bf16 v[48:51], v[170:173], v[4:7], v[16:19]
	v_mfma_f32_16x16x32_bf16 v[16:19], v[166:169], v[188:191], v[56:59]
	v_mfma_f32_16x16x32_bf16 v[52:55], v[170:173], v[194:197], v[16:19]
	v_mfma_f32_16x16x32_bf16 v[16:19], v[174:177], v[0:3], v[202:205]
	v_mfma_f32_16x16x32_bf16 v[32:35], v[178:181], v[4:7], v[16:19]
	v_mfma_f32_16x16x32_bf16 v[16:19], v[174:177], v[188:191], v[224:227]
	v_mfma_f32_16x16x32_bf16 v[36:39], v[178:181], v[194:197], v[16:19]
	v_mfma_f32_16x16x32_bf16 v[16:19], v[182:185], v[0:3], v[44:47]
	v_mfma_f32_16x16x32_bf16 v[0:3], v[220:223], v[0:3], v[128:131]
	v_mfma_f32_16x16x32_bf16 v[16:19], v[216:219], v[4:7], v[16:19]
	v_mfma_f32_16x16x32_bf16 v[20:23], v[182:185], v[188:191], v[40:43]
	v_mfma_f32_16x16x32_bf16 v[0:3], v[140:143], v[4:7], v[0:3]
	v_mfma_f32_16x16x32_bf16 v[4:7], v[220:223], v[188:191], v[150:153]
	v_mfma_f32_16x16x32_bf16 v[20:23], v[216:219], v[194:197], v[20:23]
	v_mfma_f32_16x16x32_bf16 v[4:7], v[140:143], v[194:197], v[4:7]
	v_mfma_f32_16x16x32_bf16 v[24:27], v[166:169], v[236:239], v[24:27]
	v_mfma_f32_16x16x32_bf16 v[28:31], v[166:169], v[208:211], v[28:31]
	v_mfma_f32_16x16x32_bf16 v[60:63], v[170:173], v[144:147], v[24:27]
	v_mfma_f32_16x16x32_bf16 v[24:27], v[174:177], v[208:211], v[154:157]
	v_mfma_f32_16x16x32_bf16 v[8:11], v[182:185], v[236:239], v[8:11]
	v_mfma_f32_16x16x32_bf16 v[56:59], v[170:173], v[212:215], v[28:31]
	v_mfma_f32_16x16x32_bf16 v[40:43], v[178:181], v[212:215], v[24:27]
	v_mfma_f32_16x16x32_bf16 v[24:27], v[174:177], v[236:239], v[162:165]
	v_mfma_f32_16x16x32_bf16 v[12:15], v[182:185], v[208:211], v[12:15]
	v_mfma_f32_16x16x32_bf16 v[28:31], v[216:219], v[144:147], v[8:11]
	v_mfma_f32_16x16x32_bf16 v[8:11], v[220:223], v[208:211], v[228:231]
	v_mfma_f32_16x16x32_bf16 v[44:47], v[178:181], v[144:147], v[24:27]
	v_mfma_f32_16x16x32_bf16 v[24:27], v[216:219], v[212:215], v[12:15]
	v_mfma_f32_16x16x32_bf16 v[12:15], v[140:143], v[212:215], v[8:11]
	v_mfma_f32_16x16x32_bf16 v[8:11], v[220:223], v[236:239], v[158:161]
	v_mfma_f32_16x16x32_bf16 v[8:11], v[140:143], v[144:147], v[8:11]
	v_cmp_gt_u32_e32 vcc, s83, v135
	s_barrier
	s_and_saveexec_b64 s[66:67], vcc
	s_cbranch_execz .LBB0_973
	s_barrier
	s_branch .LBB0_973

; #define STAGE_A(P, hf, kt) do { if constexpr (ABLK) { const bf16* _gp = A + ((long)(brow >> 8) * nt + (kt)) * 16384 + (hf) * 8192; GLDS2(_gp, 4096, offA, P); } \
;     else { const bf16* _gp = A + (long)(brow + (hf) * HALF) * lda + (long)(kt) * BK; GLDS2(_gp, 64 * (long)lda, offA, P); } } while (0)
; #define STAGE_B(P, hf, kt) do { const bf16* _gp = Bt + (long)(bcol + (hf) * 2) * ldb + (long)(kt) * BK; GLDS2(_gp, 128 * (long)ldb, offB, P); } while (0)
; #define LDA(dst, b, h) for (int m = 0; m < 4; ++m) for (int k = 0; k < 2; ++k) \
;     dst[m][k] = *reinterpret_cast<const bf16x8*>((char*)SA(b, h) + lds_byte(wr * 64 + m * 16 + fr, k * 32 + fq * 8))
; #define LDB(dst, b, h) for (int n = 0; n < 2; ++n) for (int k = 0; k < 2; ++k) \
;     dst[n][k] = *reinterpret_cast<const bf16x8*>((char*)SB(b, h) + lds_byte(wc * 32 + n * 16 + fr, k * 32 + fq * 8))
; #define MMA(ai, bj, At, Bt_) do { __builtin_amdgcn_s_setprio(1); \
;     for (int m = 0; m < 4; ++m) for (int n = 0; n < 2; ++n) for (int k = 0; k < 2; ++k) \
;       acc[ai][bj][m][n] = __builtin_amdgcn_mfma_f32_16x16x32_bf16(At[m][k], Bt_[n][k], acc[ai][bj][m][n], 0, 0, 0); \
;     __builtin_amdgcn_s_setprio(0); } while (0)
; #define WAIT_V(n) asm volatile("s_waitcnt vmcnt(" #n ")" ::: "memory")
; #define BAR __builtin_amdgcn_s_barrier()
; template <bool ABLK, class Epi>
; __device__ __forceinline__ void gemm_tile(const bf16* __restrict__ A, int lda, const bf16* __restrict__ Bt, int ldb, int K,
;                                           int brow, int bcol, bf16* shm, const Epi& epi, int wv) {
;     ...
;   for (int t = 0; t < nt - 2; t += 2) {
;     LDB(B0, 0, 0); SCHED; LDA(At, 0, 0); STAGE_A(SA(1, 1), 1, t + 1);
;     WAIT_L(8); BAR; MMA(0, 0, At, B0); BAR; SCHED;
;     LDB(B1, 0, 1); STAGE_B(SB(0, 0), 0, t + 2);
;     BAR; MMA(0, 1, At, B1); BAR;
;     LDA(At, 0, 1); STAGE_A(SA(0, 0), 0, t + 2);
;     BAR; MMA(1, 0, At, B0); BAR; SCHED;
;     STAGE_B(SB(0, 1), 1, t + 2);
;     WAIT_V(6); BAR; MMA(1, 1, At, B1); BAR;
;     LDB(B0, 1, 0); SCHED; LDA(At, 1, 0); STAGE_A(SA(0, 1), 1, t + 2);
;     WAIT_L(8); BAR; MMA(0, 0, At, B0); BAR; SCHED;
;     LDB(B1, 1, 1); STAGE_B(SB(1, 0), 0, t + 3);
;     BAR; MMA(0, 1, At, B1); BAR;
;     LDA(At, 1, 1); STAGE_A(SA(1, 0), 0, t + 3);
;     BAR; MMA(1, 0, At, B0); BAR; SCHED;
;     STAGE_B(SB(1, 1), 1, t + 3);
;     WAIT_V(6); BAR; MMA(1, 1, At, B1); BAR;
;   }
.LBB0_1064:
	ds_read_b128 v[166:169], v162
	ds_read_b128 v[170:173], v162 offset:1024
	ds_read_b128 v[174:177], v162 offset:2048
	ds_read_b128 v[178:181], v162 offset:3072
	v_add_u32_e32 v163, 0xc000, v148
	v_lshl_add_u64 v[164:165], v[132:133], 0, s[24:25]
	s_add_i32 m0, s99, 0xc000
	ds_read_b128 v[182:185], v144
	ds_read_b128 v[186:189], v144 offset:1024
	ds_read_b128 v[194:197], v143
	ds_read_b128 v[202:205], v143 offset:1024
	ds_read_b128 v[208:211], v142
	ds_read_b128 v[212:215], v142 offset:1024
	ds_read_b128 v[216:219], v141
	ds_read_b128 v[220:223], v141 offset:1024
	global_load_lds_dwordx4 v[164:165], off
	v_add_u32_e32 v164, 0xe000, v148
	s_add_i32 m0, s99, 0xe000
	v_lshl_add_u64 v[190:191], v[132:133], 0, s[26:27]
	global_load_lds_dwordx4 v[190:191], off
	s_waitcnt lgkmcnt(8)
	s_barrier
	s_waitcnt lgkmcnt(0)
	v_mfma_f32_16x16x32_bf16 v[124:127], v[182:185], v[166:169], v[124:127]
	v_mfma_f32_16x16x32_bf16 v[120:123], v[182:185], v[174:177], v[120:123]
	v_mfma_f32_16x16x32_bf16 v[116:119], v[194:197], v[166:169], v[116:119]
	v_mfma_f32_16x16x32_bf16 v[112:115], v[194:197], v[174:177], v[112:115]
	v_mfma_f32_16x16x32_bf16 v[108:111], v[208:211], v[166:169], v[108:111]
	v_mfma_f32_16x16x32_bf16 v[104:107], v[208:211], v[174:177], v[104:107]
	v_mfma_f32_16x16x32_bf16 v[100:103], v[216:219], v[166:169], v[100:103]
	v_mfma_f32_16x16x32_bf16 v[96:99], v[216:219], v[174:177], v[96:99]
	v_mfma_f32_16x16x32_bf16 v[124:127], v[186:189], v[170:173], v[124:127]
	v_mfma_f32_16x16x32_bf16 v[120:123], v[186:189], v[178:181], v[120:123]
	v_mfma_f32_16x16x32_bf16 v[116:119], v[202:205], v[170:173], v[116:119]
	v_mfma_f32_16x16x32_bf16 v[112:115], v[202:205], v[178:181], v[112:115]
	v_mfma_f32_16x16x32_bf16 v[108:111], v[212:215], v[170:173], v[108:111]
	v_mfma_f32_16x16x32_bf16 v[104:107], v[212:215], v[178:181], v[104:107]
	v_mfma_f32_16x16x32_bf16 v[100:103], v[220:223], v[170:173], v[100:103]
	v_mfma_f32_16x16x32_bf16 v[96:99], v[220:223], v[178:181], v[96:99]
	s_barrier
	v_lshl_add_u64 v[190:191], v[134:135], 0, s[28:29]
	s_add_i32 m0, s99, 0x10000
	ds_read_b128 v[224:227], v161
	ds_read_b128 v[228:231], v161 offset:1024
	ds_read_b128 v[232:235], v161 offset:2048
	ds_read_b128 v[236:239], v161 offset:3072
	global_load_lds_dwordx4 v[190:191], off
	s_add_i32 m0, s99, 0x12000
	v_lshl_add_u64 v[190:191], v[134:135], 0, s[30:31]
	global_load_lds_dwordx4 v[190:191], off
	s_barrier
	s_waitcnt lgkmcnt(0)
	v_mfma_f32_16x16x32_bf16 v[92:95], v[182:185], v[224:227], v[92:95]
	v_mfma_f32_16x16x32_bf16 v[88:91], v[182:185], v[232:235], v[88:91]
	v_mfma_f32_16x16x32_bf16 v[84:87], v[194:197], v[224:227], v[84:87]
	v_mfma_f32_16x16x32_bf16 v[80:83], v[194:197], v[232:235], v[80:83]
	v_mfma_f32_16x16x32_bf16 v[76:79], v[208:211], v[224:227], v[76:79]
	v_mfma_f32_16x16x32_bf16 v[72:75], v[208:211], v[232:235], v[72:75]
	v_mfma_f32_16x16x32_bf16 v[68:71], v[216:219], v[224:227], v[68:71]
	v_mfma_f32_16x16x32_bf16 v[64:67], v[216:219], v[232:235], v[64:67]
	v_mfma_f32_16x16x32_bf16 v[92:95], v[186:189], v[228:231], v[92:95]
	v_mfma_f32_16x16x32_bf16 v[88:91], v[186:189], v[236:239], v[88:91]
	v_mfma_f32_16x16x32_bf16 v[84:87], v[202:205], v[228:231], v[84:87]
	v_mfma_f32_16x16x32_bf16 v[80:83], v[202:205], v[236:239], v[80:83]
	v_mfma_f32_16x16x32_bf16 v[76:79], v[212:215], v[228:231], v[76:79]
	v_mfma_f32_16x16x32_bf16 v[72:75], v[212:215], v[236:239], v[72:75]
	v_mfma_f32_16x16x32_bf16 v[68:71], v[220:223], v[228:231], v[68:71]
	v_mfma_f32_16x16x32_bf16 v[64:67], v[220:223], v[236:239], v[64:67]
	v_lshl_add_u64 v[190:191], v[132:133], 0, s[34:35]
	s_add_i32 m0, s99, 0x0
	s_barrier
	ds_read_b128 v[182:185], v144 offset:16384
	ds_read_b128 v[186:189], v144 offset:17408
	ds_read_b128 v[194:197], v143 offset:16384
	ds_read_b128 v[202:205], v143 offset:17408
	ds_read_b128 v[208:211], v142 offset:16384
	ds_read_b128 v[212:215], v142 offset:17408
	ds_read_b128 v[216:219], v141 offset:16384
	ds_read_b128 v[220:223], v141 offset:17408
	global_load_lds_dwordx4 v[190:191], off
	s_add_i32 m0, s99, 0x2000
	v_lshl_add_u64 v[190:191], v[132:133], 0, s[36:37]
	global_load_lds_dwordx4 v[190:191], off
	s_barrier
	s_waitcnt lgkmcnt(0)
	v_mfma_f32_16x16x32_bf16 v[60:63], v[182:185], v[166:169], v[60:63]
	v_mfma_f32_16x16x32_bf16 v[56:59], v[182:185], v[174:177], v[56:59]
	v_mfma_f32_16x16x32_bf16 v[52:55], v[194:197], v[166:169], v[52:55]
	v_mfma_f32_16x16x32_bf16 v[48:51], v[194:197], v[174:177], v[48:51]
	v_mfma_f32_16x16x32_bf16 v[44:47], v[208:211], v[166:169], v[44:47]
	v_mfma_f32_16x16x32_bf16 v[40:43], v[208:211], v[174:177], v[40:43]
	v_mfma_f32_16x16x32_bf16 v[36:39], v[216:219], v[166:169], v[36:39]
	v_mfma_f32_16x16x32_bf16 v[32:35], v[216:219], v[174:177], v[32:35]
	v_mfma_f32_16x16x32_bf16 v[60:63], v[186:189], v[170:173], v[60:63]
	v_mfma_f32_16x16x32_bf16 v[56:59], v[186:189], v[178:181], v[56:59]
	v_mfma_f32_16x16x32_bf16 v[52:55], v[202:205], v[170:173], v[52:55]
	v_mfma_f32_16x16x32_bf16 v[48:51], v[202:205], v[178:181], v[48:51]
	v_mfma_f32_16x16x32_bf16 v[44:47], v[212:215], v[170:173], v[44:47]
	v_mfma_f32_16x16x32_bf16 v[40:43], v[212:215], v[178:181], v[40:43]
	v_mfma_f32_16x16x32_bf16 v[36:39], v[220:223], v[170:173], v[36:39]
	v_mfma_f32_16x16x32_bf16 v[32:35], v[220:223], v[178:181], v[32:35]
	s_barrier
	s_add_i32 m0, s99, 0x14000
	v_lshl_add_u64 v[166:167], v[134:135], 0, s[38:39]
	global_load_lds_dwordx4 v[166:167], off
	s_add_i32 m0, s99, 0x16000
	v_lshl_add_u64 v[166:167], v[134:135], 0, s[40:41]
	global_load_lds_dwordx4 v[166:167], off
	s_waitcnt vmcnt(6)
	s_barrier
; #define STAGE_A(P, hf, kt) do { if constexpr (ABLK) { const bf16* _gp = A + ((long)(brow >> 8) * nt + (kt)) * 16384 + (hf) * 8192; GLDS2(_gp, 4096, offA, P); } \
;     else { const bf16* _gp = A + (long)(brow + (hf) * HALF) * lda + (long)(kt) * BK; GLDS2(_gp, 64 * (long)lda, offA, P); } } while (0)
; #define STAGE_B(P, hf, kt) do { const bf16* _gp = Bt + (long)(bcol + (hf) * 2) * ldb + (long)(kt) * BK; GLDS2(_gp, 128 * (long)ldb, offB, P); } while (0)
; #define LDA(dst, b, h) for (int m = 0; m < 4; ++m) for (int k = 0; k < 2; ++k) \
;     dst[m][k] = *reinterpret_cast<const bf16x8*>((char*)SA(b, h) + lds_byte(wr * 64 + m * 16 + fr, k * 32 + fq * 8))
; #define LDB(dst, b, h) for (int n = 0; n < 2; ++n) for (int k = 0; k < 2; ++k) \
;     dst[n][k] = *reinterpret_cast<const bf16x8*>((char*)SB(b, h) + lds_byte(wc * 32 + n * 16 + fr, k * 32 + fq * 8))
; #define MMA(ai, bj, At, Bt_) do { __builtin_amdgcn_s_setprio(1); \
;     for (int m = 0; m < 4; ++m) for (int n = 0; n < 2; ++n) for (int k = 0; k < 2; ++k) \
;       acc[ai][bj][m][n] = __builtin_amdgcn_mfma_f32_16x16x32_bf16(At[m][k], Bt_[n][k], acc[ai][bj][m][n], 0, 0, 0); \
;     __builtin_amdgcn_s_setprio(0); } while (0)
; #define WAIT_V(n) asm volatile("s_waitcnt vmcnt(" #n ")" ::: "memory")
; #define BAR __builtin_amdgcn_s_barrier()
; template <bool ABLK, class Epi>
; __device__ __forceinline__ void gemm_tile(const bf16* __restrict__ A, int lda, const bf16* __restrict__ Bt, int ldb, int K,
;                                           int brow, int bcol, bf16* shm, const Epi& epi, int wv) {
;     ...
;   for (int t = 0; t < nt - 2; t += 2) {
;     LDB(B0, 0, 0); SCHED; LDA(At, 0, 0); STAGE_A(SA(1, 1), 1, t + 1);
;     WAIT_L(8); BAR; MMA(0, 0, At, B0); BAR; SCHED;
;     LDB(B1, 0, 1); STAGE_B(SB(0, 0), 0, t + 2);
;     BAR; MMA(0, 1, At, B1); BAR;
;     LDA(At, 0, 1); STAGE_A(SA(0, 0), 0, t + 2);
;     BAR; MMA(1, 0, At, B0); BAR; SCHED;
;     STAGE_B(SB(0, 1), 1, t + 2);
;     WAIT_V(6); BAR; MMA(1, 1, At, B1); BAR;
;     LDB(B0, 1, 0); SCHED; LDA(At, 1, 0); STAGE_A(SA(0, 1), 1, t + 2);
;     WAIT_L(8); BAR; MMA(0, 0, At, B0); BAR; SCHED;
;     LDB(B1, 1, 1); STAGE_B(SB(1, 0), 0, t + 3);
;     BAR; MMA(0, 1, At, B1); BAR;
;     LDA(At, 1, 1); STAGE_A(SA(1, 0), 0, t + 3);
;     BAR; MMA(1, 0, At, B0); BAR; SCHED;
;     STAGE_B(SB(1, 1), 1, t + 3);
;     WAIT_V(6); BAR; MMA(1, 1, At, B1); BAR;
;   }
	v_mfma_f32_16x16x32_bf16 v[28:31], v[182:185], v[224:227], v[28:31]
	v_mfma_f32_16x16x32_bf16 v[24:27], v[182:185], v[232:235], v[24:27]
	v_mfma_f32_16x16x32_bf16 v[20:23], v[194:197], v[224:227], v[20:23]
	v_mfma_f32_16x16x32_bf16 v[16:19], v[194:197], v[232:235], v[16:19]
	v_mfma_f32_16x16x32_bf16 v[12:15], v[208:211], v[224:227], v[12:15]
	v_mfma_f32_16x16x32_bf16 v[8:11], v[208:211], v[232:235], v[8:11]
	v_mfma_f32_16x16x32_bf16 v[4:7], v[216:219], v[224:227], v[4:7]
	v_mfma_f32_16x16x32_bf16 v[0:3], v[216:219], v[232:235], v[0:3]
	v_mfma_f32_16x16x32_bf16 v[28:31], v[186:189], v[228:231], v[28:31]
	v_mfma_f32_16x16x32_bf16 v[24:27], v[186:189], v[236:239], v[24:27]
	v_mfma_f32_16x16x32_bf16 v[20:23], v[202:205], v[228:231], v[20:23]
	v_mfma_f32_16x16x32_bf16 v[16:19], v[202:205], v[236:239], v[16:19]
	v_mfma_f32_16x16x32_bf16 v[12:15], v[212:215], v[228:231], v[12:15]
	v_mfma_f32_16x16x32_bf16 v[8:11], v[212:215], v[236:239], v[8:11]
	v_mfma_f32_16x16x32_bf16 v[4:7], v[220:223], v[228:231], v[4:7]
	v_mfma_f32_16x16x32_bf16 v[0:3], v[220:223], v[236:239], v[0:3]
	s_barrier
	ds_read_b128 v[166:169], v150
	ds_read_b128 v[170:173], v150 offset:1024
	ds_read_b128 v[174:177], v150 offset:2048
	ds_read_b128 v[178:181], v150 offset:3072
	v_lshl_add_u64 v[190:191], v[132:133], 0, s[42:43]
	s_add_i32 m0, s99, 0x4000
	ds_read_b128 v[182:185], v144 offset:32768
	ds_read_b128 v[186:189], v144 offset:33792
	ds_read_b128 v[194:197], v143 offset:32768
	ds_read_b128 v[202:205], v143 offset:33792
	ds_read_b128 v[208:211], v142 offset:32768
	ds_read_b128 v[212:215], v142 offset:33792
	ds_read_b128 v[216:219], v141 offset:32768
	ds_read_b128 v[220:223], v141 offset:33792
	global_load_lds_dwordx4 v[190:191], off
	s_add_i32 m0, s99, 0x6000
	v_lshl_add_u64 v[190:191], v[132:133], 0, s[44:45]
	global_load_lds_dwordx4 v[190:191], off
	s_waitcnt lgkmcnt(8)
	s_barrier
	s_waitcnt lgkmcnt(0)
	v_mfma_f32_16x16x32_bf16 v[124:127], v[182:185], v[166:169], v[124:127]
	v_mfma_f32_16x16x32_bf16 v[120:123], v[182:185], v[174:177], v[120:123]
	v_mfma_f32_16x16x32_bf16 v[116:119], v[194:197], v[166:169], v[116:119]
	v_mfma_f32_16x16x32_bf16 v[112:115], v[194:197], v[174:177], v[112:115]
	v_mfma_f32_16x16x32_bf16 v[108:111], v[208:211], v[166:169], v[108:111]
	v_mfma_f32_16x16x32_bf16 v[104:107], v[208:211], v[174:177], v[104:107]
	v_mfma_f32_16x16x32_bf16 v[100:103], v[216:219], v[166:169], v[100:103]
	v_mfma_f32_16x16x32_bf16 v[96:99], v[216:219], v[174:177], v[96:99]
	v_mfma_f32_16x16x32_bf16 v[124:127], v[186:189], v[170:173], v[124:127]
	v_mfma_f32_16x16x32_bf16 v[120:123], v[186:189], v[178:181], v[120:123]
	v_mfma_f32_16x16x32_bf16 v[116:119], v[202:205], v[170:173], v[116:119]
	v_mfma_f32_16x16x32_bf16 v[112:115], v[202:205], v[178:181], v[112:115]
	v_mfma_f32_16x16x32_bf16 v[108:111], v[212:215], v[170:173], v[108:111]
	v_mfma_f32_16x16x32_bf16 v[104:107], v[212:215], v[178:181], v[104:107]
	v_mfma_f32_16x16x32_bf16 v[100:103], v[220:223], v[170:173], v[100:103]
	v_mfma_f32_16x16x32_bf16 v[96:99], v[220:223], v[178:181], v[96:99]
	s_barrier
	v_lshl_add_u64 v[190:191], v[134:135], 0, s[46:47]
	s_add_i32 m0, s99, 0x18000
	ds_read_b128 v[224:227], v147
	ds_read_b128 v[228:231], v147 offset:1024
	ds_read_b128 v[232:235], v147 offset:2048
	ds_read_b128 v[236:239], v147 offset:3072
	global_load_lds_dwordx4 v[190:191], off
	s_add_i32 m0, s99, 0x1a000
	v_lshl_add_u64 v[190:191], v[134:135], 0, s[48:49]
	global_load_lds_dwordx4 v[190:191], off
	s_barrier
	s_waitcnt lgkmcnt(0)
	v_mfma_f32_16x16x32_bf16 v[92:95], v[182:185], v[224:227], v[92:95]
	v_mfma_f32_16x16x32_bf16 v[88:91], v[182:185], v[232:235], v[88:91]
	v_mfma_f32_16x16x32_bf16 v[84:87], v[194:197], v[224:227], v[84:87]
	v_mfma_f32_16x16x32_bf16 v[80:83], v[194:197], v[232:235], v[80:83]
	v_mfma_f32_16x16x32_bf16 v[76:79], v[208:211], v[224:227], v[76:79]
	v_mfma_f32_16x16x32_bf16 v[72:75], v[208:211], v[232:235], v[72:75]
	v_mfma_f32_16x16x32_bf16 v[68:71], v[216:219], v[224:227], v[68:71]
	v_mfma_f32_16x16x32_bf16 v[64:67], v[216:219], v[232:235], v[64:67]
	v_mfma_f32_16x16x32_bf16 v[92:95], v[186:189], v[228:231], v[92:95]
	v_mfma_f32_16x16x32_bf16 v[88:91], v[186:189], v[236:239], v[88:91]
	v_mfma_f32_16x16x32_bf16 v[84:87], v[202:205], v[228:231], v[84:87]
	v_mfma_f32_16x16x32_bf16 v[80:83], v[202:205], v[236:239], v[80:83]
	v_mfma_f32_16x16x32_bf16 v[76:79], v[212:215], v[228:231], v[76:79]
	v_mfma_f32_16x16x32_bf16 v[72:75], v[212:215], v[236:239], v[72:75]
	v_mfma_f32_16x16x32_bf16 v[68:71], v[220:223], v[228:231], v[68:71]
	v_mfma_f32_16x16x32_bf16 v[64:67], v[220:223], v[236:239], v[64:67]
	v_lshl_add_u64 v[190:191], v[132:133], 0, s[48:49]
	s_add_i32 m0, s99, 0x8000
	s_barrier
	ds_read_b128 v[182:185], v144 offset:49152
	ds_read_b128 v[186:189], v144 offset:50176
	ds_read_b128 v[194:197], v143 offset:49152
	ds_read_b128 v[202:205], v143 offset:50176
	ds_read_b128 v[208:211], v142 offset:49152
	ds_read_b128 v[212:215], v142 offset:50176
	ds_read_b128 v[216:219], v141 offset:49152
	ds_read_b128 v[220:223], v141 offset:50176
	global_load_lds_dwordx4 v[190:191], off
	s_add_i32 m0, s99, 0xa000
	s_nop 0
	global_load_lds_dwordx4 v[132:133], off
	s_barrier
; #define STAGE_A(P, hf, kt) do { if constexpr (ABLK) { const bf16* _gp = A + ((long)(brow >> 8) * nt + (kt)) * 16384 + (hf) * 8192; GLDS2(_gp, 4096, offA, P); } \
;     else { const bf16* _gp = A + (long)(brow + (hf) * HALF) * lda + (long)(kt) * BK; GLDS2(_gp, 64 * (long)lda, offA, P); } } while (0)
; #define STAGE_B(P, hf, kt) do { const bf16* _gp = Bt + (long)(bcol + (hf) * 2) * ldb + (long)(kt) * BK; GLDS2(_gp, 128 * (long)ldb, offB, P); } while (0)
; #define LDA(dst, b, h) for (int m = 0; m < 4; ++m) for (int k = 0; k < 2; ++k) \
;     dst[m][k] = *reinterpret_cast<const bf16x8*>((char*)SA(b, h) + lds_byte(wr * 64 + m * 16 + fr, k * 32 + fq * 8))
; #define LDB(dst, b, h) for (int n = 0; n < 2; ++n) for (int k = 0; k < 2; ++k) \
;     dst[n][k] = *reinterpret_cast<const bf16x8*>((char*)SB(b, h) + lds_byte(wc * 32 + n * 16 + fr, k * 32 + fq * 8))
; #define MMA(ai, bj, At, Bt_) do { __builtin_amdgcn_s_setprio(1); \
;     for (int m = 0; m < 4; ++m) for (int n = 0; n < 2; ++n) for (int k = 0; k < 2; ++k) \
;       acc[ai][bj][m][n] = __builtin_amdgcn_mfma_f32_16x16x32_bf16(At[m][k], Bt_[n][k], acc[ai][bj][m][n], 0, 0, 0); \
;     __builtin_amdgcn_s_setprio(0); } while (0)
; #define WAIT_V(n) asm volatile("s_waitcnt vmcnt(" #n ")" ::: "memory")
; #define WAIT_L(n) asm volatile("s_waitcnt lgkmcnt(" #n ")" ::: "memory")
; #define BAR __builtin_amdgcn_s_barrier()
; #define SCHED __builtin_amdgcn_sched_barrier(0)
; template <bool ABLK, class Epi>
; __device__ __forceinline__ void gemm_tile(const bf16* __restrict__ A, int lda, const bf16* __restrict__ Bt, int ldb, int K,
;                                           int brow, int bcol, bf16* shm, const Epi& epi, int wv) {
;     ...
;     WAIT_L(8); BAR; MMA(0, 0, At, B0); BAR; SCHED;
;     LDB(B1, 1, 1); STAGE_B(SB(1, 0), 0, t + 3);
;     BAR; MMA(0, 1, At, B1); BAR;
;     LDA(At, 1, 1); STAGE_A(SA(1, 0), 0, t + 3);
;     BAR; MMA(1, 0, At, B0); BAR; SCHED;
;     STAGE_B(SB(1, 1), 1, t + 3);
;     WAIT_V(6); BAR; MMA(1, 1, At, B1); BAR;
;   }
;   { LDB(B0, 0, 0); LDA(At, 0, 0); STAGE_A(SA(1, 1), 1, nt - 1);
;     BAR; WAIT_L(0); MMA(0, 0, At, B0); BAR;
;     LDB(B1, 0, 1); BAR; WAIT_L(0); MMA(0, 1, At, B1); BAR;
;     LDA(At, 0, 1); WAIT_V(4); BAR; WAIT_L(0); MMA(1, 0, At, B0); MMA(1, 1, At, B1); BAR; }
	s_waitcnt lgkmcnt(0)
	v_mfma_f32_16x16x32_bf16 v[60:63], v[182:185], v[166:169], v[60:63]
	v_mfma_f32_16x16x32_bf16 v[56:59], v[182:185], v[174:177], v[56:59]
	v_mfma_f32_16x16x32_bf16 v[52:55], v[194:197], v[166:169], v[52:55]
	v_mfma_f32_16x16x32_bf16 v[48:51], v[194:197], v[174:177], v[48:51]
	v_mfma_f32_16x16x32_bf16 v[44:47], v[208:211], v[166:169], v[44:47]
	v_mfma_f32_16x16x32_bf16 v[40:43], v[208:211], v[174:177], v[40:43]
	v_mfma_f32_16x16x32_bf16 v[36:39], v[216:219], v[166:169], v[36:39]
	v_mfma_f32_16x16x32_bf16 v[32:35], v[216:219], v[174:177], v[32:35]
	v_mfma_f32_16x16x32_bf16 v[60:63], v[186:189], v[170:173], v[60:63]
	v_mfma_f32_16x16x32_bf16 v[56:59], v[186:189], v[178:181], v[56:59]
	v_mfma_f32_16x16x32_bf16 v[52:55], v[202:205], v[170:173], v[52:55]
	v_mfma_f32_16x16x32_bf16 v[48:51], v[202:205], v[178:181], v[48:51]
	v_mfma_f32_16x16x32_bf16 v[44:47], v[212:215], v[170:173], v[44:47]
	v_mfma_f32_16x16x32_bf16 v[40:43], v[212:215], v[178:181], v[40:43]
	v_mfma_f32_16x16x32_bf16 v[36:39], v[220:223], v[170:173], v[36:39]
	v_mfma_f32_16x16x32_bf16 v[32:35], v[220:223], v[178:181], v[32:35]
	s_barrier
	s_add_i32 m0, s99, 0x1c000
	v_lshl_add_u64 v[166:167], v[134:135], 0, s[50:51]
	global_load_lds_dwordx4 v[166:167], off
	s_add_i32 m0, s99, 0x1e000
	s_nop 0
	global_load_lds_dwordx4 v[134:135], off
	s_waitcnt vmcnt(6)
	s_barrier
	v_mfma_f32_16x16x32_bf16 v[28:31], v[182:185], v[224:227], v[28:31]
	v_mfma_f32_16x16x32_bf16 v[24:27], v[182:185], v[232:235], v[24:27]
	v_mfma_f32_16x16x32_bf16 v[20:23], v[194:197], v[224:227], v[20:23]
	v_mfma_f32_16x16x32_bf16 v[16:19], v[194:197], v[232:235], v[16:19]
	v_mfma_f32_16x16x32_bf16 v[12:15], v[208:211], v[224:227], v[12:15]
	v_mfma_f32_16x16x32_bf16 v[8:11], v[208:211], v[232:235], v[8:11]
	v_mfma_f32_16x16x32_bf16 v[4:7], v[216:219], v[224:227], v[4:7]
	v_mfma_f32_16x16x32_bf16 v[0:3], v[216:219], v[232:235], v[0:3]
	v_mfma_f32_16x16x32_bf16 v[28:31], v[186:189], v[228:231], v[28:31]
	v_mfma_f32_16x16x32_bf16 v[24:27], v[186:189], v[236:239], v[24:27]
	v_mfma_f32_16x16x32_bf16 v[20:23], v[202:205], v[228:231], v[20:23]
	v_mfma_f32_16x16x32_bf16 v[16:19], v[202:205], v[236:239], v[16:19]
	v_mfma_f32_16x16x32_bf16 v[12:15], v[212:215], v[228:231], v[12:15]
	v_mfma_f32_16x16x32_bf16 v[8:11], v[212:215], v[236:239], v[8:11]
	v_mfma_f32_16x16x32_bf16 v[4:7], v[220:223], v[228:231], v[4:7]
	v_mfma_f32_16x16x32_bf16 v[0:3], v[220:223], v[236:239], v[0:3]
	s_add_i32 s33, s33, 2
	v_lshl_add_u64 v[132:133], v[132:133], 0, s[52:53]
	s_cmp_lt_u32 s33, 28
	v_lshl_add_u64 v[134:135], v[134:135], 0, s[54:55]
	s_barrier
	s_cbranch_scc1 .LBB0_1064
	v_readfirstlane_b32 s2, v163
	v_lshl_add_u64 v[148:149], v[130:131], 0, s[56:57]
	s_mov_b32 m0, s2
	v_readfirstlane_b32 s2, v164
	ds_read_b128 v[132:135], v162
	ds_read_b128 v[152:155], v162 offset:1024
	ds_read_b128 v[156:159], v162 offset:2048
	ds_read_b128 v[166:169], v162 offset:3072
	ds_read_b128 v[170:173], v144
	ds_read_b128 v[174:177], v144 offset:1024
	ds_read_b128 v[178:181], v143
	ds_read_b128 v[182:185], v143 offset:1024
	ds_read_b128 v[186:189], v142
	ds_read_b128 v[194:197], v142 offset:1024
	ds_read_b128 v[202:205], v141
	ds_read_b128 v[208:211], v141 offset:1024
	global_load_lds_dwordx4 v[148:149], off
	v_lshl_add_u64 v[130:131], v[130:131], 0, s[58:59]
	s_mov_b32 m0, s2
	s_nop 0
	global_load_lds_dwordx4 v[130:131], off
	s_barrier
	s_waitcnt lgkmcnt(0)
	s_waitcnt lgkmcnt(0)
	v_mfma_f32_16x16x32_bf16 v[124:127], v[170:173], v[132:135], v[124:127]
	v_mfma_f32_16x16x32_bf16 v[120:123], v[170:173], v[156:159], v[120:123]
	v_mfma_f32_16x16x32_bf16 v[108:111], v[186:189], v[132:135], v[108:111]
	v_mfma_f32_16x16x32_bf16 v[104:107], v[186:189], v[156:159], v[104:107]
	v_mfma_f32_16x16x32_bf16 v[124:127], v[174:177], v[152:155], v[124:127]
	v_mfma_f32_16x16x32_bf16 v[120:123], v[174:177], v[166:169], v[120:123]
	v_mfma_f32_16x16x32_bf16 v[116:119], v[178:181], v[132:135], v[116:119]
	v_mfma_f32_16x16x32_bf16 v[112:115], v[178:181], v[156:159], v[112:115]
	v_mfma_f32_16x16x32_bf16 v[108:111], v[194:197], v[152:155], v[108:111]
	v_mfma_f32_16x16x32_bf16 v[104:107], v[194:197], v[166:169], v[104:107]
	v_mfma_f32_16x16x32_bf16 v[100:103], v[202:205], v[132:135], v[100:103]
	v_mfma_f32_16x16x32_bf16 v[96:99], v[202:205], v[156:159], v[96:99]
	v_mfma_f32_16x16x32_bf16 v[162:165], v[182:185], v[152:155], v[116:119]
	v_mfma_f32_16x16x32_bf16 v[212:215], v[182:185], v[166:169], v[112:115]
	v_mfma_f32_16x16x32_bf16 v[216:219], v[208:211], v[152:155], v[100:103]
	v_mfma_f32_16x16x32_bf16 v[220:223], v[208:211], v[166:169], v[96:99]
	s_barrier
	s_nop 1
	ds_read_b128 v[96:99], v161
	ds_read_b128 v[100:103], v161 offset:1024
	ds_read_b128 v[112:115], v161 offset:2048
	ds_read_b128 v[116:119], v161 offset:3072
	s_barrier
	s_waitcnt lgkmcnt(0)
	s_waitcnt lgkmcnt(0)
	v_mfma_f32_16x16x32_bf16 v[92:95], v[170:173], v[96:99], v[92:95]
	v_mfma_f32_16x16x32_bf16 v[88:91], v[170:173], v[112:115], v[88:91]
	v_mfma_f32_16x16x32_bf16 v[76:79], v[186:189], v[96:99], v[76:79]
	v_mfma_f32_16x16x32_bf16 v[72:75], v[186:189], v[112:115], v[72:75]
	v_mfma_f32_16x16x32_bf16 v[92:95], v[174:177], v[100:103], v[92:95]
	v_mfma_f32_16x16x32_bf16 v[88:91], v[174:177], v[116:119], v[88:91]
	v_mfma_f32_16x16x32_bf16 v[84:87], v[178:181], v[96:99], v[84:87]
	v_mfma_f32_16x16x32_bf16 v[80:83], v[178:181], v[112:115], v[80:83]
	v_mfma_f32_16x16x32_bf16 v[76:79], v[194:197], v[100:103], v[76:79]
	v_mfma_f32_16x16x32_bf16 v[72:75], v[194:197], v[116:119], v[72:75]
	v_mfma_f32_16x16x32_bf16 v[68:71], v[202:205], v[96:99], v[68:71]
	v_mfma_f32_16x16x32_bf16 v[64:67], v[202:205], v[112:115], v[64:67]
	v_mfma_f32_16x16x32_bf16 v[170:173], v[182:185], v[100:103], v[84:87]
	v_mfma_f32_16x16x32_bf16 v[174:177], v[182:185], v[116:119], v[80:83]
	v_mfma_f32_16x16x32_bf16 v[178:181], v[208:211], v[100:103], v[68:71]
	v_mfma_f32_16x16x32_bf16 v[182:185], v[208:211], v[116:119], v[64:67]
	s_barrier
; #define STAGE_A(P, hf, kt) do { if constexpr (ABLK) { const bf16* _gp = A + ((long)(brow >> 8) * nt + (kt)) * 16384 + (hf) * 8192; GLDS2(_gp, 4096, offA, P); } \
;     else { const bf16* _gp = A + (long)(brow + (hf) * HALF) * lda + (long)(kt) * BK; GLDS2(_gp, 64 * (long)lda, offA, P); } } while (0)
; #define LDA(dst, b, h) for (int m = 0; m < 4; ++m) for (int k = 0; k < 2; ++k) \
;     dst[m][k] = *reinterpret_cast<const bf16x8*>((char*)SA(b, h) + lds_byte(wr * 64 + m * 16 + fr, k * 32 + fq * 8))
; #define LDB(dst, b, h) for (int n = 0; n < 2; ++n) for (int k = 0; k < 2; ++k) \
;     dst[n][k] = *reinterpret_cast<const bf16x8*>((char*)SB(b, h) + lds_byte(wc * 32 + n * 16 + fr, k * 32 + fq * 8))
; #define MMA(ai, bj, At, Bt_) do { __builtin_amdgcn_s_setprio(1); \
;     for (int m = 0; m < 4; ++m) for (int n = 0; n < 2; ++n) for (int k = 0; k < 2; ++k) \
;       acc[ai][bj][m][n] = __builtin_amdgcn_mfma_f32_16x16x32_bf16(At[m][k], Bt_[n][k], acc[ai][bj][m][n], 0, 0, 0); \
;     __builtin_amdgcn_s_setprio(0); } while (0)
; #define WAIT_V(n) asm volatile("s_waitcnt vmcnt(" #n ")" ::: "memory")
; #define WAIT_L(n) asm volatile("s_waitcnt lgkmcnt(" #n ")" ::: "memory")
; #define BAR __builtin_amdgcn_s_barrier()
; template <bool ABLK, class Epi>
; __device__ __forceinline__ void gemm_tile(const bf16* __restrict__ A, int lda, const bf16* __restrict__ Bt, int ldb, int K,
;                                           int brow, int bcol, bf16* shm, const Epi& epi, int wv) {
;     ...
;   { LDB(B0, 0, 0); LDA(At, 0, 0); STAGE_A(SA(1, 1), 1, nt - 1);
;     BAR; WAIT_L(0); MMA(0, 0, At, B0); BAR;
;     LDB(B1, 0, 1); BAR; WAIT_L(0); MMA(0, 1, At, B1); BAR;
;     LDA(At, 0, 1); WAIT_V(4); BAR; WAIT_L(0); MMA(1, 0, At, B0); MMA(1, 1, At, B1); BAR; }
;   { LDB(B0, 1, 0); LDA(At, 1, 0); WAIT_V(2); BAR; WAIT_L(0); MMA(0, 0, At, B0); BAR;
;     LDB(B1, 1, 1); WAIT_V(0); BAR; WAIT_L(0); MMA(0, 1, At, B1); BAR;
;     LDA(At, 1, 1); BAR; WAIT_L(0); MMA(1, 0, At, B0); MMA(1, 1, At, B1); BAR; }
	s_nop 1
	ds_read_b128 v[64:67], v144 offset:16384
	ds_read_b128 v[68:71], v144 offset:17408
	ds_read_b128 v[80:83], v143 offset:16384
	ds_read_b128 v[84:87], v143 offset:17408
	ds_read_b128 v[186:189], v142 offset:16384
	ds_read_b128 v[194:197], v142 offset:17408
	ds_read_b128 v[202:205], v141 offset:16384
	ds_read_b128 v[208:211], v141 offset:17408
	s_waitcnt vmcnt(4)
	s_barrier
	s_waitcnt lgkmcnt(0)
	s_waitcnt lgkmcnt(0)
	v_mfma_f32_16x16x32_bf16 v[60:63], v[64:67], v[132:135], v[60:63]
	v_mfma_f32_16x16x32_bf16 v[56:59], v[64:67], v[156:159], v[56:59]
	v_mfma_f32_16x16x32_bf16 v[44:47], v[186:189], v[132:135], v[44:47]
	v_mfma_f32_16x16x32_bf16 v[40:43], v[186:189], v[156:159], v[40:43]
	v_mfma_f32_16x16x32_bf16 v[60:63], v[68:71], v[152:155], v[60:63]
	v_mfma_f32_16x16x32_bf16 v[56:59], v[68:71], v[166:169], v[56:59]
	v_mfma_f32_16x16x32_bf16 v[52:55], v[80:83], v[132:135], v[52:55]
	v_mfma_f32_16x16x32_bf16 v[48:51], v[80:83], v[156:159], v[48:51]
	v_mfma_f32_16x16x32_bf16 v[44:47], v[194:197], v[152:155], v[44:47]
	v_mfma_f32_16x16x32_bf16 v[40:43], v[194:197], v[166:169], v[40:43]
	v_mfma_f32_16x16x32_bf16 v[36:39], v[202:205], v[132:135], v[36:39]
	v_mfma_f32_16x16x32_bf16 v[32:35], v[202:205], v[156:159], v[32:35]
	v_mfma_f32_16x16x32_bf16 v[224:227], v[84:87], v[152:155], v[52:55]
	v_mfma_f32_16x16x32_bf16 v[228:231], v[84:87], v[166:169], v[48:51]
	v_mfma_f32_16x16x32_bf16 v[130:133], v[208:211], v[152:155], v[36:39]
	v_mfma_f32_16x16x32_bf16 v[152:155], v[208:211], v[166:169], v[32:35]
	v_mfma_f32_16x16x32_bf16 v[28:31], v[64:67], v[96:99], v[28:31]
	v_mfma_f32_16x16x32_bf16 v[24:27], v[64:67], v[112:115], v[24:27]
	v_mfma_f32_16x16x32_bf16 v[12:15], v[186:189], v[96:99], v[12:15]
	v_mfma_f32_16x16x32_bf16 v[8:11], v[186:189], v[112:115], v[8:11]
	v_mfma_f32_16x16x32_bf16 v[28:31], v[68:71], v[100:103], v[28:31]
	v_mfma_f32_16x16x32_bf16 v[24:27], v[68:71], v[116:119], v[24:27]
	v_mfma_f32_16x16x32_bf16 v[20:23], v[80:83], v[96:99], v[20:23]
	v_mfma_f32_16x16x32_bf16 v[16:19], v[80:83], v[112:115], v[16:19]
	v_mfma_f32_16x16x32_bf16 v[12:15], v[194:197], v[100:103], v[12:15]
	v_mfma_f32_16x16x32_bf16 v[8:11], v[194:197], v[116:119], v[8:11]
	v_mfma_f32_16x16x32_bf16 v[4:7], v[202:205], v[96:99], v[4:7]
	v_mfma_f32_16x16x32_bf16 v[0:3], v[202:205], v[112:115], v[0:3]
	v_mfma_f32_16x16x32_bf16 v[156:159], v[84:87], v[100:103], v[20:23]
	v_mfma_f32_16x16x32_bf16 v[166:169], v[84:87], v[116:119], v[16:19]
	v_mfma_f32_16x16x32_bf16 v[186:189], v[208:211], v[100:103], v[4:7]
	v_mfma_f32_16x16x32_bf16 v[194:197], v[208:211], v[116:119], v[0:3]
	s_barrier
	s_nop 1
	ds_read_b128 v[0:3], v150
	ds_read_b128 v[4:7], v150 offset:1024
	ds_read_b128 v[202:205], v150 offset:2048
	ds_read_b128 v[148:151], v150 offset:3072
	ds_read_b128 v[16:19], v144 offset:32768
	ds_read_b128 v[20:23], v144 offset:33792
	ds_read_b128 v[32:35], v143 offset:32768
	ds_read_b128 v[36:39], v143 offset:33792
	ds_read_b128 v[48:51], v142 offset:32768
	ds_read_b128 v[52:55], v142 offset:33792
	ds_read_b128 v[208:211], v141 offset:32768
	ds_read_b128 v[232:235], v141 offset:33792
	s_waitcnt vmcnt(2)
	s_barrier
	s_waitcnt lgkmcnt(0)
	s_waitcnt lgkmcnt(0)
	v_mfma_f32_16x16x32_bf16 v[64:67], v[16:19], v[0:3], v[124:127]
	v_mfma_f32_16x16x32_bf16 v[112:115], v[20:23], v[4:7], v[64:67]
	v_mfma_f32_16x16x32_bf16 v[64:67], v[16:19], v[202:205], v[120:123]
	v_mfma_f32_16x16x32_bf16 v[116:119], v[20:23], v[148:151], v[64:67]
	v_mfma_f32_16x16x32_bf16 v[64:67], v[32:35], v[0:3], v[162:165]
	v_mfma_f32_16x16x32_bf16 v[96:99], v[36:39], v[4:7], v[64:67]
	v_mfma_f32_16x16x32_bf16 v[64:67], v[32:35], v[202:205], v[212:215]
	v_mfma_f32_16x16x32_bf16 v[100:103], v[36:39], v[148:151], v[64:67]
	v_mfma_f32_16x16x32_bf16 v[64:67], v[48:51], v[0:3], v[108:111]
	v_mfma_f32_16x16x32_bf16 v[80:83], v[52:55], v[4:7], v[64:67]
	v_mfma_f32_16x16x32_bf16 v[64:67], v[48:51], v[202:205], v[104:107]
	v_mfma_f32_16x16x32_bf16 v[84:87], v[52:55], v[148:151], v[64:67]
	v_mfma_f32_16x16x32_bf16 v[64:67], v[208:211], v[0:3], v[216:219]
	v_mfma_f32_16x16x32_bf16 v[68:71], v[208:211], v[202:205], v[220:223]
	v_mfma_f32_16x16x32_bf16 v[64:67], v[232:235], v[4:7], v[64:67]
	v_mfma_f32_16x16x32_bf16 v[68:71], v[232:235], v[148:151], v[68:71]
	s_barrier
; #define STAGE_A(P, hf, kt) do { if constexpr (ABLK) { const bf16* _gp = A + ((long)(brow >> 8) * nt + (kt)) * 16384 + (hf) * 8192; GLDS2(_gp, 4096, offA, P); } \
;     else { const bf16* _gp = A + (long)(brow + (hf) * HALF) * lda + (long)(kt) * BK; GLDS2(_gp, 64 * (long)lda, offA, P); } } while (0)
; #define LDA(dst, b, h) for (int m = 0; m < 4; ++m) for (int k = 0; k < 2; ++k) \
;     dst[m][k] = *reinterpret_cast<const bf16x8*>((char*)SA(b, h) + lds_byte(wr * 64 + m * 16 + fr, k * 32 + fq * 8))
; #define LDB(dst, b, h) for (int n = 0; n < 2; ++n) for (int k = 0; k < 2; ++k) \
;     dst[n][k] = *reinterpret_cast<const bf16x8*>((char*)SB(b, h) + lds_byte(wc * 32 + n * 16 + fr, k * 32 + fq * 8))
; #define MMA(ai, bj, At, Bt_) do { __builtin_amdgcn_s_setprio(1); \
;     for (int m = 0; m < 4; ++m) for (int n = 0; n < 2; ++n) for (int k = 0; k < 2; ++k) \
;       acc[ai][bj][m][n] = __builtin_amdgcn_mfma_f32_16x16x32_bf16(At[m][k], Bt_[n][k], acc[ai][bj][m][n], 0, 0, 0); \
;     __builtin_amdgcn_s_setprio(0); } while (0)
; #define WAIT_V(n) asm volatile("s_waitcnt vmcnt(" #n ")" ::: "memory")
; #define WAIT_L(n) asm volatile("s_waitcnt lgkmcnt(" #n ")" ::: "memory")
; #define BAR __builtin_amdgcn_s_barrier()
; template <bool ABLK, class Epi>
; __device__ __forceinline__ void gemm_tile(const bf16* __restrict__ A, int lda, const bf16* __restrict__ Bt, int ldb, int K,
;                                           int brow, int bcol, bf16* shm, const Epi& epi, int wv) {
;     ...
;   { LDB(B0, 0, 0); LDA(At, 0, 0); STAGE_A(SA(1, 1), 1, nt - 1);
;     BAR; WAIT_L(0); MMA(0, 0, At, B0); BAR;
;     LDB(B1, 0, 1); BAR; WAIT_L(0); MMA(0, 1, At, B1); BAR;
;     LDA(At, 0, 1); WAIT_V(4); BAR; WAIT_L(0); MMA(1, 0, At, B0); MMA(1, 1, At, B1); BAR; }
;   { LDB(B0, 1, 0); LDA(At, 1, 0); WAIT_V(2); BAR; WAIT_L(0); MMA(0, 0, At, B0); BAR;
;     LDB(B1, 1, 1); WAIT_V(0); BAR; WAIT_L(0); MMA(0, 1, At, B1); BAR;
;     LDA(At, 1, 1); BAR; WAIT_L(0); MMA(1, 0, At, B0); MMA(1, 1, At, B1); BAR; }
;   if (wr == 0) BAR;
	ds_read_b128 v[160:163], v147
	ds_read_b128 v[212:215], v147 offset:1024
	ds_read_b128 v[216:219], v147 offset:2048
	ds_read_b128 v[220:223], v147 offset:3072
	s_waitcnt vmcnt(0)
	s_barrier
	s_waitcnt lgkmcnt(0)
	s_waitcnt lgkmcnt(0)
	v_mfma_f32_16x16x32_bf16 v[92:95], v[16:19], v[160:163], v[92:95]
	v_mfma_f32_16x16x32_bf16 v[16:19], v[16:19], v[216:219], v[88:91]
	v_mfma_f32_16x16x32_bf16 v[124:127], v[20:23], v[220:223], v[16:19]
	v_mfma_f32_16x16x32_bf16 v[16:19], v[32:35], v[160:163], v[170:173]
	v_mfma_f32_16x16x32_bf16 v[104:107], v[36:39], v[212:215], v[16:19]
	v_mfma_f32_16x16x32_bf16 v[16:19], v[32:35], v[216:219], v[174:177]
	v_mfma_f32_16x16x32_bf16 v[108:111], v[36:39], v[220:223], v[16:19]
	v_mfma_f32_16x16x32_bf16 v[16:19], v[48:51], v[160:163], v[76:79]
	v_mfma_f32_16x16x32_bf16 v[88:91], v[52:55], v[212:215], v[16:19]
	v_mfma_f32_16x16x32_bf16 v[16:19], v[48:51], v[216:219], v[72:75]
	v_mfma_f32_16x16x32_bf16 v[120:123], v[20:23], v[212:215], v[92:95]
	v_mfma_f32_16x16x32_bf16 v[92:95], v[52:55], v[220:223], v[16:19]
	v_mfma_f32_16x16x32_bf16 v[16:19], v[208:211], v[160:163], v[178:181]
	v_mfma_f32_16x16x32_bf16 v[72:75], v[232:235], v[212:215], v[16:19]
	v_mfma_f32_16x16x32_bf16 v[16:19], v[208:211], v[216:219], v[182:185]
	v_mfma_f32_16x16x32_bf16 v[76:79], v[232:235], v[220:223], v[16:19]
	s_barrier
	ds_read_b128 v[170:173], v144 offset:49152
	ds_read_b128 v[144:147], v144 offset:50176
	ds_read_b128 v[174:177], v143 offset:49152
	ds_read_b128 v[178:181], v143 offset:50176
	ds_read_b128 v[182:185], v142 offset:49152
	ds_read_b128 v[208:211], v142 offset:50176
	ds_read_b128 v[232:235], v141 offset:49152
	ds_read_b128 v[236:239], v141 offset:50176
	s_barrier
	s_waitcnt lgkmcnt(0)
	s_waitcnt lgkmcnt(0)
	v_mfma_f32_16x16x32_bf16 v[16:19], v[170:173], v[0:3], v[60:63]
	v_mfma_f32_16x16x32_bf16 v[48:51], v[144:147], v[4:7], v[16:19]
	v_mfma_f32_16x16x32_bf16 v[16:19], v[170:173], v[202:205], v[56:59]
	v_mfma_f32_16x16x32_bf16 v[52:55], v[144:147], v[148:151], v[16:19]
	v_mfma_f32_16x16x32_bf16 v[16:19], v[174:177], v[0:3], v[224:227]
	v_mfma_f32_16x16x32_bf16 v[32:35], v[178:181], v[4:7], v[16:19]
	v_mfma_f32_16x16x32_bf16 v[16:19], v[174:177], v[202:205], v[228:231]
	v_mfma_f32_16x16x32_bf16 v[36:39], v[178:181], v[148:151], v[16:19]
	v_mfma_f32_16x16x32_bf16 v[16:19], v[182:185], v[0:3], v[44:47]
	v_mfma_f32_16x16x32_bf16 v[0:3], v[232:235], v[0:3], v[130:133]
	v_mfma_f32_16x16x32_bf16 v[16:19], v[208:211], v[4:7], v[16:19]
	v_mfma_f32_16x16x32_bf16 v[20:23], v[182:185], v[202:205], v[40:43]
	v_mfma_f32_16x16x32_bf16 v[0:3], v[236:239], v[4:7], v[0:3]
	v_mfma_f32_16x16x32_bf16 v[4:7], v[232:235], v[202:205], v[152:155]
	v_mfma_f32_16x16x32_bf16 v[20:23], v[208:211], v[148:151], v[20:23]
	v_mfma_f32_16x16x32_bf16 v[4:7], v[236:239], v[148:151], v[4:7]
	v_mfma_f32_16x16x32_bf16 v[24:27], v[170:173], v[216:219], v[24:27]
	v_mfma_f32_16x16x32_bf16 v[60:63], v[144:147], v[220:223], v[24:27]
	v_mfma_f32_16x16x32_bf16 v[24:27], v[174:177], v[160:163], v[156:159]
	v_mfma_f32_16x16x32_bf16 v[28:31], v[170:173], v[160:163], v[28:31]
	v_mfma_f32_16x16x32_bf16 v[40:43], v[178:181], v[212:215], v[24:27]
	v_mfma_f32_16x16x32_bf16 v[24:27], v[174:177], v[216:219], v[166:169]
	v_mfma_f32_16x16x32_bf16 v[12:15], v[182:185], v[160:163], v[12:15]
	v_mfma_f32_16x16x32_bf16 v[8:11], v[182:185], v[216:219], v[8:11]
	v_mfma_f32_16x16x32_bf16 v[56:59], v[144:147], v[212:215], v[28:31]
	v_mfma_f32_16x16x32_bf16 v[44:47], v[178:181], v[220:223], v[24:27]
	v_mfma_f32_16x16x32_bf16 v[24:27], v[208:211], v[212:215], v[12:15]
	v_mfma_f32_16x16x32_bf16 v[28:31], v[208:211], v[220:223], v[8:11]
	v_mfma_f32_16x16x32_bf16 v[8:11], v[232:235], v[160:163], v[186:189]
	v_mfma_f32_16x16x32_bf16 v[12:15], v[232:235], v[216:219], v[194:197]
	v_mfma_f32_16x16x32_bf16 v[8:11], v[236:239], v[212:215], v[8:11]
	v_mfma_f32_16x16x32_bf16 v[12:15], v[236:239], v[220:223], v[12:15]
	v_cmp_gt_u32_e32 vcc, s82, v128
	s_barrier
	s_and_saveexec_b64 s[64:65], vcc
	s_cbranch_execz .LBB0_1060
	s_barrier
	s_branch .LBB0_1060

; #define STAGE_A(P, hf, kt) do { if constexpr (ABLK) { const bf16* _gp = A + ((long)(brow >> 8) * nt + (kt)) * 16384 + (hf) * 8192; GLDS2(_gp, 4096, offA, P); } \
;     else { const bf16* _gp = A + (long)(brow + (hf) * HALF) * lda + (long)(kt) * BK; GLDS2(_gp, 64 * (long)lda, offA, P); } } while (0)
; #define STAGE_B(P, hf, kt) do { const bf16* _gp = Bt + (long)(bcol + (hf) * 2) * ldb + (long)(kt) * BK; GLDS2(_gp, 128 * (long)ldb, offB, P); } while (0)
; #define LDA(dst, b, h) for (int m = 0; m < 4; ++m) for (int k = 0; k < 2; ++k) \
;     dst[m][k] = *reinterpret_cast<const bf16x8*>((char*)SA(b, h) + lds_byte(wr * 64 + m * 16 + fr, k * 32 + fq * 8))
; #define LDB(dst, b, h) for (int n = 0; n < 2; ++n) for (int k = 0; k < 2; ++k) \
;     dst[n][k] = *reinterpret_cast<const bf16x8*>((char*)SB(b, h) + lds_byte(wc * 32 + n * 16 + fr, k * 32 + fq * 8))
; #define MMA(ai, bj, At, Bt_) do { __builtin_amdgcn_s_setprio(1); \
;     for (int m = 0; m < 4; ++m) for (int n = 0; n < 2; ++n) for (int k = 0; k < 2; ++k) \
;       acc[ai][bj][m][n] = __builtin_amdgcn_mfma_f32_16x16x32_bf16(At[m][k], Bt_[n][k], acc[ai][bj][m][n], 0, 0, 0); \
;     __builtin_amdgcn_s_setprio(0); } while (0)
; #define WAIT_V(n) asm volatile("s_waitcnt vmcnt(" #n ")" ::: "memory")
; #define WAIT_L(n) asm volatile("s_waitcnt lgkmcnt(" #n ")" ::: "memory")
; #define BAR __builtin_amdgcn_s_barrier()
; #define SCHED __builtin_amdgcn_sched_barrier(0)
; template <bool ABLK, class Epi>
; __device__ __forceinline__ void gemm_tile(const bf16* __restrict__ A, int lda, const bf16* __restrict__ Bt, int ldb, int K,
;                                           int brow, int bcol, bf16* shm, const Epi& epi, int wv) {
;     ...
;   for (int t = 0; t < nt - 2; t += 2) {
;     LDB(B0, 0, 0); SCHED; LDA(At, 0, 0); STAGE_A(SA(1, 1), 1, t + 1);
;     WAIT_L(8); BAR; MMA(0, 0, At, B0); BAR; SCHED;
;     LDB(B1, 0, 1); STAGE_B(SB(0, 0), 0, t + 2);
;     BAR; MMA(0, 1, At, B1); BAR;
;     LDA(At, 0, 1); STAGE_A(SA(0, 0), 0, t + 2);
;     BAR; MMA(1, 0, At, B0); BAR; SCHED;
;     STAGE_B(SB(0, 1), 1, t + 2);
;     WAIT_V(6); BAR; MMA(1, 1, At, B1); BAR;
.LBB0_1111:
	ds_read_b128 v[164:167], v161
	ds_read_b128 v[168:171], v161 offset:1024
	ds_read_b128 v[172:175], v161 offset:2048
	ds_read_b128 v[176:179], v161 offset:3072
	v_add_u32_e32 v162, 0xc000, v147
	v_add_u32_e32 v163, 0xe000, v147
	v_lshl_add_u64 v[198:199], v[130:131], 0, s[28:29]
	s_add_i32 m0, s99, 0xc000
	ds_read_b128 v[180:183], v143
	ds_read_b128 v[184:187], v143 offset:1024
	ds_read_b128 v[188:191], v142
	ds_read_b128 v[194:197], v142 offset:1024
	ds_read_b128 v[202:205], v141
	ds_read_b128 v[208:211], v141 offset:1024
	ds_read_b128 v[212:215], v140
	ds_read_b128 v[216:219], v140 offset:1024
	global_load_lds_dwordx4 v[198:199], off
	s_add_i32 m0, s99, 0xe000
	v_lshl_add_u64 v[198:199], v[130:131], 0, s[30:31]
	global_load_lds_dwordx4 v[198:199], off
	s_waitcnt lgkmcnt(8)
	s_barrier
	s_waitcnt lgkmcnt(0)
	v_mfma_f32_16x16x32_bf16 v[124:127], v[180:183], v[164:167], v[124:127]
	v_mfma_f32_16x16x32_bf16 v[120:123], v[180:183], v[172:175], v[120:123]
	v_mfma_f32_16x16x32_bf16 v[116:119], v[188:191], v[164:167], v[116:119]
	v_mfma_f32_16x16x32_bf16 v[112:115], v[188:191], v[172:175], v[112:115]
	v_mfma_f32_16x16x32_bf16 v[108:111], v[202:205], v[164:167], v[108:111]
	v_mfma_f32_16x16x32_bf16 v[104:107], v[202:205], v[172:175], v[104:107]
	v_mfma_f32_16x16x32_bf16 v[100:103], v[212:215], v[164:167], v[100:103]
	v_mfma_f32_16x16x32_bf16 v[96:99], v[212:215], v[172:175], v[96:99]
	v_mfma_f32_16x16x32_bf16 v[124:127], v[184:187], v[168:171], v[124:127]
	v_mfma_f32_16x16x32_bf16 v[120:123], v[184:187], v[176:179], v[120:123]
	v_mfma_f32_16x16x32_bf16 v[116:119], v[194:197], v[168:171], v[116:119]
	v_mfma_f32_16x16x32_bf16 v[112:115], v[194:197], v[176:179], v[112:115]
	v_mfma_f32_16x16x32_bf16 v[108:111], v[208:211], v[168:171], v[108:111]
	v_mfma_f32_16x16x32_bf16 v[104:107], v[208:211], v[176:179], v[104:107]
	v_mfma_f32_16x16x32_bf16 v[100:103], v[216:219], v[168:171], v[100:103]
	v_mfma_f32_16x16x32_bf16 v[96:99], v[216:219], v[176:179], v[96:99]
	s_barrier
	v_lshl_add_u64 v[198:199], v[132:133], 0, s[34:35]
	s_add_i32 m0, s99, 0x10000
	ds_read_b128 v[220:223], v160
	ds_read_b128 v[224:227], v160 offset:1024
	ds_read_b128 v[228:231], v160 offset:2048
	ds_read_b128 v[232:235], v160 offset:3072
	global_load_lds_dwordx4 v[198:199], off
	s_add_i32 m0, s99, 0x12000
	v_lshl_add_u64 v[198:199], v[132:133], 0, s[36:37]
	global_load_lds_dwordx4 v[198:199], off
	s_barrier
	s_waitcnt lgkmcnt(0)
	v_mfma_f32_16x16x32_bf16 v[92:95], v[180:183], v[220:223], v[92:95]
	v_mfma_f32_16x16x32_bf16 v[88:91], v[180:183], v[228:231], v[88:91]
	v_mfma_f32_16x16x32_bf16 v[84:87], v[188:191], v[220:223], v[84:87]
	v_mfma_f32_16x16x32_bf16 v[80:83], v[188:191], v[228:231], v[80:83]
	v_mfma_f32_16x16x32_bf16 v[76:79], v[202:205], v[220:223], v[76:79]
	v_mfma_f32_16x16x32_bf16 v[72:75], v[202:205], v[228:231], v[72:75]
	v_mfma_f32_16x16x32_bf16 v[68:71], v[212:215], v[220:223], v[68:71]
	v_mfma_f32_16x16x32_bf16 v[64:67], v[212:215], v[228:231], v[64:67]
	v_mfma_f32_16x16x32_bf16 v[92:95], v[184:187], v[224:227], v[92:95]
	v_mfma_f32_16x16x32_bf16 v[88:91], v[184:187], v[232:235], v[88:91]
	v_mfma_f32_16x16x32_bf16 v[84:87], v[194:197], v[224:227], v[84:87]
	v_mfma_f32_16x16x32_bf16 v[80:83], v[194:197], v[232:235], v[80:83]
	v_mfma_f32_16x16x32_bf16 v[76:79], v[208:211], v[224:227], v[76:79]
	v_mfma_f32_16x16x32_bf16 v[72:75], v[208:211], v[232:235], v[72:75]
	v_mfma_f32_16x16x32_bf16 v[68:71], v[216:219], v[224:227], v[68:71]
	v_mfma_f32_16x16x32_bf16 v[64:67], v[216:219], v[232:235], v[64:67]
	v_lshl_add_u64 v[198:199], v[130:131], 0, s[38:39]
	s_add_i32 m0, s99, 0x0
	s_barrier
	ds_read_b128 v[180:183], v143 offset:16384
	ds_read_b128 v[184:187], v143 offset:17408
	ds_read_b128 v[188:191], v142 offset:16384
	ds_read_b128 v[194:197], v142 offset:17408
	ds_read_b128 v[202:205], v141 offset:16384
	ds_read_b128 v[208:211], v141 offset:17408
	ds_read_b128 v[212:215], v140 offset:16384
	ds_read_b128 v[216:219], v140 offset:17408
	global_load_lds_dwordx4 v[198:199], off
	s_add_i32 m0, s99, 0x2000
	v_lshl_add_u64 v[198:199], v[130:131], 0, s[40:41]
	global_load_lds_dwordx4 v[198:199], off
	s_barrier
	s_waitcnt lgkmcnt(0)
	v_mfma_f32_16x16x32_bf16 v[60:63], v[180:183], v[164:167], v[60:63]
	v_mfma_f32_16x16x32_bf16 v[56:59], v[180:183], v[172:175], v[56:59]
	v_mfma_f32_16x16x32_bf16 v[52:55], v[188:191], v[164:167], v[52:55]
	v_mfma_f32_16x16x32_bf16 v[48:51], v[188:191], v[172:175], v[48:51]
	v_mfma_f32_16x16x32_bf16 v[44:47], v[202:205], v[164:167], v[44:47]
	v_mfma_f32_16x16x32_bf16 v[40:43], v[202:205], v[172:175], v[40:43]
	v_mfma_f32_16x16x32_bf16 v[36:39], v[212:215], v[164:167], v[36:39]
	v_mfma_f32_16x16x32_bf16 v[32:35], v[212:215], v[172:175], v[32:35]
	v_mfma_f32_16x16x32_bf16 v[60:63], v[184:187], v[168:171], v[60:63]
	v_mfma_f32_16x16x32_bf16 v[56:59], v[184:187], v[176:179], v[56:59]
	v_mfma_f32_16x16x32_bf16 v[52:55], v[194:197], v[168:171], v[52:55]
	v_mfma_f32_16x16x32_bf16 v[48:51], v[194:197], v[176:179], v[48:51]
	v_mfma_f32_16x16x32_bf16 v[44:47], v[208:211], v[168:171], v[44:47]
	v_mfma_f32_16x16x32_bf16 v[40:43], v[208:211], v[176:179], v[40:43]
	v_mfma_f32_16x16x32_bf16 v[36:39], v[216:219], v[168:171], v[36:39]
	v_mfma_f32_16x16x32_bf16 v[32:35], v[216:219], v[176:179], v[32:35]
	s_barrier
	s_add_i32 m0, s99, 0x14000
	v_lshl_add_u64 v[164:165], v[132:133], 0, s[42:43]
	global_load_lds_dwordx4 v[164:165], off
	s_add_i32 m0, s99, 0x16000
	v_lshl_add_u64 v[164:165], v[132:133], 0, s[44:45]
	global_load_lds_dwordx4 v[164:165], off
	s_waitcnt vmcnt(6)
	s_barrier
; #define STAGE_A(P, hf, kt) do { if constexpr (ABLK) { const bf16* _gp = A + ((long)(brow >> 8) * nt + (kt)) * 16384 + (hf) * 8192; GLDS2(_gp, 4096, offA, P); } \
;     else { const bf16* _gp = A + (long)(brow + (hf) * HALF) * lda + (long)(kt) * BK; GLDS2(_gp, 64 * (long)lda, offA, P); } } while (0)
; #define STAGE_B(P, hf, kt) do { const bf16* _gp = Bt + (long)(bcol + (hf) * 2) * ldb + (long)(kt) * BK; GLDS2(_gp, 128 * (long)ldb, offB, P); } while (0)
; #define LDA(dst, b, h) for (int m = 0; m < 4; ++m) for (int k = 0; k < 2; ++k) \
;     dst[m][k] = *reinterpret_cast<const bf16x8*>((char*)SA(b, h) + lds_byte(wr * 64 + m * 16 + fr, k * 32 + fq * 8))
; #define LDB(dst, b, h) for (int n = 0; n < 2; ++n) for (int k = 0; k < 2; ++k) \
;     dst[n][k] = *reinterpret_cast<const bf16x8*>((char*)SB(b, h) + lds_byte(wc * 32 + n * 16 + fr, k * 32 + fq * 8))
; #define MMA(ai, bj, At, Bt_) do { __builtin_amdgcn_s_setprio(1); \
;     for (int m = 0; m < 4; ++m) for (int n = 0; n < 2; ++n) for (int k = 0; k < 2; ++k) \
;       acc[ai][bj][m][n] = __builtin_amdgcn_mfma_f32_16x16x32_bf16(At[m][k], Bt_[n][k], acc[ai][bj][m][n], 0, 0, 0); \
;     __builtin_amdgcn_s_setprio(0); } while (0)
; #define WAIT_V(n) asm volatile("s_waitcnt vmcnt(" #n ")" ::: "memory")
; #define WAIT_L(n) asm volatile("s_waitcnt lgkmcnt(" #n ")" ::: "memory")
; #define BAR __builtin_amdgcn_s_barrier()
; #define SCHED __builtin_amdgcn_sched_barrier(0)
; template <bool ABLK, class Epi>
; __device__ __forceinline__ void gemm_tile(const bf16* __restrict__ A, int lda, const bf16* __restrict__ Bt, int ldb, int K,
;                                           int brow, int bcol, bf16* shm, const Epi& epi, int wv) {
;     ...
;     WAIT_V(6); BAR; MMA(1, 1, At, B1); BAR;
;     LDB(B0, 1, 0); SCHED; LDA(At, 1, 0); STAGE_A(SA(0, 1), 1, t + 2);
;     WAIT_L(8); BAR; MMA(0, 0, At, B0); BAR; SCHED;
;     LDB(B1, 1, 1); STAGE_B(SB(1, 0), 0, t + 3);
;     BAR; MMA(0, 1, At, B1); BAR;
;     LDA(At, 1, 1); STAGE_A(SA(1, 0), 0, t + 3);
;     BAR; MMA(1, 0, At, B0); BAR; SCHED;
	v_mfma_f32_16x16x32_bf16 v[28:31], v[180:183], v[220:223], v[28:31]
	v_mfma_f32_16x16x32_bf16 v[24:27], v[180:183], v[228:231], v[24:27]
	v_mfma_f32_16x16x32_bf16 v[20:23], v[188:191], v[220:223], v[20:23]
	v_mfma_f32_16x16x32_bf16 v[16:19], v[188:191], v[228:231], v[16:19]
	v_mfma_f32_16x16x32_bf16 v[12:15], v[202:205], v[220:223], v[12:15]
	v_mfma_f32_16x16x32_bf16 v[8:11], v[202:205], v[228:231], v[8:11]
	v_mfma_f32_16x16x32_bf16 v[4:7], v[212:215], v[220:223], v[4:7]
	v_mfma_f32_16x16x32_bf16 v[0:3], v[212:215], v[228:231], v[0:3]
	v_mfma_f32_16x16x32_bf16 v[28:31], v[184:187], v[224:227], v[28:31]
	v_mfma_f32_16x16x32_bf16 v[24:27], v[184:187], v[232:235], v[24:27]
	v_mfma_f32_16x16x32_bf16 v[20:23], v[194:197], v[224:227], v[20:23]
	v_mfma_f32_16x16x32_bf16 v[16:19], v[194:197], v[232:235], v[16:19]
	v_mfma_f32_16x16x32_bf16 v[12:15], v[208:211], v[224:227], v[12:15]
	v_mfma_f32_16x16x32_bf16 v[8:11], v[208:211], v[232:235], v[8:11]
	v_mfma_f32_16x16x32_bf16 v[4:7], v[216:219], v[224:227], v[4:7]
	v_mfma_f32_16x16x32_bf16 v[0:3], v[216:219], v[232:235], v[0:3]
	s_barrier
	ds_read_b128 v[164:167], v149
	ds_read_b128 v[168:171], v149 offset:1024
	ds_read_b128 v[172:175], v149 offset:2048
	ds_read_b128 v[176:179], v149 offset:3072
	v_lshl_add_u64 v[198:199], v[130:131], 0, s[46:47]
	s_add_i32 m0, s99, 0x4000
	ds_read_b128 v[180:183], v143 offset:32768
	ds_read_b128 v[184:187], v143 offset:33792
	ds_read_b128 v[188:191], v142 offset:32768
	ds_read_b128 v[194:197], v142 offset:33792
	ds_read_b128 v[202:205], v141 offset:32768
	ds_read_b128 v[208:211], v141 offset:33792
	ds_read_b128 v[212:215], v140 offset:32768
	ds_read_b128 v[216:219], v140 offset:33792
	global_load_lds_dwordx4 v[198:199], off
	s_add_i32 m0, s99, 0x6000
	v_lshl_add_u64 v[198:199], v[130:131], 0, s[48:49]
	global_load_lds_dwordx4 v[198:199], off
	s_waitcnt lgkmcnt(8)
	s_barrier
	s_waitcnt lgkmcnt(0)
	v_mfma_f32_16x16x32_bf16 v[124:127], v[180:183], v[164:167], v[124:127]
	v_mfma_f32_16x16x32_bf16 v[120:123], v[180:183], v[172:175], v[120:123]
	v_mfma_f32_16x16x32_bf16 v[116:119], v[188:191], v[164:167], v[116:119]
	v_mfma_f32_16x16x32_bf16 v[112:115], v[188:191], v[172:175], v[112:115]
	v_mfma_f32_16x16x32_bf16 v[108:111], v[202:205], v[164:167], v[108:111]
	v_mfma_f32_16x16x32_bf16 v[104:107], v[202:205], v[172:175], v[104:107]
	v_mfma_f32_16x16x32_bf16 v[100:103], v[212:215], v[164:167], v[100:103]
	v_mfma_f32_16x16x32_bf16 v[96:99], v[212:215], v[172:175], v[96:99]
	v_mfma_f32_16x16x32_bf16 v[124:127], v[184:187], v[168:171], v[124:127]
	v_mfma_f32_16x16x32_bf16 v[120:123], v[184:187], v[176:179], v[120:123]
	v_mfma_f32_16x16x32_bf16 v[116:119], v[194:197], v[168:171], v[116:119]
	v_mfma_f32_16x16x32_bf16 v[112:115], v[194:197], v[176:179], v[112:115]
	v_mfma_f32_16x16x32_bf16 v[108:111], v[208:211], v[168:171], v[108:111]
	v_mfma_f32_16x16x32_bf16 v[104:107], v[208:211], v[176:179], v[104:107]
	v_mfma_f32_16x16x32_bf16 v[100:103], v[216:219], v[168:171], v[100:103]
	v_mfma_f32_16x16x32_bf16 v[96:99], v[216:219], v[176:179], v[96:99]
	s_barrier
	v_lshl_add_u64 v[198:199], v[132:133], 0, s[50:51]
	s_add_i32 m0, s99, 0x18000
	ds_read_b128 v[220:223], v144
	ds_read_b128 v[224:227], v144 offset:1024
	ds_read_b128 v[228:231], v144 offset:2048
	ds_read_b128 v[232:235], v144 offset:3072
	global_load_lds_dwordx4 v[198:199], off
	s_add_i32 m0, s99, 0x1a000
	v_lshl_add_u64 v[198:199], v[132:133], 0, s[52:53]
	global_load_lds_dwordx4 v[198:199], off
	s_barrier
	s_waitcnt lgkmcnt(0)
	v_mfma_f32_16x16x32_bf16 v[92:95], v[180:183], v[220:223], v[92:95]
	v_mfma_f32_16x16x32_bf16 v[88:91], v[180:183], v[228:231], v[88:91]
	v_mfma_f32_16x16x32_bf16 v[84:87], v[188:191], v[220:223], v[84:87]
	v_mfma_f32_16x16x32_bf16 v[80:83], v[188:191], v[228:231], v[80:83]
	v_mfma_f32_16x16x32_bf16 v[76:79], v[202:205], v[220:223], v[76:79]
	v_mfma_f32_16x16x32_bf16 v[72:75], v[202:205], v[228:231], v[72:75]
	v_mfma_f32_16x16x32_bf16 v[68:71], v[212:215], v[220:223], v[68:71]
	v_mfma_f32_16x16x32_bf16 v[64:67], v[212:215], v[228:231], v[64:67]
	v_mfma_f32_16x16x32_bf16 v[92:95], v[184:187], v[224:227], v[92:95]
	v_mfma_f32_16x16x32_bf16 v[88:91], v[184:187], v[232:235], v[88:91]
	v_mfma_f32_16x16x32_bf16 v[84:87], v[194:197], v[224:227], v[84:87]
	v_mfma_f32_16x16x32_bf16 v[80:83], v[194:197], v[232:235], v[80:83]
	v_mfma_f32_16x16x32_bf16 v[76:79], v[208:211], v[224:227], v[76:79]
	v_mfma_f32_16x16x32_bf16 v[72:75], v[208:211], v[232:235], v[72:75]
	v_mfma_f32_16x16x32_bf16 v[68:71], v[216:219], v[224:227], v[68:71]
	v_mfma_f32_16x16x32_bf16 v[64:67], v[216:219], v[232:235], v[64:67]
	v_lshl_add_u64 v[198:199], v[130:131], 0, s[54:55]
	s_add_i32 m0, s99, 0x8000
	s_barrier
	ds_read_b128 v[180:183], v143 offset:49152
	ds_read_b128 v[184:187], v143 offset:50176
	ds_read_b128 v[188:191], v142 offset:49152
	ds_read_b128 v[194:197], v142 offset:50176
	ds_read_b128 v[202:205], v141 offset:49152
	ds_read_b128 v[208:211], v141 offset:50176
	ds_read_b128 v[212:215], v140 offset:49152
	ds_read_b128 v[216:219], v140 offset:50176
	global_load_lds_dwordx4 v[198:199], off
	s_add_i32 m0, s99, 0xa000
	s_nop 0
	global_load_lds_dwordx4 v[130:131], off
	s_barrier
; #define STAGE_A(P, hf, kt) do { if constexpr (ABLK) { const bf16* _gp = A + ((long)(brow >> 8) * nt + (kt)) * 16384 + (hf) * 8192; GLDS2(_gp, 4096, offA, P); } \
;     else { const bf16* _gp = A + (long)(brow + (hf) * HALF) * lda + (long)(kt) * BK; GLDS2(_gp, 64 * (long)lda, offA, P); } } while (0)
; #define STAGE_B(P, hf, kt) do { const bf16* _gp = Bt + (long)(bcol + (hf) * 2) * ldb + (long)(kt) * BK; GLDS2(_gp, 128 * (long)ldb, offB, P); } while (0)
; #define LDA(dst, b, h) for (int m = 0; m < 4; ++m) for (int k = 0; k < 2; ++k) \
;     dst[m][k] = *reinterpret_cast<const bf16x8*>((char*)SA(b, h) + lds_byte(wr * 64 + m * 16 + fr, k * 32 + fq * 8))
; #define LDB(dst, b, h) for (int n = 0; n < 2; ++n) for (int k = 0; k < 2; ++k) \
;     dst[n][k] = *reinterpret_cast<const bf16x8*>((char*)SB(b, h) + lds_byte(wc * 32 + n * 16 + fr, k * 32 + fq * 8))
; #define MMA(ai, bj, At, Bt_) do { __builtin_amdgcn_s_setprio(1); \
;     for (int m = 0; m < 4; ++m) for (int n = 0; n < 2; ++n) for (int k = 0; k < 2; ++k) \
;       acc[ai][bj][m][n] = __builtin_amdgcn_mfma_f32_16x16x32_bf16(At[m][k], Bt_[n][k], acc[ai][bj][m][n], 0, 0, 0); \
;     __builtin_amdgcn_s_setprio(0); } while (0)
; #define WAIT_V(n) asm volatile("s_waitcnt vmcnt(" #n ")" ::: "memory")
; #define WAIT_L(n) asm volatile("s_waitcnt lgkmcnt(" #n ")" ::: "memory")
; #define BAR __builtin_amdgcn_s_barrier()
; #define SCHED __builtin_amdgcn_sched_barrier(0)
; template <bool ABLK, class Epi>
; __device__ __forceinline__ void gemm_tile(const bf16* __restrict__ A, int lda, const bf16* __restrict__ Bt, int ldb, int K,
;                                           int brow, int bcol, bf16* shm, const Epi& epi, int wv) {
;     ...
;     BAR; MMA(1, 0, At, B0); BAR; SCHED;
;     STAGE_B(SB(1, 1), 1, t + 3);
;     WAIT_V(6); BAR; MMA(1, 1, At, B1); BAR;
;   }
;   { LDB(B0, 0, 0); LDA(At, 0, 0); STAGE_A(SA(1, 1), 1, nt - 1);
;     BAR; WAIT_L(0); MMA(0, 0, At, B0); BAR;
;     LDB(B1, 0, 1); BAR; WAIT_L(0); MMA(0, 1, At, B1); BAR;
	s_waitcnt lgkmcnt(0)
	v_mfma_f32_16x16x32_bf16 v[60:63], v[180:183], v[164:167], v[60:63]
	v_mfma_f32_16x16x32_bf16 v[56:59], v[180:183], v[172:175], v[56:59]
	v_mfma_f32_16x16x32_bf16 v[52:55], v[188:191], v[164:167], v[52:55]
	v_mfma_f32_16x16x32_bf16 v[48:51], v[188:191], v[172:175], v[48:51]
	v_mfma_f32_16x16x32_bf16 v[44:47], v[202:205], v[164:167], v[44:47]
	v_mfma_f32_16x16x32_bf16 v[40:43], v[202:205], v[172:175], v[40:43]
	v_mfma_f32_16x16x32_bf16 v[36:39], v[212:215], v[164:167], v[36:39]
	v_mfma_f32_16x16x32_bf16 v[32:35], v[212:215], v[172:175], v[32:35]
	v_mfma_f32_16x16x32_bf16 v[60:63], v[184:187], v[168:171], v[60:63]
	v_mfma_f32_16x16x32_bf16 v[56:59], v[184:187], v[176:179], v[56:59]
	v_mfma_f32_16x16x32_bf16 v[52:55], v[194:197], v[168:171], v[52:55]
	v_mfma_f32_16x16x32_bf16 v[48:51], v[194:197], v[176:179], v[48:51]
	v_mfma_f32_16x16x32_bf16 v[44:47], v[208:211], v[168:171], v[44:47]
	v_mfma_f32_16x16x32_bf16 v[40:43], v[208:211], v[176:179], v[40:43]
	v_mfma_f32_16x16x32_bf16 v[36:39], v[216:219], v[168:171], v[36:39]
	v_mfma_f32_16x16x32_bf16 v[32:35], v[216:219], v[176:179], v[32:35]
	s_barrier
	s_add_i32 m0, s99, 0x1c000
	v_lshl_add_u64 v[164:165], v[132:133], 0, s[56:57]
	global_load_lds_dwordx4 v[164:165], off
	s_add_i32 m0, s99, 0x1e000
	s_nop 0
	global_load_lds_dwordx4 v[132:133], off
	s_waitcnt vmcnt(6)
	s_barrier
	v_mfma_f32_16x16x32_bf16 v[28:31], v[180:183], v[220:223], v[28:31]
	v_mfma_f32_16x16x32_bf16 v[24:27], v[180:183], v[228:231], v[24:27]
	v_mfma_f32_16x16x32_bf16 v[20:23], v[188:191], v[220:223], v[20:23]
	v_mfma_f32_16x16x32_bf16 v[16:19], v[188:191], v[228:231], v[16:19]
	v_mfma_f32_16x16x32_bf16 v[12:15], v[202:205], v[220:223], v[12:15]
	v_mfma_f32_16x16x32_bf16 v[8:11], v[202:205], v[228:231], v[8:11]
	v_mfma_f32_16x16x32_bf16 v[4:7], v[212:215], v[220:223], v[4:7]
	v_mfma_f32_16x16x32_bf16 v[0:3], v[212:215], v[228:231], v[0:3]
	v_mfma_f32_16x16x32_bf16 v[28:31], v[184:187], v[224:227], v[28:31]
	v_mfma_f32_16x16x32_bf16 v[24:27], v[184:187], v[232:235], v[24:27]
	v_mfma_f32_16x16x32_bf16 v[20:23], v[194:197], v[224:227], v[20:23]
	v_mfma_f32_16x16x32_bf16 v[16:19], v[194:197], v[232:235], v[16:19]
	v_mfma_f32_16x16x32_bf16 v[12:15], v[208:211], v[224:227], v[12:15]
	v_mfma_f32_16x16x32_bf16 v[8:11], v[208:211], v[232:235], v[8:11]
	v_mfma_f32_16x16x32_bf16 v[4:7], v[216:219], v[224:227], v[4:7]
	v_mfma_f32_16x16x32_bf16 v[0:3], v[216:219], v[232:235], v[0:3]
	s_add_i32 s33, s33, 2
	v_lshl_add_u64 v[130:131], v[130:131], 0, s[58:59]
	s_cmpk_lt_u32 s33, 0x54
	v_lshl_add_u64 v[132:133], v[132:133], 0, s[60:61]
	s_barrier
	s_cbranch_scc1 .LBB0_1111
	v_readfirstlane_b32 s2, v162
	v_lshl_add_u64 v[146:147], v[128:129], 0, s[62:63]
	s_mov_b32 m0, s2
	v_readfirstlane_b32 s2, v163
	ds_read_b128 v[130:133], v161
	ds_read_b128 v[150:153], v161 offset:1024
	ds_read_b128 v[154:157], v161 offset:2048
	ds_read_b128 v[164:167], v161 offset:3072
	ds_read_b128 v[168:171], v143
	ds_read_b128 v[172:175], v143 offset:1024
	ds_read_b128 v[176:179], v142
	ds_read_b128 v[180:183], v142 offset:1024
	ds_read_b128 v[184:187], v141
	ds_read_b128 v[188:191], v141 offset:1024
	ds_read_b128 v[194:197], v140
	ds_read_b128 v[202:205], v140 offset:1024
	global_load_lds_dwordx4 v[146:147], off
	v_lshl_add_u64 v[128:129], v[128:129], 0, s[64:65]
	s_mov_b32 m0, s2
	s_nop 0
	global_load_lds_dwordx4 v[128:129], off
	s_barrier
	s_waitcnt lgkmcnt(0)
	s_waitcnt lgkmcnt(0)
	v_mfma_f32_16x16x32_bf16 v[124:127], v[168:171], v[130:133], v[124:127]
	v_mfma_f32_16x16x32_bf16 v[116:119], v[176:179], v[130:133], v[116:119]
	v_mfma_f32_16x16x32_bf16 v[108:111], v[184:187], v[130:133], v[108:111]
	v_mfma_f32_16x16x32_bf16 v[104:107], v[184:187], v[154:157], v[104:107]
	v_mfma_f32_16x16x32_bf16 v[100:103], v[194:197], v[130:133], v[100:103]
	v_mfma_f32_16x16x32_bf16 v[96:99], v[194:197], v[154:157], v[96:99]
	v_mfma_f32_16x16x32_bf16 v[124:127], v[172:175], v[150:153], v[124:127]
	v_mfma_f32_16x16x32_bf16 v[120:123], v[168:171], v[154:157], v[120:123]
	v_mfma_f32_16x16x32_bf16 v[116:119], v[180:183], v[150:153], v[116:119]
	v_mfma_f32_16x16x32_bf16 v[112:115], v[176:179], v[154:157], v[112:115]
	v_mfma_f32_16x16x32_bf16 v[108:111], v[188:191], v[150:153], v[108:111]
	v_mfma_f32_16x16x32_bf16 v[104:107], v[188:191], v[164:167], v[104:107]
	v_mfma_f32_16x16x32_bf16 v[100:103], v[202:205], v[150:153], v[100:103]
	v_mfma_f32_16x16x32_bf16 v[96:99], v[202:205], v[164:167], v[96:99]
	v_mfma_f32_16x16x32_bf16 v[208:211], v[172:175], v[164:167], v[120:123]
	v_mfma_f32_16x16x32_bf16 v[212:215], v[180:183], v[164:167], v[112:115]
	s_barrier
	s_nop 0
	ds_read_b128 v[112:115], v160
	ds_read_b128 v[120:123], v160 offset:1024
	ds_read_b128 v[216:219], v160 offset:2048
	ds_read_b128 v[158:161], v160 offset:3072
	s_barrier
	s_waitcnt lgkmcnt(0)
	s_waitcnt lgkmcnt(0)
	v_mfma_f32_16x16x32_bf16 v[84:87], v[176:179], v[112:115], v[84:87]
	v_mfma_f32_16x16x32_bf16 v[80:83], v[176:179], v[216:219], v[80:83]
	v_mfma_f32_16x16x32_bf16 v[92:95], v[168:171], v[112:115], v[92:95]
	v_mfma_f32_16x16x32_bf16 v[88:91], v[168:171], v[216:219], v[88:91]
	v_mfma_f32_16x16x32_bf16 v[84:87], v[180:183], v[120:123], v[84:87]
	v_mfma_f32_16x16x32_bf16 v[80:83], v[180:183], v[158:161], v[80:83]
	v_mfma_f32_16x16x32_bf16 v[76:79], v[184:187], v[112:115], v[76:79]
	v_mfma_f32_16x16x32_bf16 v[72:75], v[184:187], v[216:219], v[72:75]
	v_mfma_f32_16x16x32_bf16 v[68:71], v[194:197], v[112:115], v[68:71]
	v_mfma_f32_16x16x32_bf16 v[64:67], v[194:197], v[216:219], v[64:67]
	v_mfma_f32_16x16x32_bf16 v[220:223], v[172:175], v[120:123], v[92:95]
	v_mfma_f32_16x16x32_bf16 v[168:171], v[172:175], v[158:161], v[88:91]
	v_mfma_f32_16x16x32_bf16 v[172:175], v[188:191], v[120:123], v[76:79]
	v_mfma_f32_16x16x32_bf16 v[176:179], v[188:191], v[158:161], v[72:75]
	v_mfma_f32_16x16x32_bf16 v[180:183], v[202:205], v[120:123], v[68:71]
	v_mfma_f32_16x16x32_bf16 v[184:187], v[202:205], v[158:161], v[64:67]
	s_barrier
; #define LDA(dst, b, h) for (int m = 0; m < 4; ++m) for (int k = 0; k < 2; ++k) \
;     dst[m][k] = *reinterpret_cast<const bf16x8*>((char*)SA(b, h) + lds_byte(wr * 64 + m * 16 + fr, k * 32 + fq * 8))
; #define LDB(dst, b, h) for (int n = 0; n < 2; ++n) for (int k = 0; k < 2; ++k) \
;     dst[n][k] = *reinterpret_cast<const bf16x8*>((char*)SB(b, h) + lds_byte(wc * 32 + n * 16 + fr, k * 32 + fq * 8))
; #define MMA(ai, bj, At, Bt_) do { __builtin_amdgcn_s_setprio(1); \
;     for (int m = 0; m < 4; ++m) for (int n = 0; n < 2; ++n) for (int k = 0; k < 2; ++k) \
;       acc[ai][bj][m][n] = __builtin_amdgcn_mfma_f32_16x16x32_bf16(At[m][k], Bt_[n][k], acc[ai][bj][m][n], 0, 0, 0); \
;     __builtin_amdgcn_s_setprio(0); } while (0)
; #define WAIT_V(n) asm volatile("s_waitcnt vmcnt(" #n ")" ::: "memory")
; #define WAIT_L(n) asm volatile("s_waitcnt lgkmcnt(" #n ")" ::: "memory")
; #define BAR __builtin_amdgcn_s_barrier()
; template <bool ABLK, class Epi>
; __device__ __forceinline__ void gemm_tile(const bf16* __restrict__ A, int lda, const bf16* __restrict__ Bt, int ldb, int K,
;                                           int brow, int bcol, bf16* shm, const Epi& epi, int wv) {
;     ...
;     LDA(At, 0, 1); WAIT_V(4); BAR; WAIT_L(0); MMA(1, 0, At, B0); MMA(1, 1, At, B1); BAR; }
;   { LDB(B0, 1, 0); LDA(At, 1, 0); WAIT_V(2); BAR; WAIT_L(0); MMA(0, 0, At, B0); BAR;
	s_nop 0
	ds_read_b128 v[64:67], v143 offset:16384
	ds_read_b128 v[68:71], v143 offset:17408
	ds_read_b128 v[72:75], v142 offset:16384
	ds_read_b128 v[76:79], v142 offset:17408
	ds_read_b128 v[88:91], v141 offset:16384
	ds_read_b128 v[92:95], v141 offset:17408
	ds_read_b128 v[188:191], v140 offset:16384
	ds_read_b128 v[194:197], v140 offset:17408
	s_waitcnt vmcnt(4)
	s_barrier
	s_waitcnt lgkmcnt(0)
	s_waitcnt lgkmcnt(0)
	v_mfma_f32_16x16x32_bf16 v[60:63], v[64:67], v[130:133], v[60:63]
	v_mfma_f32_16x16x32_bf16 v[56:59], v[64:67], v[154:157], v[56:59]
	v_mfma_f32_16x16x32_bf16 v[44:47], v[88:91], v[130:133], v[44:47]
	v_mfma_f32_16x16x32_bf16 v[40:43], v[88:91], v[154:157], v[40:43]
	v_mfma_f32_16x16x32_bf16 v[60:63], v[68:71], v[150:153], v[60:63]
	v_mfma_f32_16x16x32_bf16 v[56:59], v[68:71], v[164:167], v[56:59]
	v_mfma_f32_16x16x32_bf16 v[52:55], v[72:75], v[130:133], v[52:55]
	v_mfma_f32_16x16x32_bf16 v[48:51], v[72:75], v[154:157], v[48:51]
	v_mfma_f32_16x16x32_bf16 v[44:47], v[92:95], v[150:153], v[44:47]
	v_mfma_f32_16x16x32_bf16 v[40:43], v[92:95], v[164:167], v[40:43]
	v_mfma_f32_16x16x32_bf16 v[36:39], v[188:191], v[130:133], v[36:39]
	v_mfma_f32_16x16x32_bf16 v[32:35], v[188:191], v[154:157], v[32:35]
	v_mfma_f32_16x16x32_bf16 v[202:205], v[76:79], v[150:153], v[52:55]
	v_mfma_f32_16x16x32_bf16 v[224:227], v[76:79], v[164:167], v[48:51]
	v_mfma_f32_16x16x32_bf16 v[128:131], v[194:197], v[150:153], v[36:39]
	v_mfma_f32_16x16x32_bf16 v[150:153], v[194:197], v[164:167], v[32:35]
	v_mfma_f32_16x16x32_bf16 v[28:31], v[64:67], v[112:115], v[28:31]
	v_mfma_f32_16x16x32_bf16 v[24:27], v[64:67], v[216:219], v[24:27]
	v_mfma_f32_16x16x32_bf16 v[12:15], v[88:91], v[112:115], v[12:15]
	v_mfma_f32_16x16x32_bf16 v[8:11], v[88:91], v[216:219], v[8:11]
	v_mfma_f32_16x16x32_bf16 v[28:31], v[68:71], v[120:123], v[28:31]
	v_mfma_f32_16x16x32_bf16 v[24:27], v[68:71], v[158:161], v[24:27]
	v_mfma_f32_16x16x32_bf16 v[20:23], v[72:75], v[112:115], v[20:23]
	v_mfma_f32_16x16x32_bf16 v[16:19], v[72:75], v[216:219], v[16:19]
	v_mfma_f32_16x16x32_bf16 v[12:15], v[92:95], v[120:123], v[12:15]
	v_mfma_f32_16x16x32_bf16 v[8:11], v[92:95], v[158:161], v[8:11]
	v_mfma_f32_16x16x32_bf16 v[4:7], v[188:191], v[112:115], v[4:7]
	v_mfma_f32_16x16x32_bf16 v[0:3], v[188:191], v[216:219], v[0:3]
	v_mfma_f32_16x16x32_bf16 v[154:157], v[76:79], v[120:123], v[20:23]
	v_mfma_f32_16x16x32_bf16 v[162:165], v[76:79], v[158:161], v[16:19]
	v_mfma_f32_16x16x32_bf16 v[228:231], v[194:197], v[120:123], v[4:7]
	v_mfma_f32_16x16x32_bf16 v[158:161], v[194:197], v[158:161], v[0:3]
	s_barrier
	s_nop 1
	ds_read_b128 v[0:3], v149
	ds_read_b128 v[4:7], v149 offset:1024
	ds_read_b128 v[188:191], v149 offset:2048
	ds_read_b128 v[146:149], v149 offset:3072
	ds_read_b128 v[16:19], v143 offset:32768
	ds_read_b128 v[20:23], v143 offset:33792
	ds_read_b128 v[32:35], v142 offset:32768
	ds_read_b128 v[36:39], v142 offset:33792
	ds_read_b128 v[48:51], v141 offset:32768
	ds_read_b128 v[52:55], v141 offset:33792
	ds_read_b128 v[194:197], v140 offset:32768
	ds_read_b128 v[216:219], v140 offset:33792
	s_waitcnt vmcnt(2)
	s_barrier
	s_waitcnt lgkmcnt(0)
	s_waitcnt lgkmcnt(0)
	v_mfma_f32_16x16x32_bf16 v[64:67], v[16:19], v[0:3], v[124:127]
	v_mfma_f32_16x16x32_bf16 v[120:123], v[20:23], v[4:7], v[64:67]
	v_mfma_f32_16x16x32_bf16 v[64:67], v[16:19], v[188:191], v[208:211]
	v_mfma_f32_16x16x32_bf16 v[112:115], v[20:23], v[146:149], v[64:67]
	v_mfma_f32_16x16x32_bf16 v[64:67], v[32:35], v[0:3], v[116:119]
	v_mfma_f32_16x16x32_bf16 v[88:91], v[36:39], v[4:7], v[64:67]
	v_mfma_f32_16x16x32_bf16 v[64:67], v[32:35], v[188:191], v[212:215]
	v_mfma_f32_16x16x32_bf16 v[92:95], v[36:39], v[146:149], v[64:67]
	v_mfma_f32_16x16x32_bf16 v[64:67], v[48:51], v[0:3], v[108:111]
	v_mfma_f32_16x16x32_bf16 v[72:75], v[52:55], v[4:7], v[64:67]
	v_mfma_f32_16x16x32_bf16 v[64:67], v[48:51], v[188:191], v[104:107]
	v_mfma_f32_16x16x32_bf16 v[76:79], v[52:55], v[146:149], v[64:67]
	v_mfma_f32_16x16x32_bf16 v[64:67], v[194:197], v[0:3], v[100:103]
	v_mfma_f32_16x16x32_bf16 v[68:71], v[194:197], v[188:191], v[96:99]
	v_mfma_f32_16x16x32_bf16 v[64:67], v[216:219], v[4:7], v[64:67]
	v_mfma_f32_16x16x32_bf16 v[68:71], v[216:219], v[146:149], v[68:71]
	s_barrier
; #define LDA(dst, b, h) for (int m = 0; m < 4; ++m) for (int k = 0; k < 2; ++k) \
;     dst[m][k] = *reinterpret_cast<const bf16x8*>((char*)SA(b, h) + lds_byte(wr * 64 + m * 16 + fr, k * 32 + fq * 8))
; #define LDB(dst, b, h) for (int n = 0; n < 2; ++n) for (int k = 0; k < 2; ++k) \
;     dst[n][k] = *reinterpret_cast<const bf16x8*>((char*)SB(b, h) + lds_byte(wc * 32 + n * 16 + fr, k * 32 + fq * 8))
; #define MMA(ai, bj, At, Bt_) do { __builtin_amdgcn_s_setprio(1); \
;     for (int m = 0; m < 4; ++m) for (int n = 0; n < 2; ++n) for (int k = 0; k < 2; ++k) \
;       acc[ai][bj][m][n] = __builtin_amdgcn_mfma_f32_16x16x32_bf16(At[m][k], Bt_[n][k], acc[ai][bj][m][n], 0, 0, 0); \
;     __builtin_amdgcn_s_setprio(0); } while (0)
; #define WAIT_V(n) asm volatile("s_waitcnt vmcnt(" #n ")" ::: "memory")
; #define WAIT_L(n) asm volatile("s_waitcnt lgkmcnt(" #n ")" ::: "memory")
; #define BAR __builtin_amdgcn_s_barrier()
; template <bool ABLK, class Epi>
; __device__ __forceinline__ void gemm_tile(const bf16* __restrict__ A, int lda, const bf16* __restrict__ Bt, int ldb, int K,
;                                           int brow, int bcol, bf16* shm, const Epi& epi, int wv) {
;     ...
;     LDB(B1, 1, 1); WAIT_V(0); BAR; WAIT_L(0); MMA(0, 1, At, B1); BAR;
;     LDA(At, 1, 1); BAR; WAIT_L(0); MMA(1, 0, At, B0); MMA(1, 1, At, B1); BAR; }
;   if (wr == 0) BAR;
	ds_read_b128 v[208:211], v144
	ds_read_b128 v[212:215], v144 offset:1024
	ds_read_b128 v[232:235], v144 offset:2048
	ds_read_b128 v[236:239], v144 offset:3072
	s_waitcnt vmcnt(0)
	s_barrier
	s_waitcnt lgkmcnt(0)
	s_waitcnt lgkmcnt(0)
	v_mfma_f32_16x16x32_bf16 v[96:99], v[16:19], v[208:211], v[220:223]
	v_mfma_f32_16x16x32_bf16 v[16:19], v[16:19], v[232:235], v[168:171]
	v_mfma_f32_16x16x32_bf16 v[116:119], v[20:23], v[236:239], v[16:19]
	v_mfma_f32_16x16x32_bf16 v[16:19], v[32:35], v[208:211], v[84:87]
	v_mfma_f32_16x16x32_bf16 v[104:107], v[36:39], v[212:215], v[16:19]
	v_mfma_f32_16x16x32_bf16 v[16:19], v[32:35], v[232:235], v[80:83]
	v_mfma_f32_16x16x32_bf16 v[108:111], v[36:39], v[236:239], v[16:19]
	v_mfma_f32_16x16x32_bf16 v[16:19], v[48:51], v[208:211], v[172:175]
	v_mfma_f32_16x16x32_bf16 v[124:127], v[20:23], v[212:215], v[96:99]
	v_mfma_f32_16x16x32_bf16 v[96:99], v[52:55], v[212:215], v[16:19]
	v_mfma_f32_16x16x32_bf16 v[16:19], v[48:51], v[232:235], v[176:179]
	v_mfma_f32_16x16x32_bf16 v[100:103], v[52:55], v[236:239], v[16:19]
	v_mfma_f32_16x16x32_bf16 v[16:19], v[194:197], v[208:211], v[180:183]
	v_mfma_f32_16x16x32_bf16 v[80:83], v[216:219], v[212:215], v[16:19]
	v_mfma_f32_16x16x32_bf16 v[16:19], v[194:197], v[232:235], v[184:187]
	v_mfma_f32_16x16x32_bf16 v[84:87], v[216:219], v[236:239], v[16:19]
	s_barrier
	ds_read_b128 v[166:169], v143 offset:49152
	ds_read_b128 v[170:173], v143 offset:50176
	ds_read_b128 v[174:177], v142 offset:49152
	ds_read_b128 v[142:145], v142 offset:50176
	ds_read_b128 v[178:181], v141 offset:49152
	ds_read_b128 v[182:185], v141 offset:50176
	ds_read_b128 v[194:197], v140 offset:49152
	ds_read_b128 v[216:219], v140 offset:50176
	s_barrier
	s_waitcnt lgkmcnt(0)
	s_waitcnt lgkmcnt(0)
	v_mfma_f32_16x16x32_bf16 v[16:19], v[166:169], v[0:3], v[60:63]
	v_mfma_f32_16x16x32_bf16 v[48:51], v[170:173], v[4:7], v[16:19]
	v_mfma_f32_16x16x32_bf16 v[16:19], v[166:169], v[188:191], v[56:59]
	v_mfma_f32_16x16x32_bf16 v[52:55], v[170:173], v[146:149], v[16:19]
	v_mfma_f32_16x16x32_bf16 v[16:19], v[174:177], v[0:3], v[202:205]
	v_mfma_f32_16x16x32_bf16 v[32:35], v[142:145], v[4:7], v[16:19]
	v_mfma_f32_16x16x32_bf16 v[16:19], v[174:177], v[188:191], v[224:227]
	v_mfma_f32_16x16x32_bf16 v[36:39], v[142:145], v[146:149], v[16:19]
	v_mfma_f32_16x16x32_bf16 v[16:19], v[178:181], v[0:3], v[44:47]
	v_mfma_f32_16x16x32_bf16 v[0:3], v[194:197], v[0:3], v[128:131]
	v_mfma_f32_16x16x32_bf16 v[16:19], v[182:185], v[4:7], v[16:19]
	v_mfma_f32_16x16x32_bf16 v[20:23], v[178:181], v[188:191], v[40:43]
	v_mfma_f32_16x16x32_bf16 v[0:3], v[216:219], v[4:7], v[0:3]
	v_mfma_f32_16x16x32_bf16 v[4:7], v[194:197], v[188:191], v[150:153]
	v_mfma_f32_16x16x32_bf16 v[20:23], v[182:185], v[146:149], v[20:23]
	v_mfma_f32_16x16x32_bf16 v[4:7], v[216:219], v[146:149], v[4:7]
	v_mfma_f32_16x16x32_bf16 v[24:27], v[166:169], v[232:235], v[24:27]
	v_mfma_f32_16x16x32_bf16 v[28:31], v[166:169], v[208:211], v[28:31]
	v_mfma_f32_16x16x32_bf16 v[60:63], v[170:173], v[236:239], v[24:27]
	v_mfma_f32_16x16x32_bf16 v[24:27], v[174:177], v[208:211], v[154:157]
	v_mfma_f32_16x16x32_bf16 v[8:11], v[178:181], v[232:235], v[8:11]
	v_mfma_f32_16x16x32_bf16 v[56:59], v[170:173], v[212:215], v[28:31]
	v_mfma_f32_16x16x32_bf16 v[40:43], v[142:145], v[212:215], v[24:27]
	v_mfma_f32_16x16x32_bf16 v[24:27], v[174:177], v[232:235], v[162:165]
	v_mfma_f32_16x16x32_bf16 v[12:15], v[178:181], v[208:211], v[12:15]
	v_mfma_f32_16x16x32_bf16 v[28:31], v[182:185], v[236:239], v[8:11]
	v_mfma_f32_16x16x32_bf16 v[8:11], v[194:197], v[208:211], v[228:231]
	v_mfma_f32_16x16x32_bf16 v[44:47], v[142:145], v[236:239], v[24:27]
	v_mfma_f32_16x16x32_bf16 v[24:27], v[182:185], v[212:215], v[12:15]
	v_mfma_f32_16x16x32_bf16 v[12:15], v[216:219], v[212:215], v[8:11]
	v_mfma_f32_16x16x32_bf16 v[8:11], v[194:197], v[232:235], v[158:161]
	v_mfma_f32_16x16x32_bf16 v[8:11], v[216:219], v[236:239], v[8:11]
	v_cmp_gt_u32_e32 vcc, s81, v135
	s_barrier
	s_and_saveexec_b64 s[66:67], vcc
	s_cbranch_execz .LBB0_1107
	s_barrier
	s_branch .LBB0_1107
